# RWKV scan rewritten: shared LDS ring per workgroup with LDS progress counters (4x less record traffic), conflict-free slot layout, batched y reduction, 2-step LDS lookahead; plus GEMM epilogue load ho
# speedup vs baseline: 1.1524x; 1.0758x over previous
; DEVINL int otid() { int t = threadIdx.x; asm volatile("" : "+v"(t)); return t; }
; DEVINL void phase3(const Params& p) {
;   const int tid = otid(); const int wave = tid >> 6, lane = tid & 63;
;   const int nb = gridDim.x;
;   int vb = blockIdx.x;
;   if ((nb & 7) == 0) vb = (blockIdx.x & 7) * (nb >> 3) + (blockIdx.x >> 3);
;   if (wave < 4) {
.LBB0_439:
	s_or_b64 exec, exec, s[0:1]
	s_and_b32 s0, s94, 7
	s_waitcnt lgkmcnt(0)
	v_mov_b32_e32 v1, v189
	s_cmp_lg_u32 s0, 0
	s_mov_b32 s38, s2
	v_mov_b32_e32 v2, 0
	v_mov_b32_e32 v3, 0
	v_mov_b32_e32 v4, 0
	v_mov_b32_e32 v5, 0
	v_mov_b32_e32 v6, 0x20010
	ds_write_b128 v6, v[2:5]
	ds_write_b128 v6, v[2:5] offset:16
	s_waitcnt lgkmcnt(0)
	s_barrier
	s_cbranch_scc1 .LBB0_441
	s_and_b32 s0, s2, 7
	s_ashr_i32 s1, s94, 3
	s_mul_i32 s0, s1, s0
	s_lshr_b32 s1, s2, 3
	s_add_i32 s38, s0, s1

; #define RW_LANDED(WN, XN, KN, VN) asm volatile("s_waitcnt lgkmcnt(0)" : "+v"(WN), "+v"(XN), "+v"(KN), "+v"(VN) :: "memory")
; #define RW_DMA4(B) RW_DMA_ONLY(B); RW_DMA_ONLY((B) + 1); RW_DMA_ONLY((B) + 2); RW_DMA_ONLY((B) + 3)
; template <int DIR>
; DEVINL void rwkv_scan_dir(const Params& p, int task, int lane, int wave) {
;   const int b = (task >> 8) & 1, head = (task >> 4) & 15, rg = task & 15;
;   const int seg = lane & 15, rl = lane >> 4, row = rg * 4 + rl;
;   constexpr int DIST = 24;
;   constexpr int WOFS = DIR ? 8 : 0;
;   const char* recbase = p.ws + O_REC + ((long)(b * 16 + head) * 4096) * 1024 + lane * 16;
;   const unsigned ring_lds = (unsigned)(unsigned long)(__attribute__((address_space(3))) char*)(dynsmem + wave * 32768);
;   const unsigned ring_u = __builtin_amdgcn_readfirstlane(ring_lds);
;   const unsigned a_seg = ring_lds + seg * 64;
;   const unsigned a_v = ring_lds + (row >> 2) * 64 + 48 + (row & 3) * 2;
;   u16* yo = (u16*)(p.ws + (DIR ? O_YB : O_YSUM)) + ((long)b * 4096) * 1024 + head * 64 + row;
;   float s0 = 0.f, s1 = 0.f, s2 = 0.f, s3 = 0.f;
;   float ykeep = 0.f;
;   const char* recdir = recbase + (DIR ? (long)4095 * 1024 : 0);
;     ...
;   u32x2 WvA, WvB; u32x4 XA, XB, KrA, KrB; unsigned vhA, vhB;
;   RW_DMA4(0); RW_DMA4(4); RW_DMA4(8); RW_DMA4(12); RW_DMA4(16); RW_DMA4(20);
;   RW_READ(0, WvA, XA, KrA, vhA, 23);
;   RW_LANDED(WvA, XA, KrA, vhA);
;   float ypart = 0.f;
; #pragma unroll 1
;   for (int st = 0; st < 4096; st += 32) {
.LBB0_481:
	s_andn2_saveexec_b64 s[0:1], s[20:21]
	s_cbranch_execz .LBB0_498
	v_and_b32_e32 v3, 15, v0
	v_lshrrev_b32_e32 v4, 4, v0
	v_lshlrev_b32_e32 v5, 4, v4
	v_lshl_add_u32 v5, v3, 6, v5
	v_readfirstlane_b32 s6, v2
	s_nop 3
	s_lshl_b32 s7, s38, 2
	s_add_u32 s7, s7, s6
	s_lshl_b32 s8, s94, 2
	s_mov_b32 s48, 0xaaaaaaaa
	s_mov_b32 s49, 0xaaaaaaaa
	s_mov_b32 s50, 0xcccccccc
	s_mov_b32 s51, 0xcccccccc
	v_mov_b32_e32 v9, 0x20010
	s_lshl_b32 s3, s6, 2
	s_add_u32 s3, s3, 0x20010
	v_mov_b32_e32 v23, s3
	v_add_u32_e32 v68, 16, v23
	s_mov_b32 s15, 0
.Lrw_task:
	s_cmp_ge_u32 s7, 0x400
	s_cbranch_scc1 .Lrw_done
	s_and_b32 s24, s7, 15
	s_bfe_u32 s26, s7, 0x40004
	s_bfe_u32 s32, s7, 0x10008
	s_lshr_b32 s36, s7, 9
	s_lshl_b32 s3, s32, 4
	s_add_u32 s3, s3, s26
	s_lshl_b32 s3, s3, 22
	s_add_u32 s10, s92, s3
	s_addc_u32 s11, s93, 0
	s_add_u32 s10, s10, 0xf400000
	s_addc_u32 s11, s11, 0
	s_lshl_b32 s3, s32, 23
	s_lshl_b32 s37, s26, 7
	s_add_u32 s3, s3, s37
	s_add_u32 s12, s92, s3
	s_addc_u32 s13, s93, 0
	s_lshl_b32 s3, s24, 3
	v_lshl_add_u32 v8, v4, 1, s3
	s_lshl_b32 s37, s24, 4
	s_lshl_b32 s39, s6, 12
	s_cmp_lg_u32 s36, 0
	s_cbranch_scc1 .Lrw_bwd
	s_add_u32 s12, s12, 0x2000000
	s_addc_u32 s13, s13, 0
	v_lshl_add_u32 v8, v3, 11, v8
	s_add_u32 s10, s10, s39
	s_addc_u32 s11, s11, 0
	s_mov_b32 s40, s39
	s_mov_b32 s41, 0
	v_lshlrev_b32_e32 v6, 4, v3
	s_add_u32 s3, s37, 0x300
	v_lshl_add_u32 v7, v4, 1, s3
	s_add_u32 s3, s40, s41
	s_and_b32 s3, s3, 0x1ffff
	s_add_u32 s3, s3, 16
	s_mov_b32 m0, s3
	s_nop 0
	global_load_lds_dwordx4 v5, s[10:11] offset:0
	global_load_lds_dwordx4 v5, s[10:11] offset:1024
	global_load_lds_dwordx4 v5, s[10:11] offset:2048
	global_load_lds_dwordx4 v5, s[10:11] offset:3072
	s_add_u32 s10, s10, 0x4000
	s_addc_u32 s11, s11, 0
	s_add_u32 s41, s41, 0x4000
	s_and_b32 s41, s41, 0x1ffff
	s_add_u32 s3, s40, s41
	s_and_b32 s3, s3, 0x1ffff
	s_add_u32 s3, s3, 16
	s_mov_b32 m0, s3
	s_nop 0
	global_load_lds_dwordx4 v5, s[10:11] offset:0
	global_load_lds_dwordx4 v5, s[10:11] offset:1024
	global_load_lds_dwordx4 v5, s[10:11] offset:2048
	global_load_lds_dwordx4 v5, s[10:11] offset:3072
	s_add_u32 s10, s10, 0x4000
	s_addc_u32 s11, s11, 0
	s_add_u32 s41, s41, 0x4000
	s_and_b32 s41, s41, 0x1ffff
	s_add_u32 s3, s40, s41
	s_and_b32 s3, s3, 0x1ffff
	s_add_u32 s3, s3, 16
	s_mov_b32 m0, s3
	s_nop 0
	global_load_lds_dwordx4 v5, s[10:11] offset:0
	global_load_lds_dwordx4 v5, s[10:11] offset:1024
	global_load_lds_dwordx4 v5, s[10:11] offset:2048
	global_load_lds_dwordx4 v5, s[10:11] offset:3072
	s_add_u32 s10, s10, 0x4000
	s_addc_u32 s11, s11, 0
	s_add_u32 s41, s41, 0x4000
	s_and_b32 s41, s41, 0x1ffff
	s_waitcnt vmcnt(0)
	v_mov_b32_e32 v10, 0
	v_mov_b32_e32 v11, 0
	v_mov_b32_e32 v12, 0
	v_mov_b32_e32 v13, 0
	s_mov_b32 s14, 0
	s_add_u32 s3, s15, 3
	v_mov_b32_e32 v69, s3
	ds_write_b32 v23, v69
	s_add_u32 s43, s15, 2
	s_sub_u32 s44, s15, 4
	s_max_i32 s44, s44, 0
	s_mov_b32 s42, 0
.Lrw_poll_d0p:
	ds_read_b128 v[100:103], v9
	ds_read_b128 v[104:107], v9 offset:16
	s_waitcnt lgkmcnt(0)
	v_min3_u32 v100, v100, v101, v102
	v_min3_u32 v104, v104, v105, v106
	v_min_u32_e32 v100, v100, v103
	v_min_u32_e32 v104, v104, v107
	s_nop 0
	v_readfirstlane_b32 s24, v100
	v_readfirstlane_b32 s26, v104
	s_nop 3
	s_cmp_lt_u32 s24, s43
	s_cbranch_scc1 .Lrw_again_d0p
	s_cmp_ge_u32 s26, s44
	s_cbranch_scc1 .Lrw_ready_d0p
.Lrw_again_d0p:
	s_sleep 1
	s_add_u32 s42, s42, 1
	s_cmp_lt_u32 s42, 0x400
	s_cbranch_scc1 .Lrw_poll_d0p
.Lrw_ready_d0p:
	ds_read_b64 v[24:25], v6 offset:16
	ds_read_b128 v[26:29], v6 offset:272
	ds_read_b128 v[30:33], v6 offset:528
	ds_read_u16 v34, v7 offset:16
	ds_read_b64 v[36:37], v6 offset:1040
	ds_read_b128 v[38:41], v6 offset:1296
	ds_read_b128 v[42:45], v6 offset:1552
	ds_read_u16 v46, v7 offset:1040
	s_waitcnt lgkmcnt(0)
.Lrw_blk_d0:
	s_cmp_gt_u32 s14, 1
	s_cbranch_scc1 .Lrw_nofull_d0
	s_waitcnt vmcnt(0)
.Lrw_nofull_d0:
	s_waitcnt vmcnt(1)
	s_add_u32 s3, s15, 3
	v_mov_b32_e32 v69, s3
	ds_write_b32 v23, v69
	s_add_u32 s43, s15, 2
	s_sub_u32 s44, s15, 4
	s_max_i32 s44, s44, 0
	s_mov_b32 s42, 0

; DEVINL u16 f2bf(float a) { return (u16)(pk2(a, 0.f) & 0xffffu); }
; #define RW_STEP2(B) RW_STEP(B, WvA, XA, KrA, vhA, WvB, XB, KrB, vhB); RW_STEP((B) + 1, WvB, XB, KrB, vhB, WvA, XA, KrA, vhA)
; #define RW_STEP4(B) RW_STEP2(B); RW_STEP2((B) + 2)
; template <int DIR>
; DEVINL void rwkv_scan_dir(const Params& p, int task, int lane, int wave) {
;     ...
;     if (st > 0) { const int q0 = st - 16 + seg; yo[(long)(DIR ? (4095 - q0) : q0) * 1024] = f2bf(ykeep); }
;     RW_STEP(1, WvB, XB, KrB, vhB, WvA, XA, KrA, vhA);
;     RW_STEP2(2); RW_STEP4(4); RW_STEP4(8); RW_STEP4(12);
;     RW_STEP(16, WvA, XA, KrA, vhA, WvB, XB, KrB, vhB);
;     { const int q0 = st + seg; yo[(long)(DIR ? (4095 - q0) : q0) * 1024] = f2bf(ykeep); }
.Lrw_ready_d0:
	s_add_u32 s3, s40, s41
	s_and_b32 s3, s3, 0x1ffff
	s_add_u32 s3, s3, 16
	s_mov_b32 m0, s3
	s_nop 0
	global_load_lds_dwordx4 v5, s[10:11] offset:0
	global_load_lds_dwordx4 v5, s[10:11] offset:1024
	global_load_lds_dwordx4 v5, s[10:11] offset:2048
	global_load_lds_dwordx4 v5, s[10:11] offset:3072
	s_add_u32 s10, s10, 0x4000
	s_addc_u32 s11, s11, 0
	s_add_u32 s41, s41, 0x4000
	s_and_b32 s41, s41, 0x1ffff
	ds_read_b64 v[72:73], v6 offset:2064
	ds_read_b128 v[74:77], v6 offset:2320
	ds_read_b128 v[78:81], v6 offset:2576
	ds_read_u16 v82, v7 offset:2064
	v_fma_mix_f32 v14, v10, v26, 0 op_sel:[0,0,0] op_sel_hi:[0,1,0]
	v_fma_mix_f32 v15, v12, v27, 0 op_sel:[0,0,0] op_sel_hi:[0,1,0]
	v_fma_mix_f32 v14, v11, v26, v14 op_sel:[0,1,0] op_sel_hi:[0,1,0]
	v_fma_mix_f32 v15, v13, v27, v15 op_sel:[0,1,0] op_sel_hi:[0,1,0]
	v_fma_mix_f32 v21, v10, v92, 0 op_sel:[0,0,0] op_sel_hi:[0,1,0]
	v_add_f32_e32 v20, v14, v15
	v_fma_mix_f32 v22, v12, v93, 0 op_sel:[0,0,0] op_sel_hi:[0,1,0]
	v_fma_mix_f32 v21, v11, v92, v21 op_sel:[0,1,0] op_sel_hi:[0,1,0]
	v_add_f32_dpp v20, v20, v20 quad_perm:[1,0,3,2] row_mask:0xf bank_mask:0xf bound_ctrl:1
	v_fma_mix_f32 v22, v13, v93, v22 op_sel:[0,1,0] op_sel_hi:[0,1,0]
	v_fma_mix_f32 v16, v10, v24, 0 op_sel:[0,0,0] op_sel_hi:[0,1,0]
	v_add_f32_dpp v20, v20, v20 quad_perm:[2,3,0,1] row_mask:0xf bank_mask:0xf bound_ctrl:1
	v_fma_mix_f32 v17, v11, v24, 0 op_sel:[0,1,0] op_sel_hi:[0,1,0]
	v_fma_mix_f32 v18, v12, v25, 0 op_sel:[0,0,0] op_sel_hi:[0,1,0]
	v_add_f32_dpp v20, v20, v20 row_half_mirror row_mask:0xf bank_mask:0xf bound_ctrl:1
	v_fma_mix_f32 v19, v13, v25, 0 op_sel:[0,1,0] op_sel_hi:[0,1,0]
	v_fma_mix_f32 v16, v34, v30, v16 op_sel:[0,0,0] op_sel_hi:[1,1,0]
	v_add_f32_dpp v20, v20, v20 row_mirror row_mask:0xf bank_mask:0xf bound_ctrl:1
	v_fma_mix_f32 v17, v34, v30, v17 op_sel:[0,1,0] op_sel_hi:[1,1,0]
	v_fma_mix_f32 v18, v34, v31, v18 op_sel:[0,0,0] op_sel_hi:[1,1,0]
	v_fma_mix_f32 v19, v34, v31, v19 op_sel:[0,1,0] op_sel_hi:[1,1,0]
	v_add_f32_e32 v63, v21, v22
	v_fma_mix_f32 v10, v20, v28, v16 op_sel:[0,0,0] op_sel_hi:[0,1,0]
	v_fma_mix_f32 v11, v20, v28, v17 op_sel:[0,1,0] op_sel_hi:[0,1,0]
	v_fma_mix_f32 v12, v20, v29, v18 op_sel:[0,0,0] op_sel_hi:[0,1,0]
	v_fma_mix_f32 v13, v20, v29, v19 op_sel:[0,1,0] op_sel_hi:[0,1,0]
	s_waitcnt lgkmcnt(4)
	s_cmp_eq_u32 s14, 0
	s_cbranch_scc1 .Lrw_skip_d0
	v_add_f32_dpp v48, v48, v48 row_ror:8 row_mask:0xf bank_mask:0x3
	v_add_f32_dpp v49, v49, v49 row_ror:8 row_mask:0xf bank_mask:0x3
	v_add_f32_dpp v50, v50, v50 row_ror:8 row_mask:0xf bank_mask:0x3
	v_add_f32_dpp v51, v51, v51 row_ror:8 row_mask:0xf bank_mask:0x3
	v_add_f32_dpp v52, v52, v52 row_ror:8 row_mask:0xf bank_mask:0x3
	v_add_f32_dpp v53, v53, v53 row_ror:8 row_mask:0xf bank_mask:0x3
	v_add_f32_dpp v54, v54, v54 row_ror:8 row_mask:0xf bank_mask:0x3
	v_add_f32_dpp v55, v55, v55 row_ror:8 row_mask:0xf bank_mask:0x3
	v_add_f32_dpp v48, v56, v56 row_ror:8 row_mask:0xf bank_mask:0xc
	v_add_f32_dpp v49, v57, v57 row_ror:8 row_mask:0xf bank_mask:0xc
	v_add_f32_dpp v50, v58, v58 row_ror:8 row_mask:0xf bank_mask:0xc
	v_add_f32_dpp v51, v59, v59 row_ror:8 row_mask:0xf bank_mask:0xc
	v_add_f32_dpp v52, v60, v60 row_ror:8 row_mask:0xf bank_mask:0xc
	v_add_f32_dpp v53, v61, v61 row_ror:8 row_mask:0xf bank_mask:0xc
	v_add_f32_dpp v54, v62, v62 row_ror:8 row_mask:0xf bank_mask:0xc
	v_add_f32_dpp v55, v63, v63 row_ror:8 row_mask:0xf bank_mask:0xc
	v_add_f32_dpp v48, v48, v48 row_ror:12 row_mask:0xf bank_mask:0x5
	v_add_f32_dpp v49, v49, v49 row_ror:12 row_mask:0xf bank_mask:0x5
	v_add_f32_dpp v50, v50, v50 row_ror:12 row_mask:0xf bank_mask:0x5
	v_add_f32_dpp v51, v51, v51 row_ror:12 row_mask:0xf bank_mask:0x5
	v_add_f32_dpp v48, v52, v52 row_ror:4 row_mask:0xf bank_mask:0xa
	v_add_f32_dpp v49, v53, v53 row_ror:4 row_mask:0xf bank_mask:0xa
	v_add_f32_dpp v50, v54, v54 row_ror:4 row_mask:0xf bank_mask:0xa
	v_add_f32_dpp v51, v55, v55 row_ror:4 row_mask:0xf bank_mask:0xa
	v_add_f32_dpp v64, v48, v48 quad_perm:[2,3,0,1] row_mask:0xf bank_mask:0xf bound_ctrl:1
	v_add_f32_dpp v65, v50, v50 quad_perm:[2,3,0,1] row_mask:0xf bank_mask:0xf bound_ctrl:1
	v_cndmask_b32_e64 v56, v64, v65, s[50:51]
	v_add_f32_dpp v64, v49, v49 quad_perm:[2,3,0,1] row_mask:0xf bank_mask:0xf bound_ctrl:1
	v_add_f32_dpp v65, v51, v51 quad_perm:[2,3,0,1] row_mask:0xf bank_mask:0xf bound_ctrl:1
	v_cndmask_b32_e64 v57, v64, v65, s[50:51]
	v_add_f32_dpp v64, v56, v56 quad_perm:[1,0,3,2] row_mask:0xf bank_mask:0xf bound_ctrl:1
	s_nop 0
	v_add_f32_dpp v65, v57, v57 quad_perm:[1,0,3,2] row_mask:0xf bank_mask:0xf bound_ctrl:1
	v_cndmask_b32_e64 v66, v64, v65, s[48:49]
	v_cvt_pk_bf16_f32 v66, v66, v66
	global_store_short v8, v66, s[12:13]
	s_add_u32 s12, s12, 0x8000
	s_addc_u32 s13, s13, 0
.Lrw_skip_d0:
	ds_read_b64 v[84:85], v6 offset:3088
	ds_read_b128 v[86:89], v6 offset:3344
	ds_read_b128 v[90:93], v6 offset:3600
	ds_read_u16 v94, v7 offset:3088
	v_fma_mix_f32 v14, v10, v38, 0 op_sel:[0,0,0] op_sel_hi:[0,1,0]
	v_fma_mix_f32 v15, v12, v39, 0 op_sel:[0,0,0] op_sel_hi:[0,1,0]
	v_fma_mix_f32 v14, v11, v38, v14 op_sel:[0,1,0] op_sel_hi:[0,1,0]
	v_fma_mix_f32 v15, v13, v39, v15 op_sel:[0,1,0] op_sel_hi:[0,1,0]
	v_fma_mix_f32 v21, v10, v32, 0 op_sel:[0,0,0] op_sel_hi:[0,1,0]
	v_add_f32_e32 v20, v14, v15
	v_fma_mix_f32 v22, v12, v33, 0 op_sel:[0,0,0] op_sel_hi:[0,1,0]
	v_fma_mix_f32 v21, v11, v32, v21 op_sel:[0,1,0] op_sel_hi:[0,1,0]
	v_add_f32_dpp v20, v20, v20 quad_perm:[1,0,3,2] row_mask:0xf bank_mask:0xf bound_ctrl:1
	v_fma_mix_f32 v22, v13, v33, v22 op_sel:[0,1,0] op_sel_hi:[0,1,0]
	v_fma_mix_f32 v16, v10, v36, 0 op_sel:[0,0,0] op_sel_hi:[0,1,0]
	v_add_f32_dpp v20, v20, v20 quad_perm:[2,3,0,1] row_mask:0xf bank_mask:0xf bound_ctrl:1
	v_fma_mix_f32 v17, v11, v36, 0 op_sel:[0,1,0] op_sel_hi:[0,1,0]
	v_fma_mix_f32 v18, v12, v37, 0 op_sel:[0,0,0] op_sel_hi:[0,1,0]
	v_add_f32_dpp v20, v20, v20 row_half_mirror row_mask:0xf bank_mask:0xf bound_ctrl:1
	v_fma_mix_f32 v19, v13, v37, 0 op_sel:[0,1,0] op_sel_hi:[0,1,0]
	v_fma_mix_f32 v16, v46, v42, v16 op_sel:[0,0,0] op_sel_hi:[1,1,0]
	v_add_f32_dpp v20, v20, v20 row_mirror row_mask:0xf bank_mask:0xf bound_ctrl:1
	v_fma_mix_f32 v17, v46, v42, v17 op_sel:[0,1,0] op_sel_hi:[1,1,0]
	v_fma_mix_f32 v18, v46, v43, v18 op_sel:[0,0,0] op_sel_hi:[1,1,0]
	v_fma_mix_f32 v19, v46, v43, v19 op_sel:[0,1,0] op_sel_hi:[1,1,0]
	v_add_f32_e32 v48, v21, v22
	v_fma_mix_f32 v10, v20, v40, v16 op_sel:[0,0,0] op_sel_hi:[0,1,0]
	v_fma_mix_f32 v11, v20, v40, v17 op_sel:[0,1,0] op_sel_hi:[0,1,0]
	v_fma_mix_f32 v12, v20, v41, v18 op_sel:[0,0,0] op_sel_hi:[0,1,0]
	v_fma_mix_f32 v13, v20, v41, v19 op_sel:[0,1,0] op_sel_hi:[0,1,0]
	s_waitcnt lgkmcnt(4)
	ds_read_b64 v[24:25], v6 offset:4112
	ds_read_b128 v[26:29], v6 offset:4368
	ds_read_b128 v[30:33], v6 offset:4624
	ds_read_u16 v34, v7 offset:4112
	v_fma_mix_f32 v14, v10, v74, 0 op_sel:[0,0,0] op_sel_hi:[0,1,0]
	v_fma_mix_f32 v15, v12, v75, 0 op_sel:[0,0,0] op_sel_hi:[0,1,0]
	v_fma_mix_f32 v14, v11, v74, v14 op_sel:[0,1,0] op_sel_hi:[0,1,0]
	v_fma_mix_f32 v15, v13, v75, v15 op_sel:[0,1,0] op_sel_hi:[0,1,0]
	v_fma_mix_f32 v21, v10, v44, 0 op_sel:[0,0,0] op_sel_hi:[0,1,0]
	v_add_f32_e32 v20, v14, v15
	v_fma_mix_f32 v22, v12, v45, 0 op_sel:[0,0,0] op_sel_hi:[0,1,0]
	v_fma_mix_f32 v21, v11, v44, v21 op_sel:[0,1,0] op_sel_hi:[0,1,0]
	v_add_f32_dpp v20, v20, v20 quad_perm:[1,0,3,2] row_mask:0xf bank_mask:0xf bound_ctrl:1
	v_fma_mix_f32 v22, v13, v45, v22 op_sel:[0,1,0] op_sel_hi:[0,1,0]
	v_fma_mix_f32 v16, v10, v72, 0 op_sel:[0,0,0] op_sel_hi:[0,1,0]
	v_add_f32_dpp v20, v20, v20 quad_perm:[2,3,0,1] row_mask:0xf bank_mask:0xf bound_ctrl:1
	v_fma_mix_f32 v17, v11, v72, 0 op_sel:[0,1,0] op_sel_hi:[0,1,0]
	v_fma_mix_f32 v18, v12, v73, 0 op_sel:[0,0,0] op_sel_hi:[0,1,0]
	v_add_f32_dpp v20, v20, v20 row_half_mirror row_mask:0xf bank_mask:0xf bound_ctrl:1
	v_fma_mix_f32 v19, v13, v73, 0 op_sel:[0,1,0] op_sel_hi:[0,1,0]
	v_fma_mix_f32 v16, v82, v78, v16 op_sel:[0,0,0] op_sel_hi:[1,1,0]
	v_add_f32_dpp v20, v20, v20 row_mirror row_mask:0xf bank_mask:0xf bound_ctrl:1
	v_fma_mix_f32 v17, v82, v78, v17 op_sel:[0,1,0] op_sel_hi:[1,1,0]
	v_fma_mix_f32 v18, v82, v79, v18 op_sel:[0,0,0] op_sel_hi:[1,1,0]
	v_fma_mix_f32 v19, v82, v79, v19 op_sel:[0,1,0] op_sel_hi:[1,1,0]
	v_add_f32_e32 v49, v21, v22
	v_fma_mix_f32 v10, v20, v76, v16 op_sel:[0,0,0] op_sel_hi:[0,1,0]
	v_fma_mix_f32 v11, v20, v76, v17 op_sel:[0,1,0] op_sel_hi:[0,1,0]
	v_fma_mix_f32 v12, v20, v77, v18 op_sel:[0,0,0] op_sel_hi:[0,1,0]
	v_fma_mix_f32 v13, v20, v77, v19 op_sel:[0,1,0] op_sel_hi:[0,1,0]
	s_waitcnt lgkmcnt(4)
	ds_read_b64 v[36:37], v6 offset:5136
	ds_read_b128 v[38:41], v6 offset:5392
	ds_read_b128 v[42:45], v6 offset:5648
	ds_read_u16 v46, v7 offset:5136
	v_fma_mix_f32 v14, v10, v86, 0 op_sel:[0,0,0] op_sel_hi:[0,1,0]
	v_fma_mix_f32 v15, v12, v87, 0 op_sel:[0,0,0] op_sel_hi:[0,1,0]
	v_fma_mix_f32 v14, v11, v86, v14 op_sel:[0,1,0] op_sel_hi:[0,1,0]
	v_fma_mix_f32 v15, v13, v87, v15 op_sel:[0,1,0] op_sel_hi:[0,1,0]
	v_fma_mix_f32 v21, v10, v80, 0 op_sel:[0,0,0] op_sel_hi:[0,1,0]
	v_add_f32_e32 v20, v14, v15
	v_fma_mix_f32 v22, v12, v81, 0 op_sel:[0,0,0] op_sel_hi:[0,1,0]
	v_fma_mix_f32 v21, v11, v80, v21 op_sel:[0,1,0] op_sel_hi:[0,1,0]
	v_add_f32_dpp v20, v20, v20 quad_perm:[1,0,3,2] row_mask:0xf bank_mask:0xf bound_ctrl:1
	v_fma_mix_f32 v22, v13, v81, v22 op_sel:[0,1,0] op_sel_hi:[0,1,0]
	v_fma_mix_f32 v16, v10, v84, 0 op_sel:[0,0,0] op_sel_hi:[0,1,0]
	v_add_f32_dpp v20, v20, v20 quad_perm:[2,3,0,1] row_mask:0xf bank_mask:0xf bound_ctrl:1
	v_fma_mix_f32 v17, v11, v84, 0 op_sel:[0,1,0] op_sel_hi:[0,1,0]
	v_fma_mix_f32 v18, v12, v85, 0 op_sel:[0,0,0] op_sel_hi:[0,1,0]
	v_add_f32_dpp v20, v20, v20 row_half_mirror row_mask:0xf bank_mask:0xf bound_ctrl:1
	v_fma_mix_f32 v19, v13, v85, 0 op_sel:[0,1,0] op_sel_hi:[0,1,0]
	v_fma_mix_f32 v16, v94, v90, v16 op_sel:[0,0,0] op_sel_hi:[1,1,0]
	v_add_f32_dpp v20, v20, v20 row_mirror row_mask:0xf bank_mask:0xf bound_ctrl:1
	v_fma_mix_f32 v17, v94, v90, v17 op_sel:[0,1,0] op_sel_hi:[1,1,0]
	v_fma_mix_f32 v18, v94, v91, v18 op_sel:[0,0,0] op_sel_hi:[1,1,0]
	v_fma_mix_f32 v19, v94, v91, v19 op_sel:[0,1,0] op_sel_hi:[1,1,0]
	v_add_f32_e32 v50, v21, v22
	v_fma_mix_f32 v10, v20, v88, v16 op_sel:[0,0,0] op_sel_hi:[0,1,0]
	v_fma_mix_f32 v11, v20, v88, v17 op_sel:[0,1,0] op_sel_hi:[0,1,0]
	v_fma_mix_f32 v12, v20, v89, v18 op_sel:[0,0,0] op_sel_hi:[0,1,0]
	v_fma_mix_f32 v13, v20, v89, v19 op_sel:[0,1,0] op_sel_hi:[0,1,0]
	s_waitcnt lgkmcnt(4)
	ds_read_b64 v[72:73], v6 offset:6160
	ds_read_b128 v[74:77], v6 offset:6416
	ds_read_b128 v[78:81], v6 offset:6672
	ds_read_u16 v82, v7 offset:6160
	v_fma_mix_f32 v14, v10, v26, 0 op_sel:[0,0,0] op_sel_hi:[0,1,0]
	v_fma_mix_f32 v15, v12, v27, 0 op_sel:[0,0,0] op_sel_hi:[0,1,0]
	v_fma_mix_f32 v14, v11, v26, v14 op_sel:[0,1,0] op_sel_hi:[0,1,0]
	v_fma_mix_f32 v15, v13, v27, v15 op_sel:[0,1,0] op_sel_hi:[0,1,0]
	v_fma_mix_f32 v21, v10, v92, 0 op_sel:[0,0,0] op_sel_hi:[0,1,0]
	v_add_f32_e32 v20, v14, v15
	v_fma_mix_f32 v22, v12, v93, 0 op_sel:[0,0,0] op_sel_hi:[0,1,0]
	v_fma_mix_f32 v21, v11, v92, v21 op_sel:[0,1,0] op_sel_hi:[0,1,0]
	v_add_f32_dpp v20, v20, v20 quad_perm:[1,0,3,2] row_mask:0xf bank_mask:0xf bound_ctrl:1
	v_fma_mix_f32 v22, v13, v93, v22 op_sel:[0,1,0] op_sel_hi:[0,1,0]
	v_fma_mix_f32 v16, v10, v24, 0 op_sel:[0,0,0] op_sel_hi:[0,1,0]
	v_add_f32_dpp v20, v20, v20 quad_perm:[2,3,0,1] row_mask:0xf bank_mask:0xf bound_ctrl:1
	v_fma_mix_f32 v17, v11, v24, 0 op_sel:[0,1,0] op_sel_hi:[0,1,0]
	v_fma_mix_f32 v18, v12, v25, 0 op_sel:[0,0,0] op_sel_hi:[0,1,0]
	v_add_f32_dpp v20, v20, v20 row_half_mirror row_mask:0xf bank_mask:0xf bound_ctrl:1
	v_fma_mix_f32 v19, v13, v25, 0 op_sel:[0,1,0] op_sel_hi:[0,1,0]
	v_fma_mix_f32 v16, v34, v30, v16 op_sel:[0,0,0] op_sel_hi:[1,1,0]
	v_add_f32_dpp v20, v20, v20 row_mirror row_mask:0xf bank_mask:0xf bound_ctrl:1
	v_fma_mix_f32 v17, v34, v30, v17 op_sel:[0,1,0] op_sel_hi:[1,1,0]
	v_fma_mix_f32 v18, v34, v31, v18 op_sel:[0,0,0] op_sel_hi:[1,1,0]
	v_fma_mix_f32 v19, v34, v31, v19 op_sel:[0,1,0] op_sel_hi:[1,1,0]
	v_add_f32_e32 v51, v21, v22
	v_fma_mix_f32 v10, v20, v28, v16 op_sel:[0,0,0] op_sel_hi:[0,1,0]
	v_fma_mix_f32 v11, v20, v28, v17 op_sel:[0,1,0] op_sel_hi:[0,1,0]
	v_fma_mix_f32 v12, v20, v29, v18 op_sel:[0,0,0] op_sel_hi:[0,1,0]
	v_fma_mix_f32 v13, v20, v29, v19 op_sel:[0,1,0] op_sel_hi:[0,1,0]
	s_waitcnt lgkmcnt(4)
	ds_read_b64 v[84:85], v6 offset:7184
	ds_read_b128 v[86:89], v6 offset:7440
	ds_read_b128 v[90:93], v6 offset:7696
	ds_read_u16 v94, v7 offset:7184
	v_fma_mix_f32 v14, v10, v38, 0 op_sel:[0,0,0] op_sel_hi:[0,1,0]
	v_fma_mix_f32 v15, v12, v39, 0 op_sel:[0,0,0] op_sel_hi:[0,1,0]
	v_fma_mix_f32 v14, v11, v38, v14 op_sel:[0,1,0] op_sel_hi:[0,1,0]
	v_fma_mix_f32 v15, v13, v39, v15 op_sel:[0,1,0] op_sel_hi:[0,1,0]
	v_fma_mix_f32 v21, v10, v32, 0 op_sel:[0,0,0] op_sel_hi:[0,1,0]
	v_add_f32_e32 v20, v14, v15
	v_fma_mix_f32 v22, v12, v33, 0 op_sel:[0,0,0] op_sel_hi:[0,1,0]
	v_fma_mix_f32 v21, v11, v32, v21 op_sel:[0,1,0] op_sel_hi:[0,1,0]
	v_add_f32_dpp v20, v20, v20 quad_perm:[1,0,3,2] row_mask:0xf bank_mask:0xf bound_ctrl:1
	v_fma_mix_f32 v22, v13, v33, v22 op_sel:[0,1,0] op_sel_hi:[0,1,0]
	v_fma_mix_f32 v16, v10, v36, 0 op_sel:[0,0,0] op_sel_hi:[0,1,0]
	v_add_f32_dpp v20, v20, v20 quad_perm:[2,3,0,1] row_mask:0xf bank_mask:0xf bound_ctrl:1
	v_fma_mix_f32 v17, v11, v36, 0 op_sel:[0,1,0] op_sel_hi:[0,1,0]
	v_fma_mix_f32 v18, v12, v37, 0 op_sel:[0,0,0] op_sel_hi:[0,1,0]
	v_add_f32_dpp v20, v20, v20 row_half_mirror row_mask:0xf bank_mask:0xf bound_ctrl:1
	v_fma_mix_f32 v19, v13, v37, 0 op_sel:[0,1,0] op_sel_hi:[0,1,0]
	v_fma_mix_f32 v16, v46, v42, v16 op_sel:[0,0,0] op_sel_hi:[1,1,0]
	v_add_f32_dpp v20, v20, v20 row_mirror row_mask:0xf bank_mask:0xf bound_ctrl:1
	v_fma_mix_f32 v17, v46, v42, v17 op_sel:[0,1,0] op_sel_hi:[1,1,0]
	v_fma_mix_f32 v18, v46, v43, v18 op_sel:[0,0,0] op_sel_hi:[1,1,0]
	v_fma_mix_f32 v19, v46, v43, v19 op_sel:[0,1,0] op_sel_hi:[1,1,0]
	v_add_f32_e32 v52, v21, v22
	v_fma_mix_f32 v10, v20, v40, v16 op_sel:[0,0,0] op_sel_hi:[0,1,0]
	v_fma_mix_f32 v11, v20, v40, v17 op_sel:[0,1,0] op_sel_hi:[0,1,0]
	v_fma_mix_f32 v12, v20, v41, v18 op_sel:[0,0,0] op_sel_hi:[0,1,0]
	v_fma_mix_f32 v13, v20, v41, v19 op_sel:[0,1,0] op_sel_hi:[0,1,0]
	s_waitcnt lgkmcnt(4)
	ds_read_b64 v[24:25], v6 offset:8208
	ds_read_b128 v[26:29], v6 offset:8464
	ds_read_b128 v[30:33], v6 offset:8720
	ds_read_u16 v34, v7 offset:8208
	v_fma_mix_f32 v14, v10, v74, 0 op_sel:[0,0,0] op_sel_hi:[0,1,0]
	v_fma_mix_f32 v15, v12, v75, 0 op_sel:[0,0,0] op_sel_hi:[0,1,0]
	v_fma_mix_f32 v14, v11, v74, v14 op_sel:[0,1,0] op_sel_hi:[0,1,0]
	v_fma_mix_f32 v15, v13, v75, v15 op_sel:[0,1,0] op_sel_hi:[0,1,0]
	v_fma_mix_f32 v21, v10, v44, 0 op_sel:[0,0,0] op_sel_hi:[0,1,0]
	v_add_f32_e32 v20, v14, v15
	v_fma_mix_f32 v22, v12, v45, 0 op_sel:[0,0,0] op_sel_hi:[0,1,0]
	v_fma_mix_f32 v21, v11, v44, v21 op_sel:[0,1,0] op_sel_hi:[0,1,0]
	v_add_f32_dpp v20, v20, v20 quad_perm:[1,0,3,2] row_mask:0xf bank_mask:0xf bound_ctrl:1
	v_fma_mix_f32 v22, v13, v45, v22 op_sel:[0,1,0] op_sel_hi:[0,1,0]
	v_fma_mix_f32 v16, v10, v72, 0 op_sel:[0,0,0] op_sel_hi:[0,1,0]
	v_add_f32_dpp v20, v20, v20 quad_perm:[2,3,0,1] row_mask:0xf bank_mask:0xf bound_ctrl:1
	v_fma_mix_f32 v17, v11, v72, 0 op_sel:[0,1,0] op_sel_hi:[0,1,0]
	v_fma_mix_f32 v18, v12, v73, 0 op_sel:[0,0,0] op_sel_hi:[0,1,0]
	v_add_f32_dpp v20, v20, v20 row_half_mirror row_mask:0xf bank_mask:0xf bound_ctrl:1
	v_fma_mix_f32 v19, v13, v73, 0 op_sel:[0,1,0] op_sel_hi:[0,1,0]
	v_fma_mix_f32 v16, v82, v78, v16 op_sel:[0,0,0] op_sel_hi:[1,1,0]
	v_add_f32_dpp v20, v20, v20 row_mirror row_mask:0xf bank_mask:0xf bound_ctrl:1
	v_fma_mix_f32 v17, v82, v78, v17 op_sel:[0,1,0] op_sel_hi:[1,1,0]
	v_fma_mix_f32 v18, v82, v79, v18 op_sel:[0,0,0] op_sel_hi:[1,1,0]
	v_fma_mix_f32 v19, v82, v79, v19 op_sel:[0,1,0] op_sel_hi:[1,1,0]
	v_add_f32_e32 v53, v21, v22
	v_fma_mix_f32 v10, v20, v76, v16 op_sel:[0,0,0] op_sel_hi:[0,1,0]
	v_fma_mix_f32 v11, v20, v76, v17 op_sel:[0,1,0] op_sel_hi:[0,1,0]
	v_fma_mix_f32 v12, v20, v77, v18 op_sel:[0,0,0] op_sel_hi:[0,1,0]
	v_fma_mix_f32 v13, v20, v77, v19 op_sel:[0,1,0] op_sel_hi:[0,1,0]
	s_waitcnt lgkmcnt(4)
	ds_read_b64 v[36:37], v6 offset:9232
	ds_read_b128 v[38:41], v6 offset:9488
	ds_read_b128 v[42:45], v6 offset:9744
	ds_read_u16 v46, v7 offset:9232
	v_fma_mix_f32 v14, v10, v86, 0 op_sel:[0,0,0] op_sel_hi:[0,1,0]
	v_fma_mix_f32 v15, v12, v87, 0 op_sel:[0,0,0] op_sel_hi:[0,1,0]
	v_fma_mix_f32 v14, v11, v86, v14 op_sel:[0,1,0] op_sel_hi:[0,1,0]
	v_fma_mix_f32 v15, v13, v87, v15 op_sel:[0,1,0] op_sel_hi:[0,1,0]
	v_fma_mix_f32 v21, v10, v80, 0 op_sel:[0,0,0] op_sel_hi:[0,1,0]
	v_add_f32_e32 v20, v14, v15
	v_fma_mix_f32 v22, v12, v81, 0 op_sel:[0,0,0] op_sel_hi:[0,1,0]
	v_fma_mix_f32 v21, v11, v80, v21 op_sel:[0,1,0] op_sel_hi:[0,1,0]
	v_add_f32_dpp v20, v20, v20 quad_perm:[1,0,3,2] row_mask:0xf bank_mask:0xf bound_ctrl:1
	v_fma_mix_f32 v22, v13, v81, v22 op_sel:[0,1,0] op_sel_hi:[0,1,0]
	v_fma_mix_f32 v16, v10, v84, 0 op_sel:[0,0,0] op_sel_hi:[0,1,0]
	v_add_f32_dpp v20, v20, v20 quad_perm:[2,3,0,1] row_mask:0xf bank_mask:0xf bound_ctrl:1
	v_fma_mix_f32 v17, v11, v84, 0 op_sel:[0,1,0] op_sel_hi:[0,1,0]
	v_fma_mix_f32 v18, v12, v85, 0 op_sel:[0,0,0] op_sel_hi:[0,1,0]
	v_add_f32_dpp v20, v20, v20 row_half_mirror row_mask:0xf bank_mask:0xf bound_ctrl:1
	v_fma_mix_f32 v19, v13, v85, 0 op_sel:[0,1,0] op_sel_hi:[0,1,0]
	v_fma_mix_f32 v16, v94, v90, v16 op_sel:[0,0,0] op_sel_hi:[1,1,0]
	v_add_f32_dpp v20, v20, v20 row_mirror row_mask:0xf bank_mask:0xf bound_ctrl:1
	v_fma_mix_f32 v17, v94, v90, v17 op_sel:[0,1,0] op_sel_hi:[1,1,0]
	v_fma_mix_f32 v18, v94, v91, v18 op_sel:[0,0,0] op_sel_hi:[1,1,0]
	v_fma_mix_f32 v19, v94, v91, v19 op_sel:[0,1,0] op_sel_hi:[1,1,0]
	v_add_f32_e32 v54, v21, v22
	v_fma_mix_f32 v10, v20, v88, v16 op_sel:[0,0,0] op_sel_hi:[0,1,0]
	v_fma_mix_f32 v11, v20, v88, v17 op_sel:[0,1,0] op_sel_hi:[0,1,0]
	v_fma_mix_f32 v12, v20, v89, v18 op_sel:[0,0,0] op_sel_hi:[0,1,0]
	v_fma_mix_f32 v13, v20, v89, v19 op_sel:[0,1,0] op_sel_hi:[0,1,0]
	s_waitcnt lgkmcnt(4)
	ds_read_b64 v[72:73], v6 offset:10256
	ds_read_b128 v[74:77], v6 offset:10512
	ds_read_b128 v[78:81], v6 offset:10768
	ds_read_u16 v82, v7 offset:10256
	v_fma_mix_f32 v14, v10, v26, 0 op_sel:[0,0,0] op_sel_hi:[0,1,0]
	v_fma_mix_f32 v15, v12, v27, 0 op_sel:[0,0,0] op_sel_hi:[0,1,0]
	v_fma_mix_f32 v14, v11, v26, v14 op_sel:[0,1,0] op_sel_hi:[0,1,0]
	v_fma_mix_f32 v15, v13, v27, v15 op_sel:[0,1,0] op_sel_hi:[0,1,0]
	v_fma_mix_f32 v21, v10, v92, 0 op_sel:[0,0,0] op_sel_hi:[0,1,0]
	v_add_f32_e32 v20, v14, v15
	v_fma_mix_f32 v22, v12, v93, 0 op_sel:[0,0,0] op_sel_hi:[0,1,0]
	v_fma_mix_f32 v21, v11, v92, v21 op_sel:[0,1,0] op_sel_hi:[0,1,0]
	v_add_f32_dpp v20, v20, v20 quad_perm:[1,0,3,2] row_mask:0xf bank_mask:0xf bound_ctrl:1
	v_fma_mix_f32 v22, v13, v93, v22 op_sel:[0,1,0] op_sel_hi:[0,1,0]
	v_fma_mix_f32 v16, v10, v24, 0 op_sel:[0,0,0] op_sel_hi:[0,1,0]
	v_add_f32_dpp v20, v20, v20 quad_perm:[2,3,0,1] row_mask:0xf bank_mask:0xf bound_ctrl:1
	v_fma_mix_f32 v17, v11, v24, 0 op_sel:[0,1,0] op_sel_hi:[0,1,0]
	v_fma_mix_f32 v18, v12, v25, 0 op_sel:[0,0,0] op_sel_hi:[0,1,0]
	v_add_f32_dpp v20, v20, v20 row_half_mirror row_mask:0xf bank_mask:0xf bound_ctrl:1
	v_fma_mix_f32 v19, v13, v25, 0 op_sel:[0,1,0] op_sel_hi:[0,1,0]
	v_fma_mix_f32 v16, v34, v30, v16 op_sel:[0,0,0] op_sel_hi:[1,1,0]
	v_add_f32_dpp v20, v20, v20 row_mirror row_mask:0xf bank_mask:0xf bound_ctrl:1
	v_fma_mix_f32 v17, v34, v30, v17 op_sel:[0,1,0] op_sel_hi:[1,1,0]
	v_fma_mix_f32 v18, v34, v31, v18 op_sel:[0,0,0] op_sel_hi:[1,1,0]
	v_fma_mix_f32 v19, v34, v31, v19 op_sel:[0,1,0] op_sel_hi:[1,1,0]
	v_add_f32_e32 v55, v21, v22
	v_fma_mix_f32 v10, v20, v28, v16 op_sel:[0,0,0] op_sel_hi:[0,1,0]
	v_fma_mix_f32 v11, v20, v28, v17 op_sel:[0,1,0] op_sel_hi:[0,1,0]
	v_fma_mix_f32 v12, v20, v29, v18 op_sel:[0,0,0] op_sel_hi:[0,1,0]
	v_fma_mix_f32 v13, v20, v29, v19 op_sel:[0,1,0] op_sel_hi:[0,1,0]
	s_waitcnt lgkmcnt(4)
	ds_read_b64 v[84:85], v6 offset:11280
	ds_read_b128 v[86:89], v6 offset:11536
	ds_read_b128 v[90:93], v6 offset:11792
	ds_read_u16 v94, v7 offset:11280
	v_fma_mix_f32 v14, v10, v38, 0 op_sel:[0,0,0] op_sel_hi:[0,1,0]
	v_fma_mix_f32 v15, v12, v39, 0 op_sel:[0,0,0] op_sel_hi:[0,1,0]
	v_fma_mix_f32 v14, v11, v38, v14 op_sel:[0,1,0] op_sel_hi:[0,1,0]
	v_fma_mix_f32 v15, v13, v39, v15 op_sel:[0,1,0] op_sel_hi:[0,1,0]
	v_fma_mix_f32 v21, v10, v32, 0 op_sel:[0,0,0] op_sel_hi:[0,1,0]
	v_add_f32_e32 v20, v14, v15
	v_fma_mix_f32 v22, v12, v33, 0 op_sel:[0,0,0] op_sel_hi:[0,1,0]
	v_fma_mix_f32 v21, v11, v32, v21 op_sel:[0,1,0] op_sel_hi:[0,1,0]
	v_add_f32_dpp v20, v20, v20 quad_perm:[1,0,3,2] row_mask:0xf bank_mask:0xf bound_ctrl:1
	v_fma_mix_f32 v22, v13, v33, v22 op_sel:[0,1,0] op_sel_hi:[0,1,0]
	v_fma_mix_f32 v16, v10, v36, 0 op_sel:[0,0,0] op_sel_hi:[0,1,0]
	v_add_f32_dpp v20, v20, v20 quad_perm:[2,3,0,1] row_mask:0xf bank_mask:0xf bound_ctrl:1
	v_fma_mix_f32 v17, v11, v36, 0 op_sel:[0,1,0] op_sel_hi:[0,1,0]
	v_fma_mix_f32 v18, v12, v37, 0 op_sel:[0,0,0] op_sel_hi:[0,1,0]
	v_add_f32_dpp v20, v20, v20 row_half_mirror row_mask:0xf bank_mask:0xf bound_ctrl:1
	v_fma_mix_f32 v19, v13, v37, 0 op_sel:[0,1,0] op_sel_hi:[0,1,0]
	v_fma_mix_f32 v16, v46, v42, v16 op_sel:[0,0,0] op_sel_hi:[1,1,0]
	v_add_f32_dpp v20, v20, v20 row_mirror row_mask:0xf bank_mask:0xf bound_ctrl:1
	v_fma_mix_f32 v17, v46, v42, v17 op_sel:[0,1,0] op_sel_hi:[1,1,0]
	v_fma_mix_f32 v18, v46, v43, v18 op_sel:[0,0,0] op_sel_hi:[1,1,0]
	v_fma_mix_f32 v19, v46, v43, v19 op_sel:[0,1,0] op_sel_hi:[1,1,0]
	v_add_f32_e32 v56, v21, v22
	v_fma_mix_f32 v10, v20, v40, v16 op_sel:[0,0,0] op_sel_hi:[0,1,0]
	v_fma_mix_f32 v11, v20, v40, v17 op_sel:[0,1,0] op_sel_hi:[0,1,0]
	v_fma_mix_f32 v12, v20, v41, v18 op_sel:[0,0,0] op_sel_hi:[0,1,0]
	v_fma_mix_f32 v13, v20, v41, v19 op_sel:[0,1,0] op_sel_hi:[0,1,0]
	s_waitcnt lgkmcnt(4)
	ds_read_b64 v[24:25], v6 offset:12304
	ds_read_b128 v[26:29], v6 offset:12560
	ds_read_b128 v[30:33], v6 offset:12816
	ds_read_u16 v34, v7 offset:12304
	v_fma_mix_f32 v14, v10, v74, 0 op_sel:[0,0,0] op_sel_hi:[0,1,0]
	v_fma_mix_f32 v15, v12, v75, 0 op_sel:[0,0,0] op_sel_hi:[0,1,0]
	v_fma_mix_f32 v14, v11, v74, v14 op_sel:[0,1,0] op_sel_hi:[0,1,0]
	v_fma_mix_f32 v15, v13, v75, v15 op_sel:[0,1,0] op_sel_hi:[0,1,0]
	v_fma_mix_f32 v21, v10, v44, 0 op_sel:[0,0,0] op_sel_hi:[0,1,0]
	v_add_f32_e32 v20, v14, v15
	v_fma_mix_f32 v22, v12, v45, 0 op_sel:[0,0,0] op_sel_hi:[0,1,0]
	v_fma_mix_f32 v21, v11, v44, v21 op_sel:[0,1,0] op_sel_hi:[0,1,0]
	v_add_f32_dpp v20, v20, v20 quad_perm:[1,0,3,2] row_mask:0xf bank_mask:0xf bound_ctrl:1
	v_fma_mix_f32 v22, v13, v45, v22 op_sel:[0,1,0] op_sel_hi:[0,1,0]
	v_fma_mix_f32 v16, v10, v72, 0 op_sel:[0,0,0] op_sel_hi:[0,1,0]
	v_add_f32_dpp v20, v20, v20 quad_perm:[2,3,0,1] row_mask:0xf bank_mask:0xf bound_ctrl:1
	v_fma_mix_f32 v17, v11, v72, 0 op_sel:[0,1,0] op_sel_hi:[0,1,0]
	v_fma_mix_f32 v18, v12, v73, 0 op_sel:[0,0,0] op_sel_hi:[0,1,0]
	v_add_f32_dpp v20, v20, v20 row_half_mirror row_mask:0xf bank_mask:0xf bound_ctrl:1
	v_fma_mix_f32 v19, v13, v73, 0 op_sel:[0,1,0] op_sel_hi:[0,1,0]
	v_fma_mix_f32 v16, v82, v78, v16 op_sel:[0,0,0] op_sel_hi:[1,1,0]
	v_add_f32_dpp v20, v20, v20 row_mirror row_mask:0xf bank_mask:0xf bound_ctrl:1
	v_fma_mix_f32 v17, v82, v78, v17 op_sel:[0,1,0] op_sel_hi:[1,1,0]
	v_fma_mix_f32 v18, v82, v79, v18 op_sel:[0,0,0] op_sel_hi:[1,1,0]
	v_fma_mix_f32 v19, v82, v79, v19 op_sel:[0,1,0] op_sel_hi:[1,1,0]
	v_add_f32_e32 v57, v21, v22
	v_fma_mix_f32 v10, v20, v76, v16 op_sel:[0,0,0] op_sel_hi:[0,1,0]
	v_fma_mix_f32 v11, v20, v76, v17 op_sel:[0,1,0] op_sel_hi:[0,1,0]
	v_fma_mix_f32 v12, v20, v77, v18 op_sel:[0,0,0] op_sel_hi:[0,1,0]
	v_fma_mix_f32 v13, v20, v77, v19 op_sel:[0,1,0] op_sel_hi:[0,1,0]
	s_waitcnt lgkmcnt(4)
	ds_read_b64 v[36:37], v6 offset:13328
	ds_read_b128 v[38:41], v6 offset:13584
	ds_read_b128 v[42:45], v6 offset:13840
	ds_read_u16 v46, v7 offset:13328
	v_fma_mix_f32 v14, v10, v86, 0 op_sel:[0,0,0] op_sel_hi:[0,1,0]
	v_fma_mix_f32 v15, v12, v87, 0 op_sel:[0,0,0] op_sel_hi:[0,1,0]
	v_fma_mix_f32 v14, v11, v86, v14 op_sel:[0,1,0] op_sel_hi:[0,1,0]
	v_fma_mix_f32 v15, v13, v87, v15 op_sel:[0,1,0] op_sel_hi:[0,1,0]
	v_fma_mix_f32 v21, v10, v80, 0 op_sel:[0,0,0] op_sel_hi:[0,1,0]
	v_add_f32_e32 v20, v14, v15
	v_fma_mix_f32 v22, v12, v81, 0 op_sel:[0,0,0] op_sel_hi:[0,1,0]
	v_fma_mix_f32 v21, v11, v80, v21 op_sel:[0,1,0] op_sel_hi:[0,1,0]
	v_add_f32_dpp v20, v20, v20 quad_perm:[1,0,3,2] row_mask:0xf bank_mask:0xf bound_ctrl:1
	v_fma_mix_f32 v22, v13, v81, v22 op_sel:[0,1,0] op_sel_hi:[0,1,0]
	v_fma_mix_f32 v16, v10, v84, 0 op_sel:[0,0,0] op_sel_hi:[0,1,0]
	v_add_f32_dpp v20, v20, v20 quad_perm:[2,3,0,1] row_mask:0xf bank_mask:0xf bound_ctrl:1
	v_fma_mix_f32 v17, v11, v84, 0 op_sel:[0,1,0] op_sel_hi:[0,1,0]
	v_fma_mix_f32 v18, v12, v85, 0 op_sel:[0,0,0] op_sel_hi:[0,1,0]
	v_add_f32_dpp v20, v20, v20 row_half_mirror row_mask:0xf bank_mask:0xf bound_ctrl:1
	v_fma_mix_f32 v19, v13, v85, 0 op_sel:[0,1,0] op_sel_hi:[0,1,0]
	v_fma_mix_f32 v16, v94, v90, v16 op_sel:[0,0,0] op_sel_hi:[1,1,0]
	v_add_f32_dpp v20, v20, v20 row_mirror row_mask:0xf bank_mask:0xf bound_ctrl:1
	v_fma_mix_f32 v17, v94, v90, v17 op_sel:[0,1,0] op_sel_hi:[1,1,0]
	v_fma_mix_f32 v18, v94, v91, v18 op_sel:[0,0,0] op_sel_hi:[1,1,0]
	v_fma_mix_f32 v19, v94, v91, v19 op_sel:[0,1,0] op_sel_hi:[1,1,0]
	v_add_f32_e32 v58, v21, v22
	v_fma_mix_f32 v10, v20, v88, v16 op_sel:[0,0,0] op_sel_hi:[0,1,0]
	v_fma_mix_f32 v11, v20, v88, v17 op_sel:[0,1,0] op_sel_hi:[0,1,0]
	v_fma_mix_f32 v12, v20, v89, v18 op_sel:[0,0,0] op_sel_hi:[0,1,0]
	v_fma_mix_f32 v13, v20, v89, v19 op_sel:[0,1,0] op_sel_hi:[0,1,0]
	s_waitcnt lgkmcnt(4)
	ds_read_b64 v[72:73], v6 offset:14352
	ds_read_b128 v[74:77], v6 offset:14608
	ds_read_b128 v[78:81], v6 offset:14864
	ds_read_u16 v82, v7 offset:14352
	v_fma_mix_f32 v14, v10, v26, 0 op_sel:[0,0,0] op_sel_hi:[0,1,0]
	v_fma_mix_f32 v15, v12, v27, 0 op_sel:[0,0,0] op_sel_hi:[0,1,0]
	v_fma_mix_f32 v14, v11, v26, v14 op_sel:[0,1,0] op_sel_hi:[0,1,0]
	v_fma_mix_f32 v15, v13, v27, v15 op_sel:[0,1,0] op_sel_hi:[0,1,0]
	v_fma_mix_f32 v21, v10, v92, 0 op_sel:[0,0,0] op_sel_hi:[0,1,0]
	v_add_f32_e32 v20, v14, v15
	v_fma_mix_f32 v22, v12, v93, 0 op_sel:[0,0,0] op_sel_hi:[0,1,0]
	v_fma_mix_f32 v21, v11, v92, v21 op_sel:[0,1,0] op_sel_hi:[0,1,0]
	v_add_f32_dpp v20, v20, v20 quad_perm:[1,0,3,2] row_mask:0xf bank_mask:0xf bound_ctrl:1
	v_fma_mix_f32 v22, v13, v93, v22 op_sel:[0,1,0] op_sel_hi:[0,1,0]
	v_fma_mix_f32 v16, v10, v24, 0 op_sel:[0,0,0] op_sel_hi:[0,1,0]
	v_add_f32_dpp v20, v20, v20 quad_perm:[2,3,0,1] row_mask:0xf bank_mask:0xf bound_ctrl:1
	v_fma_mix_f32 v17, v11, v24, 0 op_sel:[0,1,0] op_sel_hi:[0,1,0]
	v_fma_mix_f32 v18, v12, v25, 0 op_sel:[0,0,0] op_sel_hi:[0,1,0]
	v_add_f32_dpp v20, v20, v20 row_half_mirror row_mask:0xf bank_mask:0xf bound_ctrl:1
	v_fma_mix_f32 v19, v13, v25, 0 op_sel:[0,1,0] op_sel_hi:[0,1,0]
	v_fma_mix_f32 v16, v34, v30, v16 op_sel:[0,0,0] op_sel_hi:[1,1,0]
	v_add_f32_dpp v20, v20, v20 row_mirror row_mask:0xf bank_mask:0xf bound_ctrl:1
	v_fma_mix_f32 v17, v34, v30, v17 op_sel:[0,1,0] op_sel_hi:[1,1,0]
	v_fma_mix_f32 v18, v34, v31, v18 op_sel:[0,0,0] op_sel_hi:[1,1,0]
	v_fma_mix_f32 v19, v34, v31, v19 op_sel:[0,1,0] op_sel_hi:[1,1,0]
	v_add_f32_e32 v59, v21, v22
	v_fma_mix_f32 v10, v20, v28, v16 op_sel:[0,0,0] op_sel_hi:[0,1,0]
	v_fma_mix_f32 v11, v20, v28, v17 op_sel:[0,1,0] op_sel_hi:[0,1,0]
	v_fma_mix_f32 v12, v20, v29, v18 op_sel:[0,0,0] op_sel_hi:[0,1,0]
	v_fma_mix_f32 v13, v20, v29, v19 op_sel:[0,1,0] op_sel_hi:[0,1,0]
	s_waitcnt lgkmcnt(4)
; template <int DIR>
; DEVINL void rwkv_scan_dir(const Params& p, int task, int lane, int wave) {
;     ...
;   for (int st = 0; st < 4096; st += 32) {
	ds_read_b64 v[84:85], v6 offset:15376
	ds_read_b128 v[86:89], v6 offset:15632
	ds_read_b128 v[90:93], v6 offset:15888
	ds_read_u16 v94, v7 offset:15376
	v_fma_mix_f32 v14, v10, v38, 0 op_sel:[0,0,0] op_sel_hi:[0,1,0]
	v_fma_mix_f32 v15, v12, v39, 0 op_sel:[0,0,0] op_sel_hi:[0,1,0]
	v_fma_mix_f32 v14, v11, v38, v14 op_sel:[0,1,0] op_sel_hi:[0,1,0]
	v_fma_mix_f32 v15, v13, v39, v15 op_sel:[0,1,0] op_sel_hi:[0,1,0]
	v_fma_mix_f32 v21, v10, v32, 0 op_sel:[0,0,0] op_sel_hi:[0,1,0]
	v_add_f32_e32 v20, v14, v15
	v_fma_mix_f32 v22, v12, v33, 0 op_sel:[0,0,0] op_sel_hi:[0,1,0]
	v_fma_mix_f32 v21, v11, v32, v21 op_sel:[0,1,0] op_sel_hi:[0,1,0]
	v_add_f32_dpp v20, v20, v20 quad_perm:[1,0,3,2] row_mask:0xf bank_mask:0xf bound_ctrl:1
	v_fma_mix_f32 v22, v13, v33, v22 op_sel:[0,1,0] op_sel_hi:[0,1,0]
	v_fma_mix_f32 v16, v10, v36, 0 op_sel:[0,0,0] op_sel_hi:[0,1,0]
	v_add_f32_dpp v20, v20, v20 quad_perm:[2,3,0,1] row_mask:0xf bank_mask:0xf bound_ctrl:1
	v_fma_mix_f32 v17, v11, v36, 0 op_sel:[0,1,0] op_sel_hi:[0,1,0]
	v_fma_mix_f32 v18, v12, v37, 0 op_sel:[0,0,0] op_sel_hi:[0,1,0]
	v_add_f32_dpp v20, v20, v20 row_half_mirror row_mask:0xf bank_mask:0xf bound_ctrl:1
	v_fma_mix_f32 v19, v13, v37, 0 op_sel:[0,1,0] op_sel_hi:[0,1,0]
	v_fma_mix_f32 v16, v46, v42, v16 op_sel:[0,0,0] op_sel_hi:[1,1,0]
	v_add_f32_dpp v20, v20, v20 row_mirror row_mask:0xf bank_mask:0xf bound_ctrl:1
	v_fma_mix_f32 v17, v46, v42, v17 op_sel:[0,1,0] op_sel_hi:[1,1,0]
	v_fma_mix_f32 v18, v46, v43, v18 op_sel:[0,0,0] op_sel_hi:[1,1,0]
	v_fma_mix_f32 v19, v46, v43, v19 op_sel:[0,1,0] op_sel_hi:[1,1,0]
	v_add_f32_e32 v60, v21, v22
	v_fma_mix_f32 v10, v20, v40, v16 op_sel:[0,0,0] op_sel_hi:[0,1,0]
	v_fma_mix_f32 v11, v20, v40, v17 op_sel:[0,1,0] op_sel_hi:[0,1,0]
	v_fma_mix_f32 v12, v20, v41, v18 op_sel:[0,0,0] op_sel_hi:[0,1,0]
	v_fma_mix_f32 v13, v20, v41, v19 op_sel:[0,1,0] op_sel_hi:[0,1,0]
	s_waitcnt lgkmcnt(4)
	v_add_u32_e32 v6, 0x4000, v6
	v_add_u32_e32 v7, 0x4000, v7
	v_and_b32_e32 v6, 0x1ffff, v6
	v_and_b32_e32 v7, 0x1ffff, v7
	ds_read_b64 v[24:25], v6 offset:16
	ds_read_b128 v[26:29], v6 offset:272
	ds_read_b128 v[30:33], v6 offset:528
	ds_read_u16 v34, v7 offset:16
	v_fma_mix_f32 v14, v10, v74, 0 op_sel:[0,0,0] op_sel_hi:[0,1,0]
	v_fma_mix_f32 v15, v12, v75, 0 op_sel:[0,0,0] op_sel_hi:[0,1,0]
	v_fma_mix_f32 v14, v11, v74, v14 op_sel:[0,1,0] op_sel_hi:[0,1,0]
	v_fma_mix_f32 v15, v13, v75, v15 op_sel:[0,1,0] op_sel_hi:[0,1,0]
	v_fma_mix_f32 v21, v10, v44, 0 op_sel:[0,0,0] op_sel_hi:[0,1,0]
	v_add_f32_e32 v20, v14, v15
	v_fma_mix_f32 v22, v12, v45, 0 op_sel:[0,0,0] op_sel_hi:[0,1,0]
	v_fma_mix_f32 v21, v11, v44, v21 op_sel:[0,1,0] op_sel_hi:[0,1,0]
	v_add_f32_dpp v20, v20, v20 quad_perm:[1,0,3,2] row_mask:0xf bank_mask:0xf bound_ctrl:1
	v_fma_mix_f32 v22, v13, v45, v22 op_sel:[0,1,0] op_sel_hi:[0,1,0]
	v_fma_mix_f32 v16, v10, v72, 0 op_sel:[0,0,0] op_sel_hi:[0,1,0]
	v_add_f32_dpp v20, v20, v20 quad_perm:[2,3,0,1] row_mask:0xf bank_mask:0xf bound_ctrl:1
	v_fma_mix_f32 v17, v11, v72, 0 op_sel:[0,1,0] op_sel_hi:[0,1,0]
	v_fma_mix_f32 v18, v12, v73, 0 op_sel:[0,0,0] op_sel_hi:[0,1,0]
	v_add_f32_dpp v20, v20, v20 row_half_mirror row_mask:0xf bank_mask:0xf bound_ctrl:1
	v_fma_mix_f32 v19, v13, v73, 0 op_sel:[0,1,0] op_sel_hi:[0,1,0]
	v_fma_mix_f32 v16, v82, v78, v16 op_sel:[0,0,0] op_sel_hi:[1,1,0]
	v_add_f32_dpp v20, v20, v20 row_mirror row_mask:0xf bank_mask:0xf bound_ctrl:1
	v_fma_mix_f32 v17, v82, v78, v17 op_sel:[0,1,0] op_sel_hi:[1,1,0]
	v_fma_mix_f32 v18, v82, v79, v18 op_sel:[0,0,0] op_sel_hi:[1,1,0]
	v_fma_mix_f32 v19, v82, v79, v19 op_sel:[0,1,0] op_sel_hi:[1,1,0]
	v_add_f32_e32 v61, v21, v22
	v_fma_mix_f32 v10, v20, v76, v16 op_sel:[0,0,0] op_sel_hi:[0,1,0]
	v_fma_mix_f32 v11, v20, v76, v17 op_sel:[0,1,0] op_sel_hi:[0,1,0]
	v_fma_mix_f32 v12, v20, v77, v18 op_sel:[0,0,0] op_sel_hi:[0,1,0]
	v_fma_mix_f32 v13, v20, v77, v19 op_sel:[0,1,0] op_sel_hi:[0,1,0]
	s_waitcnt lgkmcnt(4)
	ds_read_b64 v[36:37], v6 offset:1040
	ds_read_b128 v[38:41], v6 offset:1296
	ds_read_b128 v[42:45], v6 offset:1552
	ds_read_u16 v46, v7 offset:1040
	v_fma_mix_f32 v14, v10, v86, 0 op_sel:[0,0,0] op_sel_hi:[0,1,0]
	v_fma_mix_f32 v15, v12, v87, 0 op_sel:[0,0,0] op_sel_hi:[0,1,0]
	v_fma_mix_f32 v14, v11, v86, v14 op_sel:[0,1,0] op_sel_hi:[0,1,0]
	v_fma_mix_f32 v15, v13, v87, v15 op_sel:[0,1,0] op_sel_hi:[0,1,0]
	v_fma_mix_f32 v21, v10, v80, 0 op_sel:[0,0,0] op_sel_hi:[0,1,0]
	v_add_f32_e32 v20, v14, v15
	v_fma_mix_f32 v22, v12, v81, 0 op_sel:[0,0,0] op_sel_hi:[0,1,0]
	v_fma_mix_f32 v21, v11, v80, v21 op_sel:[0,1,0] op_sel_hi:[0,1,0]
	v_add_f32_dpp v20, v20, v20 quad_perm:[1,0,3,2] row_mask:0xf bank_mask:0xf bound_ctrl:1
	v_fma_mix_f32 v22, v13, v81, v22 op_sel:[0,1,0] op_sel_hi:[0,1,0]
	v_fma_mix_f32 v16, v10, v84, 0 op_sel:[0,0,0] op_sel_hi:[0,1,0]
	v_add_f32_dpp v20, v20, v20 quad_perm:[2,3,0,1] row_mask:0xf bank_mask:0xf bound_ctrl:1
	v_fma_mix_f32 v17, v11, v84, 0 op_sel:[0,1,0] op_sel_hi:[0,1,0]
	v_fma_mix_f32 v18, v12, v85, 0 op_sel:[0,0,0] op_sel_hi:[0,1,0]
	v_add_f32_dpp v20, v20, v20 row_half_mirror row_mask:0xf bank_mask:0xf bound_ctrl:1
	v_fma_mix_f32 v19, v13, v85, 0 op_sel:[0,1,0] op_sel_hi:[0,1,0]
	v_fma_mix_f32 v16, v94, v90, v16 op_sel:[0,0,0] op_sel_hi:[1,1,0]
	v_add_f32_dpp v20, v20, v20 row_mirror row_mask:0xf bank_mask:0xf bound_ctrl:1
	v_fma_mix_f32 v17, v94, v90, v17 op_sel:[0,1,0] op_sel_hi:[1,1,0]
	v_fma_mix_f32 v18, v94, v91, v18 op_sel:[0,0,0] op_sel_hi:[1,1,0]
	v_fma_mix_f32 v19, v94, v91, v19 op_sel:[0,1,0] op_sel_hi:[1,1,0]
	v_add_f32_e32 v62, v21, v22
	v_fma_mix_f32 v10, v20, v88, v16 op_sel:[0,0,0] op_sel_hi:[0,1,0]
	v_fma_mix_f32 v11, v20, v88, v17 op_sel:[0,1,0] op_sel_hi:[0,1,0]
	v_fma_mix_f32 v12, v20, v89, v18 op_sel:[0,0,0] op_sel_hi:[0,1,0]
	v_fma_mix_f32 v13, v20, v89, v19 op_sel:[0,1,0] op_sel_hi:[0,1,0]
	s_waitcnt lgkmcnt(4)
	s_add_u32 s15, s15, 1
	s_add_u32 s14, s14, 1
	v_mov_b32_e32 v69, s15
	ds_write_b32 v68, v69
	s_cmp_lt_u32 s14, 0x100
	s_cbranch_scc1 .Lrw_blk_d0
; DEVINL u16 f2bf(float a) { return (u16)(pk2(a, 0.f) & 0xffffu); }
; template <int DIR>
; DEVINL void rwkv_scan_dir(const Params& p, int task, int lane, int wave) {
;     ...
;   const char* recbase = p.ws + O_REC + ((long)(b * 16 + head) * 4096) * 1024 + lane * 16;
;   const unsigned ring_lds = (unsigned)(unsigned long)(__attribute__((address_space(3))) char*)(dynsmem + wave * 32768);
;   const unsigned ring_u = __builtin_amdgcn_readfirstlane(ring_lds);
;   const unsigned a_seg = ring_lds + seg * 64;
;   const unsigned a_v = ring_lds + (row >> 2) * 64 + 48 + (row & 3) * 2;
;   u16* yo = (u16*)(p.ws + (DIR ? O_YB : O_YSUM)) + ((long)b * 4096) * 1024 + head * 64 + row;
;   float s0 = 0.f, s1 = 0.f, s2 = 0.f, s3 = 0.f;
;   float ykeep = 0.f;
;   const char* recdir = recbase + (DIR ? (long)4095 * 1024 : 0);
;     ...
;   {
;     const float ylast = allred16(ypart);
;     ykeep = (seg == 15) ? ylast : ykeep;
;     const int q0 = 4096 - 16 + seg; yo[(long)(DIR ? (4095 - q0) : q0) * 1024] = f2bf(ykeep);
	v_fma_mix_f32 v21, v10, v92, 0 op_sel:[0,0,0] op_sel_hi:[0,1,0]
	v_fma_mix_f32 v22, v12, v93, 0 op_sel:[0,0,0] op_sel_hi:[0,1,0]
	v_fma_mix_f32 v21, v11, v92, v21 op_sel:[0,1,0] op_sel_hi:[0,1,0]
	v_fma_mix_f32 v22, v13, v93, v22 op_sel:[0,1,0] op_sel_hi:[0,1,0]
	v_add_f32_e32 v63, v21, v22
	s_nop 1
	v_add_f32_dpp v48, v48, v48 row_ror:8 row_mask:0xf bank_mask:0x3
	v_add_f32_dpp v49, v49, v49 row_ror:8 row_mask:0xf bank_mask:0x3
	v_add_f32_dpp v50, v50, v50 row_ror:8 row_mask:0xf bank_mask:0x3
	v_add_f32_dpp v51, v51, v51 row_ror:8 row_mask:0xf bank_mask:0x3
	v_add_f32_dpp v52, v52, v52 row_ror:8 row_mask:0xf bank_mask:0x3
	v_add_f32_dpp v53, v53, v53 row_ror:8 row_mask:0xf bank_mask:0x3
	v_add_f32_dpp v54, v54, v54 row_ror:8 row_mask:0xf bank_mask:0x3
	v_add_f32_dpp v55, v55, v55 row_ror:8 row_mask:0xf bank_mask:0x3
	v_add_f32_dpp v48, v56, v56 row_ror:8 row_mask:0xf bank_mask:0xc
	v_add_f32_dpp v49, v57, v57 row_ror:8 row_mask:0xf bank_mask:0xc
	v_add_f32_dpp v50, v58, v58 row_ror:8 row_mask:0xf bank_mask:0xc
	v_add_f32_dpp v51, v59, v59 row_ror:8 row_mask:0xf bank_mask:0xc
	v_add_f32_dpp v52, v60, v60 row_ror:8 row_mask:0xf bank_mask:0xc
	v_add_f32_dpp v53, v61, v61 row_ror:8 row_mask:0xf bank_mask:0xc
	v_add_f32_dpp v54, v62, v62 row_ror:8 row_mask:0xf bank_mask:0xc
	v_add_f32_dpp v55, v63, v63 row_ror:8 row_mask:0xf bank_mask:0xc
	v_add_f32_dpp v48, v48, v48 row_ror:12 row_mask:0xf bank_mask:0x5
	v_add_f32_dpp v49, v49, v49 row_ror:12 row_mask:0xf bank_mask:0x5
	v_add_f32_dpp v50, v50, v50 row_ror:12 row_mask:0xf bank_mask:0x5
	v_add_f32_dpp v51, v51, v51 row_ror:12 row_mask:0xf bank_mask:0x5
	v_add_f32_dpp v48, v52, v52 row_ror:4 row_mask:0xf bank_mask:0xa
	v_add_f32_dpp v49, v53, v53 row_ror:4 row_mask:0xf bank_mask:0xa
	v_add_f32_dpp v50, v54, v54 row_ror:4 row_mask:0xf bank_mask:0xa
	v_add_f32_dpp v51, v55, v55 row_ror:4 row_mask:0xf bank_mask:0xa
	v_add_f32_dpp v64, v48, v48 quad_perm:[2,3,0,1] row_mask:0xf bank_mask:0xf bound_ctrl:1
	v_add_f32_dpp v65, v50, v50 quad_perm:[2,3,0,1] row_mask:0xf bank_mask:0xf bound_ctrl:1
	v_cndmask_b32_e64 v56, v64, v65, s[50:51]
	v_add_f32_dpp v64, v49, v49 quad_perm:[2,3,0,1] row_mask:0xf bank_mask:0xf bound_ctrl:1
	v_add_f32_dpp v65, v51, v51 quad_perm:[2,3,0,1] row_mask:0xf bank_mask:0xf bound_ctrl:1
	v_cndmask_b32_e64 v57, v64, v65, s[50:51]
	v_add_f32_dpp v64, v56, v56 quad_perm:[1,0,3,2] row_mask:0xf bank_mask:0xf bound_ctrl:1
	s_nop 0
	v_add_f32_dpp v65, v57, v57 quad_perm:[1,0,3,2] row_mask:0xf bank_mask:0xf bound_ctrl:1
	v_cndmask_b32_e64 v66, v64, v65, s[48:49]
	v_cvt_pk_bf16_f32 v66, v66, v66
	global_store_short v8, v66, s[12:13]
	s_add_u32 s12, s12, 0x8000
	s_addc_u32 s13, s13, 0
	s_branch .Lrw_next
.Lrw_bwd:
	s_add_u32 s12, s12, 0x1f700000
	s_addc_u32 s13, s13, 0
	v_sub_u32_e32 v69, 0xfff, v3
	v_lshl_add_u32 v8, v69, 11, v8
	s_add_u32 s10, s10, 0x3ff000
	s_addc_u32 s11, s11, 0
	s_sub_u32 s10, s10, s39
	s_subb_u32 s11, s11, 0
	s_sub_u32 s40, 0x1f000, s39
	s_mov_b32 s41, 0
	v_lshlrev_b32_e32 v6, 4, v3
	v_add_u32_e32 v6, 0x1c000, v6
	s_add_u32 s3, s37, 0x1c300
	v_lshl_add_u32 v7, v4, 1, s3
	s_add_u32 s3, s40, s41
	s_and_b32 s3, s3, 0x1ffff
	s_add_u32 s3, s3, 16
	s_mov_b32 m0, s3
	s_nop 0
	global_load_lds_dwordx4 v5, s[10:11] offset:0
	global_load_lds_dwordx4 v5, s[10:11] offset:1024
	global_load_lds_dwordx4 v5, s[10:11] offset:2048
	global_load_lds_dwordx4 v5, s[10:11] offset:3072
	s_sub_u32 s10, s10, 0x4000
	s_subb_u32 s11, s11, 0
	s_sub_u32 s41, s41, 0x4000
	s_and_b32 s41, s41, 0x1ffff
	s_add_u32 s3, s40, s41
	s_and_b32 s3, s3, 0x1ffff
	s_add_u32 s3, s3, 16
	s_mov_b32 m0, s3
	s_nop 0
	global_load_lds_dwordx4 v5, s[10:11] offset:0
	global_load_lds_dwordx4 v5, s[10:11] offset:1024
	global_load_lds_dwordx4 v5, s[10:11] offset:2048
	global_load_lds_dwordx4 v5, s[10:11] offset:3072
	s_sub_u32 s10, s10, 0x4000
	s_subb_u32 s11, s11, 0
	s_sub_u32 s41, s41, 0x4000
	s_and_b32 s41, s41, 0x1ffff
	s_add_u32 s3, s40, s41
	s_and_b32 s3, s3, 0x1ffff
	s_add_u32 s3, s3, 16
	s_mov_b32 m0, s3
	s_nop 0
	global_load_lds_dwordx4 v5, s[10:11] offset:0
	global_load_lds_dwordx4 v5, s[10:11] offset:1024
	global_load_lds_dwordx4 v5, s[10:11] offset:2048
	global_load_lds_dwordx4 v5, s[10:11] offset:3072
	s_sub_u32 s10, s10, 0x4000
	s_subb_u32 s11, s11, 0
	s_sub_u32 s41, s41, 0x4000
	s_and_b32 s41, s41, 0x1ffff
	s_waitcnt vmcnt(0)
	v_mov_b32_e32 v10, 0
	v_mov_b32_e32 v11, 0
	v_mov_b32_e32 v12, 0
	v_mov_b32_e32 v13, 0
	s_mov_b32 s14, 0
	s_add_u32 s3, s15, 3
	v_mov_b32_e32 v69, s3
	ds_write_b32 v23, v69
	s_add_u32 s43, s15, 2
	s_sub_u32 s44, s15, 4
	s_max_i32 s44, s44, 0
	s_mov_b32 s42, 0

.Lrw_ready_d1p:
	ds_read_b64 v[24:25], v6 offset:15384
	ds_read_b128 v[26:29], v6 offset:15632
	ds_read_b128 v[30:33], v6 offset:15888
	ds_read_u16 v34, v7 offset:15376
	ds_read_b64 v[36:37], v6 offset:14360
	ds_read_b128 v[38:41], v6 offset:14608
	ds_read_b128 v[42:45], v6 offset:14864
	ds_read_u16 v46, v7 offset:14352
	s_waitcnt lgkmcnt(0)

; DEVINL u16 f2bf(float a) { return (u16)(pk2(a, 0.f) & 0xffffu); }
; #define RW_STEP2(B) RW_STEP(B, WvA, XA, KrA, vhA, WvB, XB, KrB, vhB); RW_STEP((B) + 1, WvB, XB, KrB, vhB, WvA, XA, KrA, vhA)
; #define RW_STEP4(B) RW_STEP2(B); RW_STEP2((B) + 2)
; template <int DIR>
; DEVINL void rwkv_scan_dir(const Params& p, int task, int lane, int wave) {
;     ...
;     if (st > 0) { const int q0 = st - 16 + seg; yo[(long)(DIR ? (4095 - q0) : q0) * 1024] = f2bf(ykeep); }
;     RW_STEP(1, WvB, XB, KrB, vhB, WvA, XA, KrA, vhA);
;     RW_STEP2(2); RW_STEP4(4); RW_STEP4(8); RW_STEP4(12);
;     RW_STEP(16, WvA, XA, KrA, vhA, WvB, XB, KrB, vhB);
;     { const int q0 = st + seg; yo[(long)(DIR ? (4095 - q0) : q0) * 1024] = f2bf(ykeep); }
.Lrw_ready_d1:
	s_add_u32 s3, s40, s41
	s_and_b32 s3, s3, 0x1ffff
	s_add_u32 s3, s3, 16
	s_mov_b32 m0, s3
	s_nop 0
	global_load_lds_dwordx4 v5, s[10:11] offset:0
	global_load_lds_dwordx4 v5, s[10:11] offset:1024
	global_load_lds_dwordx4 v5, s[10:11] offset:2048
	global_load_lds_dwordx4 v5, s[10:11] offset:3072
	s_sub_u32 s10, s10, 0x4000
	s_subb_u32 s11, s11, 0
	s_sub_u32 s41, s41, 0x4000
	s_and_b32 s41, s41, 0x1ffff
	ds_read_b64 v[72:73], v6 offset:13336
	ds_read_b128 v[74:77], v6 offset:13584
	ds_read_b128 v[78:81], v6 offset:13840
	ds_read_u16 v82, v7 offset:13328
	v_fma_mix_f32 v14, v10, v26, 0 op_sel:[0,0,0] op_sel_hi:[0,1,0]
	v_fma_mix_f32 v15, v12, v27, 0 op_sel:[0,0,0] op_sel_hi:[0,1,0]
	v_fma_mix_f32 v14, v11, v26, v14 op_sel:[0,1,0] op_sel_hi:[0,1,0]
	v_fma_mix_f32 v15, v13, v27, v15 op_sel:[0,1,0] op_sel_hi:[0,1,0]
	v_fma_mix_f32 v21, v10, v92, 0 op_sel:[0,0,0] op_sel_hi:[0,1,0]
	v_add_f32_e32 v20, v14, v15
	v_fma_mix_f32 v22, v12, v93, 0 op_sel:[0,0,0] op_sel_hi:[0,1,0]
	v_fma_mix_f32 v21, v11, v92, v21 op_sel:[0,1,0] op_sel_hi:[0,1,0]
	v_add_f32_dpp v20, v20, v20 quad_perm:[1,0,3,2] row_mask:0xf bank_mask:0xf bound_ctrl:1
	v_fma_mix_f32 v22, v13, v93, v22 op_sel:[0,1,0] op_sel_hi:[0,1,0]
	v_fma_mix_f32 v16, v10, v24, 0 op_sel:[0,0,0] op_sel_hi:[0,1,0]
	v_add_f32_dpp v20, v20, v20 quad_perm:[2,3,0,1] row_mask:0xf bank_mask:0xf bound_ctrl:1
	v_fma_mix_f32 v17, v11, v24, 0 op_sel:[0,1,0] op_sel_hi:[0,1,0]
	v_fma_mix_f32 v18, v12, v25, 0 op_sel:[0,0,0] op_sel_hi:[0,1,0]
	v_add_f32_dpp v20, v20, v20 row_half_mirror row_mask:0xf bank_mask:0xf bound_ctrl:1
	v_fma_mix_f32 v19, v13, v25, 0 op_sel:[0,1,0] op_sel_hi:[0,1,0]
	v_fma_mix_f32 v16, v34, v30, v16 op_sel:[0,0,0] op_sel_hi:[1,1,0]
	v_add_f32_dpp v20, v20, v20 row_mirror row_mask:0xf bank_mask:0xf bound_ctrl:1
	v_fma_mix_f32 v17, v34, v30, v17 op_sel:[0,1,0] op_sel_hi:[1,1,0]
	v_fma_mix_f32 v18, v34, v31, v18 op_sel:[0,0,0] op_sel_hi:[1,1,0]
	v_fma_mix_f32 v19, v34, v31, v19 op_sel:[0,1,0] op_sel_hi:[1,1,0]
	v_add_f32_e32 v63, v21, v22
	v_fma_mix_f32 v10, v20, v28, v16 op_sel:[0,0,0] op_sel_hi:[0,1,0]
	v_fma_mix_f32 v11, v20, v28, v17 op_sel:[0,1,0] op_sel_hi:[0,1,0]
	v_fma_mix_f32 v12, v20, v29, v18 op_sel:[0,0,0] op_sel_hi:[0,1,0]
	v_fma_mix_f32 v13, v20, v29, v19 op_sel:[0,1,0] op_sel_hi:[0,1,0]
	s_waitcnt lgkmcnt(4)
	s_cmp_eq_u32 s14, 0
	s_cbranch_scc1 .Lrw_skip_d1
	v_add_f32_dpp v48, v48, v48 row_ror:8 row_mask:0xf bank_mask:0x3
	v_add_f32_dpp v49, v49, v49 row_ror:8 row_mask:0xf bank_mask:0x3
	v_add_f32_dpp v50, v50, v50 row_ror:8 row_mask:0xf bank_mask:0x3
	v_add_f32_dpp v51, v51, v51 row_ror:8 row_mask:0xf bank_mask:0x3
	v_add_f32_dpp v52, v52, v52 row_ror:8 row_mask:0xf bank_mask:0x3
	v_add_f32_dpp v53, v53, v53 row_ror:8 row_mask:0xf bank_mask:0x3
	v_add_f32_dpp v54, v54, v54 row_ror:8 row_mask:0xf bank_mask:0x3
	v_add_f32_dpp v55, v55, v55 row_ror:8 row_mask:0xf bank_mask:0x3
	v_add_f32_dpp v48, v56, v56 row_ror:8 row_mask:0xf bank_mask:0xc
	v_add_f32_dpp v49, v57, v57 row_ror:8 row_mask:0xf bank_mask:0xc
	v_add_f32_dpp v50, v58, v58 row_ror:8 row_mask:0xf bank_mask:0xc
	v_add_f32_dpp v51, v59, v59 row_ror:8 row_mask:0xf bank_mask:0xc
	v_add_f32_dpp v52, v60, v60 row_ror:8 row_mask:0xf bank_mask:0xc
	v_add_f32_dpp v53, v61, v61 row_ror:8 row_mask:0xf bank_mask:0xc
	v_add_f32_dpp v54, v62, v62 row_ror:8 row_mask:0xf bank_mask:0xc
	v_add_f32_dpp v55, v63, v63 row_ror:8 row_mask:0xf bank_mask:0xc
	v_add_f32_dpp v48, v48, v48 row_ror:12 row_mask:0xf bank_mask:0x5
	v_add_f32_dpp v49, v49, v49 row_ror:12 row_mask:0xf bank_mask:0x5
	v_add_f32_dpp v50, v50, v50 row_ror:12 row_mask:0xf bank_mask:0x5
	v_add_f32_dpp v51, v51, v51 row_ror:12 row_mask:0xf bank_mask:0x5
	v_add_f32_dpp v48, v52, v52 row_ror:4 row_mask:0xf bank_mask:0xa
	v_add_f32_dpp v49, v53, v53 row_ror:4 row_mask:0xf bank_mask:0xa
	v_add_f32_dpp v50, v54, v54 row_ror:4 row_mask:0xf bank_mask:0xa
	v_add_f32_dpp v51, v55, v55 row_ror:4 row_mask:0xf bank_mask:0xa
	v_add_f32_dpp v64, v48, v48 quad_perm:[2,3,0,1] row_mask:0xf bank_mask:0xf bound_ctrl:1
	v_add_f32_dpp v65, v50, v50 quad_perm:[2,3,0,1] row_mask:0xf bank_mask:0xf bound_ctrl:1
	v_cndmask_b32_e64 v56, v64, v65, s[50:51]
	v_add_f32_dpp v64, v49, v49 quad_perm:[2,3,0,1] row_mask:0xf bank_mask:0xf bound_ctrl:1
	v_add_f32_dpp v65, v51, v51 quad_perm:[2,3,0,1] row_mask:0xf bank_mask:0xf bound_ctrl:1
	v_cndmask_b32_e64 v57, v64, v65, s[50:51]
	v_add_f32_dpp v64, v56, v56 quad_perm:[1,0,3,2] row_mask:0xf bank_mask:0xf bound_ctrl:1
	s_nop 0
	v_add_f32_dpp v65, v57, v57 quad_perm:[1,0,3,2] row_mask:0xf bank_mask:0xf bound_ctrl:1
	v_cndmask_b32_e64 v66, v64, v65, s[48:49]
	v_cvt_pk_bf16_f32 v66, v66, v66
	global_store_short v8, v66, s[12:13]
	s_sub_u32 s12, s12, 0x8000
	s_subb_u32 s13, s13, 0
.Lrw_skip_d1:
	ds_read_b64 v[84:85], v6 offset:12312
	ds_read_b128 v[86:89], v6 offset:12560
	ds_read_b128 v[90:93], v6 offset:12816
	ds_read_u16 v94, v7 offset:12304
	v_fma_mix_f32 v14, v10, v38, 0 op_sel:[0,0,0] op_sel_hi:[0,1,0]
	v_fma_mix_f32 v15, v12, v39, 0 op_sel:[0,0,0] op_sel_hi:[0,1,0]
	v_fma_mix_f32 v14, v11, v38, v14 op_sel:[0,1,0] op_sel_hi:[0,1,0]
	v_fma_mix_f32 v15, v13, v39, v15 op_sel:[0,1,0] op_sel_hi:[0,1,0]
	v_fma_mix_f32 v21, v10, v32, 0 op_sel:[0,0,0] op_sel_hi:[0,1,0]
	v_add_f32_e32 v20, v14, v15
	v_fma_mix_f32 v22, v12, v33, 0 op_sel:[0,0,0] op_sel_hi:[0,1,0]
	v_fma_mix_f32 v21, v11, v32, v21 op_sel:[0,1,0] op_sel_hi:[0,1,0]
	v_add_f32_dpp v20, v20, v20 quad_perm:[1,0,3,2] row_mask:0xf bank_mask:0xf bound_ctrl:1
	v_fma_mix_f32 v22, v13, v33, v22 op_sel:[0,1,0] op_sel_hi:[0,1,0]
	v_fma_mix_f32 v16, v10, v36, 0 op_sel:[0,0,0] op_sel_hi:[0,1,0]
	v_add_f32_dpp v20, v20, v20 quad_perm:[2,3,0,1] row_mask:0xf bank_mask:0xf bound_ctrl:1
	v_fma_mix_f32 v17, v11, v36, 0 op_sel:[0,1,0] op_sel_hi:[0,1,0]
	v_fma_mix_f32 v18, v12, v37, 0 op_sel:[0,0,0] op_sel_hi:[0,1,0]
	v_add_f32_dpp v20, v20, v20 row_half_mirror row_mask:0xf bank_mask:0xf bound_ctrl:1
	v_fma_mix_f32 v19, v13, v37, 0 op_sel:[0,1,0] op_sel_hi:[0,1,0]
	v_fma_mix_f32 v16, v46, v42, v16 op_sel:[0,0,0] op_sel_hi:[1,1,0]
	v_add_f32_dpp v20, v20, v20 row_mirror row_mask:0xf bank_mask:0xf bound_ctrl:1
	v_fma_mix_f32 v17, v46, v42, v17 op_sel:[0,1,0] op_sel_hi:[1,1,0]
	v_fma_mix_f32 v18, v46, v43, v18 op_sel:[0,0,0] op_sel_hi:[1,1,0]
	v_fma_mix_f32 v19, v46, v43, v19 op_sel:[0,1,0] op_sel_hi:[1,1,0]
	v_add_f32_e32 v48, v21, v22
	v_fma_mix_f32 v10, v20, v40, v16 op_sel:[0,0,0] op_sel_hi:[0,1,0]
	v_fma_mix_f32 v11, v20, v40, v17 op_sel:[0,1,0] op_sel_hi:[0,1,0]
	v_fma_mix_f32 v12, v20, v41, v18 op_sel:[0,0,0] op_sel_hi:[0,1,0]
	v_fma_mix_f32 v13, v20, v41, v19 op_sel:[0,1,0] op_sel_hi:[0,1,0]
	s_waitcnt lgkmcnt(4)
	ds_read_b64 v[24:25], v6 offset:11288
	ds_read_b128 v[26:29], v6 offset:11536
	ds_read_b128 v[30:33], v6 offset:11792
	ds_read_u16 v34, v7 offset:11280
	v_fma_mix_f32 v14, v10, v74, 0 op_sel:[0,0,0] op_sel_hi:[0,1,0]
	v_fma_mix_f32 v15, v12, v75, 0 op_sel:[0,0,0] op_sel_hi:[0,1,0]
	v_fma_mix_f32 v14, v11, v74, v14 op_sel:[0,1,0] op_sel_hi:[0,1,0]
	v_fma_mix_f32 v15, v13, v75, v15 op_sel:[0,1,0] op_sel_hi:[0,1,0]
	v_fma_mix_f32 v21, v10, v44, 0 op_sel:[0,0,0] op_sel_hi:[0,1,0]
	v_add_f32_e32 v20, v14, v15
	v_fma_mix_f32 v22, v12, v45, 0 op_sel:[0,0,0] op_sel_hi:[0,1,0]
	v_fma_mix_f32 v21, v11, v44, v21 op_sel:[0,1,0] op_sel_hi:[0,1,0]
	v_add_f32_dpp v20, v20, v20 quad_perm:[1,0,3,2] row_mask:0xf bank_mask:0xf bound_ctrl:1
	v_fma_mix_f32 v22, v13, v45, v22 op_sel:[0,1,0] op_sel_hi:[0,1,0]
	v_fma_mix_f32 v16, v10, v72, 0 op_sel:[0,0,0] op_sel_hi:[0,1,0]
	v_add_f32_dpp v20, v20, v20 quad_perm:[2,3,0,1] row_mask:0xf bank_mask:0xf bound_ctrl:1
	v_fma_mix_f32 v17, v11, v72, 0 op_sel:[0,1,0] op_sel_hi:[0,1,0]
	v_fma_mix_f32 v18, v12, v73, 0 op_sel:[0,0,0] op_sel_hi:[0,1,0]
	v_add_f32_dpp v20, v20, v20 row_half_mirror row_mask:0xf bank_mask:0xf bound_ctrl:1
	v_fma_mix_f32 v19, v13, v73, 0 op_sel:[0,1,0] op_sel_hi:[0,1,0]
	v_fma_mix_f32 v16, v82, v78, v16 op_sel:[0,0,0] op_sel_hi:[1,1,0]
	v_add_f32_dpp v20, v20, v20 row_mirror row_mask:0xf bank_mask:0xf bound_ctrl:1
	v_fma_mix_f32 v17, v82, v78, v17 op_sel:[0,1,0] op_sel_hi:[1,1,0]
	v_fma_mix_f32 v18, v82, v79, v18 op_sel:[0,0,0] op_sel_hi:[1,1,0]
	v_fma_mix_f32 v19, v82, v79, v19 op_sel:[0,1,0] op_sel_hi:[1,1,0]
	v_add_f32_e32 v49, v21, v22
	v_fma_mix_f32 v10, v20, v76, v16 op_sel:[0,0,0] op_sel_hi:[0,1,0]
	v_fma_mix_f32 v11, v20, v76, v17 op_sel:[0,1,0] op_sel_hi:[0,1,0]
	v_fma_mix_f32 v12, v20, v77, v18 op_sel:[0,0,0] op_sel_hi:[0,1,0]
	v_fma_mix_f32 v13, v20, v77, v19 op_sel:[0,1,0] op_sel_hi:[0,1,0]
	s_waitcnt lgkmcnt(4)
	ds_read_b64 v[36:37], v6 offset:10264
	ds_read_b128 v[38:41], v6 offset:10512
	ds_read_b128 v[42:45], v6 offset:10768
	ds_read_u16 v46, v7 offset:10256
	v_fma_mix_f32 v14, v10, v86, 0 op_sel:[0,0,0] op_sel_hi:[0,1,0]
	v_fma_mix_f32 v15, v12, v87, 0 op_sel:[0,0,0] op_sel_hi:[0,1,0]
	v_fma_mix_f32 v14, v11, v86, v14 op_sel:[0,1,0] op_sel_hi:[0,1,0]
	v_fma_mix_f32 v15, v13, v87, v15 op_sel:[0,1,0] op_sel_hi:[0,1,0]
	v_fma_mix_f32 v21, v10, v80, 0 op_sel:[0,0,0] op_sel_hi:[0,1,0]
	v_add_f32_e32 v20, v14, v15
	v_fma_mix_f32 v22, v12, v81, 0 op_sel:[0,0,0] op_sel_hi:[0,1,0]
	v_fma_mix_f32 v21, v11, v80, v21 op_sel:[0,1,0] op_sel_hi:[0,1,0]
	v_add_f32_dpp v20, v20, v20 quad_perm:[1,0,3,2] row_mask:0xf bank_mask:0xf bound_ctrl:1
	v_fma_mix_f32 v22, v13, v81, v22 op_sel:[0,1,0] op_sel_hi:[0,1,0]
	v_fma_mix_f32 v16, v10, v84, 0 op_sel:[0,0,0] op_sel_hi:[0,1,0]
	v_add_f32_dpp v20, v20, v20 quad_perm:[2,3,0,1] row_mask:0xf bank_mask:0xf bound_ctrl:1
	v_fma_mix_f32 v17, v11, v84, 0 op_sel:[0,1,0] op_sel_hi:[0,1,0]
	v_fma_mix_f32 v18, v12, v85, 0 op_sel:[0,0,0] op_sel_hi:[0,1,0]
	v_add_f32_dpp v20, v20, v20 row_half_mirror row_mask:0xf bank_mask:0xf bound_ctrl:1
	v_fma_mix_f32 v19, v13, v85, 0 op_sel:[0,1,0] op_sel_hi:[0,1,0]
	v_fma_mix_f32 v16, v94, v90, v16 op_sel:[0,0,0] op_sel_hi:[1,1,0]
	v_add_f32_dpp v20, v20, v20 row_mirror row_mask:0xf bank_mask:0xf bound_ctrl:1
	v_fma_mix_f32 v17, v94, v90, v17 op_sel:[0,1,0] op_sel_hi:[1,1,0]
	v_fma_mix_f32 v18, v94, v91, v18 op_sel:[0,0,0] op_sel_hi:[1,1,0]
	v_fma_mix_f32 v19, v94, v91, v19 op_sel:[0,1,0] op_sel_hi:[1,1,0]
	v_add_f32_e32 v50, v21, v22
	v_fma_mix_f32 v10, v20, v88, v16 op_sel:[0,0,0] op_sel_hi:[0,1,0]
	v_fma_mix_f32 v11, v20, v88, v17 op_sel:[0,1,0] op_sel_hi:[0,1,0]
	v_fma_mix_f32 v12, v20, v89, v18 op_sel:[0,0,0] op_sel_hi:[0,1,0]
	v_fma_mix_f32 v13, v20, v89, v19 op_sel:[0,1,0] op_sel_hi:[0,1,0]
	s_waitcnt lgkmcnt(4)
	ds_read_b64 v[72:73], v6 offset:9240
	ds_read_b128 v[74:77], v6 offset:9488
	ds_read_b128 v[78:81], v6 offset:9744
	ds_read_u16 v82, v7 offset:9232
	v_fma_mix_f32 v14, v10, v26, 0 op_sel:[0,0,0] op_sel_hi:[0,1,0]
	v_fma_mix_f32 v15, v12, v27, 0 op_sel:[0,0,0] op_sel_hi:[0,1,0]
	v_fma_mix_f32 v14, v11, v26, v14 op_sel:[0,1,0] op_sel_hi:[0,1,0]
	v_fma_mix_f32 v15, v13, v27, v15 op_sel:[0,1,0] op_sel_hi:[0,1,0]
	v_fma_mix_f32 v21, v10, v92, 0 op_sel:[0,0,0] op_sel_hi:[0,1,0]
	v_add_f32_e32 v20, v14, v15
	v_fma_mix_f32 v22, v12, v93, 0 op_sel:[0,0,0] op_sel_hi:[0,1,0]
	v_fma_mix_f32 v21, v11, v92, v21 op_sel:[0,1,0] op_sel_hi:[0,1,0]
	v_add_f32_dpp v20, v20, v20 quad_perm:[1,0,3,2] row_mask:0xf bank_mask:0xf bound_ctrl:1
	v_fma_mix_f32 v22, v13, v93, v22 op_sel:[0,1,0] op_sel_hi:[0,1,0]
	v_fma_mix_f32 v16, v10, v24, 0 op_sel:[0,0,0] op_sel_hi:[0,1,0]
	v_add_f32_dpp v20, v20, v20 quad_perm:[2,3,0,1] row_mask:0xf bank_mask:0xf bound_ctrl:1
	v_fma_mix_f32 v17, v11, v24, 0 op_sel:[0,1,0] op_sel_hi:[0,1,0]
	v_fma_mix_f32 v18, v12, v25, 0 op_sel:[0,0,0] op_sel_hi:[0,1,0]
	v_add_f32_dpp v20, v20, v20 row_half_mirror row_mask:0xf bank_mask:0xf bound_ctrl:1
	v_fma_mix_f32 v19, v13, v25, 0 op_sel:[0,1,0] op_sel_hi:[0,1,0]
	v_fma_mix_f32 v16, v34, v30, v16 op_sel:[0,0,0] op_sel_hi:[1,1,0]
	v_add_f32_dpp v20, v20, v20 row_mirror row_mask:0xf bank_mask:0xf bound_ctrl:1
	v_fma_mix_f32 v17, v34, v30, v17 op_sel:[0,1,0] op_sel_hi:[1,1,0]
	v_fma_mix_f32 v18, v34, v31, v18 op_sel:[0,0,0] op_sel_hi:[1,1,0]
	v_fma_mix_f32 v19, v34, v31, v19 op_sel:[0,1,0] op_sel_hi:[1,1,0]
	v_add_f32_e32 v51, v21, v22
	v_fma_mix_f32 v10, v20, v28, v16 op_sel:[0,0,0] op_sel_hi:[0,1,0]
	v_fma_mix_f32 v11, v20, v28, v17 op_sel:[0,1,0] op_sel_hi:[0,1,0]
	v_fma_mix_f32 v12, v20, v29, v18 op_sel:[0,0,0] op_sel_hi:[0,1,0]
	v_fma_mix_f32 v13, v20, v29, v19 op_sel:[0,1,0] op_sel_hi:[0,1,0]
	s_waitcnt lgkmcnt(4)
	ds_read_b64 v[84:85], v6 offset:8216
	ds_read_b128 v[86:89], v6 offset:8464
	ds_read_b128 v[90:93], v6 offset:8720
	ds_read_u16 v94, v7 offset:8208
	v_fma_mix_f32 v14, v10, v38, 0 op_sel:[0,0,0] op_sel_hi:[0,1,0]
	v_fma_mix_f32 v15, v12, v39, 0 op_sel:[0,0,0] op_sel_hi:[0,1,0]
	v_fma_mix_f32 v14, v11, v38, v14 op_sel:[0,1,0] op_sel_hi:[0,1,0]
	v_fma_mix_f32 v15, v13, v39, v15 op_sel:[0,1,0] op_sel_hi:[0,1,0]
	v_fma_mix_f32 v21, v10, v32, 0 op_sel:[0,0,0] op_sel_hi:[0,1,0]
	v_add_f32_e32 v20, v14, v15
	v_fma_mix_f32 v22, v12, v33, 0 op_sel:[0,0,0] op_sel_hi:[0,1,0]
	v_fma_mix_f32 v21, v11, v32, v21 op_sel:[0,1,0] op_sel_hi:[0,1,0]
	v_add_f32_dpp v20, v20, v20 quad_perm:[1,0,3,2] row_mask:0xf bank_mask:0xf bound_ctrl:1
	v_fma_mix_f32 v22, v13, v33, v22 op_sel:[0,1,0] op_sel_hi:[0,1,0]
	v_fma_mix_f32 v16, v10, v36, 0 op_sel:[0,0,0] op_sel_hi:[0,1,0]
	v_add_f32_dpp v20, v20, v20 quad_perm:[2,3,0,1] row_mask:0xf bank_mask:0xf bound_ctrl:1
	v_fma_mix_f32 v17, v11, v36, 0 op_sel:[0,1,0] op_sel_hi:[0,1,0]
	v_fma_mix_f32 v18, v12, v37, 0 op_sel:[0,0,0] op_sel_hi:[0,1,0]
	v_add_f32_dpp v20, v20, v20 row_half_mirror row_mask:0xf bank_mask:0xf bound_ctrl:1
	v_fma_mix_f32 v19, v13, v37, 0 op_sel:[0,1,0] op_sel_hi:[0,1,0]
	v_fma_mix_f32 v16, v46, v42, v16 op_sel:[0,0,0] op_sel_hi:[1,1,0]
	v_add_f32_dpp v20, v20, v20 row_mirror row_mask:0xf bank_mask:0xf bound_ctrl:1
	v_fma_mix_f32 v17, v46, v42, v17 op_sel:[0,1,0] op_sel_hi:[1,1,0]
	v_fma_mix_f32 v18, v46, v43, v18 op_sel:[0,0,0] op_sel_hi:[1,1,0]
	v_fma_mix_f32 v19, v46, v43, v19 op_sel:[0,1,0] op_sel_hi:[1,1,0]
	v_add_f32_e32 v52, v21, v22
	v_fma_mix_f32 v10, v20, v40, v16 op_sel:[0,0,0] op_sel_hi:[0,1,0]
	v_fma_mix_f32 v11, v20, v40, v17 op_sel:[0,1,0] op_sel_hi:[0,1,0]
	v_fma_mix_f32 v12, v20, v41, v18 op_sel:[0,0,0] op_sel_hi:[0,1,0]
	v_fma_mix_f32 v13, v20, v41, v19 op_sel:[0,1,0] op_sel_hi:[0,1,0]
	s_waitcnt lgkmcnt(4)
	ds_read_b64 v[24:25], v6 offset:7192
	ds_read_b128 v[26:29], v6 offset:7440
	ds_read_b128 v[30:33], v6 offset:7696
	ds_read_u16 v34, v7 offset:7184
	v_fma_mix_f32 v14, v10, v74, 0 op_sel:[0,0,0] op_sel_hi:[0,1,0]
	v_fma_mix_f32 v15, v12, v75, 0 op_sel:[0,0,0] op_sel_hi:[0,1,0]
	v_fma_mix_f32 v14, v11, v74, v14 op_sel:[0,1,0] op_sel_hi:[0,1,0]
	v_fma_mix_f32 v15, v13, v75, v15 op_sel:[0,1,0] op_sel_hi:[0,1,0]
	v_fma_mix_f32 v21, v10, v44, 0 op_sel:[0,0,0] op_sel_hi:[0,1,0]
	v_add_f32_e32 v20, v14, v15
	v_fma_mix_f32 v22, v12, v45, 0 op_sel:[0,0,0] op_sel_hi:[0,1,0]
	v_fma_mix_f32 v21, v11, v44, v21 op_sel:[0,1,0] op_sel_hi:[0,1,0]
	v_add_f32_dpp v20, v20, v20 quad_perm:[1,0,3,2] row_mask:0xf bank_mask:0xf bound_ctrl:1
	v_fma_mix_f32 v22, v13, v45, v22 op_sel:[0,1,0] op_sel_hi:[0,1,0]
	v_fma_mix_f32 v16, v10, v72, 0 op_sel:[0,0,0] op_sel_hi:[0,1,0]
	v_add_f32_dpp v20, v20, v20 quad_perm:[2,3,0,1] row_mask:0xf bank_mask:0xf bound_ctrl:1
	v_fma_mix_f32 v17, v11, v72, 0 op_sel:[0,1,0] op_sel_hi:[0,1,0]
	v_fma_mix_f32 v18, v12, v73, 0 op_sel:[0,0,0] op_sel_hi:[0,1,0]
	v_add_f32_dpp v20, v20, v20 row_half_mirror row_mask:0xf bank_mask:0xf bound_ctrl:1
	v_fma_mix_f32 v19, v13, v73, 0 op_sel:[0,1,0] op_sel_hi:[0,1,0]
	v_fma_mix_f32 v16, v82, v78, v16 op_sel:[0,0,0] op_sel_hi:[1,1,0]
	v_add_f32_dpp v20, v20, v20 row_mirror row_mask:0xf bank_mask:0xf bound_ctrl:1
	v_fma_mix_f32 v17, v82, v78, v17 op_sel:[0,1,0] op_sel_hi:[1,1,0]
	v_fma_mix_f32 v18, v82, v79, v18 op_sel:[0,0,0] op_sel_hi:[1,1,0]
	v_fma_mix_f32 v19, v82, v79, v19 op_sel:[0,1,0] op_sel_hi:[1,1,0]
	v_add_f32_e32 v53, v21, v22
	v_fma_mix_f32 v10, v20, v76, v16 op_sel:[0,0,0] op_sel_hi:[0,1,0]
	v_fma_mix_f32 v11, v20, v76, v17 op_sel:[0,1,0] op_sel_hi:[0,1,0]
	v_fma_mix_f32 v12, v20, v77, v18 op_sel:[0,0,0] op_sel_hi:[0,1,0]
	v_fma_mix_f32 v13, v20, v77, v19 op_sel:[0,1,0] op_sel_hi:[0,1,0]
	s_waitcnt lgkmcnt(4)
	ds_read_b64 v[36:37], v6 offset:6168
	ds_read_b128 v[38:41], v6 offset:6416
	ds_read_b128 v[42:45], v6 offset:6672
	ds_read_u16 v46, v7 offset:6160
	v_fma_mix_f32 v14, v10, v86, 0 op_sel:[0,0,0] op_sel_hi:[0,1,0]
	v_fma_mix_f32 v15, v12, v87, 0 op_sel:[0,0,0] op_sel_hi:[0,1,0]
	v_fma_mix_f32 v14, v11, v86, v14 op_sel:[0,1,0] op_sel_hi:[0,1,0]
	v_fma_mix_f32 v15, v13, v87, v15 op_sel:[0,1,0] op_sel_hi:[0,1,0]
	v_fma_mix_f32 v21, v10, v80, 0 op_sel:[0,0,0] op_sel_hi:[0,1,0]
	v_add_f32_e32 v20, v14, v15
	v_fma_mix_f32 v22, v12, v81, 0 op_sel:[0,0,0] op_sel_hi:[0,1,0]
	v_fma_mix_f32 v21, v11, v80, v21 op_sel:[0,1,0] op_sel_hi:[0,1,0]
	v_add_f32_dpp v20, v20, v20 quad_perm:[1,0,3,2] row_mask:0xf bank_mask:0xf bound_ctrl:1
	v_fma_mix_f32 v22, v13, v81, v22 op_sel:[0,1,0] op_sel_hi:[0,1,0]
	v_fma_mix_f32 v16, v10, v84, 0 op_sel:[0,0,0] op_sel_hi:[0,1,0]
	v_add_f32_dpp v20, v20, v20 quad_perm:[2,3,0,1] row_mask:0xf bank_mask:0xf bound_ctrl:1
	v_fma_mix_f32 v17, v11, v84, 0 op_sel:[0,1,0] op_sel_hi:[0,1,0]
	v_fma_mix_f32 v18, v12, v85, 0 op_sel:[0,0,0] op_sel_hi:[0,1,0]
	v_add_f32_dpp v20, v20, v20 row_half_mirror row_mask:0xf bank_mask:0xf bound_ctrl:1
	v_fma_mix_f32 v19, v13, v85, 0 op_sel:[0,1,0] op_sel_hi:[0,1,0]
	v_fma_mix_f32 v16, v94, v90, v16 op_sel:[0,0,0] op_sel_hi:[1,1,0]
	v_add_f32_dpp v20, v20, v20 row_mirror row_mask:0xf bank_mask:0xf bound_ctrl:1
	v_fma_mix_f32 v17, v94, v90, v17 op_sel:[0,1,0] op_sel_hi:[1,1,0]
	v_fma_mix_f32 v18, v94, v91, v18 op_sel:[0,0,0] op_sel_hi:[1,1,0]
	v_fma_mix_f32 v19, v94, v91, v19 op_sel:[0,1,0] op_sel_hi:[1,1,0]
	v_add_f32_e32 v54, v21, v22
	v_fma_mix_f32 v10, v20, v88, v16 op_sel:[0,0,0] op_sel_hi:[0,1,0]
	v_fma_mix_f32 v11, v20, v88, v17 op_sel:[0,1,0] op_sel_hi:[0,1,0]
	v_fma_mix_f32 v12, v20, v89, v18 op_sel:[0,0,0] op_sel_hi:[0,1,0]
	v_fma_mix_f32 v13, v20, v89, v19 op_sel:[0,1,0] op_sel_hi:[0,1,0]
	s_waitcnt lgkmcnt(4)
	ds_read_b64 v[72:73], v6 offset:5144
	ds_read_b128 v[74:77], v6 offset:5392
	ds_read_b128 v[78:81], v6 offset:5648
	ds_read_u16 v82, v7 offset:5136
	v_fma_mix_f32 v14, v10, v26, 0 op_sel:[0,0,0] op_sel_hi:[0,1,0]
	v_fma_mix_f32 v15, v12, v27, 0 op_sel:[0,0,0] op_sel_hi:[0,1,0]
	v_fma_mix_f32 v14, v11, v26, v14 op_sel:[0,1,0] op_sel_hi:[0,1,0]
	v_fma_mix_f32 v15, v13, v27, v15 op_sel:[0,1,0] op_sel_hi:[0,1,0]
	v_fma_mix_f32 v21, v10, v92, 0 op_sel:[0,0,0] op_sel_hi:[0,1,0]
	v_add_f32_e32 v20, v14, v15
	v_fma_mix_f32 v22, v12, v93, 0 op_sel:[0,0,0] op_sel_hi:[0,1,0]
	v_fma_mix_f32 v21, v11, v92, v21 op_sel:[0,1,0] op_sel_hi:[0,1,0]
	v_add_f32_dpp v20, v20, v20 quad_perm:[1,0,3,2] row_mask:0xf bank_mask:0xf bound_ctrl:1
	v_fma_mix_f32 v22, v13, v93, v22 op_sel:[0,1,0] op_sel_hi:[0,1,0]
	v_fma_mix_f32 v16, v10, v24, 0 op_sel:[0,0,0] op_sel_hi:[0,1,0]
	v_add_f32_dpp v20, v20, v20 quad_perm:[2,3,0,1] row_mask:0xf bank_mask:0xf bound_ctrl:1
	v_fma_mix_f32 v17, v11, v24, 0 op_sel:[0,1,0] op_sel_hi:[0,1,0]
	v_fma_mix_f32 v18, v12, v25, 0 op_sel:[0,0,0] op_sel_hi:[0,1,0]
	v_add_f32_dpp v20, v20, v20 row_half_mirror row_mask:0xf bank_mask:0xf bound_ctrl:1
	v_fma_mix_f32 v19, v13, v25, 0 op_sel:[0,1,0] op_sel_hi:[0,1,0]
	v_fma_mix_f32 v16, v34, v30, v16 op_sel:[0,0,0] op_sel_hi:[1,1,0]
	v_add_f32_dpp v20, v20, v20 row_mirror row_mask:0xf bank_mask:0xf bound_ctrl:1
	v_fma_mix_f32 v17, v34, v30, v17 op_sel:[0,1,0] op_sel_hi:[1,1,0]
	v_fma_mix_f32 v18, v34, v31, v18 op_sel:[0,0,0] op_sel_hi:[1,1,0]
	v_fma_mix_f32 v19, v34, v31, v19 op_sel:[0,1,0] op_sel_hi:[1,1,0]
	v_add_f32_e32 v55, v21, v22
	v_fma_mix_f32 v10, v20, v28, v16 op_sel:[0,0,0] op_sel_hi:[0,1,0]
	v_fma_mix_f32 v11, v20, v28, v17 op_sel:[0,1,0] op_sel_hi:[0,1,0]
	v_fma_mix_f32 v12, v20, v29, v18 op_sel:[0,0,0] op_sel_hi:[0,1,0]
	v_fma_mix_f32 v13, v20, v29, v19 op_sel:[0,1,0] op_sel_hi:[0,1,0]
	s_waitcnt lgkmcnt(4)
	ds_read_b64 v[84:85], v6 offset:4120
	ds_read_b128 v[86:89], v6 offset:4368
	ds_read_b128 v[90:93], v6 offset:4624
	ds_read_u16 v94, v7 offset:4112
	v_fma_mix_f32 v14, v10, v38, 0 op_sel:[0,0,0] op_sel_hi:[0,1,0]
	v_fma_mix_f32 v15, v12, v39, 0 op_sel:[0,0,0] op_sel_hi:[0,1,0]
	v_fma_mix_f32 v14, v11, v38, v14 op_sel:[0,1,0] op_sel_hi:[0,1,0]
	v_fma_mix_f32 v15, v13, v39, v15 op_sel:[0,1,0] op_sel_hi:[0,1,0]
	v_fma_mix_f32 v21, v10, v32, 0 op_sel:[0,0,0] op_sel_hi:[0,1,0]
	v_add_f32_e32 v20, v14, v15
	v_fma_mix_f32 v22, v12, v33, 0 op_sel:[0,0,0] op_sel_hi:[0,1,0]
	v_fma_mix_f32 v21, v11, v32, v21 op_sel:[0,1,0] op_sel_hi:[0,1,0]
	v_add_f32_dpp v20, v20, v20 quad_perm:[1,0,3,2] row_mask:0xf bank_mask:0xf bound_ctrl:1
	v_fma_mix_f32 v22, v13, v33, v22 op_sel:[0,1,0] op_sel_hi:[0,1,0]
	v_fma_mix_f32 v16, v10, v36, 0 op_sel:[0,0,0] op_sel_hi:[0,1,0]
	v_add_f32_dpp v20, v20, v20 quad_perm:[2,3,0,1] row_mask:0xf bank_mask:0xf bound_ctrl:1
	v_fma_mix_f32 v17, v11, v36, 0 op_sel:[0,1,0] op_sel_hi:[0,1,0]
	v_fma_mix_f32 v18, v12, v37, 0 op_sel:[0,0,0] op_sel_hi:[0,1,0]
	v_add_f32_dpp v20, v20, v20 row_half_mirror row_mask:0xf bank_mask:0xf bound_ctrl:1
	v_fma_mix_f32 v19, v13, v37, 0 op_sel:[0,1,0] op_sel_hi:[0,1,0]
	v_fma_mix_f32 v16, v46, v42, v16 op_sel:[0,0,0] op_sel_hi:[1,1,0]
	v_add_f32_dpp v20, v20, v20 row_mirror row_mask:0xf bank_mask:0xf bound_ctrl:1
	v_fma_mix_f32 v17, v46, v42, v17 op_sel:[0,1,0] op_sel_hi:[1,1,0]
	v_fma_mix_f32 v18, v46, v43, v18 op_sel:[0,0,0] op_sel_hi:[1,1,0]
	v_fma_mix_f32 v19, v46, v43, v19 op_sel:[0,1,0] op_sel_hi:[1,1,0]
	v_add_f32_e32 v56, v21, v22
	v_fma_mix_f32 v10, v20, v40, v16 op_sel:[0,0,0] op_sel_hi:[0,1,0]
	v_fma_mix_f32 v11, v20, v40, v17 op_sel:[0,1,0] op_sel_hi:[0,1,0]
	v_fma_mix_f32 v12, v20, v41, v18 op_sel:[0,0,0] op_sel_hi:[0,1,0]
	v_fma_mix_f32 v13, v20, v41, v19 op_sel:[0,1,0] op_sel_hi:[0,1,0]
	s_waitcnt lgkmcnt(4)
	ds_read_b64 v[24:25], v6 offset:3096
	ds_read_b128 v[26:29], v6 offset:3344
	ds_read_b128 v[30:33], v6 offset:3600
	ds_read_u16 v34, v7 offset:3088
	v_fma_mix_f32 v14, v10, v74, 0 op_sel:[0,0,0] op_sel_hi:[0,1,0]
	v_fma_mix_f32 v15, v12, v75, 0 op_sel:[0,0,0] op_sel_hi:[0,1,0]
	v_fma_mix_f32 v14, v11, v74, v14 op_sel:[0,1,0] op_sel_hi:[0,1,0]
	v_fma_mix_f32 v15, v13, v75, v15 op_sel:[0,1,0] op_sel_hi:[0,1,0]
	v_fma_mix_f32 v21, v10, v44, 0 op_sel:[0,0,0] op_sel_hi:[0,1,0]
	v_add_f32_e32 v20, v14, v15
	v_fma_mix_f32 v22, v12, v45, 0 op_sel:[0,0,0] op_sel_hi:[0,1,0]
	v_fma_mix_f32 v21, v11, v44, v21 op_sel:[0,1,0] op_sel_hi:[0,1,0]
	v_add_f32_dpp v20, v20, v20 quad_perm:[1,0,3,2] row_mask:0xf bank_mask:0xf bound_ctrl:1
	v_fma_mix_f32 v22, v13, v45, v22 op_sel:[0,1,0] op_sel_hi:[0,1,0]
	v_fma_mix_f32 v16, v10, v72, 0 op_sel:[0,0,0] op_sel_hi:[0,1,0]
	v_add_f32_dpp v20, v20, v20 quad_perm:[2,3,0,1] row_mask:0xf bank_mask:0xf bound_ctrl:1
	v_fma_mix_f32 v17, v11, v72, 0 op_sel:[0,1,0] op_sel_hi:[0,1,0]
	v_fma_mix_f32 v18, v12, v73, 0 op_sel:[0,0,0] op_sel_hi:[0,1,0]
	v_add_f32_dpp v20, v20, v20 row_half_mirror row_mask:0xf bank_mask:0xf bound_ctrl:1
	v_fma_mix_f32 v19, v13, v73, 0 op_sel:[0,1,0] op_sel_hi:[0,1,0]
	v_fma_mix_f32 v16, v82, v78, v16 op_sel:[0,0,0] op_sel_hi:[1,1,0]
	v_add_f32_dpp v20, v20, v20 row_mirror row_mask:0xf bank_mask:0xf bound_ctrl:1
	v_fma_mix_f32 v17, v82, v78, v17 op_sel:[0,1,0] op_sel_hi:[1,1,0]
	v_fma_mix_f32 v18, v82, v79, v18 op_sel:[0,0,0] op_sel_hi:[1,1,0]
	v_fma_mix_f32 v19, v82, v79, v19 op_sel:[0,1,0] op_sel_hi:[1,1,0]
	v_add_f32_e32 v57, v21, v22
	v_fma_mix_f32 v10, v20, v76, v16 op_sel:[0,0,0] op_sel_hi:[0,1,0]
	v_fma_mix_f32 v11, v20, v76, v17 op_sel:[0,1,0] op_sel_hi:[0,1,0]
	v_fma_mix_f32 v12, v20, v77, v18 op_sel:[0,0,0] op_sel_hi:[0,1,0]
	v_fma_mix_f32 v13, v20, v77, v19 op_sel:[0,1,0] op_sel_hi:[0,1,0]
	s_waitcnt lgkmcnt(4)
	ds_read_b64 v[36:37], v6 offset:2072
	ds_read_b128 v[38:41], v6 offset:2320
	ds_read_b128 v[42:45], v6 offset:2576
	ds_read_u16 v46, v7 offset:2064
	v_fma_mix_f32 v14, v10, v86, 0 op_sel:[0,0,0] op_sel_hi:[0,1,0]
	v_fma_mix_f32 v15, v12, v87, 0 op_sel:[0,0,0] op_sel_hi:[0,1,0]
	v_fma_mix_f32 v14, v11, v86, v14 op_sel:[0,1,0] op_sel_hi:[0,1,0]
	v_fma_mix_f32 v15, v13, v87, v15 op_sel:[0,1,0] op_sel_hi:[0,1,0]
	v_fma_mix_f32 v21, v10, v80, 0 op_sel:[0,0,0] op_sel_hi:[0,1,0]
	v_add_f32_e32 v20, v14, v15
	v_fma_mix_f32 v22, v12, v81, 0 op_sel:[0,0,0] op_sel_hi:[0,1,0]
	v_fma_mix_f32 v21, v11, v80, v21 op_sel:[0,1,0] op_sel_hi:[0,1,0]
	v_add_f32_dpp v20, v20, v20 quad_perm:[1,0,3,2] row_mask:0xf bank_mask:0xf bound_ctrl:1
	v_fma_mix_f32 v22, v13, v81, v22 op_sel:[0,1,0] op_sel_hi:[0,1,0]
	v_fma_mix_f32 v16, v10, v84, 0 op_sel:[0,0,0] op_sel_hi:[0,1,0]
	v_add_f32_dpp v20, v20, v20 quad_perm:[2,3,0,1] row_mask:0xf bank_mask:0xf bound_ctrl:1
	v_fma_mix_f32 v17, v11, v84, 0 op_sel:[0,1,0] op_sel_hi:[0,1,0]
	v_fma_mix_f32 v18, v12, v85, 0 op_sel:[0,0,0] op_sel_hi:[0,1,0]
	v_add_f32_dpp v20, v20, v20 row_half_mirror row_mask:0xf bank_mask:0xf bound_ctrl:1
	v_fma_mix_f32 v19, v13, v85, 0 op_sel:[0,1,0] op_sel_hi:[0,1,0]
	v_fma_mix_f32 v16, v94, v90, v16 op_sel:[0,0,0] op_sel_hi:[1,1,0]
	v_add_f32_dpp v20, v20, v20 row_mirror row_mask:0xf bank_mask:0xf bound_ctrl:1
	v_fma_mix_f32 v17, v94, v90, v17 op_sel:[0,1,0] op_sel_hi:[1,1,0]
	v_fma_mix_f32 v18, v94, v91, v18 op_sel:[0,0,0] op_sel_hi:[1,1,0]
	v_fma_mix_f32 v19, v94, v91, v19 op_sel:[0,1,0] op_sel_hi:[1,1,0]
	v_add_f32_e32 v58, v21, v22
	v_fma_mix_f32 v10, v20, v88, v16 op_sel:[0,0,0] op_sel_hi:[0,1,0]
	v_fma_mix_f32 v11, v20, v88, v17 op_sel:[0,1,0] op_sel_hi:[0,1,0]
	v_fma_mix_f32 v12, v20, v89, v18 op_sel:[0,0,0] op_sel_hi:[0,1,0]
	v_fma_mix_f32 v13, v20, v89, v19 op_sel:[0,1,0] op_sel_hi:[0,1,0]
	s_waitcnt lgkmcnt(4)
	ds_read_b64 v[72:73], v6 offset:1048
	ds_read_b128 v[74:77], v6 offset:1296
	ds_read_b128 v[78:81], v6 offset:1552
	ds_read_u16 v82, v7 offset:1040
	v_fma_mix_f32 v14, v10, v26, 0 op_sel:[0,0,0] op_sel_hi:[0,1,0]
	v_fma_mix_f32 v15, v12, v27, 0 op_sel:[0,0,0] op_sel_hi:[0,1,0]
	v_fma_mix_f32 v14, v11, v26, v14 op_sel:[0,1,0] op_sel_hi:[0,1,0]
	v_fma_mix_f32 v15, v13, v27, v15 op_sel:[0,1,0] op_sel_hi:[0,1,0]
	v_fma_mix_f32 v21, v10, v92, 0 op_sel:[0,0,0] op_sel_hi:[0,1,0]
	v_add_f32_e32 v20, v14, v15
	v_fma_mix_f32 v22, v12, v93, 0 op_sel:[0,0,0] op_sel_hi:[0,1,0]
	v_fma_mix_f32 v21, v11, v92, v21 op_sel:[0,1,0] op_sel_hi:[0,1,0]
	v_add_f32_dpp v20, v20, v20 quad_perm:[1,0,3,2] row_mask:0xf bank_mask:0xf bound_ctrl:1
	v_fma_mix_f32 v22, v13, v93, v22 op_sel:[0,1,0] op_sel_hi:[0,1,0]
	v_fma_mix_f32 v16, v10, v24, 0 op_sel:[0,0,0] op_sel_hi:[0,1,0]
	v_add_f32_dpp v20, v20, v20 quad_perm:[2,3,0,1] row_mask:0xf bank_mask:0xf bound_ctrl:1
	v_fma_mix_f32 v17, v11, v24, 0 op_sel:[0,1,0] op_sel_hi:[0,1,0]
	v_fma_mix_f32 v18, v12, v25, 0 op_sel:[0,0,0] op_sel_hi:[0,1,0]
	v_add_f32_dpp v20, v20, v20 row_half_mirror row_mask:0xf bank_mask:0xf bound_ctrl:1
	v_fma_mix_f32 v19, v13, v25, 0 op_sel:[0,1,0] op_sel_hi:[0,1,0]
	v_fma_mix_f32 v16, v34, v30, v16 op_sel:[0,0,0] op_sel_hi:[1,1,0]
	v_add_f32_dpp v20, v20, v20 row_mirror row_mask:0xf bank_mask:0xf bound_ctrl:1
	v_fma_mix_f32 v17, v34, v30, v17 op_sel:[0,1,0] op_sel_hi:[1,1,0]
	v_fma_mix_f32 v18, v34, v31, v18 op_sel:[0,0,0] op_sel_hi:[1,1,0]
	v_fma_mix_f32 v19, v34, v31, v19 op_sel:[0,1,0] op_sel_hi:[1,1,0]
	v_add_f32_e32 v59, v21, v22
	v_fma_mix_f32 v10, v20, v28, v16 op_sel:[0,0,0] op_sel_hi:[0,1,0]
	v_fma_mix_f32 v11, v20, v28, v17 op_sel:[0,1,0] op_sel_hi:[0,1,0]
	v_fma_mix_f32 v12, v20, v29, v18 op_sel:[0,0,0] op_sel_hi:[0,1,0]
	v_fma_mix_f32 v13, v20, v29, v19 op_sel:[0,1,0] op_sel_hi:[0,1,0]
	s_waitcnt lgkmcnt(4)
; DEVINL u16 f2bf(float a) { return (u16)(pk2(a, 0.f) & 0xffffu); }
; #define RW_LANDED(WN, XN, KN, VN) asm volatile("s_waitcnt lgkmcnt(0)" : "+v"(WN), "+v"(XN), "+v"(KN), "+v"(VN) :: "memory")
; #define RW_STEP2(B) RW_STEP(B, WvA, XA, KrA, vhA, WvB, XB, KrB, vhB); RW_STEP((B) + 1, WvB, XB, KrB, vhB, WvA, XA, KrA, vhA)
; #define RW_STEP4(B) RW_STEP2(B); RW_STEP2((B) + 2)
; #define RW_DMA4(B) RW_DMA_ONLY(B); RW_DMA_ONLY((B) + 1); RW_DMA_ONLY((B) + 2); RW_DMA_ONLY((B) + 3)
; template <int DIR>
; DEVINL void rwkv_scan_dir(const Params& p, int task, int lane, int wave) {
;     ...
;   u32x2 WvA, WvB; u32x4 XA, XB, KrA, KrB; unsigned vhA, vhB;
;   RW_DMA4(0); RW_DMA4(4); RW_DMA4(8); RW_DMA4(12); RW_DMA4(16); RW_DMA4(20);
;   RW_READ(0, WvA, XA, KrA, vhA, 23);
;   RW_LANDED(WvA, XA, KrA, vhA);
;   float ypart = 0.f;
; #pragma unroll 1
;   for (int st = 0; st < 4096; st += 32) {
;     RW_STEP(0, WvA, XA, KrA, vhA, WvB, XB, KrB, vhB);
;     if (st > 0) { const int q0 = st - 16 + seg; yo[(long)(DIR ? (4095 - q0) : q0) * 1024] = f2bf(ykeep); }
;     RW_STEP(1, WvB, XB, KrB, vhB, WvA, XA, KrA, vhA);
;     RW_STEP2(2); RW_STEP4(4); RW_STEP4(8); RW_STEP4(12);
;     RW_STEP(16, WvA, XA, KrA, vhA, WvB, XB, KrB, vhB);
;     { const int q0 = st + seg; yo[(long)(DIR ? (4095 - q0) : q0) * 1024] = f2bf(ykeep); }
;     RW_STEP(17, WvB, XB, KrB, vhB, WvA, XA, KrA, vhA);
;     RW_STEP2(18); RW_STEP4(20); RW_STEP4(24); RW_STEP4(28);
	ds_read_b64 v[84:85], v6 offset:24
	ds_read_b128 v[86:89], v6 offset:272
	ds_read_b128 v[90:93], v6 offset:528
	ds_read_u16 v94, v7 offset:16
	v_fma_mix_f32 v14, v10, v38, 0 op_sel:[0,0,0] op_sel_hi:[0,1,0]
	v_fma_mix_f32 v15, v12, v39, 0 op_sel:[0,0,0] op_sel_hi:[0,1,0]
	v_fma_mix_f32 v14, v11, v38, v14 op_sel:[0,1,0] op_sel_hi:[0,1,0]
	v_fma_mix_f32 v15, v13, v39, v15 op_sel:[0,1,0] op_sel_hi:[0,1,0]
	v_fma_mix_f32 v21, v10, v32, 0 op_sel:[0,0,0] op_sel_hi:[0,1,0]
	v_add_f32_e32 v20, v14, v15
	v_fma_mix_f32 v22, v12, v33, 0 op_sel:[0,0,0] op_sel_hi:[0,1,0]
	v_fma_mix_f32 v21, v11, v32, v21 op_sel:[0,1,0] op_sel_hi:[0,1,0]
	v_add_f32_dpp v20, v20, v20 quad_perm:[1,0,3,2] row_mask:0xf bank_mask:0xf bound_ctrl:1
	v_fma_mix_f32 v22, v13, v33, v22 op_sel:[0,1,0] op_sel_hi:[0,1,0]
	v_fma_mix_f32 v16, v10, v36, 0 op_sel:[0,0,0] op_sel_hi:[0,1,0]
	v_add_f32_dpp v20, v20, v20 quad_perm:[2,3,0,1] row_mask:0xf bank_mask:0xf bound_ctrl:1
	v_fma_mix_f32 v17, v11, v36, 0 op_sel:[0,1,0] op_sel_hi:[0,1,0]
	v_fma_mix_f32 v18, v12, v37, 0 op_sel:[0,0,0] op_sel_hi:[0,1,0]
	v_add_f32_dpp v20, v20, v20 row_half_mirror row_mask:0xf bank_mask:0xf bound_ctrl:1
	v_fma_mix_f32 v19, v13, v37, 0 op_sel:[0,1,0] op_sel_hi:[0,1,0]
	v_fma_mix_f32 v16, v46, v42, v16 op_sel:[0,0,0] op_sel_hi:[1,1,0]
	v_add_f32_dpp v20, v20, v20 row_mirror row_mask:0xf bank_mask:0xf bound_ctrl:1
	v_fma_mix_f32 v17, v46, v42, v17 op_sel:[0,1,0] op_sel_hi:[1,1,0]
	v_fma_mix_f32 v18, v46, v43, v18 op_sel:[0,0,0] op_sel_hi:[1,1,0]
	v_fma_mix_f32 v19, v46, v43, v19 op_sel:[0,1,0] op_sel_hi:[1,1,0]
	v_add_f32_e32 v60, v21, v22
	v_fma_mix_f32 v10, v20, v40, v16 op_sel:[0,0,0] op_sel_hi:[0,1,0]
	v_fma_mix_f32 v11, v20, v40, v17 op_sel:[0,1,0] op_sel_hi:[0,1,0]
	v_fma_mix_f32 v12, v20, v41, v18 op_sel:[0,0,0] op_sel_hi:[0,1,0]
	v_fma_mix_f32 v13, v20, v41, v19 op_sel:[0,1,0] op_sel_hi:[0,1,0]
	s_waitcnt lgkmcnt(4)
	v_add_u32_e32 v6, 0xffffc000, v6
	v_add_u32_e32 v7, 0xffffc000, v7
	v_and_b32_e32 v6, 0x1ffff, v6
	v_and_b32_e32 v7, 0x1ffff, v7
	ds_read_b64 v[24:25], v6 offset:15384
	ds_read_b128 v[26:29], v6 offset:15632
	ds_read_b128 v[30:33], v6 offset:15888
	ds_read_u16 v34, v7 offset:15376
	v_fma_mix_f32 v14, v10, v74, 0 op_sel:[0,0,0] op_sel_hi:[0,1,0]
	v_fma_mix_f32 v15, v12, v75, 0 op_sel:[0,0,0] op_sel_hi:[0,1,0]
	v_fma_mix_f32 v14, v11, v74, v14 op_sel:[0,1,0] op_sel_hi:[0,1,0]
	v_fma_mix_f32 v15, v13, v75, v15 op_sel:[0,1,0] op_sel_hi:[0,1,0]
	v_fma_mix_f32 v21, v10, v44, 0 op_sel:[0,0,0] op_sel_hi:[0,1,0]
	v_add_f32_e32 v20, v14, v15
	v_fma_mix_f32 v22, v12, v45, 0 op_sel:[0,0,0] op_sel_hi:[0,1,0]
	v_fma_mix_f32 v21, v11, v44, v21 op_sel:[0,1,0] op_sel_hi:[0,1,0]
	v_add_f32_dpp v20, v20, v20 quad_perm:[1,0,3,2] row_mask:0xf bank_mask:0xf bound_ctrl:1
	v_fma_mix_f32 v22, v13, v45, v22 op_sel:[0,1,0] op_sel_hi:[0,1,0]
	v_fma_mix_f32 v16, v10, v72, 0 op_sel:[0,0,0] op_sel_hi:[0,1,0]
	v_add_f32_dpp v20, v20, v20 quad_perm:[2,3,0,1] row_mask:0xf bank_mask:0xf bound_ctrl:1
	v_fma_mix_f32 v17, v11, v72, 0 op_sel:[0,1,0] op_sel_hi:[0,1,0]
	v_fma_mix_f32 v18, v12, v73, 0 op_sel:[0,0,0] op_sel_hi:[0,1,0]
	v_add_f32_dpp v20, v20, v20 row_half_mirror row_mask:0xf bank_mask:0xf bound_ctrl:1
	v_fma_mix_f32 v19, v13, v73, 0 op_sel:[0,1,0] op_sel_hi:[0,1,0]
	v_fma_mix_f32 v16, v82, v78, v16 op_sel:[0,0,0] op_sel_hi:[1,1,0]
	v_add_f32_dpp v20, v20, v20 row_mirror row_mask:0xf bank_mask:0xf bound_ctrl:1
	v_fma_mix_f32 v17, v82, v78, v17 op_sel:[0,1,0] op_sel_hi:[1,1,0]
	v_fma_mix_f32 v18, v82, v79, v18 op_sel:[0,0,0] op_sel_hi:[1,1,0]
	v_fma_mix_f32 v19, v82, v79, v19 op_sel:[0,1,0] op_sel_hi:[1,1,0]
	v_add_f32_e32 v61, v21, v22
	v_fma_mix_f32 v10, v20, v76, v16 op_sel:[0,0,0] op_sel_hi:[0,1,0]
	v_fma_mix_f32 v11, v20, v76, v17 op_sel:[0,1,0] op_sel_hi:[0,1,0]
	v_fma_mix_f32 v12, v20, v77, v18 op_sel:[0,0,0] op_sel_hi:[0,1,0]
	v_fma_mix_f32 v13, v20, v77, v19 op_sel:[0,1,0] op_sel_hi:[0,1,0]
	s_waitcnt lgkmcnt(4)
	ds_read_b64 v[36:37], v6 offset:14360
	ds_read_b128 v[38:41], v6 offset:14608
	ds_read_b128 v[42:45], v6 offset:14864
	ds_read_u16 v46, v7 offset:14352
	v_fma_mix_f32 v14, v10, v86, 0 op_sel:[0,0,0] op_sel_hi:[0,1,0]
	v_fma_mix_f32 v15, v12, v87, 0 op_sel:[0,0,0] op_sel_hi:[0,1,0]
	v_fma_mix_f32 v14, v11, v86, v14 op_sel:[0,1,0] op_sel_hi:[0,1,0]
	v_fma_mix_f32 v15, v13, v87, v15 op_sel:[0,1,0] op_sel_hi:[0,1,0]
	v_fma_mix_f32 v21, v10, v80, 0 op_sel:[0,0,0] op_sel_hi:[0,1,0]
	v_add_f32_e32 v20, v14, v15
	v_fma_mix_f32 v22, v12, v81, 0 op_sel:[0,0,0] op_sel_hi:[0,1,0]
	v_fma_mix_f32 v21, v11, v80, v21 op_sel:[0,1,0] op_sel_hi:[0,1,0]
	v_add_f32_dpp v20, v20, v20 quad_perm:[1,0,3,2] row_mask:0xf bank_mask:0xf bound_ctrl:1
	v_fma_mix_f32 v22, v13, v81, v22 op_sel:[0,1,0] op_sel_hi:[0,1,0]
	v_fma_mix_f32 v16, v10, v84, 0 op_sel:[0,0,0] op_sel_hi:[0,1,0]
	v_add_f32_dpp v20, v20, v20 quad_perm:[2,3,0,1] row_mask:0xf bank_mask:0xf bound_ctrl:1
	v_fma_mix_f32 v17, v11, v84, 0 op_sel:[0,1,0] op_sel_hi:[0,1,0]
	v_fma_mix_f32 v18, v12, v85, 0 op_sel:[0,0,0] op_sel_hi:[0,1,0]
	v_add_f32_dpp v20, v20, v20 row_half_mirror row_mask:0xf bank_mask:0xf bound_ctrl:1
	v_fma_mix_f32 v19, v13, v85, 0 op_sel:[0,1,0] op_sel_hi:[0,1,0]
	v_fma_mix_f32 v16, v94, v90, v16 op_sel:[0,0,0] op_sel_hi:[1,1,0]
	v_add_f32_dpp v20, v20, v20 row_mirror row_mask:0xf bank_mask:0xf bound_ctrl:1
	v_fma_mix_f32 v17, v94, v90, v17 op_sel:[0,1,0] op_sel_hi:[1,1,0]
	v_fma_mix_f32 v18, v94, v91, v18 op_sel:[0,0,0] op_sel_hi:[1,1,0]
	v_fma_mix_f32 v19, v94, v91, v19 op_sel:[0,1,0] op_sel_hi:[1,1,0]
	v_add_f32_e32 v62, v21, v22
	v_fma_mix_f32 v10, v20, v88, v16 op_sel:[0,0,0] op_sel_hi:[0,1,0]
	v_fma_mix_f32 v11, v20, v88, v17 op_sel:[0,1,0] op_sel_hi:[0,1,0]
	v_fma_mix_f32 v12, v20, v89, v18 op_sel:[0,0,0] op_sel_hi:[0,1,0]
	v_fma_mix_f32 v13, v20, v89, v19 op_sel:[0,1,0] op_sel_hi:[0,1,0]
	s_waitcnt lgkmcnt(4)
	s_add_u32 s15, s15, 1
	s_add_u32 s14, s14, 1
	v_mov_b32_e32 v69, s15
	ds_write_b32 v68, v69
	s_cmp_lt_u32 s14, 0x100
	s_cbranch_scc1 .Lrw_blk_d1
; DEVINL u16 f2bf(float a) { return (u16)(pk2(a, 0.f) & 0xffffu); }
; #define RW_STEP2(B) RW_STEP(B, WvA, XA, KrA, vhA, WvB, XB, KrB, vhB); RW_STEP((B) + 1, WvB, XB, KrB, vhB, WvA, XA, KrA, vhA)
; #define RW_STEP4(B) RW_STEP2(B); RW_STEP2((B) + 2)
; DEVINL unsigned xb_ld(unsigned* p_) { return __hip_atomic_load(p_, __ATOMIC_RELAXED, __HIP_MEMORY_SCOPE_AGENT); }
; template <int DIR>
; DEVINL void rwkv_scan_dir(const Params& p, int task, int lane, int wave) {
;     ...
;     if (st > 0) { const int q0 = st - 16 + seg; yo[(long)(DIR ? (4095 - q0) : q0) * 1024] = f2bf(ykeep); }
;     RW_STEP(1, WvB, XB, KrB, vhB, WvA, XA, KrA, vhA);
;     RW_STEP2(2); RW_STEP4(4); RW_STEP4(8); RW_STEP4(12);
;     RW_STEP(16, WvA, XA, KrA, vhA, WvB, XB, KrB, vhB);
;     { const int q0 = st + seg; yo[(long)(DIR ? (4095 - q0) : q0) * 1024] = f2bf(ykeep); }
;     RW_STEP(17, WvB, XB, KrB, vhB, WvA, XA, KrA, vhA);
;     RW_STEP2(18); RW_STEP4(20); RW_STEP4(24); RW_STEP4(28);
;   }
;   {
;     const float ylast = allred16(ypart);
;     ykeep = (seg == 15) ? ylast : ykeep;
;     const int q0 = 4096 - 16 + seg; yo[(long)(DIR ? (4095 - q0) : q0) * 1024] = f2bf(ykeep);
; DEVINL void xcd_barrier_complete(unsigned* bar, unsigned x, unsigned& nloc, unsigned& nx) {
;   const unsigned G = gridDim.x * gridDim.y * gridDim.z;
;   unsigned sum, cnt, mine, sp = 0u;
;   for (;;) {
;     sum = 0u; cnt = 0u; mine = 0u;
; #pragma unroll
;     for (unsigned j = 0; j < 16; ++j) { const unsigned c = xb_ld(&bar[XB_XCNT(j)]); sum += c; cnt += (c > 0u) ? 1u : 0u; mine = (j == x) ? c : mine; }
;     if (sum == G) break;
;     __builtin_amdgcn_s_sleep(1);
;     if ((++sp & 255u) == 0u) { if (xb_ld(&bar[XB_TMO])) break; if (sp > XB_SPIN_CAP) { atomicAdd(&bar[XB_TMO], 1u); break; } }
;   }
;   nloc = mine > 0u ? mine : 1u; nx = cnt > 0u ? cnt : 1u;
; }
; DEVINL void xcd_barrier(const XcdBarrier& b) {
;   asm volatile("s_waitcnt vmcnt(0)" ::: "memory");
;   __syncthreads();
;   if (threadIdx.x == 0) {
;     unsigned* bar = b.bar;
;     __builtin_amdgcn_s_waitcnt(0);
;     unsigned nloc = b.st[0], nx = b.st[1];
;     if (nloc == 0u) { xcd_barrier_complete(bar, b.x, nloc, nx); b.st[0] = nloc; b.st[1] = nx; }
	v_fma_mix_f32 v21, v10, v92, 0 op_sel:[0,0,0] op_sel_hi:[0,1,0]
	v_fma_mix_f32 v22, v12, v93, 0 op_sel:[0,0,0] op_sel_hi:[0,1,0]
	v_fma_mix_f32 v21, v11, v92, v21 op_sel:[0,1,0] op_sel_hi:[0,1,0]
	v_fma_mix_f32 v22, v13, v93, v22 op_sel:[0,1,0] op_sel_hi:[0,1,0]
	v_add_f32_e32 v63, v21, v22
	s_nop 1
	v_add_f32_dpp v48, v48, v48 row_ror:8 row_mask:0xf bank_mask:0x3
	v_add_f32_dpp v49, v49, v49 row_ror:8 row_mask:0xf bank_mask:0x3
	v_add_f32_dpp v50, v50, v50 row_ror:8 row_mask:0xf bank_mask:0x3
	v_add_f32_dpp v51, v51, v51 row_ror:8 row_mask:0xf bank_mask:0x3
	v_add_f32_dpp v52, v52, v52 row_ror:8 row_mask:0xf bank_mask:0x3
	v_add_f32_dpp v53, v53, v53 row_ror:8 row_mask:0xf bank_mask:0x3
	v_add_f32_dpp v54, v54, v54 row_ror:8 row_mask:0xf bank_mask:0x3
	v_add_f32_dpp v55, v55, v55 row_ror:8 row_mask:0xf bank_mask:0x3
	v_add_f32_dpp v48, v56, v56 row_ror:8 row_mask:0xf bank_mask:0xc
	v_add_f32_dpp v49, v57, v57 row_ror:8 row_mask:0xf bank_mask:0xc
	v_add_f32_dpp v50, v58, v58 row_ror:8 row_mask:0xf bank_mask:0xc
	v_add_f32_dpp v51, v59, v59 row_ror:8 row_mask:0xf bank_mask:0xc
	v_add_f32_dpp v52, v60, v60 row_ror:8 row_mask:0xf bank_mask:0xc
	v_add_f32_dpp v53, v61, v61 row_ror:8 row_mask:0xf bank_mask:0xc
	v_add_f32_dpp v54, v62, v62 row_ror:8 row_mask:0xf bank_mask:0xc
	v_add_f32_dpp v55, v63, v63 row_ror:8 row_mask:0xf bank_mask:0xc
	v_add_f32_dpp v48, v48, v48 row_ror:12 row_mask:0xf bank_mask:0x5
	v_add_f32_dpp v49, v49, v49 row_ror:12 row_mask:0xf bank_mask:0x5
	v_add_f32_dpp v50, v50, v50 row_ror:12 row_mask:0xf bank_mask:0x5
	v_add_f32_dpp v51, v51, v51 row_ror:12 row_mask:0xf bank_mask:0x5
	v_add_f32_dpp v48, v52, v52 row_ror:4 row_mask:0xf bank_mask:0xa
	v_add_f32_dpp v49, v53, v53 row_ror:4 row_mask:0xf bank_mask:0xa
	v_add_f32_dpp v50, v54, v54 row_ror:4 row_mask:0xf bank_mask:0xa
	v_add_f32_dpp v51, v55, v55 row_ror:4 row_mask:0xf bank_mask:0xa
	v_add_f32_dpp v64, v48, v48 quad_perm:[2,3,0,1] row_mask:0xf bank_mask:0xf bound_ctrl:1
	v_add_f32_dpp v65, v50, v50 quad_perm:[2,3,0,1] row_mask:0xf bank_mask:0xf bound_ctrl:1
	v_cndmask_b32_e64 v56, v64, v65, s[50:51]
	v_add_f32_dpp v64, v49, v49 quad_perm:[2,3,0,1] row_mask:0xf bank_mask:0xf bound_ctrl:1
	v_add_f32_dpp v65, v51, v51 quad_perm:[2,3,0,1] row_mask:0xf bank_mask:0xf bound_ctrl:1
	v_cndmask_b32_e64 v57, v64, v65, s[50:51]
	v_add_f32_dpp v64, v56, v56 quad_perm:[1,0,3,2] row_mask:0xf bank_mask:0xf bound_ctrl:1
	s_nop 0
	v_add_f32_dpp v65, v57, v57 quad_perm:[1,0,3,2] row_mask:0xf bank_mask:0xf bound_ctrl:1
	v_cndmask_b32_e64 v66, v64, v65, s[48:49]
	v_cvt_pk_bf16_f32 v66, v66, v66
	global_store_short v8, v66, s[12:13]
	s_sub_u32 s12, s12, 0x8000
	s_subb_u32 s13, s13, 0
.Lrw_next:
	s_waitcnt vmcnt(0)
	s_add_u32 s7, s7, s8
	s_branch .Lrw_task
.Lrw_done:
.LBB0_498:
	s_or_b64 exec, exec, s[0:1]
	s_waitcnt vmcnt(0)
	s_barrier
	s_mov_b64 s[0:1], exec
	v_readlane_b32 s6, v254, 0
	v_readlane_b32 s7, v254, 1
	s_and_b64 s[6:7], s[0:1], s[6:7]
	s_mov_b64 exec, s[6:7]
	s_cbranch_execz .LBB0_550
	v_mov_b32_e32 v0, 0
	s_waitcnt vmcnt(0) expcnt(0) lgkmcnt(0)
	ds_read_b32 v2, v0
	ds_read_b32 v1, v0 offset:4
	s_waitcnt lgkmcnt(1)
	v_cmp_ne_u32_e32 vcc, 0, v2
	s_cbranch_vccnz .LBB0_514
	s_add_u32 s6, s92, 0x217c0200
	s_addc_u32 s7, s93, 0
	s_add_u32 s8, s92, 0x217c0400
	s_addc_u32 s9, s93, 0
	s_add_u32 s10, s92, 0x217c0500
	s_addc_u32 s11, s93, 0
	s_add_u32 s12, s92, 0x217c0600
	s_addc_u32 s13, s93, 0
	s_add_u32 s14, s92, 0x217c0700
	s_addc_u32 s15, s93, 0
	s_add_u32 s16, s92, 0x217c0800
	s_addc_u32 s17, s93, 0
	s_add_u32 s18, s92, 0x217c0900
	s_addc_u32 s19, s93, 0
	s_add_u32 s20, s92, 0x217c0a00
	s_addc_u32 s21, s93, 0
	s_add_u32 s22, s92, 0x217c0b00
	s_addc_u32 s23, s93, 0
	s_add_u32 s24, s92, 0x217c0c00
	s_addc_u32 s25, s93, 0
	s_add_u32 s26, s92, 0x217c0d00
	s_addc_u32 s27, s93, 0
	s_add_u32 s36, s92, 0x217c0e00
	s_addc_u32 s37, s93, 0
	s_add_u32 s38, s92, 0x217c0f00
	s_addc_u32 s39, s93, 0
	s_add_u32 s40, s92, 0x217c1000
	s_addc_u32 s41, s93, 0
	s_add_u32 s42, s92, 0x217c1100
	s_addc_u32 s43, s93, 0
	s_add_u32 s44, s92, 0x217c1200
	s_addc_u32 s45, s93, 0
	s_mul_i32 s3, s95, s54
	s_add_u32 s46, s92, 0x217c1300
	s_mul_i32 s3, s3, s94
	s_addc_u32 s47, s93, 0
	s_mov_b32 s55, 1
	s_branch .LBB0_502

; DEVINL float bflo(unsigned u) { return __uint_as_float(u << 16); }
; DEVINL float bfhi(unsigned u) { return __uint_as_float(u & 0xffff0000u); }
; DEVINL float sigm(float x) { return 1.f / (1.f + __expf(-x)); }
; template <int EPI, bool GATHER>
; DEVINL void gemm_tile(const Params& p, const u16* __restrict__ A, int lda, const int* __restrict__ rowidx,
;                       const u16* __restrict__ Bt, int ldb, int K, int brow, int bcol, int orow, int ocol) {
;     ...
;   const int row0 = orow + wr * 64 + fq * 4;
;   const int col0 = ocol + wc * 32 + fr;
;   const bool odd = (fr & 1) != 0;
;   const int colp = col0 - (odd ? 1 : 0);
; #pragma unroll
;   for (int ai = 0; ai < 2; ++ai)
; #pragma unroll
;     for (int m = 0; m < 4; ++m) {
;       const int rA = row0 + ai * HALF + m * 16 + (odd ? 2 : 0);
;       float gate[2] = {0.f, 0.f};
;       if (EPI == EPI_MOE2) { gate[0] = ((const float*)(ws + O_SELG))[rA]; gate[1] = ((const float*)(ws + O_SELG))[rA + 1]; }
; #pragma unroll
;       for (int bj = 0; bj < (EPI == EPI_HID ? 1 : 2); ++bj)
; #pragma unroll
;         for (int n = 0; n < 2; ++n) {
;           const int cc = bj * HALF + n * 16;
;           f32x4 v = acc[ai][bj][m][n];
;           if (EPI == EPI_HID) {
; #pragma unroll
;             for (int j = 0; j < 4; ++j) { const float a1 = acc[ai][0][m][n][j], a3 = acc[ai][1][m][n][j]; v[j] = a1 * sigm(a1) * a3; }
;           }
;           float lo[2], hi[2];
;           xchg_pairs(v, odd, lo, hi);
; #pragma unroll
;           for (int k = 0; k < 2; ++k) {
;             const unsigned row = (unsigned)(rA + k);
;             if (EPI == EPI_HID) {
;               *(unsigned*)(ws + O_HID + (row * 1024u + (unsigned)(colp + cc)) * 2u) = pk2(lo[k], hi[k]);
;             } else if (EPI == EPI_COLS) {
;               *(unsigned*)(ws + O_COLS + (row * (unsigned)NCP + (unsigned)(colp + cc)) * 2u) = pk2(lo[k], hi[k]);
;             } else if (EPI == EPI_MOE2) {
;               *(unsigned*)(ws + O_EO + (row * 2048u + (unsigned)(colp + cc)) * 2u) = pk2(gate[k] * lo[k], gate[k] * hi[k]);
;             } else if (EPI == EPI_M1) {
;               const unsigned g2 = *(const unsigned*)(ws + O_COLS + (row * (unsigned)NCP + (unsigned)(C_GG + colp + cc)) * 2u);
;               *(unsigned*)(ws + O_M1 + (row * 2048u + (unsigned)(colp + cc)) * 2u) = pk2(sigm(bflo(g2)) * lo[k], sigm(bfhi(g2)) * hi[k]);
.LBB0_609:
	s_or_b64 exec, exec, s[6:7]
	v_and_b32_e32 v182, 1, v141
	v_or_b32_e32 v183, s0, v143
	v_sub_u32_e32 v183, v183, v182
	v_add_u32_e32 v184, s55, v145
	v_lshlrev_b32_e32 v185, 2, v144
	v_lshl_add_u32 v186, v142, 5, v183
	v_lshlrev_b32_e32 v183, 1, v182
	v_or3_b32 v183, v184, v183, v185
	v_add_u32_e32 v185, 0x1960, v186
	v_mul_lo_u32 v187, v183, s49
	v_add_lshl_u32 v184, v187, v185, 1
	global_load_dword v150, v184, s[8:9]
	v_add_u32_e32 v182, 0x2a00, v187
	v_add_lshl_u32 v188, v182, v185, 1
	global_load_dword v151, v188, s[8:9]
	v_add_u32_e32 v190, 0x1970, v186
	v_add_lshl_u32 v191, v187, v190, 1
	global_load_dword v152, v191, s[8:9]
	v_add_lshl_u32 v191, v182, v190, 1
	global_load_dword v153, v191, s[8:9]
	v_add_u32_e32 v192, 0x19e0, v186
	v_add_lshl_u32 v193, v187, v192, 1
	global_load_dword v154, v193, s[8:9]
	v_add_lshl_u32 v193, v182, v192, 1
	global_load_dword v155, v193, s[8:9]
	v_add_u32_e32 v194, 0x19f0, v186
	v_add_lshl_u32 v195, v187, v194, 1
	global_load_dword v156, v195, s[8:9]
	v_add_lshl_u32 v195, v182, v194, 1
	global_load_dword v157, v195, s[8:9]
	v_and_b32_e32 v182, 1, v141
	v_or_b32_e32 v183, s0, v143
	v_sub_u32_e32 v183, v183, v182
	v_add_u32_e32 v184, s55, v145
	v_lshlrev_b32_e32 v185, 2, v144
	v_lshl_add_u32 v186, v142, 5, v183
	v_lshlrev_b32_e32 v183, 1, v182
	v_or3_b32 v183, v184, v183, v185
	v_add_u32_e32 v185, 0x1960, v186
	v_add_u32_e32 v187, 0x1970, v186
	v_add_u32_e32 v188, 0x19e0, v186
	v_add_u32_e32 v190, 0x19f0, v186
	v_or_b32_e32 v191, 16, v183
	v_mul_lo_u32 v192, v191, s49
	v_add_lshl_u32 v193, v192, v185, 1
	global_load_dword v166, v193, s[8:9]
	v_add_u32_e32 v194, 0x2a00, v192
	v_add_lshl_u32 v195, v194, v185, 1
	global_load_dword v167, v195, s[8:9]
	v_add_lshl_u32 v196, v192, v187, 1
	global_load_dword v168, v196, s[8:9]
	v_add_lshl_u32 v196, v194, v187, 1
	global_load_dword v169, v196, s[8:9]
	v_add_lshl_u32 v197, v192, v188, 1
	global_load_dword v170, v197, s[8:9]
	v_add_lshl_u32 v197, v194, v188, 1
	global_load_dword v171, v197, s[8:9]
	v_add_lshl_u32 v198, v192, v190, 1
	global_load_dword v172, v198, s[8:9]
	v_add_lshl_u32 v198, v194, v190, 1
	global_load_dword v173, v198, s[8:9]
	v_and_b32_e32 v131, 1, v141
	v_or_b32_e32 v130, s0, v143
	v_sub_u32_e32 v130, v130, v131
	v_add_u32_e32 v128, s55, v145
	v_lshlrev_b32_e32 v129, 2, v144
	v_lshl_add_u32 v132, v142, 5, v130
	v_lshlrev_b32_e32 v130, 1, v131
	v_or3_b32 v130, v128, v130, v129
	v_add_u32_e32 v129, 0x1960, v132
	v_mul_lo_u32 v133, v130, s49
	v_add_lshl_u32 v128, v133, v129, 1
	s_nop 0
	v_cmp_eq_u32_e64 s[6:7], 0, v131
	s_waitcnt vmcnt(15)
	v_lshlrev_b32_e32 v131, 16, v150
	v_and_b32_e32 v134, 0xffff0000, v150
	v_mul_f32_e32 v131, 0xbfb8aa3b, v131
	v_mul_f32_e32 v134, 0xbfb8aa3b, v134
	v_exp_f32_e32 v137, v131
	v_exp_f32_e32 v134, v134
	v_cndmask_b32_e64 v128, v124, v126, s[6:7]
	v_add_u32_e32 v131, 0x2a00, v133
	v_add_f32_e32 v137, 1.0, v137
	v_add_f32_e32 v134, 1.0, v134
	v_div_scale_f32 v139, s[0:1], v137, v137, 1.0
	v_div_scale_f32 v142, s[0:1], v134, v134, 1.0
	v_rcp_f32_e32 v143, v139
	v_rcp_f32_e32 v144, v142
	v_div_scale_f32 v141, vcc, 1.0, v137, 1.0
	v_fma_f32 v146, -v139, v143, 1.0
	v_fma_f32 v147, -v142, v144, 1.0
	v_fmac_f32_e32 v143, v146, v143
	v_div_scale_f32 v145, s[0:1], 1.0, v134, 1.0
	v_fmac_f32_e32 v144, v147, v144
	v_mul_f32_e32 v146, v141, v143
	v_mul_f32_e32 v147, v145, v144
	v_fma_f32 v148, -v139, v146, v141
	v_fma_f32 v149, -v142, v147, v145
	v_fmac_f32_e32 v146, v148, v143
	v_fmac_f32_e32 v147, v149, v144
	v_fma_f32 v139, -v139, v146, v141
	v_fma_f32 v141, -v142, v147, v145
	v_div_fmas_f32 v139, v139, v143, v146
	s_mov_b64 vcc, s[0:1]
	v_mov_b32_dpp v128, v128 quad_perm:[1,0,3,2] row_mask:0xf bank_mask:0xf bound_ctrl:1
	v_div_fixup_f32 v137, v139, v137, 1.0
	v_div_fmas_f32 v139, v141, v144, v147
	v_cndmask_b32_e64 v135, v128, v124, s[6:7]
	v_cndmask_b32_e64 v126, v126, v128, s[6:7]
	v_div_fixup_f32 v134, v139, v134, 1.0
	v_lshlrev_b32_e32 v124, 1, v132
	v_lshlrev_b32_e32 v128, 12, v130
	v_mul_f32_e32 v135, v135, v137
	v_mul_f32_e32 v126, v126, v134
	v_add_u32_e32 v136, v128, v124
	v_cvt_pk_bf16_f32 v126, v135, v126
	v_add_lshl_u32 v138, v131, v129, 1
	global_store_dword v136, v126, s[10:11]
	s_nop 0
	v_cndmask_b32_e64 v126, v125, v127, s[6:7]
	s_nop 1
	v_mov_b32_dpp v135, v126 quad_perm:[1,0,3,2] row_mask:0xf bank_mask:0xf bound_ctrl:1
	v_cndmask_b32_e64 v136, v135, v125, s[6:7]
	v_cndmask_b32_e64 v127, v127, v135, s[6:7]
	v_or_b32_e32 v125, 0x1000, v128
	v_add_u32_e32 v126, 0x1970, v132
	v_add_u32_e32 v138, v125, v124
	v_add_lshl_u32 v137, v133, v126, 1
	s_waitcnt vmcnt(15)
	v_lshlrev_b32_e32 v135, 16, v151
	v_and_b32_e32 v134, 0xffff0000, v151
	v_mul_f32_e32 v135, 0xbfb8aa3b, v135
	v_mul_f32_e32 v134, 0xbfb8aa3b, v134
	v_exp_f32_e32 v135, v135
	v_exp_f32_e32 v134, v134
	v_add_f32_e32 v135, 1.0, v135
	v_add_f32_e32 v134, 1.0, v134
	v_div_scale_f32 v139, s[0:1], v135, v135, 1.0
	v_div_scale_f32 v142, s[0:1], v134, v134, 1.0
	v_rcp_f32_e32 v143, v139
	v_rcp_f32_e32 v144, v142
	v_div_scale_f32 v141, vcc, 1.0, v135, 1.0
	v_fma_f32 v146, -v139, v143, 1.0
	v_fma_f32 v147, -v142, v144, 1.0
	v_fmac_f32_e32 v143, v146, v143
	v_div_scale_f32 v145, s[0:1], 1.0, v134, 1.0
	v_fmac_f32_e32 v144, v147, v144
	v_mul_f32_e32 v146, v141, v143
	v_mul_f32_e32 v147, v145, v144
	v_fma_f32 v148, -v139, v146, v141
	v_fma_f32 v149, -v142, v147, v145
	v_fmac_f32_e32 v146, v148, v143
	v_fmac_f32_e32 v147, v149, v144
	v_fma_f32 v139, -v139, v146, v141
	v_fma_f32 v141, -v142, v147, v145
	v_div_fmas_f32 v139, v139, v143, v146
	s_mov_b64 vcc, s[0:1]
	v_div_fixup_f32 v135, v139, v135, 1.0
	v_div_fmas_f32 v139, v141, v144, v147
	v_div_fixup_f32 v134, v139, v134, 1.0
	v_mul_f32_e32 v135, v136, v135
	v_mul_f32_e32 v127, v127, v134
	v_cvt_pk_bf16_f32 v127, v135, v127
	global_store_dword v138, v127, s[10:11]
	s_nop 0
	v_cndmask_b32_e64 v134, v120, v122, s[6:7]
	v_add_lshl_u32 v137, v131, v126, 1
	s_nop 0
	v_mov_b32_dpp v134, v134 quad_perm:[1,0,3,2] row_mask:0xf bank_mask:0xf bound_ctrl:1
	v_cndmask_b32_e64 v135, v134, v120, s[6:7]
	v_cndmask_b32_e64 v122, v122, v134, s[6:7]
	v_add_u32_e32 v120, 32, v124
	v_add_u32_e32 v136, v128, v120
	s_waitcnt vmcnt(15)
; DEVINL float bflo(unsigned u) { return __uint_as_float(u << 16); }
; DEVINL float bfhi(unsigned u) { return __uint_as_float(u & 0xffff0000u); }
; DEVINL float sigm(float x) { return 1.f / (1.f + __expf(-x)); }
; template <int EPI, bool GATHER>
; DEVINL void gemm_tile(const Params& p, const u16* __restrict__ A, int lda, const int* __restrict__ rowidx,
;                       const u16* __restrict__ Bt, int ldb, int K, int brow, int bcol, int orow, int ocol) {
;     ...
;           f32x4 v = acc[ai][bj][m][n];
;           if (EPI == EPI_HID) {
; #pragma unroll
;             for (int j = 0; j < 4; ++j) { const float a1 = acc[ai][0][m][n][j], a3 = acc[ai][1][m][n][j]; v[j] = a1 * sigm(a1) * a3; }
;           }
;           float lo[2], hi[2];
;           xchg_pairs(v, odd, lo, hi);
; #pragma unroll
;           for (int k = 0; k < 2; ++k) {
;             const unsigned row = (unsigned)(rA + k);
;             if (EPI == EPI_HID) {
;               *(unsigned*)(ws + O_HID + (row * 1024u + (unsigned)(colp + cc)) * 2u) = pk2(lo[k], hi[k]);
;             } else if (EPI == EPI_COLS) {
;               *(unsigned*)(ws + O_COLS + (row * (unsigned)NCP + (unsigned)(colp + cc)) * 2u) = pk2(lo[k], hi[k]);
;             } else if (EPI == EPI_MOE2) {
;               *(unsigned*)(ws + O_EO + (row * 2048u + (unsigned)(colp + cc)) * 2u) = pk2(gate[k] * lo[k], gate[k] * hi[k]);
;             } else if (EPI == EPI_M1) {
;               const unsigned g2 = *(const unsigned*)(ws + O_COLS + (row * (unsigned)NCP + (unsigned)(C_GG + colp + cc)) * 2u);
;               *(unsigned*)(ws + O_M1 + (row * 2048u + (unsigned)(colp + cc)) * 2u) = pk2(sigm(bflo(g2)) * lo[k], sigm(bfhi(g2)) * hi[k]);
	v_lshlrev_b32_e32 v134, 16, v152
	v_and_b32_e32 v127, 0xffff0000, v152
	v_mul_f32_e32 v134, 0xbfb8aa3b, v134
	v_mul_f32_e32 v127, 0xbfb8aa3b, v127
	v_exp_f32_e32 v134, v134
	v_exp_f32_e32 v127, v127
	v_add_f32_e32 v134, 1.0, v134
	v_add_f32_e32 v127, 1.0, v127
	v_div_scale_f32 v138, s[0:1], v134, v134, 1.0
	v_div_scale_f32 v141, s[0:1], v127, v127, 1.0
	v_rcp_f32_e32 v142, v138
	v_rcp_f32_e32 v143, v141
	v_div_scale_f32 v139, vcc, 1.0, v134, 1.0
	v_fma_f32 v145, -v138, v142, 1.0
	v_fma_f32 v146, -v141, v143, 1.0
	v_fmac_f32_e32 v142, v145, v142
	v_div_scale_f32 v144, s[0:1], 1.0, v127, 1.0
	v_fmac_f32_e32 v143, v146, v143
	v_mul_f32_e32 v145, v139, v142
	v_mul_f32_e32 v146, v144, v143
	v_fma_f32 v147, -v138, v145, v139
	v_fma_f32 v148, -v141, v146, v144
	v_fmac_f32_e32 v145, v147, v142
	v_fmac_f32_e32 v146, v148, v143
	v_fma_f32 v138, -v138, v145, v139
	v_fma_f32 v139, -v141, v146, v144
	v_div_fmas_f32 v138, v138, v142, v145
	s_mov_b64 vcc, s[0:1]
	v_div_fixup_f32 v134, v138, v134, 1.0
	v_div_fmas_f32 v138, v139, v143, v146
	v_div_fixup_f32 v127, v138, v127, 1.0
	v_mul_f32_e32 v134, v135, v134
	v_mul_f32_e32 v122, v122, v127
	v_cvt_pk_bf16_f32 v122, v134, v122
	global_store_dword v136, v122, s[10:11]
	s_nop 0
	v_cndmask_b32_e64 v122, v121, v123, s[6:7]
	v_add_u32_e32 v136, v125, v120
	s_nop 0
	v_mov_b32_dpp v134, v122 quad_perm:[1,0,3,2] row_mask:0xf bank_mask:0xf bound_ctrl:1
	v_cndmask_b32_e64 v121, v134, v121, s[6:7]
	v_cndmask_b32_e64 v123, v123, v134, s[6:7]
	v_add_u32_e32 v122, 0x19e0, v132
	v_add_lshl_u32 v135, v133, v122, 1
	s_waitcnt vmcnt(15)
	v_lshlrev_b32_e32 v134, 16, v153
	v_and_b32_e32 v127, 0xffff0000, v153
	v_mul_f32_e32 v134, 0xbfb8aa3b, v134
	v_mul_f32_e32 v127, 0xbfb8aa3b, v127
	v_exp_f32_e32 v134, v134
	v_exp_f32_e32 v127, v127
	v_add_f32_e32 v134, 1.0, v134
	v_add_f32_e32 v127, 1.0, v127
	v_div_scale_f32 v137, s[0:1], v134, v134, 1.0
	v_div_scale_f32 v139, s[0:1], v127, v127, 1.0
	v_rcp_f32_e32 v141, v137
	v_rcp_f32_e32 v142, v139
	v_div_scale_f32 v138, vcc, 1.0, v134, 1.0
	v_fma_f32 v144, -v137, v141, 1.0
	v_fma_f32 v145, -v139, v142, 1.0
	v_fmac_f32_e32 v141, v144, v141
	v_div_scale_f32 v143, s[0:1], 1.0, v127, 1.0
	v_fmac_f32_e32 v142, v145, v142
	v_mul_f32_e32 v144, v138, v141
	v_mul_f32_e32 v145, v143, v142
	v_fma_f32 v146, -v137, v144, v138
	v_fma_f32 v147, -v139, v145, v143
	v_fmac_f32_e32 v144, v146, v141
	v_fmac_f32_e32 v145, v147, v142
	v_fma_f32 v137, -v137, v144, v138
	v_fma_f32 v138, -v139, v145, v143
	v_div_fmas_f32 v137, v137, v141, v144
	s_mov_b64 vcc, s[0:1]
	v_div_fixup_f32 v134, v137, v134, 1.0
	v_div_fmas_f32 v137, v138, v142, v145
	v_div_fixup_f32 v127, v137, v127, 1.0
	v_mul_f32_e32 v121, v121, v134
	v_mul_f32_e32 v123, v123, v127
	v_cvt_pk_bf16_f32 v121, v121, v123
	global_store_dword v136, v121, s[10:11]
	s_nop 0
	v_cndmask_b32_e64 v123, v116, v118, s[6:7]
	v_add_lshl_u32 v135, v131, v122, 1
	s_waitcnt vmcnt(15)
	v_lshlrev_b32_e32 v127, 16, v154
	v_and_b32_e32 v121, 0xffff0000, v154
	v_mul_f32_e32 v127, 0xbfb8aa3b, v127
	v_mul_f32_e32 v121, 0xbfb8aa3b, v121
	v_exp_f32_e32 v127, v127
	v_exp_f32_e32 v121, v121
	v_mov_b32_dpp v123, v123 quad_perm:[1,0,3,2] row_mask:0xf bank_mask:0xf bound_ctrl:1
	v_cndmask_b32_e64 v116, v123, v116, s[6:7]
	v_add_f32_e32 v127, 1.0, v127
	v_add_f32_e32 v121, 1.0, v121
	v_div_scale_f32 v136, s[0:1], v127, v127, 1.0
	v_div_scale_f32 v138, s[0:1], v121, v121, 1.0
	v_rcp_f32_e32 v139, v136
	v_rcp_f32_e32 v141, v138
	v_div_scale_f32 v137, vcc, 1.0, v127, 1.0
	v_fma_f32 v143, -v136, v139, 1.0
	v_fma_f32 v144, -v138, v141, 1.0
	v_fmac_f32_e32 v139, v143, v139
	v_div_scale_f32 v142, s[0:1], 1.0, v121, 1.0
	v_fmac_f32_e32 v141, v144, v141
	v_mul_f32_e32 v143, v137, v139
	v_mul_f32_e32 v144, v142, v141
	v_fma_f32 v145, -v136, v143, v137
	v_fma_f32 v146, -v138, v144, v142
	v_fmac_f32_e32 v143, v145, v139
	v_fmac_f32_e32 v144, v146, v141
	v_fma_f32 v136, -v136, v143, v137
	v_fma_f32 v137, -v138, v144, v142
	v_div_fmas_f32 v136, v136, v139, v143
	s_mov_b64 vcc, s[0:1]
	v_div_fixup_f32 v127, v136, v127, 1.0
	v_div_fmas_f32 v136, v137, v141, v144
	v_cndmask_b32_e64 v123, v118, v123, s[6:7]
	v_div_fixup_f32 v121, v136, v121, 1.0
	v_add_u32_e32 v118, 0x100, v124
	v_mul_f32_e32 v116, v116, v127
	v_mul_f32_e32 v121, v123, v121
	v_add_u32_e32 v134, v128, v118
	v_cvt_pk_bf16_f32 v116, v116, v121
	global_store_dword v134, v116, s[10:11]
	s_nop 0
	v_cndmask_b32_e64 v123, v117, v119, s[6:7]
	v_add_u32_e32 v116, 0x19f0, v132
	v_add_lshl_u32 v127, v133, v116, 1
	v_mov_b32_dpp v123, v123 quad_perm:[1,0,3,2] row_mask:0xf bank_mask:0xf bound_ctrl:1
	v_cndmask_b32_e64 v117, v123, v117, s[6:7]
	v_cndmask_b32_e64 v119, v119, v123, s[6:7]
	v_add_u32_e32 v132, v125, v118
	s_waitcnt vmcnt(15)
	v_lshlrev_b32_e32 v123, 16, v155
	v_and_b32_e32 v121, 0xffff0000, v155
	v_mul_f32_e32 v123, 0xbfb8aa3b, v123
	v_mul_f32_e32 v121, 0xbfb8aa3b, v121
	v_exp_f32_e32 v123, v123
	v_exp_f32_e32 v121, v121
	v_add_f32_e32 v123, 1.0, v123
	v_add_f32_e32 v121, 1.0, v121
	v_div_scale_f32 v133, s[0:1], v123, v123, 1.0
	v_div_scale_f32 v135, s[0:1], v121, v121, 1.0
	v_rcp_f32_e32 v136, v133
	v_rcp_f32_e32 v137, v135
	v_div_scale_f32 v134, vcc, 1.0, v123, 1.0
	v_fma_f32 v139, -v133, v136, 1.0
	v_fma_f32 v141, -v135, v137, 1.0
	v_fmac_f32_e32 v136, v139, v136
	v_div_scale_f32 v138, s[0:1], 1.0, v121, 1.0
	v_fmac_f32_e32 v137, v141, v137
	v_mul_f32_e32 v139, v134, v136
	v_mul_f32_e32 v141, v138, v137
	v_fma_f32 v142, -v133, v139, v134
	v_fma_f32 v143, -v135, v141, v138
	v_fmac_f32_e32 v139, v142, v136
	v_fmac_f32_e32 v141, v143, v137
	v_fma_f32 v133, -v133, v139, v134
	v_fma_f32 v134, -v135, v141, v138
	v_div_fmas_f32 v133, v133, v136, v139
	s_mov_b64 vcc, s[0:1]
	v_div_fixup_f32 v123, v133, v123, 1.0
	v_div_fmas_f32 v133, v134, v137, v141
	v_div_fixup_f32 v121, v133, v121, 1.0
	v_mul_f32_e32 v117, v117, v123
	v_mul_f32_e32 v119, v119, v121
	v_cvt_pk_bf16_f32 v117, v117, v119
	global_store_dword v132, v117, s[10:11]
	s_nop 0
	v_cndmask_b32_e64 v119, v112, v114, s[6:7]
	v_add_lshl_u32 v127, v131, v116, 1
	s_nop 0
	v_mov_b32_dpp v119, v119 quad_perm:[1,0,3,2] row_mask:0xf bank_mask:0xf bound_ctrl:1
	v_cndmask_b32_e64 v121, v119, v112, s[6:7]
	v_cndmask_b32_e64 v114, v114, v119, s[6:7]
	v_add_u32_e32 v112, 0x120, v124
	v_add_u32_e32 v123, v128, v112
	s_waitcnt vmcnt(15)
; DEVINL float bflo(unsigned u) { return __uint_as_float(u << 16); }
; DEVINL float bfhi(unsigned u) { return __uint_as_float(u & 0xffff0000u); }
; DEVINL float sigm(float x) { return 1.f / (1.f + __expf(-x)); }
; template <int EPI, bool GATHER>
; DEVINL void gemm_tile(const Params& p, const u16* __restrict__ A, int lda, const int* __restrict__ rowidx,
;                       const u16* __restrict__ Bt, int ldb, int K, int brow, int bcol, int orow, int ocol) {
;     ...
;           f32x4 v = acc[ai][bj][m][n];
;           if (EPI == EPI_HID) {
; #pragma unroll
;             for (int j = 0; j < 4; ++j) { const float a1 = acc[ai][0][m][n][j], a3 = acc[ai][1][m][n][j]; v[j] = a1 * sigm(a1) * a3; }
;           }
;           float lo[2], hi[2];
;           xchg_pairs(v, odd, lo, hi);
; #pragma unroll
;           for (int k = 0; k < 2; ++k) {
;             const unsigned row = (unsigned)(rA + k);
;             if (EPI == EPI_HID) {
;               *(unsigned*)(ws + O_HID + (row * 1024u + (unsigned)(colp + cc)) * 2u) = pk2(lo[k], hi[k]);
;             } else if (EPI == EPI_COLS) {
;               *(unsigned*)(ws + O_COLS + (row * (unsigned)NCP + (unsigned)(colp + cc)) * 2u) = pk2(lo[k], hi[k]);
;             } else if (EPI == EPI_MOE2) {
;               *(unsigned*)(ws + O_EO + (row * 2048u + (unsigned)(colp + cc)) * 2u) = pk2(gate[k] * lo[k], gate[k] * hi[k]);
;             } else if (EPI == EPI_M1) {
;               const unsigned g2 = *(const unsigned*)(ws + O_COLS + (row * (unsigned)NCP + (unsigned)(C_GG + colp + cc)) * 2u);
;               *(unsigned*)(ws + O_M1 + (row * 2048u + (unsigned)(colp + cc)) * 2u) = pk2(sigm(bflo(g2)) * lo[k], sigm(bfhi(g2)) * hi[k]);
	v_lshlrev_b32_e32 v119, 16, v156
	v_and_b32_e32 v117, 0xffff0000, v156
	v_mul_f32_e32 v119, 0xbfb8aa3b, v119
	v_mul_f32_e32 v117, 0xbfb8aa3b, v117
	v_exp_f32_e32 v119, v119
	v_exp_f32_e32 v117, v117
	v_add_f32_e32 v119, 1.0, v119
	v_add_f32_e32 v117, 1.0, v117
	v_div_scale_f32 v131, s[0:1], v119, v119, 1.0
	v_div_scale_f32 v133, s[0:1], v117, v117, 1.0
	v_rcp_f32_e32 v134, v131
	v_rcp_f32_e32 v135, v133
	v_div_scale_f32 v132, vcc, 1.0, v119, 1.0
	v_fma_f32 v137, -v131, v134, 1.0
	v_fma_f32 v138, -v133, v135, 1.0
	v_fmac_f32_e32 v134, v137, v134
	v_div_scale_f32 v136, s[0:1], 1.0, v117, 1.0
	v_fmac_f32_e32 v135, v138, v135
	v_mul_f32_e32 v137, v132, v134
	v_mul_f32_e32 v138, v136, v135
	v_fma_f32 v139, -v131, v137, v132
	v_fma_f32 v141, -v133, v138, v136
	v_fmac_f32_e32 v137, v139, v134
	v_fmac_f32_e32 v138, v141, v135
	v_fma_f32 v131, -v131, v137, v132
	v_fma_f32 v132, -v133, v138, v136
	v_div_fmas_f32 v131, v131, v134, v137
	s_mov_b64 vcc, s[0:1]
	v_div_fixup_f32 v119, v131, v119, 1.0
	v_div_fmas_f32 v131, v132, v135, v138
	v_div_fixup_f32 v117, v131, v117, 1.0
	v_mul_f32_e32 v119, v121, v119
	v_mul_f32_e32 v114, v114, v117
	v_cvt_pk_bf16_f32 v114, v119, v114
	global_store_dword v123, v114, s[10:11]
	s_nop 0
	v_cndmask_b32_e64 v117, v113, v115, s[6:7]
	s_waitcnt vmcnt(15)
	v_lshlrev_b32_e32 v119, 16, v157
	v_and_b32_e32 v114, 0xffff0000, v157
	v_mul_f32_e32 v119, 0xbfb8aa3b, v119
	v_mul_f32_e32 v114, 0xbfb8aa3b, v114
	v_exp_f32_e32 v119, v119
	v_exp_f32_e32 v114, v114
	v_mov_b32_dpp v117, v117 quad_perm:[1,0,3,2] row_mask:0xf bank_mask:0xf bound_ctrl:1
	v_cndmask_b32_e64 v113, v117, v113, s[6:7]
	v_cndmask_b32_e64 v115, v115, v117, s[6:7]
	v_add_f32_e32 v117, 1.0, v119
	v_add_f32_e32 v114, 1.0, v114
	v_div_scale_f32 v119, s[0:1], v117, v117, 1.0
	v_div_scale_f32 v123, s[0:1], v114, v114, 1.0
	v_rcp_f32_e32 v127, v119
	v_rcp_f32_e32 v131, v123
	v_div_scale_f32 v121, vcc, 1.0, v117, 1.0
	v_fma_f32 v133, -v119, v127, 1.0
	v_fma_f32 v134, -v123, v131, 1.0
	v_fmac_f32_e32 v127, v133, v127
	v_div_scale_f32 v132, s[0:1], 1.0, v114, 1.0
	v_fmac_f32_e32 v131, v134, v131
	v_mul_f32_e32 v133, v121, v127
	v_mul_f32_e32 v134, v132, v131
	v_fma_f32 v135, -v119, v133, v121
	v_fma_f32 v136, -v123, v134, v132
	v_fmac_f32_e32 v133, v135, v127
	v_fmac_f32_e32 v134, v136, v131
	v_fma_f32 v119, -v119, v133, v121
	v_fma_f32 v121, -v123, v134, v132
	v_div_fmas_f32 v119, v119, v127, v133
	s_mov_b64 vcc, s[0:1]
	v_div_fixup_f32 v117, v119, v117, 1.0
	v_div_fmas_f32 v119, v121, v131, v134
	v_div_fixup_f32 v114, v119, v114, 1.0
	v_mul_f32_e32 v113, v113, v117
	v_mul_f32_e32 v114, v115, v114
	v_cvt_pk_bf16_f32 v113, v113, v114
	v_add_u32_e32 v114, v125, v112
	global_store_dword v114, v113, s[10:11]
	v_or_b32_e32 v182, 16, v130
	v_mul_lo_u32 v183, v182, s49
	v_add_u32_e32 v184, 0x2a000, v183
	v_add_lshl_u32 v185, v184, v129, 1
	global_load_dword v150, v185, s[8:9]
	v_add_u32_e32 v186, 0x2ca00, v183
	v_add_lshl_u32 v187, v186, v129, 1
	global_load_dword v151, v187, s[8:9]
	v_add_lshl_u32 v188, v184, v126, 1
	global_load_dword v152, v188, s[8:9]
	v_add_lshl_u32 v190, v186, v126, 1
	global_load_dword v153, v190, s[8:9]
	v_add_lshl_u32 v191, v184, v122, 1
	global_load_dword v154, v191, s[8:9]
	v_add_lshl_u32 v192, v186, v122, 1
	global_load_dword v155, v192, s[8:9]
	v_add_lshl_u32 v193, v184, v116, 1
	global_load_dword v156, v193, s[8:9]
	v_add_lshl_u32 v194, v186, v116, 1
	global_load_dword v157, v194, s[8:9]
	v_or_b32_e32 v114, 16, v130
	v_mul_lo_u32 v113, v114, s49
	v_add_lshl_u32 v115, v113, v129, 1
	s_nop 0
	v_cndmask_b32_e64 v117, v108, v110, s[6:7]
	v_lshlrev_b32_e32 v114, 12, v114
	v_add_u32_e32 v119, v114, v124
	v_mov_b32_dpp v117, v117 quad_perm:[1,0,3,2] row_mask:0xf bank_mask:0xf bound_ctrl:1
	v_cndmask_b32_e64 v108, v117, v108, s[6:7]
	v_cndmask_b32_e64 v117, v110, v117, s[6:7]
	s_waitcnt vmcnt(23)
	v_lshlrev_b32_e32 v110, 16, v166
	v_and_b32_e32 v115, 0xffff0000, v166
	v_mul_f32_e32 v110, 0xbfb8aa3b, v110
	v_mul_f32_e32 v115, 0xbfb8aa3b, v115
	v_exp_f32_e32 v121, v110
	v_exp_f32_e32 v115, v115
	v_add_u32_e32 v110, 0x2a00, v113
	v_add_lshl_u32 v123, v110, v129, 1
	v_add_f32_e32 v121, 1.0, v121
	v_add_f32_e32 v115, 1.0, v115
	v_div_scale_f32 v125, s[0:1], v121, v121, 1.0
	v_div_scale_f32 v130, s[0:1], v115, v115, 1.0
	v_rcp_f32_e32 v131, v125
	v_rcp_f32_e32 v132, v130
	v_div_scale_f32 v127, vcc, 1.0, v121, 1.0
	v_fma_f32 v134, -v125, v131, 1.0
	v_fma_f32 v135, -v130, v132, 1.0
	v_fmac_f32_e32 v131, v134, v131
	v_div_scale_f32 v133, s[0:1], 1.0, v115, 1.0
	v_fmac_f32_e32 v132, v135, v132
	v_mul_f32_e32 v134, v127, v131
	v_mul_f32_e32 v135, v133, v132
	v_fma_f32 v136, -v125, v134, v127
	v_fma_f32 v137, -v130, v135, v133
	v_fmac_f32_e32 v134, v136, v131
	v_fmac_f32_e32 v135, v137, v132
	v_fma_f32 v125, -v125, v134, v127
	v_fma_f32 v127, -v130, v135, v133
	v_div_fmas_f32 v125, v125, v131, v134
	s_mov_b64 vcc, s[0:1]
	v_div_fixup_f32 v121, v125, v121, 1.0
	v_div_fmas_f32 v125, v127, v132, v135
	v_div_fixup_f32 v115, v125, v115, 1.0
	v_mul_f32_e32 v108, v108, v121
	v_mul_f32_e32 v115, v117, v115
	v_cvt_pk_bf16_f32 v108, v108, v115
	global_store_dword v119, v108, s[10:11]
	s_nop 0
	v_cndmask_b32_e64 v117, v109, v111, s[6:7]
	v_or_b32_e32 v108, 0x11000, v128
	v_add_u32_e32 v119, v108, v124
	v_mov_b32_dpp v117, v117 quad_perm:[1,0,3,2] row_mask:0xf bank_mask:0xf bound_ctrl:1
	v_cndmask_b32_e64 v109, v117, v109, s[6:7]
	v_cndmask_b32_e64 v111, v111, v117, s[6:7]
	v_add_lshl_u32 v117, v113, v126, 1
	s_waitcnt vmcnt(23)
; DEVINL float bflo(unsigned u) { return __uint_as_float(u << 16); }
; DEVINL float bfhi(unsigned u) { return __uint_as_float(u & 0xffff0000u); }
; DEVINL float sigm(float x) { return 1.f / (1.f + __expf(-x)); }
; template <int EPI, bool GATHER>
; DEVINL void gemm_tile(const Params& p, const u16* __restrict__ A, int lda, const int* __restrict__ rowidx,
;                       const u16* __restrict__ Bt, int ldb, int K, int brow, int bcol, int orow, int ocol) {
;     ...
;           f32x4 v = acc[ai][bj][m][n];
;           if (EPI == EPI_HID) {
; #pragma unroll
;             for (int j = 0; j < 4; ++j) { const float a1 = acc[ai][0][m][n][j], a3 = acc[ai][1][m][n][j]; v[j] = a1 * sigm(a1) * a3; }
;           }
;           float lo[2], hi[2];
;           xchg_pairs(v, odd, lo, hi);
; #pragma unroll
;           for (int k = 0; k < 2; ++k) {
;             const unsigned row = (unsigned)(rA + k);
;             if (EPI == EPI_HID) {
;               *(unsigned*)(ws + O_HID + (row * 1024u + (unsigned)(colp + cc)) * 2u) = pk2(lo[k], hi[k]);
;             } else if (EPI == EPI_COLS) {
;               *(unsigned*)(ws + O_COLS + (row * (unsigned)NCP + (unsigned)(colp + cc)) * 2u) = pk2(lo[k], hi[k]);
;             } else if (EPI == EPI_MOE2) {
;               *(unsigned*)(ws + O_EO + (row * 2048u + (unsigned)(colp + cc)) * 2u) = pk2(gate[k] * lo[k], gate[k] * hi[k]);
;             } else if (EPI == EPI_M1) {
;               const unsigned g2 = *(const unsigned*)(ws + O_COLS + (row * (unsigned)NCP + (unsigned)(C_GG + colp + cc)) * 2u);
;               *(unsigned*)(ws + O_M1 + (row * 2048u + (unsigned)(colp + cc)) * 2u) = pk2(sigm(bflo(g2)) * lo[k], sigm(bfhi(g2)) * hi[k]);
	v_lshlrev_b32_e32 v121, 16, v167
	v_and_b32_e32 v115, 0xffff0000, v167
	v_mul_f32_e32 v121, 0xbfb8aa3b, v121
	v_mul_f32_e32 v115, 0xbfb8aa3b, v115
	v_exp_f32_e32 v121, v121
	v_exp_f32_e32 v115, v115
	v_add_f32_e32 v121, 1.0, v121
	v_add_f32_e32 v115, 1.0, v115
	v_div_scale_f32 v123, s[0:1], v121, v121, 1.0
	v_div_scale_f32 v127, s[0:1], v115, v115, 1.0
	v_rcp_f32_e32 v130, v123
	v_rcp_f32_e32 v131, v127
	v_div_scale_f32 v125, vcc, 1.0, v121, 1.0
	v_fma_f32 v133, -v123, v130, 1.0
	v_fma_f32 v134, -v127, v131, 1.0
	v_fmac_f32_e32 v130, v133, v130
	v_div_scale_f32 v132, s[0:1], 1.0, v115, 1.0
	v_fmac_f32_e32 v131, v134, v131
	v_mul_f32_e32 v133, v125, v130
	v_mul_f32_e32 v134, v132, v131
	v_fma_f32 v135, -v123, v133, v125
	v_fma_f32 v136, -v127, v134, v132
	v_fmac_f32_e32 v133, v135, v130
	v_fmac_f32_e32 v134, v136, v131
	v_fma_f32 v123, -v123, v133, v125
	v_fma_f32 v125, -v127, v134, v132
	v_div_fmas_f32 v123, v123, v130, v133
	s_mov_b64 vcc, s[0:1]
	v_div_fixup_f32 v121, v123, v121, 1.0
	v_div_fmas_f32 v123, v125, v131, v134
	v_div_fixup_f32 v115, v123, v115, 1.0
	v_mul_f32_e32 v109, v109, v121
	v_mul_f32_e32 v111, v111, v115
	v_cvt_pk_bf16_f32 v109, v109, v111
	global_store_dword v119, v109, s[10:11]
	s_nop 0
	v_cndmask_b32_e64 v111, v104, v106, s[6:7]
	v_add_u32_e32 v115, v114, v120
	v_add_lshl_u32 v117, v110, v126, 1
	v_mov_b32_dpp v111, v111 quad_perm:[1,0,3,2] row_mask:0xf bank_mask:0xf bound_ctrl:1
	v_cndmask_b32_e64 v104, v111, v104, s[6:7]
	v_cndmask_b32_e64 v106, v106, v111, s[6:7]
	s_waitcnt vmcnt(23)
	v_lshlrev_b32_e32 v111, 16, v168
	v_and_b32_e32 v109, 0xffff0000, v168
	v_mul_f32_e32 v111, 0xbfb8aa3b, v111
	v_mul_f32_e32 v109, 0xbfb8aa3b, v109
	v_exp_f32_e32 v111, v111
	v_exp_f32_e32 v109, v109
	v_add_f32_e32 v111, 1.0, v111
	v_add_f32_e32 v109, 1.0, v109
	v_div_scale_f32 v119, s[0:1], v111, v111, 1.0
	v_div_scale_f32 v123, s[0:1], v109, v109, 1.0
	v_rcp_f32_e32 v125, v119
	v_rcp_f32_e32 v127, v123
	v_div_scale_f32 v121, vcc, 1.0, v111, 1.0
	v_fma_f32 v131, -v119, v125, 1.0
	v_fma_f32 v132, -v123, v127, 1.0
	v_fmac_f32_e32 v125, v131, v125
	v_div_scale_f32 v130, s[0:1], 1.0, v109, 1.0
	v_fmac_f32_e32 v127, v132, v127
	v_mul_f32_e32 v131, v121, v125
	v_mul_f32_e32 v132, v130, v127
	v_fma_f32 v133, -v119, v131, v121
	v_fma_f32 v134, -v123, v132, v130
	v_fmac_f32_e32 v131, v133, v125
	v_fmac_f32_e32 v132, v134, v127
	v_fma_f32 v119, -v119, v131, v121
	v_fma_f32 v121, -v123, v132, v130
	v_div_fmas_f32 v119, v119, v125, v131
	s_mov_b64 vcc, s[0:1]
	v_div_fixup_f32 v111, v119, v111, 1.0
	v_div_fmas_f32 v119, v121, v127, v132
	v_div_fixup_f32 v109, v119, v109, 1.0
	v_mul_f32_e32 v104, v104, v111
	v_mul_f32_e32 v106, v106, v109
	v_cvt_pk_bf16_f32 v104, v104, v106
	global_store_dword v115, v104, s[10:11]
	s_nop 0
	v_cndmask_b32_e64 v106, v105, v107, s[6:7]
	v_add_u32_e32 v109, v108, v120
	s_waitcnt vmcnt(23)
	v_lshlrev_b32_e32 v111, 16, v169
	v_and_b32_e32 v104, 0xffff0000, v169
	v_mul_f32_e32 v111, 0xbfb8aa3b, v111
	v_mul_f32_e32 v104, 0xbfb8aa3b, v104
	v_exp_f32_e32 v111, v111
	v_exp_f32_e32 v104, v104
	v_mov_b32_dpp v106, v106 quad_perm:[1,0,3,2] row_mask:0xf bank_mask:0xf bound_ctrl:1
	v_cndmask_b32_e64 v105, v106, v105, s[6:7]
	v_add_f32_e32 v111, 1.0, v111
	v_add_f32_e32 v104, 1.0, v104
	v_div_scale_f32 v115, s[0:1], v111, v111, 1.0
	v_div_scale_f32 v119, s[0:1], v104, v104, 1.0
	v_rcp_f32_e32 v121, v115
	v_rcp_f32_e32 v123, v119
	v_div_scale_f32 v117, vcc, 1.0, v111, 1.0
	v_fma_f32 v127, -v115, v121, 1.0
	v_fma_f32 v130, -v119, v123, 1.0
	v_fmac_f32_e32 v121, v127, v121
	v_div_scale_f32 v125, s[0:1], 1.0, v104, 1.0
	v_fmac_f32_e32 v123, v130, v123
	v_mul_f32_e32 v127, v117, v121
	v_mul_f32_e32 v130, v125, v123
	v_fma_f32 v131, -v115, v127, v117
	v_fma_f32 v132, -v119, v130, v125
	v_fmac_f32_e32 v127, v131, v121
	v_fmac_f32_e32 v130, v132, v123
	v_fma_f32 v115, -v115, v127, v117
	v_fma_f32 v117, -v119, v130, v125
	v_div_fmas_f32 v115, v115, v121, v127
	s_mov_b64 vcc, s[0:1]
	v_div_fixup_f32 v111, v115, v111, 1.0
	v_div_fmas_f32 v115, v117, v123, v130
	v_cndmask_b32_e64 v106, v107, v106, s[6:7]
	v_div_fixup_f32 v104, v115, v104, 1.0
	v_mul_f32_e32 v105, v105, v111
	v_mul_f32_e32 v104, v106, v104
	v_cvt_pk_bf16_f32 v104, v105, v104
	v_add_lshl_u32 v107, v113, v122, 1
	global_store_dword v109, v104, s[10:11]
	s_nop 0
	v_cndmask_b32_e64 v105, v100, v102, s[6:7]
	v_add_u32_e32 v106, v114, v118
	v_add_lshl_u32 v107, v110, v122, 1
	v_mov_b32_dpp v105, v105 quad_perm:[1,0,3,2] row_mask:0xf bank_mask:0xf bound_ctrl:1
	v_cndmask_b32_e64 v100, v105, v100, s[6:7]
	v_cndmask_b32_e64 v102, v102, v105, s[6:7]
	s_waitcnt vmcnt(23)
	v_lshlrev_b32_e32 v105, 16, v170
	v_and_b32_e32 v104, 0xffff0000, v170
	v_mul_f32_e32 v105, 0xbfb8aa3b, v105
	v_mul_f32_e32 v104, 0xbfb8aa3b, v104
	v_exp_f32_e32 v105, v105
	v_exp_f32_e32 v104, v104
	v_add_f32_e32 v105, 1.0, v105
	v_add_f32_e32 v104, 1.0, v104
	v_div_scale_f32 v109, s[0:1], v105, v105, 1.0
	v_div_scale_f32 v115, s[0:1], v104, v104, 1.0
	v_rcp_f32_e32 v117, v109
	v_rcp_f32_e32 v119, v115
	v_div_scale_f32 v111, vcc, 1.0, v105, 1.0
	v_fma_f32 v123, -v109, v117, 1.0
	v_fma_f32 v125, -v115, v119, 1.0
	v_fmac_f32_e32 v117, v123, v117
	v_div_scale_f32 v121, s[0:1], 1.0, v104, 1.0
	v_fmac_f32_e32 v119, v125, v119
	v_mul_f32_e32 v123, v111, v117
	v_mul_f32_e32 v125, v121, v119
	v_fma_f32 v127, -v109, v123, v111
	v_fma_f32 v130, -v115, v125, v121
	v_fmac_f32_e32 v123, v127, v117
	v_fmac_f32_e32 v125, v130, v119
	v_fma_f32 v109, -v109, v123, v111
	v_fma_f32 v111, -v115, v125, v121
	v_div_fmas_f32 v109, v109, v117, v123
	s_mov_b64 vcc, s[0:1]
	v_div_fixup_f32 v105, v109, v105, 1.0
	v_div_fmas_f32 v109, v111, v119, v125
	v_div_fixup_f32 v104, v109, v104, 1.0
	v_mul_f32_e32 v100, v100, v105
	v_mul_f32_e32 v102, v102, v104
	v_cvt_pk_bf16_f32 v100, v100, v102
	global_store_dword v106, v100, s[10:11]
	s_nop 0
	v_cndmask_b32_e64 v102, v101, v103, s[6:7]
	v_add_u32_e32 v104, v108, v118
	s_waitcnt vmcnt(23)
; DEVINL float bflo(unsigned u) { return __uint_as_float(u << 16); }
; DEVINL float bfhi(unsigned u) { return __uint_as_float(u & 0xffff0000u); }
; DEVINL float sigm(float x) { return 1.f / (1.f + __expf(-x)); }
; template <int EPI, bool GATHER>
; DEVINL void gemm_tile(const Params& p, const u16* __restrict__ A, int lda, const int* __restrict__ rowidx,
;                       const u16* __restrict__ Bt, int ldb, int K, int brow, int bcol, int orow, int ocol) {
;     ...
;           f32x4 v = acc[ai][bj][m][n];
;           if (EPI == EPI_HID) {
; #pragma unroll
;             for (int j = 0; j < 4; ++j) { const float a1 = acc[ai][0][m][n][j], a3 = acc[ai][1][m][n][j]; v[j] = a1 * sigm(a1) * a3; }
;           }
;           float lo[2], hi[2];
;           xchg_pairs(v, odd, lo, hi);
; #pragma unroll
;           for (int k = 0; k < 2; ++k) {
;             const unsigned row = (unsigned)(rA + k);
;             if (EPI == EPI_HID) {
;               *(unsigned*)(ws + O_HID + (row * 1024u + (unsigned)(colp + cc)) * 2u) = pk2(lo[k], hi[k]);
;             } else if (EPI == EPI_COLS) {
;               *(unsigned*)(ws + O_COLS + (row * (unsigned)NCP + (unsigned)(colp + cc)) * 2u) = pk2(lo[k], hi[k]);
;             } else if (EPI == EPI_MOE2) {
;               *(unsigned*)(ws + O_EO + (row * 2048u + (unsigned)(colp + cc)) * 2u) = pk2(gate[k] * lo[k], gate[k] * hi[k]);
;             } else if (EPI == EPI_M1) {
;               const unsigned g2 = *(const unsigned*)(ws + O_COLS + (row * (unsigned)NCP + (unsigned)(C_GG + colp + cc)) * 2u);
;               *(unsigned*)(ws + O_M1 + (row * 2048u + (unsigned)(colp + cc)) * 2u) = pk2(sigm(bflo(g2)) * lo[k], sigm(bfhi(g2)) * hi[k]);
	v_lshlrev_b32_e32 v105, 16, v171
	v_and_b32_e32 v100, 0xffff0000, v171
	v_mul_f32_e32 v105, 0xbfb8aa3b, v105
	v_mul_f32_e32 v100, 0xbfb8aa3b, v100
	v_exp_f32_e32 v105, v105
	v_exp_f32_e32 v100, v100
	v_mov_b32_dpp v102, v102 quad_perm:[1,0,3,2] row_mask:0xf bank_mask:0xf bound_ctrl:1
	v_cndmask_b32_e64 v101, v102, v101, s[6:7]
	v_add_f32_e32 v105, 1.0, v105
	v_add_f32_e32 v100, 1.0, v100
	v_div_scale_f32 v106, s[0:1], v105, v105, 1.0
	v_div_scale_f32 v109, s[0:1], v100, v100, 1.0
	v_rcp_f32_e32 v111, v106
	v_rcp_f32_e32 v115, v109
	v_div_scale_f32 v107, vcc, 1.0, v105, 1.0
	v_fma_f32 v119, -v106, v111, 1.0
	v_fma_f32 v121, -v109, v115, 1.0
	v_fmac_f32_e32 v111, v119, v111
	v_div_scale_f32 v117, s[0:1], 1.0, v100, 1.0
	v_fmac_f32_e32 v115, v121, v115
	v_mul_f32_e32 v119, v107, v111
	v_mul_f32_e32 v121, v117, v115
	v_fma_f32 v123, -v106, v119, v107
	v_fma_f32 v125, -v109, v121, v117
	v_fmac_f32_e32 v119, v123, v111
	v_fmac_f32_e32 v121, v125, v115
	v_fma_f32 v106, -v106, v119, v107
	v_fma_f32 v107, -v109, v121, v117
	v_div_fmas_f32 v106, v106, v111, v119
	s_mov_b64 vcc, s[0:1]
	v_div_fixup_f32 v105, v106, v105, 1.0
	v_div_fmas_f32 v106, v107, v115, v121
	v_cndmask_b32_e64 v102, v103, v102, s[6:7]
	v_div_fixup_f32 v100, v106, v100, 1.0
	v_mul_f32_e32 v101, v101, v105
	v_mul_f32_e32 v100, v102, v100
	v_cvt_pk_bf16_f32 v100, v101, v100
	v_add_lshl_u32 v103, v113, v116, 1
	global_store_dword v104, v100, s[10:11]
	s_nop 0
	v_cndmask_b32_e64 v101, v96, v98, s[6:7]
	v_add_u32_e32 v102, v114, v112
	v_add_lshl_u32 v103, v110, v116, 1
	v_mov_b32_dpp v101, v101 quad_perm:[1,0,3,2] row_mask:0xf bank_mask:0xf bound_ctrl:1
	v_cndmask_b32_e64 v96, v101, v96, s[6:7]
	v_cndmask_b32_e64 v98, v98, v101, s[6:7]
	s_waitcnt vmcnt(23)
	v_lshlrev_b32_e32 v101, 16, v172
	v_and_b32_e32 v100, 0xffff0000, v172
	v_mul_f32_e32 v101, 0xbfb8aa3b, v101
	v_mul_f32_e32 v100, 0xbfb8aa3b, v100
	v_exp_f32_e32 v101, v101
	v_exp_f32_e32 v100, v100
	v_add_f32_e32 v101, 1.0, v101
	v_add_f32_e32 v100, 1.0, v100
	v_div_scale_f32 v104, s[0:1], v101, v101, 1.0
	v_div_scale_f32 v106, s[0:1], v100, v100, 1.0
	v_rcp_f32_e32 v107, v104
	v_rcp_f32_e32 v109, v106
	v_div_scale_f32 v105, vcc, 1.0, v101, 1.0
	v_fma_f32 v111, -v104, v107, 1.0
	v_fma_f32 v114, -v106, v109, 1.0
	v_fmac_f32_e32 v107, v111, v107
	v_div_scale_f32 v110, s[0:1], 1.0, v100, 1.0
	v_fmac_f32_e32 v109, v114, v109
	v_mul_f32_e32 v111, v105, v107
	v_mul_f32_e32 v114, v110, v109
	v_fma_f32 v115, -v104, v111, v105
	v_fma_f32 v117, -v106, v114, v110
	v_fmac_f32_e32 v111, v115, v107
	v_fmac_f32_e32 v114, v117, v109
	v_fma_f32 v104, -v104, v111, v105
	v_fma_f32 v105, -v106, v114, v110
	v_div_fmas_f32 v104, v104, v107, v111
	s_mov_b64 vcc, s[0:1]
	v_div_fixup_f32 v101, v104, v101, 1.0
	v_div_fmas_f32 v104, v105, v109, v114
	v_div_fixup_f32 v100, v104, v100, 1.0
	v_mul_f32_e32 v96, v96, v101
	v_mul_f32_e32 v98, v98, v100
	v_cvt_pk_bf16_f32 v96, v96, v98
	global_store_dword v102, v96, s[10:11]
	s_nop 0
	v_cndmask_b32_e64 v98, v97, v99, s[6:7]
	s_waitcnt vmcnt(23)
	v_lshlrev_b32_e32 v100, 16, v173
	v_and_b32_e32 v96, 0xffff0000, v173
	v_mul_f32_e32 v100, 0xbfb8aa3b, v100
	v_mul_f32_e32 v96, 0xbfb8aa3b, v96
	v_exp_f32_e32 v100, v100
	v_exp_f32_e32 v96, v96
	v_mov_b32_dpp v98, v98 quad_perm:[1,0,3,2] row_mask:0xf bank_mask:0xf bound_ctrl:1
	v_cndmask_b32_e64 v97, v98, v97, s[6:7]
	v_cndmask_b32_e64 v98, v99, v98, s[6:7]
	v_add_f32_e32 v99, 1.0, v100
	v_add_f32_e32 v96, 1.0, v96
	v_div_scale_f32 v100, s[0:1], v99, v99, 1.0
	v_div_scale_f32 v102, s[0:1], v96, v96, 1.0
	v_rcp_f32_e32 v103, v100
	v_rcp_f32_e32 v104, v102
	v_div_scale_f32 v101, vcc, 1.0, v99, 1.0
	v_fma_f32 v106, -v100, v103, 1.0
	v_fma_f32 v107, -v102, v104, 1.0
	v_fmac_f32_e32 v103, v106, v103
	v_div_scale_f32 v105, s[0:1], 1.0, v96, 1.0
	v_fmac_f32_e32 v104, v107, v104
	v_mul_f32_e32 v106, v101, v103
	v_mul_f32_e32 v107, v105, v104
	v_fma_f32 v109, -v100, v106, v101
	v_fma_f32 v110, -v102, v107, v105
	v_fmac_f32_e32 v106, v109, v103
	v_fmac_f32_e32 v107, v110, v104
	v_fma_f32 v100, -v100, v106, v101
	v_fma_f32 v101, -v102, v107, v105
	v_div_fmas_f32 v100, v100, v103, v106
	s_mov_b64 vcc, s[0:1]
	v_div_fixup_f32 v99, v100, v99, 1.0
	v_div_fmas_f32 v100, v101, v104, v107
	v_div_fixup_f32 v96, v100, v96, 1.0
	v_mul_f32_e32 v97, v97, v99
	v_mul_f32_e32 v96, v98, v96
	v_cvt_pk_bf16_f32 v96, v97, v96
	v_add_u32_e32 v97, v108, v112
	global_store_dword v97, v96, s[10:11]
	v_add_u32_e32 v182, 0x54000, v113
	v_add_lshl_u32 v183, v182, v129, 1
	global_load_dword v166, v183, s[8:9]
	v_add_u32_e32 v184, 0x56a00, v113
	v_add_lshl_u32 v185, v184, v129, 1
	global_load_dword v167, v185, s[8:9]
	v_add_lshl_u32 v186, v182, v126, 1
	global_load_dword v168, v186, s[8:9]
	v_add_lshl_u32 v187, v184, v126, 1
	global_load_dword v169, v187, s[8:9]
	v_add_lshl_u32 v188, v182, v122, 1
	global_load_dword v170, v188, s[8:9]
	v_add_lshl_u32 v190, v184, v122, 1
	global_load_dword v171, v190, s[8:9]
	v_add_lshl_u32 v191, v182, v116, 1
	global_load_dword v172, v191, s[8:9]
	v_add_lshl_u32 v192, v184, v116, 1
	global_load_dword v173, v192, s[8:9]
	v_add_u32_e32 v98, 0x2a000, v113
	v_add_lshl_u32 v96, v98, v129, 1
	s_nop 0
	v_cndmask_b32_e64 v100, v92, v94, s[6:7]
	v_or_b32_e32 v96, 0x20000, v128
	v_add_u32_e32 v97, 0x2ca00, v113
	v_mov_b32_dpp v100, v100 quad_perm:[1,0,3,2] row_mask:0xf bank_mask:0xf bound_ctrl:1
	v_cndmask_b32_e64 v92, v100, v92, s[6:7]
	v_cndmask_b32_e64 v94, v94, v100, s[6:7]
	v_add_u32_e32 v101, v96, v124
	v_add_lshl_u32 v102, v97, v129, 1
	s_waitcnt vmcnt(23)
; DEVINL float bflo(unsigned u) { return __uint_as_float(u << 16); }
; DEVINL float bfhi(unsigned u) { return __uint_as_float(u & 0xffff0000u); }
; DEVINL float sigm(float x) { return 1.f / (1.f + __expf(-x)); }
; template <int EPI, bool GATHER>
; DEVINL void gemm_tile(const Params& p, const u16* __restrict__ A, int lda, const int* __restrict__ rowidx,
;                       const u16* __restrict__ Bt, int ldb, int K, int brow, int bcol, int orow, int ocol) {
;     ...
;           f32x4 v = acc[ai][bj][m][n];
;           if (EPI == EPI_HID) {
; #pragma unroll
;             for (int j = 0; j < 4; ++j) { const float a1 = acc[ai][0][m][n][j], a3 = acc[ai][1][m][n][j]; v[j] = a1 * sigm(a1) * a3; }
;           }
;           float lo[2], hi[2];
;           xchg_pairs(v, odd, lo, hi);
; #pragma unroll
;           for (int k = 0; k < 2; ++k) {
;             const unsigned row = (unsigned)(rA + k);
;             if (EPI == EPI_HID) {
;               *(unsigned*)(ws + O_HID + (row * 1024u + (unsigned)(colp + cc)) * 2u) = pk2(lo[k], hi[k]);
;             } else if (EPI == EPI_COLS) {
;               *(unsigned*)(ws + O_COLS + (row * (unsigned)NCP + (unsigned)(colp + cc)) * 2u) = pk2(lo[k], hi[k]);
;             } else if (EPI == EPI_MOE2) {
;               *(unsigned*)(ws + O_EO + (row * 2048u + (unsigned)(colp + cc)) * 2u) = pk2(gate[k] * lo[k], gate[k] * hi[k]);
;             } else if (EPI == EPI_M1) {
;               const unsigned g2 = *(const unsigned*)(ws + O_COLS + (row * (unsigned)NCP + (unsigned)(C_GG + colp + cc)) * 2u);
;               *(unsigned*)(ws + O_M1 + (row * 2048u + (unsigned)(colp + cc)) * 2u) = pk2(sigm(bflo(g2)) * lo[k], sigm(bfhi(g2)) * hi[k]);
	v_lshlrev_b32_e32 v103, 16, v150
	v_and_b32_e32 v99, 0xffff0000, v150
	v_mul_f32_e32 v103, 0xbfb8aa3b, v103
	v_mul_f32_e32 v99, 0xbfb8aa3b, v99
	v_exp_f32_e32 v103, v103
	v_exp_f32_e32 v99, v99
	v_add_f32_e32 v100, 1.0, v103
	v_add_f32_e32 v99, 1.0, v99
	v_div_scale_f32 v103, s[0:1], v100, v100, 1.0
	v_div_scale_f32 v105, s[0:1], v99, v99, 1.0
	v_rcp_f32_e32 v106, v103
	v_rcp_f32_e32 v107, v105
	v_div_scale_f32 v104, vcc, 1.0, v100, 1.0
	v_fma_f32 v109, -v103, v106, 1.0
	v_fma_f32 v110, -v105, v107, 1.0
	v_fmac_f32_e32 v106, v109, v106
	v_div_scale_f32 v108, s[0:1], 1.0, v99, 1.0
	v_fmac_f32_e32 v107, v110, v107
	v_mul_f32_e32 v109, v104, v106
	v_mul_f32_e32 v110, v108, v107
	v_fma_f32 v111, -v103, v109, v104
	v_fma_f32 v114, -v105, v110, v108
	v_fmac_f32_e32 v109, v111, v106
	v_fmac_f32_e32 v110, v114, v107
	v_fma_f32 v103, -v103, v109, v104
	v_fma_f32 v104, -v105, v110, v108
	v_div_fmas_f32 v103, v103, v106, v109
	s_mov_b64 vcc, s[0:1]
	v_div_fixup_f32 v100, v103, v100, 1.0
	v_div_fmas_f32 v103, v104, v107, v110
	v_div_fixup_f32 v99, v103, v99, 1.0
	v_mul_f32_e32 v92, v92, v100
	v_mul_f32_e32 v94, v94, v99
	v_cvt_pk_bf16_f32 v92, v92, v94
	global_store_dword v101, v92, s[10:11]
	s_nop 0
	v_cndmask_b32_e64 v99, v93, v95, s[6:7]
	v_or_b32_e32 v92, 0x21000, v128
	v_add_u32_e32 v100, v92, v124
	v_mov_b32_dpp v99, v99 quad_perm:[1,0,3,2] row_mask:0xf bank_mask:0xf bound_ctrl:1
	v_cndmask_b32_e64 v93, v99, v93, s[6:7]
	v_cndmask_b32_e64 v95, v95, v99, s[6:7]
	v_add_lshl_u32 v101, v98, v126, 1
	s_waitcnt vmcnt(23)
	v_lshlrev_b32_e32 v102, 16, v151
	v_and_b32_e32 v94, 0xffff0000, v151
	v_mul_f32_e32 v102, 0xbfb8aa3b, v102
	v_mul_f32_e32 v94, 0xbfb8aa3b, v94
	v_exp_f32_e32 v102, v102
	v_exp_f32_e32 v94, v94
	v_add_f32_e32 v99, 1.0, v102
	v_add_f32_e32 v94, 1.0, v94
	v_div_scale_f32 v102, s[0:1], v99, v99, 1.0
	v_div_scale_f32 v104, s[0:1], v94, v94, 1.0
	v_rcp_f32_e32 v105, v102
	v_rcp_f32_e32 v106, v104
	v_div_scale_f32 v103, vcc, 1.0, v99, 1.0
	v_fma_f32 v108, -v102, v105, 1.0
	v_fma_f32 v109, -v104, v106, 1.0
	v_fmac_f32_e32 v105, v108, v105
	v_div_scale_f32 v107, s[0:1], 1.0, v94, 1.0
	v_fmac_f32_e32 v106, v109, v106
	v_mul_f32_e32 v108, v103, v105
	v_mul_f32_e32 v109, v107, v106
	v_fma_f32 v110, -v102, v108, v103
	v_fma_f32 v111, -v104, v109, v107
	v_fmac_f32_e32 v108, v110, v105
	v_fmac_f32_e32 v109, v111, v106
	v_fma_f32 v102, -v102, v108, v103
	v_fma_f32 v103, -v104, v109, v107
	v_div_fmas_f32 v102, v102, v105, v108
	s_mov_b64 vcc, s[0:1]
	v_div_fixup_f32 v99, v102, v99, 1.0
	v_div_fmas_f32 v102, v103, v106, v109
	v_div_fixup_f32 v94, v102, v94, 1.0
	v_mul_f32_e32 v93, v93, v99
	v_mul_f32_e32 v94, v95, v94
	v_cvt_pk_bf16_f32 v93, v93, v94
	global_store_dword v100, v93, s[10:11]
	s_nop 0
	v_cndmask_b32_e64 v94, v88, v90, s[6:7]
	v_add_u32_e32 v95, v96, v120
	v_add_lshl_u32 v99, v97, v126, 1
	v_mov_b32_dpp v94, v94 quad_perm:[1,0,3,2] row_mask:0xf bank_mask:0xf bound_ctrl:1
	v_cndmask_b32_e64 v88, v94, v88, s[6:7]
	v_cndmask_b32_e64 v90, v90, v94, s[6:7]
	s_waitcnt vmcnt(23)
	v_lshlrev_b32_e32 v100, 16, v152
	v_and_b32_e32 v93, 0xffff0000, v152
	v_mul_f32_e32 v100, 0xbfb8aa3b, v100
	v_mul_f32_e32 v93, 0xbfb8aa3b, v93
	v_exp_f32_e32 v100, v100
	v_exp_f32_e32 v93, v93
	v_add_f32_e32 v94, 1.0, v100
	v_add_f32_e32 v93, 1.0, v93
	v_div_scale_f32 v100, s[0:1], v94, v94, 1.0
	v_div_scale_f32 v102, s[0:1], v93, v93, 1.0
	v_rcp_f32_e32 v103, v100
	v_rcp_f32_e32 v104, v102
	v_div_scale_f32 v101, vcc, 1.0, v94, 1.0
	v_fma_f32 v106, -v100, v103, 1.0
	v_fma_f32 v107, -v102, v104, 1.0
	v_fmac_f32_e32 v103, v106, v103
	v_div_scale_f32 v105, s[0:1], 1.0, v93, 1.0
	v_fmac_f32_e32 v104, v107, v104
	v_mul_f32_e32 v106, v101, v103
	v_mul_f32_e32 v107, v105, v104
	v_fma_f32 v108, -v100, v106, v101
	v_fma_f32 v109, -v102, v107, v105
	v_fmac_f32_e32 v106, v108, v103
	v_fmac_f32_e32 v107, v109, v104
	v_fma_f32 v100, -v100, v106, v101
	v_fma_f32 v101, -v102, v107, v105
	v_div_fmas_f32 v100, v100, v103, v106
	s_mov_b64 vcc, s[0:1]
	v_div_fixup_f32 v94, v100, v94, 1.0
	v_div_fmas_f32 v100, v101, v104, v107
	v_div_fixup_f32 v93, v100, v93, 1.0
	v_mul_f32_e32 v88, v88, v94
	v_mul_f32_e32 v90, v90, v93
	v_cvt_pk_bf16_f32 v88, v88, v90
	global_store_dword v95, v88, s[10:11]
	s_nop 0
	v_cndmask_b32_e64 v90, v89, v91, s[6:7]
	v_add_u32_e32 v93, v92, v120
	v_add_lshl_u32 v94, v98, v122, 1
	v_mov_b32_dpp v90, v90 quad_perm:[1,0,3,2] row_mask:0xf bank_mask:0xf bound_ctrl:1
	v_cndmask_b32_e64 v89, v90, v89, s[6:7]
	v_cndmask_b32_e64 v90, v91, v90, s[6:7]
	s_waitcnt vmcnt(23)
	v_lshlrev_b32_e32 v95, 16, v153
	v_and_b32_e32 v88, 0xffff0000, v153
	v_mul_f32_e32 v95, 0xbfb8aa3b, v95
	v_mul_f32_e32 v88, 0xbfb8aa3b, v88
	v_exp_f32_e32 v95, v95
	v_exp_f32_e32 v88, v88
	v_add_f32_e32 v91, 1.0, v95
	v_add_f32_e32 v88, 1.0, v88
	v_div_scale_f32 v95, s[0:1], v91, v91, 1.0
	v_div_scale_f32 v100, s[0:1], v88, v88, 1.0
	v_rcp_f32_e32 v101, v95
	v_rcp_f32_e32 v102, v100
	v_div_scale_f32 v99, vcc, 1.0, v91, 1.0
	v_fma_f32 v104, -v95, v101, 1.0
	v_fma_f32 v105, -v100, v102, 1.0
	v_fmac_f32_e32 v101, v104, v101
	v_div_scale_f32 v103, s[0:1], 1.0, v88, 1.0
	v_fmac_f32_e32 v102, v105, v102
	v_mul_f32_e32 v104, v99, v101
	v_mul_f32_e32 v105, v103, v102
	v_fma_f32 v106, -v95, v104, v99
	v_fma_f32 v107, -v100, v105, v103
	v_fmac_f32_e32 v104, v106, v101
	v_fmac_f32_e32 v105, v107, v102
	v_fma_f32 v95, -v95, v104, v99
	v_fma_f32 v99, -v100, v105, v103
	v_div_fmas_f32 v95, v95, v101, v104
	s_mov_b64 vcc, s[0:1]
	v_div_fixup_f32 v91, v95, v91, 1.0
	v_div_fmas_f32 v95, v99, v102, v105
	v_div_fixup_f32 v88, v95, v88, 1.0
	v_mul_f32_e32 v89, v89, v91
	v_mul_f32_e32 v88, v90, v88
	v_cvt_pk_bf16_f32 v88, v89, v88
	global_store_dword v93, v88, s[10:11]
	s_nop 0
	v_cndmask_b32_e64 v89, v84, v86, s[6:7]
	v_add_u32_e32 v90, v96, v118
	v_add_lshl_u32 v91, v97, v122, 1
	v_mov_b32_dpp v89, v89 quad_perm:[1,0,3,2] row_mask:0xf bank_mask:0xf bound_ctrl:1
	v_cndmask_b32_e64 v84, v89, v84, s[6:7]
	v_cndmask_b32_e64 v86, v86, v89, s[6:7]
	s_waitcnt vmcnt(23)
; DEVINL float bflo(unsigned u) { return __uint_as_float(u << 16); }
; DEVINL float bfhi(unsigned u) { return __uint_as_float(u & 0xffff0000u); }
; DEVINL float sigm(float x) { return 1.f / (1.f + __expf(-x)); }
; template <int EPI, bool GATHER>
; DEVINL void gemm_tile(const Params& p, const u16* __restrict__ A, int lda, const int* __restrict__ rowidx,
;                       const u16* __restrict__ Bt, int ldb, int K, int brow, int bcol, int orow, int ocol) {
;     ...
;           f32x4 v = acc[ai][bj][m][n];
;           if (EPI == EPI_HID) {
; #pragma unroll
;             for (int j = 0; j < 4; ++j) { const float a1 = acc[ai][0][m][n][j], a3 = acc[ai][1][m][n][j]; v[j] = a1 * sigm(a1) * a3; }
;           }
;           float lo[2], hi[2];
;           xchg_pairs(v, odd, lo, hi);
; #pragma unroll
;           for (int k = 0; k < 2; ++k) {
;             const unsigned row = (unsigned)(rA + k);
;             if (EPI == EPI_HID) {
;               *(unsigned*)(ws + O_HID + (row * 1024u + (unsigned)(colp + cc)) * 2u) = pk2(lo[k], hi[k]);
;             } else if (EPI == EPI_COLS) {
;               *(unsigned*)(ws + O_COLS + (row * (unsigned)NCP + (unsigned)(colp + cc)) * 2u) = pk2(lo[k], hi[k]);
;             } else if (EPI == EPI_MOE2) {
;               *(unsigned*)(ws + O_EO + (row * 2048u + (unsigned)(colp + cc)) * 2u) = pk2(gate[k] * lo[k], gate[k] * hi[k]);
;             } else if (EPI == EPI_M1) {
;               const unsigned g2 = *(const unsigned*)(ws + O_COLS + (row * (unsigned)NCP + (unsigned)(C_GG + colp + cc)) * 2u);
;               *(unsigned*)(ws + O_M1 + (row * 2048u + (unsigned)(colp + cc)) * 2u) = pk2(sigm(bflo(g2)) * lo[k], sigm(bfhi(g2)) * hi[k]);
	v_lshlrev_b32_e32 v93, 16, v154
	v_and_b32_e32 v88, 0xffff0000, v154
	v_mul_f32_e32 v93, 0xbfb8aa3b, v93
	v_mul_f32_e32 v88, 0xbfb8aa3b, v88
	v_exp_f32_e32 v93, v93
	v_exp_f32_e32 v88, v88
	v_add_f32_e32 v89, 1.0, v93
	v_add_f32_e32 v88, 1.0, v88
	v_div_scale_f32 v93, s[0:1], v89, v89, 1.0
	v_div_scale_f32 v95, s[0:1], v88, v88, 1.0
	v_rcp_f32_e32 v99, v93
	v_rcp_f32_e32 v100, v95
	v_div_scale_f32 v94, vcc, 1.0, v89, 1.0
	v_fma_f32 v102, -v93, v99, 1.0
	v_fma_f32 v103, -v95, v100, 1.0
	v_fmac_f32_e32 v99, v102, v99
	v_div_scale_f32 v101, s[0:1], 1.0, v88, 1.0
	v_fmac_f32_e32 v100, v103, v100
	v_mul_f32_e32 v102, v94, v99
	v_mul_f32_e32 v103, v101, v100
	v_fma_f32 v104, -v93, v102, v94
	v_fma_f32 v105, -v95, v103, v101
	v_fmac_f32_e32 v102, v104, v99
	v_fmac_f32_e32 v103, v105, v100
	v_fma_f32 v93, -v93, v102, v94
	v_fma_f32 v94, -v95, v103, v101
	v_div_fmas_f32 v93, v93, v99, v102
	s_mov_b64 vcc, s[0:1]
	v_div_fixup_f32 v89, v93, v89, 1.0
	v_div_fmas_f32 v93, v94, v100, v103
	v_div_fixup_f32 v88, v93, v88, 1.0
	v_mul_f32_e32 v84, v84, v89
	v_mul_f32_e32 v86, v86, v88
	v_cvt_pk_bf16_f32 v84, v84, v86
	global_store_dword v90, v84, s[10:11]
	s_nop 0
	v_cndmask_b32_e64 v86, v85, v87, s[6:7]
	v_add_lshl_u32 v89, v98, v116, 1
	v_add_u32_e32 v88, v92, v118
	v_mov_b32_dpp v86, v86 quad_perm:[1,0,3,2] row_mask:0xf bank_mask:0xf bound_ctrl:1
	v_cndmask_b32_e64 v85, v86, v85, s[6:7]
	v_cndmask_b32_e64 v86, v87, v86, s[6:7]
	s_waitcnt vmcnt(23)
	v_lshlrev_b32_e32 v90, 16, v155
	v_and_b32_e32 v84, 0xffff0000, v155
	v_mul_f32_e32 v90, 0xbfb8aa3b, v90
	v_mul_f32_e32 v84, 0xbfb8aa3b, v84
	v_exp_f32_e32 v90, v90
	v_exp_f32_e32 v84, v84
	v_add_f32_e32 v87, 1.0, v90
	v_add_f32_e32 v84, 1.0, v84
	v_div_scale_f32 v90, s[0:1], v87, v87, 1.0
	v_div_scale_f32 v93, s[0:1], v84, v84, 1.0
	v_rcp_f32_e32 v94, v90
	v_rcp_f32_e32 v95, v93
	v_div_scale_f32 v91, vcc, 1.0, v87, 1.0
	v_fma_f32 v99, -v90, v94, 1.0
	v_fma_f32 v100, -v93, v95, 1.0
	v_fmac_f32_e32 v94, v99, v94
	v_div_scale_f32 v98, s[0:1], 1.0, v84, 1.0
	v_fmac_f32_e32 v95, v100, v95
	v_mul_f32_e32 v99, v91, v94
	v_mul_f32_e32 v100, v98, v95
	v_fma_f32 v101, -v90, v99, v91
	v_fma_f32 v102, -v93, v100, v98
	v_fmac_f32_e32 v99, v101, v94
	v_fmac_f32_e32 v100, v102, v95
	v_fma_f32 v90, -v90, v99, v91
	v_fma_f32 v91, -v93, v100, v98
	v_div_fmas_f32 v90, v90, v94, v99
	s_mov_b64 vcc, s[0:1]
	v_div_fixup_f32 v87, v90, v87, 1.0
	v_div_fmas_f32 v90, v91, v95, v100
	v_div_fixup_f32 v84, v90, v84, 1.0
	v_mul_f32_e32 v85, v85, v87
	v_mul_f32_e32 v84, v86, v84
	v_cvt_pk_bf16_f32 v84, v85, v84
	global_store_dword v88, v84, s[10:11]
	s_nop 0
	v_cndmask_b32_e64 v85, v80, v82, s[6:7]
	v_add_u32_e32 v86, v96, v112
	v_add_lshl_u32 v87, v97, v116, 1
	v_mov_b32_dpp v85, v85 quad_perm:[1,0,3,2] row_mask:0xf bank_mask:0xf bound_ctrl:1
	v_cndmask_b32_e64 v80, v85, v80, s[6:7]
	v_cndmask_b32_e64 v82, v82, v85, s[6:7]
	s_waitcnt vmcnt(23)
	v_lshlrev_b32_e32 v88, 16, v156
	v_and_b32_e32 v84, 0xffff0000, v156
	v_mul_f32_e32 v88, 0xbfb8aa3b, v88
	v_mul_f32_e32 v84, 0xbfb8aa3b, v84
	v_exp_f32_e32 v88, v88
	v_exp_f32_e32 v84, v84
	v_add_f32_e32 v85, 1.0, v88
	v_add_f32_e32 v84, 1.0, v84
	v_div_scale_f32 v88, s[0:1], v85, v85, 1.0
	v_div_scale_f32 v90, s[0:1], v84, v84, 1.0
	v_rcp_f32_e32 v91, v88
	v_rcp_f32_e32 v93, v90
	v_div_scale_f32 v89, vcc, 1.0, v85, 1.0
	v_fma_f32 v95, -v88, v91, 1.0
	v_fma_f32 v96, -v90, v93, 1.0
	v_fmac_f32_e32 v91, v95, v91
	v_div_scale_f32 v94, s[0:1], 1.0, v84, 1.0
	v_fmac_f32_e32 v93, v96, v93
	v_mul_f32_e32 v95, v89, v91
	v_mul_f32_e32 v96, v94, v93
	v_fma_f32 v97, -v88, v95, v89
	v_fma_f32 v98, -v90, v96, v94
	v_fmac_f32_e32 v95, v97, v91
	v_fmac_f32_e32 v96, v98, v93
	v_fma_f32 v88, -v88, v95, v89
	v_fma_f32 v89, -v90, v96, v94
	v_div_fmas_f32 v88, v88, v91, v95
	s_mov_b64 vcc, s[0:1]
	v_div_fixup_f32 v85, v88, v85, 1.0
	v_div_fmas_f32 v88, v89, v93, v96
	v_div_fixup_f32 v84, v88, v84, 1.0
	v_mul_f32_e32 v80, v80, v85
	v_mul_f32_e32 v82, v82, v84
	v_cvt_pk_bf16_f32 v80, v80, v82
	global_store_dword v86, v80, s[10:11]
	s_nop 0
	v_cndmask_b32_e64 v82, v81, v83, s[6:7]
	s_waitcnt vmcnt(23)
	v_lshlrev_b32_e32 v84, 16, v157
	v_and_b32_e32 v80, 0xffff0000, v157
	v_mul_f32_e32 v84, 0xbfb8aa3b, v84
	v_mul_f32_e32 v80, 0xbfb8aa3b, v80
	v_exp_f32_e32 v84, v84
	v_exp_f32_e32 v80, v80
	v_mov_b32_dpp v82, v82 quad_perm:[1,0,3,2] row_mask:0xf bank_mask:0xf bound_ctrl:1
	v_cndmask_b32_e64 v81, v82, v81, s[6:7]
	v_cndmask_b32_e64 v82, v83, v82, s[6:7]
	v_add_f32_e32 v83, 1.0, v84
	v_add_f32_e32 v80, 1.0, v80
	v_div_scale_f32 v84, s[0:1], v83, v83, 1.0
	v_div_scale_f32 v86, s[0:1], v80, v80, 1.0
	v_rcp_f32_e32 v87, v84
	v_rcp_f32_e32 v88, v86
	v_div_scale_f32 v85, vcc, 1.0, v83, 1.0
	v_fma_f32 v90, -v84, v87, 1.0
	v_fma_f32 v91, -v86, v88, 1.0
	v_fmac_f32_e32 v87, v90, v87
	v_div_scale_f32 v89, s[0:1], 1.0, v80, 1.0
	v_fmac_f32_e32 v88, v91, v88
	v_mul_f32_e32 v90, v85, v87
	v_mul_f32_e32 v91, v89, v88
	v_fma_f32 v93, -v84, v90, v85
	v_fma_f32 v94, -v86, v91, v89
	v_fmac_f32_e32 v90, v93, v87
	v_fmac_f32_e32 v91, v94, v88
	v_fma_f32 v84, -v84, v90, v85
	v_fma_f32 v85, -v86, v91, v89
	v_div_fmas_f32 v84, v84, v87, v90
	s_mov_b64 vcc, s[0:1]
	v_div_fixup_f32 v83, v84, v83, 1.0
	v_div_fmas_f32 v84, v85, v88, v91
	v_div_fixup_f32 v80, v84, v80, 1.0
	v_mul_f32_e32 v81, v81, v83
	v_mul_f32_e32 v80, v82, v80
	v_cvt_pk_bf16_f32 v80, v81, v80
	v_add_u32_e32 v81, v92, v112
	global_store_dword v81, v80, s[10:11]
	v_add_u32_e32 v182, 0x126000, v113
	v_add_lshl_u32 v183, v182, v129, 1
	global_load_dword v150, v183, s[8:9]
	v_add_u32_e32 v184, 0x128a00, v113
	v_add_lshl_u32 v185, v184, v129, 1
	global_load_dword v151, v185, s[8:9]
	v_add_lshl_u32 v186, v182, v126, 1
	global_load_dword v152, v186, s[8:9]
	v_add_lshl_u32 v187, v184, v126, 1
	global_load_dword v153, v187, s[8:9]
	v_add_lshl_u32 v188, v182, v122, 1
	global_load_dword v154, v188, s[8:9]
	v_add_lshl_u32 v190, v184, v122, 1
	global_load_dword v155, v190, s[8:9]
	v_add_lshl_u32 v191, v182, v116, 1
	global_load_dword v156, v191, s[8:9]
	v_add_lshl_u32 v192, v184, v116, 1
	global_load_dword v157, v192, s[8:9]
	v_add_u32_e32 v82, 0x54000, v113
	v_add_lshl_u32 v80, v82, v129, 1
	s_nop 0
	v_cndmask_b32_e64 v84, v76, v78, s[6:7]
	v_or_b32_e32 v80, 0x30000, v128
	v_add_u32_e32 v81, 0x56a00, v113
	v_mov_b32_dpp v84, v84 quad_perm:[1,0,3,2] row_mask:0xf bank_mask:0xf bound_ctrl:1
	v_cndmask_b32_e64 v76, v84, v76, s[6:7]
	v_cndmask_b32_e64 v78, v78, v84, s[6:7]
	v_add_u32_e32 v85, v80, v124
	v_add_lshl_u32 v86, v81, v129, 1
	s_waitcnt vmcnt(23)
; DEVINL float bflo(unsigned u) { return __uint_as_float(u << 16); }
; DEVINL float bfhi(unsigned u) { return __uint_as_float(u & 0xffff0000u); }
; DEVINL float sigm(float x) { return 1.f / (1.f + __expf(-x)); }
; template <int EPI, bool GATHER>
; DEVINL void gemm_tile(const Params& p, const u16* __restrict__ A, int lda, const int* __restrict__ rowidx,
;                       const u16* __restrict__ Bt, int ldb, int K, int brow, int bcol, int orow, int ocol) {
;     ...
;           f32x4 v = acc[ai][bj][m][n];
;           if (EPI == EPI_HID) {
; #pragma unroll
;             for (int j = 0; j < 4; ++j) { const float a1 = acc[ai][0][m][n][j], a3 = acc[ai][1][m][n][j]; v[j] = a1 * sigm(a1) * a3; }
;           }
;           float lo[2], hi[2];
;           xchg_pairs(v, odd, lo, hi);
; #pragma unroll
;           for (int k = 0; k < 2; ++k) {
;             const unsigned row = (unsigned)(rA + k);
;             if (EPI == EPI_HID) {
;               *(unsigned*)(ws + O_HID + (row * 1024u + (unsigned)(colp + cc)) * 2u) = pk2(lo[k], hi[k]);
;             } else if (EPI == EPI_COLS) {
;               *(unsigned*)(ws + O_COLS + (row * (unsigned)NCP + (unsigned)(colp + cc)) * 2u) = pk2(lo[k], hi[k]);
;             } else if (EPI == EPI_MOE2) {
;               *(unsigned*)(ws + O_EO + (row * 2048u + (unsigned)(colp + cc)) * 2u) = pk2(gate[k] * lo[k], gate[k] * hi[k]);
;             } else if (EPI == EPI_M1) {
;               const unsigned g2 = *(const unsigned*)(ws + O_COLS + (row * (unsigned)NCP + (unsigned)(C_GG + colp + cc)) * 2u);
;               *(unsigned*)(ws + O_M1 + (row * 2048u + (unsigned)(colp + cc)) * 2u) = pk2(sigm(bflo(g2)) * lo[k], sigm(bfhi(g2)) * hi[k]);
	v_lshlrev_b32_e32 v87, 16, v166
	v_and_b32_e32 v83, 0xffff0000, v166
	v_mul_f32_e32 v87, 0xbfb8aa3b, v87
	v_mul_f32_e32 v83, 0xbfb8aa3b, v83
	v_exp_f32_e32 v87, v87
	v_exp_f32_e32 v83, v83
	v_add_f32_e32 v84, 1.0, v87
	v_add_f32_e32 v83, 1.0, v83
	v_div_scale_f32 v87, s[0:1], v84, v84, 1.0
	v_div_scale_f32 v89, s[0:1], v83, v83, 1.0
	v_rcp_f32_e32 v90, v87
	v_rcp_f32_e32 v91, v89
	v_div_scale_f32 v88, vcc, 1.0, v84, 1.0
	v_fma_f32 v93, -v87, v90, 1.0
	v_fma_f32 v94, -v89, v91, 1.0
	v_fmac_f32_e32 v90, v93, v90
	v_div_scale_f32 v92, s[0:1], 1.0, v83, 1.0
	v_fmac_f32_e32 v91, v94, v91
	v_mul_f32_e32 v93, v88, v90
	v_mul_f32_e32 v94, v92, v91
	v_fma_f32 v95, -v87, v93, v88
	v_fma_f32 v96, -v89, v94, v92
	v_fmac_f32_e32 v93, v95, v90
	v_fmac_f32_e32 v94, v96, v91
	v_fma_f32 v87, -v87, v93, v88
	v_fma_f32 v88, -v89, v94, v92
	v_div_fmas_f32 v87, v87, v90, v93
	s_mov_b64 vcc, s[0:1]
	v_div_fixup_f32 v84, v87, v84, 1.0
	v_div_fmas_f32 v87, v88, v91, v94
	v_div_fixup_f32 v83, v87, v83, 1.0
	v_mul_f32_e32 v76, v76, v84
	v_mul_f32_e32 v78, v78, v83
	v_cvt_pk_bf16_f32 v76, v76, v78
	global_store_dword v85, v76, s[10:11]
	s_nop 0
	v_cndmask_b32_e64 v83, v77, v79, s[6:7]
	v_or_b32_e32 v76, 0x31000, v128
	v_add_u32_e32 v84, v76, v124
	v_mov_b32_dpp v83, v83 quad_perm:[1,0,3,2] row_mask:0xf bank_mask:0xf bound_ctrl:1
	v_cndmask_b32_e64 v77, v83, v77, s[6:7]
	v_cndmask_b32_e64 v79, v79, v83, s[6:7]
	v_add_lshl_u32 v85, v82, v126, 1
	s_waitcnt vmcnt(23)
	v_lshlrev_b32_e32 v86, 16, v167
	v_and_b32_e32 v78, 0xffff0000, v167
	v_mul_f32_e32 v86, 0xbfb8aa3b, v86
	v_mul_f32_e32 v78, 0xbfb8aa3b, v78
	v_exp_f32_e32 v86, v86
	v_exp_f32_e32 v78, v78
	v_add_f32_e32 v83, 1.0, v86
	v_add_f32_e32 v78, 1.0, v78
	v_div_scale_f32 v86, s[0:1], v83, v83, 1.0
	v_div_scale_f32 v88, s[0:1], v78, v78, 1.0
	v_rcp_f32_e32 v89, v86
	v_rcp_f32_e32 v90, v88
	v_div_scale_f32 v87, vcc, 1.0, v83, 1.0
	v_fma_f32 v92, -v86, v89, 1.0
	v_fma_f32 v93, -v88, v90, 1.0
	v_fmac_f32_e32 v89, v92, v89
	v_div_scale_f32 v91, s[0:1], 1.0, v78, 1.0
	v_fmac_f32_e32 v90, v93, v90
	v_mul_f32_e32 v92, v87, v89
	v_mul_f32_e32 v93, v91, v90
	v_fma_f32 v94, -v86, v92, v87
	v_fma_f32 v95, -v88, v93, v91
	v_fmac_f32_e32 v92, v94, v89
	v_fmac_f32_e32 v93, v95, v90
	v_fma_f32 v86, -v86, v92, v87
	v_fma_f32 v87, -v88, v93, v91
	v_div_fmas_f32 v86, v86, v89, v92
	s_mov_b64 vcc, s[0:1]
	v_div_fixup_f32 v83, v86, v83, 1.0
	v_div_fmas_f32 v86, v87, v90, v93
	v_div_fixup_f32 v78, v86, v78, 1.0
	v_mul_f32_e32 v77, v77, v83
	v_mul_f32_e32 v78, v79, v78
	v_cvt_pk_bf16_f32 v77, v77, v78
	global_store_dword v84, v77, s[10:11]
	s_nop 0
	v_cndmask_b32_e64 v78, v72, v74, s[6:7]
	v_add_u32_e32 v79, v80, v120
	v_add_lshl_u32 v83, v81, v126, 1
	v_mov_b32_dpp v78, v78 quad_perm:[1,0,3,2] row_mask:0xf bank_mask:0xf bound_ctrl:1
	v_cndmask_b32_e64 v72, v78, v72, s[6:7]
	v_cndmask_b32_e64 v74, v74, v78, s[6:7]
	s_waitcnt vmcnt(23)
	v_lshlrev_b32_e32 v84, 16, v168
	v_and_b32_e32 v77, 0xffff0000, v168
	v_mul_f32_e32 v84, 0xbfb8aa3b, v84
	v_mul_f32_e32 v77, 0xbfb8aa3b, v77
	v_exp_f32_e32 v84, v84
	v_exp_f32_e32 v77, v77
	v_add_f32_e32 v78, 1.0, v84
	v_add_f32_e32 v77, 1.0, v77
	v_div_scale_f32 v84, s[0:1], v78, v78, 1.0
	v_div_scale_f32 v86, s[0:1], v77, v77, 1.0
	v_rcp_f32_e32 v87, v84
	v_rcp_f32_e32 v88, v86
	v_div_scale_f32 v85, vcc, 1.0, v78, 1.0
	v_fma_f32 v90, -v84, v87, 1.0
	v_fma_f32 v91, -v86, v88, 1.0
	v_fmac_f32_e32 v87, v90, v87
	v_div_scale_f32 v89, s[0:1], 1.0, v77, 1.0
	v_fmac_f32_e32 v88, v91, v88
	v_mul_f32_e32 v90, v85, v87
	v_mul_f32_e32 v91, v89, v88
	v_fma_f32 v92, -v84, v90, v85
	v_fma_f32 v93, -v86, v91, v89
	v_fmac_f32_e32 v90, v92, v87
	v_fmac_f32_e32 v91, v93, v88
	v_fma_f32 v84, -v84, v90, v85
	v_fma_f32 v85, -v86, v91, v89
	v_div_fmas_f32 v84, v84, v87, v90
	s_mov_b64 vcc, s[0:1]
	v_div_fixup_f32 v78, v84, v78, 1.0
	v_div_fmas_f32 v84, v85, v88, v91
	v_div_fixup_f32 v77, v84, v77, 1.0
	v_mul_f32_e32 v72, v72, v78
	v_mul_f32_e32 v74, v74, v77
	v_cvt_pk_bf16_f32 v72, v72, v74
	global_store_dword v79, v72, s[10:11]
	s_nop 0
	v_cndmask_b32_e64 v74, v73, v75, s[6:7]
	v_add_u32_e32 v77, v76, v120
	v_add_lshl_u32 v78, v82, v122, 1
	v_mov_b32_dpp v74, v74 quad_perm:[1,0,3,2] row_mask:0xf bank_mask:0xf bound_ctrl:1
	v_cndmask_b32_e64 v73, v74, v73, s[6:7]
	v_cndmask_b32_e64 v74, v75, v74, s[6:7]
	s_waitcnt vmcnt(23)
	v_lshlrev_b32_e32 v79, 16, v169
	v_and_b32_e32 v72, 0xffff0000, v169
	v_mul_f32_e32 v79, 0xbfb8aa3b, v79
	v_mul_f32_e32 v72, 0xbfb8aa3b, v72
	v_exp_f32_e32 v79, v79
	v_exp_f32_e32 v72, v72
	v_add_f32_e32 v75, 1.0, v79
	v_add_f32_e32 v72, 1.0, v72
	v_div_scale_f32 v79, s[0:1], v75, v75, 1.0
	v_div_scale_f32 v84, s[0:1], v72, v72, 1.0
	v_rcp_f32_e32 v85, v79
	v_rcp_f32_e32 v86, v84
	v_div_scale_f32 v83, vcc, 1.0, v75, 1.0
	v_fma_f32 v88, -v79, v85, 1.0
	v_fma_f32 v89, -v84, v86, 1.0
	v_fmac_f32_e32 v85, v88, v85
	v_div_scale_f32 v87, s[0:1], 1.0, v72, 1.0
	v_fmac_f32_e32 v86, v89, v86
	v_mul_f32_e32 v88, v83, v85
	v_mul_f32_e32 v89, v87, v86
	v_fma_f32 v90, -v79, v88, v83
	v_fma_f32 v91, -v84, v89, v87
	v_fmac_f32_e32 v88, v90, v85
	v_fmac_f32_e32 v89, v91, v86
	v_fma_f32 v79, -v79, v88, v83
	v_fma_f32 v83, -v84, v89, v87
	v_div_fmas_f32 v79, v79, v85, v88
	s_mov_b64 vcc, s[0:1]
	v_div_fixup_f32 v75, v79, v75, 1.0
	v_div_fmas_f32 v79, v83, v86, v89
	v_div_fixup_f32 v72, v79, v72, 1.0
	v_mul_f32_e32 v73, v73, v75
	v_mul_f32_e32 v72, v74, v72
	v_cvt_pk_bf16_f32 v72, v73, v72
	global_store_dword v77, v72, s[10:11]
	s_nop 0
	v_cndmask_b32_e64 v73, v68, v70, s[6:7]
	v_add_u32_e32 v74, v80, v118
	v_add_lshl_u32 v75, v81, v122, 1
	v_mov_b32_dpp v73, v73 quad_perm:[1,0,3,2] row_mask:0xf bank_mask:0xf bound_ctrl:1
	v_cndmask_b32_e64 v68, v73, v68, s[6:7]
	v_cndmask_b32_e64 v70, v70, v73, s[6:7]
	s_waitcnt vmcnt(23)
; DEVINL float bflo(unsigned u) { return __uint_as_float(u << 16); }
; DEVINL float bfhi(unsigned u) { return __uint_as_float(u & 0xffff0000u); }
; DEVINL float sigm(float x) { return 1.f / (1.f + __expf(-x)); }
; template <int EPI, bool GATHER>
; DEVINL void gemm_tile(const Params& p, const u16* __restrict__ A, int lda, const int* __restrict__ rowidx,
;                       const u16* __restrict__ Bt, int ldb, int K, int brow, int bcol, int orow, int ocol) {
;     ...
;           f32x4 v = acc[ai][bj][m][n];
;           if (EPI == EPI_HID) {
; #pragma unroll
;             for (int j = 0; j < 4; ++j) { const float a1 = acc[ai][0][m][n][j], a3 = acc[ai][1][m][n][j]; v[j] = a1 * sigm(a1) * a3; }
;           }
;           float lo[2], hi[2];
;           xchg_pairs(v, odd, lo, hi);
; #pragma unroll
;           for (int k = 0; k < 2; ++k) {
;             const unsigned row = (unsigned)(rA + k);
;             if (EPI == EPI_HID) {
;               *(unsigned*)(ws + O_HID + (row * 1024u + (unsigned)(colp + cc)) * 2u) = pk2(lo[k], hi[k]);
;             } else if (EPI == EPI_COLS) {
;               *(unsigned*)(ws + O_COLS + (row * (unsigned)NCP + (unsigned)(colp + cc)) * 2u) = pk2(lo[k], hi[k]);
;             } else if (EPI == EPI_MOE2) {
;               *(unsigned*)(ws + O_EO + (row * 2048u + (unsigned)(colp + cc)) * 2u) = pk2(gate[k] * lo[k], gate[k] * hi[k]);
;             } else if (EPI == EPI_M1) {
;               const unsigned g2 = *(const unsigned*)(ws + O_COLS + (row * (unsigned)NCP + (unsigned)(C_GG + colp + cc)) * 2u);
;               *(unsigned*)(ws + O_M1 + (row * 2048u + (unsigned)(colp + cc)) * 2u) = pk2(sigm(bflo(g2)) * lo[k], sigm(bfhi(g2)) * hi[k]);
	v_lshlrev_b32_e32 v77, 16, v170
	v_and_b32_e32 v72, 0xffff0000, v170
	v_mul_f32_e32 v77, 0xbfb8aa3b, v77
	v_mul_f32_e32 v72, 0xbfb8aa3b, v72
	v_exp_f32_e32 v77, v77
	v_exp_f32_e32 v72, v72
	v_add_f32_e32 v73, 1.0, v77
	v_add_f32_e32 v72, 1.0, v72
	v_div_scale_f32 v77, s[0:1], v73, v73, 1.0
	v_div_scale_f32 v79, s[0:1], v72, v72, 1.0
	v_rcp_f32_e32 v83, v77
	v_rcp_f32_e32 v84, v79
	v_div_scale_f32 v78, vcc, 1.0, v73, 1.0
	v_fma_f32 v86, -v77, v83, 1.0
	v_fma_f32 v87, -v79, v84, 1.0
	v_fmac_f32_e32 v83, v86, v83
	v_div_scale_f32 v85, s[0:1], 1.0, v72, 1.0
	v_fmac_f32_e32 v84, v87, v84
	v_mul_f32_e32 v86, v78, v83
	v_mul_f32_e32 v87, v85, v84
	v_fma_f32 v88, -v77, v86, v78
	v_fma_f32 v89, -v79, v87, v85
	v_fmac_f32_e32 v86, v88, v83
	v_fmac_f32_e32 v87, v89, v84
	v_fma_f32 v77, -v77, v86, v78
	v_fma_f32 v78, -v79, v87, v85
	v_div_fmas_f32 v77, v77, v83, v86
	s_mov_b64 vcc, s[0:1]
	v_div_fixup_f32 v73, v77, v73, 1.0
	v_div_fmas_f32 v77, v78, v84, v87
	v_div_fixup_f32 v72, v77, v72, 1.0
	v_mul_f32_e32 v68, v68, v73
	v_mul_f32_e32 v70, v70, v72
	v_cvt_pk_bf16_f32 v68, v68, v70
	global_store_dword v74, v68, s[10:11]
	s_nop 0
	v_cndmask_b32_e64 v70, v69, v71, s[6:7]
	v_add_lshl_u32 v73, v82, v116, 1
	v_add_u32_e32 v72, v76, v118
	v_mov_b32_dpp v70, v70 quad_perm:[1,0,3,2] row_mask:0xf bank_mask:0xf bound_ctrl:1
	v_cndmask_b32_e64 v69, v70, v69, s[6:7]
	v_cndmask_b32_e64 v70, v71, v70, s[6:7]
	s_waitcnt vmcnt(23)
	v_lshlrev_b32_e32 v74, 16, v171
	v_and_b32_e32 v68, 0xffff0000, v171
	v_mul_f32_e32 v74, 0xbfb8aa3b, v74
	v_mul_f32_e32 v68, 0xbfb8aa3b, v68
	v_exp_f32_e32 v74, v74
	v_exp_f32_e32 v68, v68
	v_add_f32_e32 v71, 1.0, v74
	v_add_f32_e32 v68, 1.0, v68
	v_div_scale_f32 v74, s[0:1], v71, v71, 1.0
	v_div_scale_f32 v77, s[0:1], v68, v68, 1.0
	v_rcp_f32_e32 v78, v74
	v_rcp_f32_e32 v79, v77
	v_div_scale_f32 v75, vcc, 1.0, v71, 1.0
	v_fma_f32 v83, -v74, v78, 1.0
	v_fma_f32 v84, -v77, v79, 1.0
	v_fmac_f32_e32 v78, v83, v78
	v_div_scale_f32 v82, s[0:1], 1.0, v68, 1.0
	v_fmac_f32_e32 v79, v84, v79
	v_mul_f32_e32 v83, v75, v78
	v_mul_f32_e32 v84, v82, v79
	v_fma_f32 v85, -v74, v83, v75
	v_fma_f32 v86, -v77, v84, v82
	v_fmac_f32_e32 v83, v85, v78
	v_fmac_f32_e32 v84, v86, v79
	v_fma_f32 v74, -v74, v83, v75
	v_fma_f32 v75, -v77, v84, v82
	v_div_fmas_f32 v74, v74, v78, v83
	s_mov_b64 vcc, s[0:1]
	v_div_fixup_f32 v71, v74, v71, 1.0
	v_div_fmas_f32 v74, v75, v79, v84
	v_div_fixup_f32 v68, v74, v68, 1.0
	v_mul_f32_e32 v69, v69, v71
	v_mul_f32_e32 v68, v70, v68
	v_cvt_pk_bf16_f32 v68, v69, v68
	global_store_dword v72, v68, s[10:11]
	s_nop 0
	v_cndmask_b32_e64 v69, v64, v66, s[6:7]
	v_add_u32_e32 v70, v80, v112
	v_add_lshl_u32 v71, v81, v116, 1
	v_mov_b32_dpp v69, v69 quad_perm:[1,0,3,2] row_mask:0xf bank_mask:0xf bound_ctrl:1
	v_cndmask_b32_e64 v64, v69, v64, s[6:7]
	v_cndmask_b32_e64 v66, v66, v69, s[6:7]
	s_waitcnt vmcnt(23)
	v_lshlrev_b32_e32 v72, 16, v172
	v_and_b32_e32 v68, 0xffff0000, v172
	v_mul_f32_e32 v72, 0xbfb8aa3b, v72
	v_mul_f32_e32 v68, 0xbfb8aa3b, v68
	v_exp_f32_e32 v72, v72
	v_exp_f32_e32 v68, v68
	v_add_f32_e32 v69, 1.0, v72
	v_add_f32_e32 v68, 1.0, v68
	v_div_scale_f32 v72, s[0:1], v69, v69, 1.0
	v_div_scale_f32 v74, s[0:1], v68, v68, 1.0
	v_rcp_f32_e32 v75, v72
	v_rcp_f32_e32 v77, v74
	v_div_scale_f32 v73, vcc, 1.0, v69, 1.0
	v_fma_f32 v79, -v72, v75, 1.0
	v_fma_f32 v80, -v74, v77, 1.0
	v_fmac_f32_e32 v75, v79, v75
	v_div_scale_f32 v78, s[0:1], 1.0, v68, 1.0
	v_fmac_f32_e32 v77, v80, v77
	v_mul_f32_e32 v79, v73, v75
	v_mul_f32_e32 v80, v78, v77
	v_fma_f32 v81, -v72, v79, v73
	v_fma_f32 v82, -v74, v80, v78
	v_fmac_f32_e32 v79, v81, v75
	v_fmac_f32_e32 v80, v82, v77
	v_fma_f32 v72, -v72, v79, v73
	v_fma_f32 v73, -v74, v80, v78
	v_div_fmas_f32 v72, v72, v75, v79
	s_mov_b64 vcc, s[0:1]
	v_div_fixup_f32 v69, v72, v69, 1.0
	v_div_fmas_f32 v72, v73, v77, v80
	v_div_fixup_f32 v68, v72, v68, 1.0
	v_mul_f32_e32 v64, v64, v69
	v_mul_f32_e32 v66, v66, v68
	v_cvt_pk_bf16_f32 v64, v64, v66
	global_store_dword v70, v64, s[10:11]
	s_nop 0
	v_cndmask_b32_e64 v66, v65, v67, s[6:7]
	s_waitcnt vmcnt(23)
	v_lshlrev_b32_e32 v68, 16, v173
	v_and_b32_e32 v64, 0xffff0000, v173
	v_mul_f32_e32 v68, 0xbfb8aa3b, v68
	v_mul_f32_e32 v64, 0xbfb8aa3b, v64
	v_exp_f32_e32 v68, v68
	v_exp_f32_e32 v64, v64
	v_mov_b32_dpp v66, v66 quad_perm:[1,0,3,2] row_mask:0xf bank_mask:0xf bound_ctrl:1
	v_cndmask_b32_e64 v65, v66, v65, s[6:7]
	v_cndmask_b32_e64 v66, v67, v66, s[6:7]
	v_add_f32_e32 v67, 1.0, v68
	v_add_f32_e32 v64, 1.0, v64
	v_div_scale_f32 v68, s[0:1], v67, v67, 1.0
	v_div_scale_f32 v70, s[0:1], v64, v64, 1.0
	v_rcp_f32_e32 v71, v68
	v_rcp_f32_e32 v72, v70
	v_div_scale_f32 v69, vcc, 1.0, v67, 1.0
	v_fma_f32 v74, -v68, v71, 1.0
	v_fma_f32 v75, -v70, v72, 1.0
	v_fmac_f32_e32 v71, v74, v71
	v_div_scale_f32 v73, s[0:1], 1.0, v64, 1.0
	v_fmac_f32_e32 v72, v75, v72
	v_mul_f32_e32 v74, v69, v71
	v_mul_f32_e32 v75, v73, v72
	v_fma_f32 v77, -v68, v74, v69
	v_fma_f32 v78, -v70, v75, v73
	v_fmac_f32_e32 v74, v77, v71
	v_fmac_f32_e32 v75, v78, v72
	v_fma_f32 v68, -v68, v74, v69
	v_fma_f32 v69, -v70, v75, v73
	v_div_fmas_f32 v68, v68, v71, v74
	s_mov_b64 vcc, s[0:1]
	v_div_fixup_f32 v67, v68, v67, 1.0
	v_div_fmas_f32 v68, v69, v72, v75
	v_div_fixup_f32 v64, v68, v64, 1.0
	v_mul_f32_e32 v65, v65, v67
	v_mul_f32_e32 v64, v66, v64
	v_cvt_pk_bf16_f32 v64, v65, v64
	v_add_u32_e32 v65, v76, v112
	global_store_dword v65, v64, s[10:11]
	v_add_u32_e32 v182, 0x150000, v113
	v_add_lshl_u32 v183, v182, v129, 1
	global_load_dword v166, v183, s[8:9]
	v_add_u32_e32 v184, 0x152a00, v113
	v_add_lshl_u32 v185, v184, v129, 1
	global_load_dword v167, v185, s[8:9]
	v_add_lshl_u32 v186, v182, v126, 1
	global_load_dword v168, v186, s[8:9]
	v_add_lshl_u32 v187, v184, v126, 1
	global_load_dword v169, v187, s[8:9]
	v_add_lshl_u32 v188, v182, v122, 1
	global_load_dword v170, v188, s[8:9]
	v_add_lshl_u32 v190, v184, v122, 1
	global_load_dword v171, v190, s[8:9]
	v_add_lshl_u32 v191, v182, v116, 1
	global_load_dword v172, v191, s[8:9]
	v_add_lshl_u32 v192, v184, v116, 1
	global_load_dword v173, v192, s[8:9]
	v_add_u32_e32 v66, 0x126000, v113
	v_add_lshl_u32 v64, v66, v129, 1
	s_nop 0
	v_cndmask_b32_e64 v68, v60, v62, s[6:7]
	v_add_u32_e32 v64, 0x80000, v128
	v_add_u32_e32 v65, 0x128a00, v113
	v_mov_b32_dpp v68, v68 quad_perm:[1,0,3,2] row_mask:0xf bank_mask:0xf bound_ctrl:1
	v_cndmask_b32_e64 v60, v68, v60, s[6:7]
	v_cndmask_b32_e64 v62, v62, v68, s[6:7]
	v_add_u32_e32 v69, v64, v124
	v_add_lshl_u32 v70, v65, v129, 1
	s_waitcnt vmcnt(23)
; DEVINL float bflo(unsigned u) { return __uint_as_float(u << 16); }
; DEVINL float bfhi(unsigned u) { return __uint_as_float(u & 0xffff0000u); }
; DEVINL float sigm(float x) { return 1.f / (1.f + __expf(-x)); }
; template <int EPI, bool GATHER>
; DEVINL void gemm_tile(const Params& p, const u16* __restrict__ A, int lda, const int* __restrict__ rowidx,
;                       const u16* __restrict__ Bt, int ldb, int K, int brow, int bcol, int orow, int ocol) {
;     ...
;           f32x4 v = acc[ai][bj][m][n];
;           if (EPI == EPI_HID) {
; #pragma unroll
;             for (int j = 0; j < 4; ++j) { const float a1 = acc[ai][0][m][n][j], a3 = acc[ai][1][m][n][j]; v[j] = a1 * sigm(a1) * a3; }
;           }
;           float lo[2], hi[2];
;           xchg_pairs(v, odd, lo, hi);
; #pragma unroll
;           for (int k = 0; k < 2; ++k) {
;             const unsigned row = (unsigned)(rA + k);
;             if (EPI == EPI_HID) {
;               *(unsigned*)(ws + O_HID + (row * 1024u + (unsigned)(colp + cc)) * 2u) = pk2(lo[k], hi[k]);
;             } else if (EPI == EPI_COLS) {
;               *(unsigned*)(ws + O_COLS + (row * (unsigned)NCP + (unsigned)(colp + cc)) * 2u) = pk2(lo[k], hi[k]);
;             } else if (EPI == EPI_MOE2) {
;               *(unsigned*)(ws + O_EO + (row * 2048u + (unsigned)(colp + cc)) * 2u) = pk2(gate[k] * lo[k], gate[k] * hi[k]);
;             } else if (EPI == EPI_M1) {
;               const unsigned g2 = *(const unsigned*)(ws + O_COLS + (row * (unsigned)NCP + (unsigned)(C_GG + colp + cc)) * 2u);
;               *(unsigned*)(ws + O_M1 + (row * 2048u + (unsigned)(colp + cc)) * 2u) = pk2(sigm(bflo(g2)) * lo[k], sigm(bfhi(g2)) * hi[k]);
	v_lshlrev_b32_e32 v71, 16, v150
	v_and_b32_e32 v67, 0xffff0000, v150
	v_mul_f32_e32 v71, 0xbfb8aa3b, v71
	v_mul_f32_e32 v67, 0xbfb8aa3b, v67
	v_exp_f32_e32 v71, v71
	v_exp_f32_e32 v67, v67
	v_add_f32_e32 v68, 1.0, v71
	v_add_f32_e32 v67, 1.0, v67
	v_div_scale_f32 v71, s[0:1], v68, v68, 1.0
	v_div_scale_f32 v73, s[0:1], v67, v67, 1.0
	v_rcp_f32_e32 v74, v71
	v_rcp_f32_e32 v75, v73
	v_div_scale_f32 v72, vcc, 1.0, v68, 1.0
	v_fma_f32 v77, -v71, v74, 1.0
	v_fma_f32 v78, -v73, v75, 1.0
	v_fmac_f32_e32 v74, v77, v74
	v_div_scale_f32 v76, s[0:1], 1.0, v67, 1.0
	v_fmac_f32_e32 v75, v78, v75
	v_mul_f32_e32 v77, v72, v74
	v_mul_f32_e32 v78, v76, v75
	v_fma_f32 v79, -v71, v77, v72
	v_fma_f32 v80, -v73, v78, v76
	v_fmac_f32_e32 v77, v79, v74
	v_fmac_f32_e32 v78, v80, v75
	v_fma_f32 v71, -v71, v77, v72
	v_fma_f32 v72, -v73, v78, v76
	v_div_fmas_f32 v71, v71, v74, v77
	s_mov_b64 vcc, s[0:1]
	v_div_fixup_f32 v68, v71, v68, 1.0
	v_div_fmas_f32 v71, v72, v75, v78
	v_div_fixup_f32 v67, v71, v67, 1.0
	v_mul_f32_e32 v60, v60, v68
	v_mul_f32_e32 v62, v62, v67
	v_cvt_pk_bf16_f32 v60, v60, v62
	global_store_dword v69, v60, s[10:11]
	s_nop 0
	v_cndmask_b32_e64 v67, v61, v63, s[6:7]
	v_add_u32_e32 v60, 0x81000, v128
	v_add_u32_e32 v68, v60, v124
	v_mov_b32_dpp v67, v67 quad_perm:[1,0,3,2] row_mask:0xf bank_mask:0xf bound_ctrl:1
	v_cndmask_b32_e64 v61, v67, v61, s[6:7]
	v_cndmask_b32_e64 v63, v63, v67, s[6:7]
	v_add_lshl_u32 v69, v66, v126, 1
	s_waitcnt vmcnt(23)
	v_lshlrev_b32_e32 v70, 16, v151
	v_and_b32_e32 v62, 0xffff0000, v151
	v_mul_f32_e32 v70, 0xbfb8aa3b, v70
	v_mul_f32_e32 v62, 0xbfb8aa3b, v62
	v_exp_f32_e32 v70, v70
	v_exp_f32_e32 v62, v62
	v_add_f32_e32 v67, 1.0, v70
	v_add_f32_e32 v62, 1.0, v62
	v_div_scale_f32 v70, s[0:1], v67, v67, 1.0
	v_div_scale_f32 v72, s[0:1], v62, v62, 1.0
	v_rcp_f32_e32 v73, v70
	v_rcp_f32_e32 v74, v72
	v_div_scale_f32 v71, vcc, 1.0, v67, 1.0
	v_fma_f32 v76, -v70, v73, 1.0
	v_fma_f32 v77, -v72, v74, 1.0
	v_fmac_f32_e32 v73, v76, v73
	v_div_scale_f32 v75, s[0:1], 1.0, v62, 1.0
	v_fmac_f32_e32 v74, v77, v74
	v_mul_f32_e32 v76, v71, v73
	v_mul_f32_e32 v77, v75, v74
	v_fma_f32 v78, -v70, v76, v71
	v_fma_f32 v79, -v72, v77, v75
	v_fmac_f32_e32 v76, v78, v73
	v_fmac_f32_e32 v77, v79, v74
	v_fma_f32 v70, -v70, v76, v71
	v_fma_f32 v71, -v72, v77, v75
	v_div_fmas_f32 v70, v70, v73, v76
	s_mov_b64 vcc, s[0:1]
	v_div_fixup_f32 v67, v70, v67, 1.0
	v_div_fmas_f32 v70, v71, v74, v77
	v_div_fixup_f32 v62, v70, v62, 1.0
	v_mul_f32_e32 v61, v61, v67
	v_mul_f32_e32 v62, v63, v62
	v_cvt_pk_bf16_f32 v61, v61, v62
	global_store_dword v68, v61, s[10:11]
	s_nop 0
	v_cndmask_b32_e64 v62, v56, v58, s[6:7]
	v_add_u32_e32 v63, v64, v120
	v_add_lshl_u32 v67, v65, v126, 1
	v_mov_b32_dpp v62, v62 quad_perm:[1,0,3,2] row_mask:0xf bank_mask:0xf bound_ctrl:1
	v_cndmask_b32_e64 v56, v62, v56, s[6:7]
	v_cndmask_b32_e64 v58, v58, v62, s[6:7]
	s_waitcnt vmcnt(23)
	v_lshlrev_b32_e32 v68, 16, v152
	v_and_b32_e32 v61, 0xffff0000, v152
	v_mul_f32_e32 v68, 0xbfb8aa3b, v68
	v_mul_f32_e32 v61, 0xbfb8aa3b, v61
	v_exp_f32_e32 v68, v68
	v_exp_f32_e32 v61, v61
	v_add_f32_e32 v62, 1.0, v68
	v_add_f32_e32 v61, 1.0, v61
	v_div_scale_f32 v68, s[0:1], v62, v62, 1.0
	v_div_scale_f32 v70, s[0:1], v61, v61, 1.0
	v_rcp_f32_e32 v71, v68
	v_rcp_f32_e32 v72, v70
	v_div_scale_f32 v69, vcc, 1.0, v62, 1.0
	v_fma_f32 v74, -v68, v71, 1.0
	v_fma_f32 v75, -v70, v72, 1.0
	v_fmac_f32_e32 v71, v74, v71
	v_div_scale_f32 v73, s[0:1], 1.0, v61, 1.0
	v_fmac_f32_e32 v72, v75, v72
	v_mul_f32_e32 v74, v69, v71
	v_mul_f32_e32 v75, v73, v72
	v_fma_f32 v76, -v68, v74, v69
	v_fma_f32 v77, -v70, v75, v73
	v_fmac_f32_e32 v74, v76, v71
	v_fmac_f32_e32 v75, v77, v72
	v_fma_f32 v68, -v68, v74, v69
	v_fma_f32 v69, -v70, v75, v73
	v_div_fmas_f32 v68, v68, v71, v74
	s_mov_b64 vcc, s[0:1]
	v_div_fixup_f32 v62, v68, v62, 1.0
	v_div_fmas_f32 v68, v69, v72, v75
	v_div_fixup_f32 v61, v68, v61, 1.0
	v_mul_f32_e32 v56, v56, v62
	v_mul_f32_e32 v58, v58, v61
	v_cvt_pk_bf16_f32 v56, v56, v58
	global_store_dword v63, v56, s[10:11]
	s_nop 0
	v_cndmask_b32_e64 v58, v57, v59, s[6:7]
	v_add_u32_e32 v61, v60, v120
	v_add_lshl_u32 v62, v66, v122, 1
	v_mov_b32_dpp v58, v58 quad_perm:[1,0,3,2] row_mask:0xf bank_mask:0xf bound_ctrl:1
	v_cndmask_b32_e64 v57, v58, v57, s[6:7]
	v_cndmask_b32_e64 v58, v59, v58, s[6:7]
	s_waitcnt vmcnt(23)
	v_lshlrev_b32_e32 v63, 16, v153
	v_and_b32_e32 v56, 0xffff0000, v153
	v_mul_f32_e32 v63, 0xbfb8aa3b, v63
	v_mul_f32_e32 v56, 0xbfb8aa3b, v56
	v_exp_f32_e32 v63, v63
	v_exp_f32_e32 v56, v56
	v_add_f32_e32 v59, 1.0, v63
	v_add_f32_e32 v56, 1.0, v56
	v_div_scale_f32 v63, s[0:1], v59, v59, 1.0
	v_div_scale_f32 v68, s[0:1], v56, v56, 1.0
	v_rcp_f32_e32 v69, v63
	v_rcp_f32_e32 v70, v68
	v_div_scale_f32 v67, vcc, 1.0, v59, 1.0
	v_fma_f32 v72, -v63, v69, 1.0
	v_fma_f32 v73, -v68, v70, 1.0
	v_fmac_f32_e32 v69, v72, v69
	v_div_scale_f32 v71, s[0:1], 1.0, v56, 1.0
	v_fmac_f32_e32 v70, v73, v70
	v_mul_f32_e32 v72, v67, v69
	v_mul_f32_e32 v73, v71, v70
	v_fma_f32 v74, -v63, v72, v67
	v_fma_f32 v75, -v68, v73, v71
	v_fmac_f32_e32 v72, v74, v69
	v_fmac_f32_e32 v73, v75, v70
	v_fma_f32 v63, -v63, v72, v67
	v_fma_f32 v67, -v68, v73, v71
	v_div_fmas_f32 v63, v63, v69, v72
	s_mov_b64 vcc, s[0:1]
	v_div_fixup_f32 v59, v63, v59, 1.0
	v_div_fmas_f32 v63, v67, v70, v73
	v_div_fixup_f32 v56, v63, v56, 1.0
	v_mul_f32_e32 v57, v57, v59
	v_mul_f32_e32 v56, v58, v56
	v_cvt_pk_bf16_f32 v56, v57, v56
	global_store_dword v61, v56, s[10:11]
	s_nop 0
	v_cndmask_b32_e64 v57, v52, v54, s[6:7]
	v_add_u32_e32 v58, v64, v118
	v_add_lshl_u32 v59, v65, v122, 1
	v_mov_b32_dpp v57, v57 quad_perm:[1,0,3,2] row_mask:0xf bank_mask:0xf bound_ctrl:1
	v_cndmask_b32_e64 v52, v57, v52, s[6:7]
	v_cndmask_b32_e64 v54, v54, v57, s[6:7]
	s_waitcnt vmcnt(23)
; DEVINL float bflo(unsigned u) { return __uint_as_float(u << 16); }
; DEVINL float bfhi(unsigned u) { return __uint_as_float(u & 0xffff0000u); }
; DEVINL float sigm(float x) { return 1.f / (1.f + __expf(-x)); }
; template <int EPI, bool GATHER>
; DEVINL void gemm_tile(const Params& p, const u16* __restrict__ A, int lda, const int* __restrict__ rowidx,
;                       const u16* __restrict__ Bt, int ldb, int K, int brow, int bcol, int orow, int ocol) {
;     ...
;           f32x4 v = acc[ai][bj][m][n];
;           if (EPI == EPI_HID) {
; #pragma unroll
;             for (int j = 0; j < 4; ++j) { const float a1 = acc[ai][0][m][n][j], a3 = acc[ai][1][m][n][j]; v[j] = a1 * sigm(a1) * a3; }
;           }
;           float lo[2], hi[2];
;           xchg_pairs(v, odd, lo, hi);
; #pragma unroll
;           for (int k = 0; k < 2; ++k) {
;             const unsigned row = (unsigned)(rA + k);
;             if (EPI == EPI_HID) {
;               *(unsigned*)(ws + O_HID + (row * 1024u + (unsigned)(colp + cc)) * 2u) = pk2(lo[k], hi[k]);
;             } else if (EPI == EPI_COLS) {
;               *(unsigned*)(ws + O_COLS + (row * (unsigned)NCP + (unsigned)(colp + cc)) * 2u) = pk2(lo[k], hi[k]);
;             } else if (EPI == EPI_MOE2) {
;               *(unsigned*)(ws + O_EO + (row * 2048u + (unsigned)(colp + cc)) * 2u) = pk2(gate[k] * lo[k], gate[k] * hi[k]);
;             } else if (EPI == EPI_M1) {
;               const unsigned g2 = *(const unsigned*)(ws + O_COLS + (row * (unsigned)NCP + (unsigned)(C_GG + colp + cc)) * 2u);
;               *(unsigned*)(ws + O_M1 + (row * 2048u + (unsigned)(colp + cc)) * 2u) = pk2(sigm(bflo(g2)) * lo[k], sigm(bfhi(g2)) * hi[k]);
	v_lshlrev_b32_e32 v61, 16, v154
	v_and_b32_e32 v56, 0xffff0000, v154
	v_mul_f32_e32 v61, 0xbfb8aa3b, v61
	v_mul_f32_e32 v56, 0xbfb8aa3b, v56
	v_exp_f32_e32 v61, v61
	v_exp_f32_e32 v56, v56
	v_add_f32_e32 v57, 1.0, v61
	v_add_f32_e32 v56, 1.0, v56
	v_div_scale_f32 v61, s[0:1], v57, v57, 1.0
	v_div_scale_f32 v63, s[0:1], v56, v56, 1.0
	v_rcp_f32_e32 v67, v61
	v_rcp_f32_e32 v68, v63
	v_div_scale_f32 v62, vcc, 1.0, v57, 1.0
	v_fma_f32 v70, -v61, v67, 1.0
	v_fma_f32 v71, -v63, v68, 1.0
	v_fmac_f32_e32 v67, v70, v67
	v_div_scale_f32 v69, s[0:1], 1.0, v56, 1.0
	v_fmac_f32_e32 v68, v71, v68
	v_mul_f32_e32 v70, v62, v67
	v_mul_f32_e32 v71, v69, v68
	v_fma_f32 v72, -v61, v70, v62
	v_fma_f32 v73, -v63, v71, v69
	v_fmac_f32_e32 v70, v72, v67
	v_fmac_f32_e32 v71, v73, v68
	v_fma_f32 v61, -v61, v70, v62
	v_fma_f32 v62, -v63, v71, v69
	v_div_fmas_f32 v61, v61, v67, v70
	s_mov_b64 vcc, s[0:1]
	v_div_fixup_f32 v57, v61, v57, 1.0
	v_div_fmas_f32 v61, v62, v68, v71
	v_div_fixup_f32 v56, v61, v56, 1.0
	v_mul_f32_e32 v52, v52, v57
	v_mul_f32_e32 v54, v54, v56
	v_cvt_pk_bf16_f32 v52, v52, v54
	global_store_dword v58, v52, s[10:11]
	s_nop 0
	v_cndmask_b32_e64 v54, v53, v55, s[6:7]
	v_add_lshl_u32 v57, v66, v116, 1
	v_add_u32_e32 v56, v60, v118
	v_mov_b32_dpp v54, v54 quad_perm:[1,0,3,2] row_mask:0xf bank_mask:0xf bound_ctrl:1
	v_cndmask_b32_e64 v53, v54, v53, s[6:7]
	v_cndmask_b32_e64 v54, v55, v54, s[6:7]
	s_waitcnt vmcnt(23)
	v_lshlrev_b32_e32 v58, 16, v155
	v_and_b32_e32 v52, 0xffff0000, v155
	v_mul_f32_e32 v58, 0xbfb8aa3b, v58
	v_mul_f32_e32 v52, 0xbfb8aa3b, v52
	v_exp_f32_e32 v58, v58
	v_exp_f32_e32 v52, v52
	v_add_f32_e32 v55, 1.0, v58
	v_add_f32_e32 v52, 1.0, v52
	v_div_scale_f32 v58, s[0:1], v55, v55, 1.0
	v_div_scale_f32 v61, s[0:1], v52, v52, 1.0
	v_rcp_f32_e32 v62, v58
	v_rcp_f32_e32 v63, v61
	v_div_scale_f32 v59, vcc, 1.0, v55, 1.0
	v_fma_f32 v67, -v58, v62, 1.0
	v_fma_f32 v68, -v61, v63, 1.0
	v_fmac_f32_e32 v62, v67, v62
	v_div_scale_f32 v66, s[0:1], 1.0, v52, 1.0
	v_fmac_f32_e32 v63, v68, v63
	v_mul_f32_e32 v67, v59, v62
	v_mul_f32_e32 v68, v66, v63
	v_fma_f32 v69, -v58, v67, v59
	v_fma_f32 v70, -v61, v68, v66
	v_fmac_f32_e32 v67, v69, v62
	v_fmac_f32_e32 v68, v70, v63
	v_fma_f32 v58, -v58, v67, v59
	v_fma_f32 v59, -v61, v68, v66
	v_div_fmas_f32 v58, v58, v62, v67
	s_mov_b64 vcc, s[0:1]
	v_div_fixup_f32 v55, v58, v55, 1.0
	v_div_fmas_f32 v58, v59, v63, v68
	v_div_fixup_f32 v52, v58, v52, 1.0
	v_mul_f32_e32 v53, v53, v55
	v_mul_f32_e32 v52, v54, v52
	v_cvt_pk_bf16_f32 v52, v53, v52
	global_store_dword v56, v52, s[10:11]
	s_nop 0
	v_cndmask_b32_e64 v53, v48, v50, s[6:7]
	v_add_u32_e32 v54, v64, v112
	v_add_lshl_u32 v55, v65, v116, 1
	v_mov_b32_dpp v53, v53 quad_perm:[1,0,3,2] row_mask:0xf bank_mask:0xf bound_ctrl:1
	v_cndmask_b32_e64 v48, v53, v48, s[6:7]
	v_cndmask_b32_e64 v50, v50, v53, s[6:7]
	s_waitcnt vmcnt(23)
	v_lshlrev_b32_e32 v56, 16, v156
	v_and_b32_e32 v52, 0xffff0000, v156
	v_mul_f32_e32 v56, 0xbfb8aa3b, v56
	v_mul_f32_e32 v52, 0xbfb8aa3b, v52
	v_exp_f32_e32 v56, v56
	v_exp_f32_e32 v52, v52
	v_add_f32_e32 v53, 1.0, v56
	v_add_f32_e32 v52, 1.0, v52
	v_div_scale_f32 v56, s[0:1], v53, v53, 1.0
	v_div_scale_f32 v58, s[0:1], v52, v52, 1.0
	v_rcp_f32_e32 v59, v56
	v_rcp_f32_e32 v61, v58
	v_div_scale_f32 v57, vcc, 1.0, v53, 1.0
	v_fma_f32 v63, -v56, v59, 1.0
	v_fma_f32 v64, -v58, v61, 1.0
	v_fmac_f32_e32 v59, v63, v59
	v_div_scale_f32 v62, s[0:1], 1.0, v52, 1.0
	v_fmac_f32_e32 v61, v64, v61
	v_mul_f32_e32 v63, v57, v59
	v_mul_f32_e32 v64, v62, v61
	v_fma_f32 v65, -v56, v63, v57
	v_fma_f32 v66, -v58, v64, v62
	v_fmac_f32_e32 v63, v65, v59
	v_fmac_f32_e32 v64, v66, v61
	v_fma_f32 v56, -v56, v63, v57
	v_fma_f32 v57, -v58, v64, v62
	v_div_fmas_f32 v56, v56, v59, v63
	s_mov_b64 vcc, s[0:1]
	v_div_fixup_f32 v53, v56, v53, 1.0
	v_div_fmas_f32 v56, v57, v61, v64
	v_div_fixup_f32 v52, v56, v52, 1.0
	v_mul_f32_e32 v48, v48, v53
	v_mul_f32_e32 v50, v50, v52
	v_cvt_pk_bf16_f32 v48, v48, v50
	global_store_dword v54, v48, s[10:11]
	s_nop 0
	v_cndmask_b32_e64 v50, v49, v51, s[6:7]
	s_waitcnt vmcnt(23)
	v_lshlrev_b32_e32 v52, 16, v157
	v_and_b32_e32 v48, 0xffff0000, v157
	v_mul_f32_e32 v52, 0xbfb8aa3b, v52
	v_mul_f32_e32 v48, 0xbfb8aa3b, v48
	v_exp_f32_e32 v52, v52
	v_exp_f32_e32 v48, v48
	v_mov_b32_dpp v50, v50 quad_perm:[1,0,3,2] row_mask:0xf bank_mask:0xf bound_ctrl:1
	v_cndmask_b32_e64 v49, v50, v49, s[6:7]
	v_cndmask_b32_e64 v50, v51, v50, s[6:7]
	v_add_f32_e32 v51, 1.0, v52
	v_add_f32_e32 v48, 1.0, v48
	v_div_scale_f32 v52, s[0:1], v51, v51, 1.0
	v_div_scale_f32 v54, s[0:1], v48, v48, 1.0
	v_rcp_f32_e32 v55, v52
	v_rcp_f32_e32 v56, v54
	v_div_scale_f32 v53, vcc, 1.0, v51, 1.0
	v_fma_f32 v58, -v52, v55, 1.0
	v_fma_f32 v59, -v54, v56, 1.0
	v_fmac_f32_e32 v55, v58, v55
	v_div_scale_f32 v57, s[0:1], 1.0, v48, 1.0
	v_fmac_f32_e32 v56, v59, v56
	v_mul_f32_e32 v58, v53, v55
	v_mul_f32_e32 v59, v57, v56
	v_fma_f32 v61, -v52, v58, v53
	v_fma_f32 v62, -v54, v59, v57
	v_fmac_f32_e32 v58, v61, v55
	v_fmac_f32_e32 v59, v62, v56
	v_fma_f32 v52, -v52, v58, v53
	v_fma_f32 v53, -v54, v59, v57
	v_div_fmas_f32 v52, v52, v55, v58
	s_mov_b64 vcc, s[0:1]
	v_div_fixup_f32 v51, v52, v51, 1.0
	v_div_fmas_f32 v52, v53, v56, v59
	v_div_fixup_f32 v48, v52, v48, 1.0
	v_mul_f32_e32 v49, v49, v51
	v_mul_f32_e32 v48, v50, v48
	v_cvt_pk_bf16_f32 v48, v49, v48
	v_add_u32_e32 v49, v60, v112
	global_store_dword v49, v48, s[10:11]
	v_add_u32_e32 v182, 0x17a000, v113
	v_add_lshl_u32 v183, v182, v129, 1
	global_load_dword v150, v183, s[8:9]
	v_add_u32_e32 v184, 0x17ca00, v113
	v_add_lshl_u32 v185, v184, v129, 1
	global_load_dword v151, v185, s[8:9]
	v_add_lshl_u32 v186, v182, v126, 1
	global_load_dword v152, v186, s[8:9]
	v_add_lshl_u32 v187, v184, v126, 1
	global_load_dword v153, v187, s[8:9]
	v_add_lshl_u32 v188, v182, v122, 1
	global_load_dword v154, v188, s[8:9]
	v_add_lshl_u32 v190, v184, v122, 1
	global_load_dword v155, v190, s[8:9]
	v_add_lshl_u32 v191, v182, v116, 1
	global_load_dword v156, v191, s[8:9]
	v_add_lshl_u32 v192, v184, v116, 1
	global_load_dword v157, v192, s[8:9]
	v_add_u32_e32 v50, 0x150000, v113
	v_add_lshl_u32 v48, v50, v129, 1
	s_nop 0
	v_cndmask_b32_e64 v52, v44, v46, s[6:7]
	v_add_u32_e32 v48, 0x90000, v128
	v_add_u32_e32 v49, 0x152a00, v113
	v_mov_b32_dpp v52, v52 quad_perm:[1,0,3,2] row_mask:0xf bank_mask:0xf bound_ctrl:1
	v_cndmask_b32_e64 v44, v52, v44, s[6:7]
	v_cndmask_b32_e64 v46, v46, v52, s[6:7]
	v_add_u32_e32 v53, v48, v124
	v_add_lshl_u32 v54, v49, v129, 1
	s_waitcnt vmcnt(23)
; DEVINL float bflo(unsigned u) { return __uint_as_float(u << 16); }
; DEVINL float bfhi(unsigned u) { return __uint_as_float(u & 0xffff0000u); }
; DEVINL float sigm(float x) { return 1.f / (1.f + __expf(-x)); }
; template <int EPI, bool GATHER>
; DEVINL void gemm_tile(const Params& p, const u16* __restrict__ A, int lda, const int* __restrict__ rowidx,
;                       const u16* __restrict__ Bt, int ldb, int K, int brow, int bcol, int orow, int ocol) {
;     ...
;           f32x4 v = acc[ai][bj][m][n];
;           if (EPI == EPI_HID) {
; #pragma unroll
;             for (int j = 0; j < 4; ++j) { const float a1 = acc[ai][0][m][n][j], a3 = acc[ai][1][m][n][j]; v[j] = a1 * sigm(a1) * a3; }
;           }
;           float lo[2], hi[2];
;           xchg_pairs(v, odd, lo, hi);
; #pragma unroll
;           for (int k = 0; k < 2; ++k) {
;             const unsigned row = (unsigned)(rA + k);
;             if (EPI == EPI_HID) {
;               *(unsigned*)(ws + O_HID + (row * 1024u + (unsigned)(colp + cc)) * 2u) = pk2(lo[k], hi[k]);
;             } else if (EPI == EPI_COLS) {
;               *(unsigned*)(ws + O_COLS + (row * (unsigned)NCP + (unsigned)(colp + cc)) * 2u) = pk2(lo[k], hi[k]);
;             } else if (EPI == EPI_MOE2) {
;               *(unsigned*)(ws + O_EO + (row * 2048u + (unsigned)(colp + cc)) * 2u) = pk2(gate[k] * lo[k], gate[k] * hi[k]);
;             } else if (EPI == EPI_M1) {
;               const unsigned g2 = *(const unsigned*)(ws + O_COLS + (row * (unsigned)NCP + (unsigned)(C_GG + colp + cc)) * 2u);
;               *(unsigned*)(ws + O_M1 + (row * 2048u + (unsigned)(colp + cc)) * 2u) = pk2(sigm(bflo(g2)) * lo[k], sigm(bfhi(g2)) * hi[k]);
	v_lshlrev_b32_e32 v55, 16, v166
	v_and_b32_e32 v51, 0xffff0000, v166
	v_mul_f32_e32 v55, 0xbfb8aa3b, v55
	v_mul_f32_e32 v51, 0xbfb8aa3b, v51
	v_exp_f32_e32 v55, v55
	v_exp_f32_e32 v51, v51
	v_add_f32_e32 v52, 1.0, v55
	v_add_f32_e32 v51, 1.0, v51
	v_div_scale_f32 v55, s[0:1], v52, v52, 1.0
	v_div_scale_f32 v57, s[0:1], v51, v51, 1.0
	v_rcp_f32_e32 v58, v55
	v_rcp_f32_e32 v59, v57
	v_div_scale_f32 v56, vcc, 1.0, v52, 1.0
	v_fma_f32 v61, -v55, v58, 1.0
	v_fma_f32 v62, -v57, v59, 1.0
	v_fmac_f32_e32 v58, v61, v58
	v_div_scale_f32 v60, s[0:1], 1.0, v51, 1.0
	v_fmac_f32_e32 v59, v62, v59
	v_mul_f32_e32 v61, v56, v58
	v_mul_f32_e32 v62, v60, v59
	v_fma_f32 v63, -v55, v61, v56
	v_fma_f32 v64, -v57, v62, v60
	v_fmac_f32_e32 v61, v63, v58
	v_fmac_f32_e32 v62, v64, v59
	v_fma_f32 v55, -v55, v61, v56
	v_fma_f32 v56, -v57, v62, v60
	v_div_fmas_f32 v55, v55, v58, v61
	s_mov_b64 vcc, s[0:1]
	v_div_fixup_f32 v52, v55, v52, 1.0
	v_div_fmas_f32 v55, v56, v59, v62
	v_div_fixup_f32 v51, v55, v51, 1.0
	v_mul_f32_e32 v44, v44, v52
	v_mul_f32_e32 v46, v46, v51
	v_cvt_pk_bf16_f32 v44, v44, v46
	global_store_dword v53, v44, s[10:11]
	s_nop 0
	v_cndmask_b32_e64 v51, v45, v47, s[6:7]
	v_add_u32_e32 v44, 0x91000, v128
	v_add_u32_e32 v52, v44, v124
	v_mov_b32_dpp v51, v51 quad_perm:[1,0,3,2] row_mask:0xf bank_mask:0xf bound_ctrl:1
	v_cndmask_b32_e64 v45, v51, v45, s[6:7]
	v_cndmask_b32_e64 v47, v47, v51, s[6:7]
	v_add_lshl_u32 v53, v50, v126, 1
	s_waitcnt vmcnt(23)
	v_lshlrev_b32_e32 v54, 16, v167
	v_and_b32_e32 v46, 0xffff0000, v167
	v_mul_f32_e32 v54, 0xbfb8aa3b, v54
	v_mul_f32_e32 v46, 0xbfb8aa3b, v46
	v_exp_f32_e32 v54, v54
	v_exp_f32_e32 v46, v46
	v_add_f32_e32 v51, 1.0, v54
	v_add_f32_e32 v46, 1.0, v46
	v_div_scale_f32 v54, s[0:1], v51, v51, 1.0
	v_div_scale_f32 v56, s[0:1], v46, v46, 1.0
	v_rcp_f32_e32 v57, v54
	v_rcp_f32_e32 v58, v56
	v_div_scale_f32 v55, vcc, 1.0, v51, 1.0
	v_fma_f32 v60, -v54, v57, 1.0
	v_fma_f32 v61, -v56, v58, 1.0
	v_fmac_f32_e32 v57, v60, v57
	v_div_scale_f32 v59, s[0:1], 1.0, v46, 1.0
	v_fmac_f32_e32 v58, v61, v58
	v_mul_f32_e32 v60, v55, v57
	v_mul_f32_e32 v61, v59, v58
	v_fma_f32 v62, -v54, v60, v55
	v_fma_f32 v63, -v56, v61, v59
	v_fmac_f32_e32 v60, v62, v57
	v_fmac_f32_e32 v61, v63, v58
	v_fma_f32 v54, -v54, v60, v55
	v_fma_f32 v55, -v56, v61, v59
	v_div_fmas_f32 v54, v54, v57, v60
	s_mov_b64 vcc, s[0:1]
	v_div_fixup_f32 v51, v54, v51, 1.0
	v_div_fmas_f32 v54, v55, v58, v61
	v_div_fixup_f32 v46, v54, v46, 1.0
	v_mul_f32_e32 v45, v45, v51
	v_mul_f32_e32 v46, v47, v46
	v_cvt_pk_bf16_f32 v45, v45, v46
	global_store_dword v52, v45, s[10:11]
	s_nop 0
	v_cndmask_b32_e64 v46, v40, v42, s[6:7]
	v_add_u32_e32 v47, v48, v120
	v_add_lshl_u32 v51, v49, v126, 1
	v_mov_b32_dpp v46, v46 quad_perm:[1,0,3,2] row_mask:0xf bank_mask:0xf bound_ctrl:1
	v_cndmask_b32_e64 v40, v46, v40, s[6:7]
	v_cndmask_b32_e64 v42, v42, v46, s[6:7]
	s_waitcnt vmcnt(23)
	v_lshlrev_b32_e32 v52, 16, v168
	v_and_b32_e32 v45, 0xffff0000, v168
	v_mul_f32_e32 v52, 0xbfb8aa3b, v52
	v_mul_f32_e32 v45, 0xbfb8aa3b, v45
	v_exp_f32_e32 v52, v52
	v_exp_f32_e32 v45, v45
	v_add_f32_e32 v46, 1.0, v52
	v_add_f32_e32 v45, 1.0, v45
	v_div_scale_f32 v52, s[0:1], v46, v46, 1.0
	v_div_scale_f32 v54, s[0:1], v45, v45, 1.0
	v_rcp_f32_e32 v55, v52
	v_rcp_f32_e32 v56, v54
	v_div_scale_f32 v53, vcc, 1.0, v46, 1.0
	v_fma_f32 v58, -v52, v55, 1.0
	v_fma_f32 v59, -v54, v56, 1.0
	v_fmac_f32_e32 v55, v58, v55
	v_div_scale_f32 v57, s[0:1], 1.0, v45, 1.0
	v_fmac_f32_e32 v56, v59, v56
	v_mul_f32_e32 v58, v53, v55
	v_mul_f32_e32 v59, v57, v56
	v_fma_f32 v60, -v52, v58, v53
	v_fma_f32 v61, -v54, v59, v57
	v_fmac_f32_e32 v58, v60, v55
	v_fmac_f32_e32 v59, v61, v56
	v_fma_f32 v52, -v52, v58, v53
	v_fma_f32 v53, -v54, v59, v57
	v_div_fmas_f32 v52, v52, v55, v58
	s_mov_b64 vcc, s[0:1]
	v_div_fixup_f32 v46, v52, v46, 1.0
	v_div_fmas_f32 v52, v53, v56, v59
	v_div_fixup_f32 v45, v52, v45, 1.0
	v_mul_f32_e32 v40, v40, v46
	v_mul_f32_e32 v42, v42, v45
	v_cvt_pk_bf16_f32 v40, v40, v42
	global_store_dword v47, v40, s[10:11]
	s_nop 0
	v_cndmask_b32_e64 v42, v41, v43, s[6:7]
	v_add_u32_e32 v45, v44, v120
	v_add_lshl_u32 v46, v50, v122, 1
	v_mov_b32_dpp v42, v42 quad_perm:[1,0,3,2] row_mask:0xf bank_mask:0xf bound_ctrl:1
	v_cndmask_b32_e64 v41, v42, v41, s[6:7]
	v_cndmask_b32_e64 v42, v43, v42, s[6:7]
	s_waitcnt vmcnt(23)
	v_lshlrev_b32_e32 v47, 16, v169
	v_and_b32_e32 v40, 0xffff0000, v169
	v_mul_f32_e32 v47, 0xbfb8aa3b, v47
	v_mul_f32_e32 v40, 0xbfb8aa3b, v40
	v_exp_f32_e32 v47, v47
	v_exp_f32_e32 v40, v40
	v_add_f32_e32 v43, 1.0, v47
	v_add_f32_e32 v40, 1.0, v40
	v_div_scale_f32 v47, s[0:1], v43, v43, 1.0
	v_div_scale_f32 v52, s[0:1], v40, v40, 1.0
	v_rcp_f32_e32 v53, v47
	v_rcp_f32_e32 v54, v52
	v_div_scale_f32 v51, vcc, 1.0, v43, 1.0
	v_fma_f32 v56, -v47, v53, 1.0
	v_fma_f32 v57, -v52, v54, 1.0
	v_fmac_f32_e32 v53, v56, v53
	v_div_scale_f32 v55, s[0:1], 1.0, v40, 1.0
	v_fmac_f32_e32 v54, v57, v54
	v_mul_f32_e32 v56, v51, v53
	v_mul_f32_e32 v57, v55, v54
	v_fma_f32 v58, -v47, v56, v51
	v_fma_f32 v59, -v52, v57, v55
	v_fmac_f32_e32 v56, v58, v53
	v_fmac_f32_e32 v57, v59, v54
	v_fma_f32 v47, -v47, v56, v51
	v_fma_f32 v51, -v52, v57, v55
	v_div_fmas_f32 v47, v47, v53, v56
	s_mov_b64 vcc, s[0:1]
	v_div_fixup_f32 v43, v47, v43, 1.0
	v_div_fmas_f32 v47, v51, v54, v57
	v_div_fixup_f32 v40, v47, v40, 1.0
	v_mul_f32_e32 v41, v41, v43
	v_mul_f32_e32 v40, v42, v40
	v_cvt_pk_bf16_f32 v40, v41, v40
	global_store_dword v45, v40, s[10:11]
	s_nop 0
	v_cndmask_b32_e64 v41, v36, v38, s[6:7]
	v_add_u32_e32 v42, v48, v118
	v_add_lshl_u32 v43, v49, v122, 1
	v_mov_b32_dpp v41, v41 quad_perm:[1,0,3,2] row_mask:0xf bank_mask:0xf bound_ctrl:1
	v_cndmask_b32_e64 v36, v41, v36, s[6:7]
	v_cndmask_b32_e64 v38, v38, v41, s[6:7]
	s_waitcnt vmcnt(23)
; DEVINL float bflo(unsigned u) { return __uint_as_float(u << 16); }
; DEVINL float bfhi(unsigned u) { return __uint_as_float(u & 0xffff0000u); }
; DEVINL float sigm(float x) { return 1.f / (1.f + __expf(-x)); }
; template <int EPI, bool GATHER>
; DEVINL void gemm_tile(const Params& p, const u16* __restrict__ A, int lda, const int* __restrict__ rowidx,
;                       const u16* __restrict__ Bt, int ldb, int K, int brow, int bcol, int orow, int ocol) {
;     ...
;           f32x4 v = acc[ai][bj][m][n];
;           if (EPI == EPI_HID) {
; #pragma unroll
;             for (int j = 0; j < 4; ++j) { const float a1 = acc[ai][0][m][n][j], a3 = acc[ai][1][m][n][j]; v[j] = a1 * sigm(a1) * a3; }
;           }
;           float lo[2], hi[2];
;           xchg_pairs(v, odd, lo, hi);
; #pragma unroll
;           for (int k = 0; k < 2; ++k) {
;             const unsigned row = (unsigned)(rA + k);
;             if (EPI == EPI_HID) {
;               *(unsigned*)(ws + O_HID + (row * 1024u + (unsigned)(colp + cc)) * 2u) = pk2(lo[k], hi[k]);
;             } else if (EPI == EPI_COLS) {
;               *(unsigned*)(ws + O_COLS + (row * (unsigned)NCP + (unsigned)(colp + cc)) * 2u) = pk2(lo[k], hi[k]);
;             } else if (EPI == EPI_MOE2) {
;               *(unsigned*)(ws + O_EO + (row * 2048u + (unsigned)(colp + cc)) * 2u) = pk2(gate[k] * lo[k], gate[k] * hi[k]);
;             } else if (EPI == EPI_M1) {
;               const unsigned g2 = *(const unsigned*)(ws + O_COLS + (row * (unsigned)NCP + (unsigned)(C_GG + colp + cc)) * 2u);
;               *(unsigned*)(ws + O_M1 + (row * 2048u + (unsigned)(colp + cc)) * 2u) = pk2(sigm(bflo(g2)) * lo[k], sigm(bfhi(g2)) * hi[k]);
	v_lshlrev_b32_e32 v45, 16, v170
	v_and_b32_e32 v40, 0xffff0000, v170
	v_mul_f32_e32 v45, 0xbfb8aa3b, v45
	v_mul_f32_e32 v40, 0xbfb8aa3b, v40
	v_exp_f32_e32 v45, v45
	v_exp_f32_e32 v40, v40
	v_add_f32_e32 v41, 1.0, v45
	v_add_f32_e32 v40, 1.0, v40
	v_div_scale_f32 v45, s[0:1], v41, v41, 1.0
	v_div_scale_f32 v47, s[0:1], v40, v40, 1.0
	v_rcp_f32_e32 v51, v45
	v_rcp_f32_e32 v52, v47
	v_div_scale_f32 v46, vcc, 1.0, v41, 1.0
	v_fma_f32 v54, -v45, v51, 1.0
	v_fma_f32 v55, -v47, v52, 1.0
	v_fmac_f32_e32 v51, v54, v51
	v_div_scale_f32 v53, s[0:1], 1.0, v40, 1.0
	v_fmac_f32_e32 v52, v55, v52
	v_mul_f32_e32 v54, v46, v51
	v_mul_f32_e32 v55, v53, v52
	v_fma_f32 v56, -v45, v54, v46
	v_fma_f32 v57, -v47, v55, v53
	v_fmac_f32_e32 v54, v56, v51
	v_fmac_f32_e32 v55, v57, v52
	v_fma_f32 v45, -v45, v54, v46
	v_fma_f32 v46, -v47, v55, v53
	v_div_fmas_f32 v45, v45, v51, v54
	s_mov_b64 vcc, s[0:1]
	v_div_fixup_f32 v41, v45, v41, 1.0
	v_div_fmas_f32 v45, v46, v52, v55
	v_div_fixup_f32 v40, v45, v40, 1.0
	v_mul_f32_e32 v36, v36, v41
	v_mul_f32_e32 v38, v38, v40
	v_cvt_pk_bf16_f32 v36, v36, v38
	global_store_dword v42, v36, s[10:11]
	s_nop 0
	v_cndmask_b32_e64 v38, v37, v39, s[6:7]
	v_add_lshl_u32 v41, v50, v116, 1
	v_add_u32_e32 v40, v44, v118
	v_mov_b32_dpp v38, v38 quad_perm:[1,0,3,2] row_mask:0xf bank_mask:0xf bound_ctrl:1
	v_cndmask_b32_e64 v37, v38, v37, s[6:7]
	v_cndmask_b32_e64 v38, v39, v38, s[6:7]
	s_waitcnt vmcnt(23)
	v_lshlrev_b32_e32 v42, 16, v171
	v_and_b32_e32 v36, 0xffff0000, v171
	v_mul_f32_e32 v42, 0xbfb8aa3b, v42
	v_mul_f32_e32 v36, 0xbfb8aa3b, v36
	v_exp_f32_e32 v42, v42
	v_exp_f32_e32 v36, v36
	v_add_f32_e32 v39, 1.0, v42
	v_add_f32_e32 v36, 1.0, v36
	v_div_scale_f32 v42, s[0:1], v39, v39, 1.0
	v_div_scale_f32 v45, s[0:1], v36, v36, 1.0
	v_rcp_f32_e32 v46, v42
	v_rcp_f32_e32 v47, v45
	v_div_scale_f32 v43, vcc, 1.0, v39, 1.0
	v_fma_f32 v51, -v42, v46, 1.0
	v_fma_f32 v52, -v45, v47, 1.0
	v_fmac_f32_e32 v46, v51, v46
	v_div_scale_f32 v50, s[0:1], 1.0, v36, 1.0
	v_fmac_f32_e32 v47, v52, v47
	v_mul_f32_e32 v51, v43, v46
	v_mul_f32_e32 v52, v50, v47
	v_fma_f32 v53, -v42, v51, v43
	v_fma_f32 v54, -v45, v52, v50
	v_fmac_f32_e32 v51, v53, v46
	v_fmac_f32_e32 v52, v54, v47
	v_fma_f32 v42, -v42, v51, v43
	v_fma_f32 v43, -v45, v52, v50
	v_div_fmas_f32 v42, v42, v46, v51
	s_mov_b64 vcc, s[0:1]
	v_div_fixup_f32 v39, v42, v39, 1.0
	v_div_fmas_f32 v42, v43, v47, v52
	v_div_fixup_f32 v36, v42, v36, 1.0
	v_mul_f32_e32 v37, v37, v39
	v_mul_f32_e32 v36, v38, v36
	v_cvt_pk_bf16_f32 v36, v37, v36
	global_store_dword v40, v36, s[10:11]
	s_nop 0
	v_cndmask_b32_e64 v37, v32, v34, s[6:7]
	v_add_u32_e32 v38, v48, v112
	v_add_lshl_u32 v39, v49, v116, 1
	v_mov_b32_dpp v37, v37 quad_perm:[1,0,3,2] row_mask:0xf bank_mask:0xf bound_ctrl:1
	v_cndmask_b32_e64 v32, v37, v32, s[6:7]
	v_cndmask_b32_e64 v34, v34, v37, s[6:7]
	s_waitcnt vmcnt(23)
	v_lshlrev_b32_e32 v40, 16, v172
	v_and_b32_e32 v36, 0xffff0000, v172
	v_mul_f32_e32 v40, 0xbfb8aa3b, v40
	v_mul_f32_e32 v36, 0xbfb8aa3b, v36
	v_exp_f32_e32 v40, v40
	v_exp_f32_e32 v36, v36
	v_add_f32_e32 v37, 1.0, v40
	v_add_f32_e32 v36, 1.0, v36
	v_div_scale_f32 v40, s[0:1], v37, v37, 1.0
	v_div_scale_f32 v42, s[0:1], v36, v36, 1.0
	v_rcp_f32_e32 v43, v40
	v_rcp_f32_e32 v45, v42
	v_div_scale_f32 v41, vcc, 1.0, v37, 1.0
	v_fma_f32 v47, -v40, v43, 1.0
	v_fma_f32 v48, -v42, v45, 1.0
	v_fmac_f32_e32 v43, v47, v43
	v_div_scale_f32 v46, s[0:1], 1.0, v36, 1.0
	v_fmac_f32_e32 v45, v48, v45
	v_mul_f32_e32 v47, v41, v43
	v_mul_f32_e32 v48, v46, v45
	v_fma_f32 v49, -v40, v47, v41
	v_fma_f32 v50, -v42, v48, v46
	v_fmac_f32_e32 v47, v49, v43
	v_fmac_f32_e32 v48, v50, v45
	v_fma_f32 v40, -v40, v47, v41
	v_fma_f32 v41, -v42, v48, v46
	v_div_fmas_f32 v40, v40, v43, v47
	s_mov_b64 vcc, s[0:1]
	v_div_fixup_f32 v37, v40, v37, 1.0
	v_div_fmas_f32 v40, v41, v45, v48
	v_div_fixup_f32 v36, v40, v36, 1.0
	v_mul_f32_e32 v32, v32, v37
	v_mul_f32_e32 v34, v34, v36
	v_cvt_pk_bf16_f32 v32, v32, v34
	global_store_dword v38, v32, s[10:11]
	s_nop 0
	v_cndmask_b32_e64 v34, v33, v35, s[6:7]
	s_waitcnt vmcnt(23)
	v_lshlrev_b32_e32 v36, 16, v173
	v_and_b32_e32 v32, 0xffff0000, v173
	v_mul_f32_e32 v36, 0xbfb8aa3b, v36
	v_mul_f32_e32 v32, 0xbfb8aa3b, v32
	v_exp_f32_e32 v36, v36
	v_exp_f32_e32 v32, v32
	v_mov_b32_dpp v34, v34 quad_perm:[1,0,3,2] row_mask:0xf bank_mask:0xf bound_ctrl:1
	v_cndmask_b32_e64 v33, v34, v33, s[6:7]
	v_cndmask_b32_e64 v34, v35, v34, s[6:7]
	v_add_f32_e32 v35, 1.0, v36
	v_add_f32_e32 v32, 1.0, v32
	v_div_scale_f32 v36, s[0:1], v35, v35, 1.0
	v_div_scale_f32 v38, s[0:1], v32, v32, 1.0
	v_rcp_f32_e32 v39, v36
	v_rcp_f32_e32 v40, v38
	v_div_scale_f32 v37, vcc, 1.0, v35, 1.0
	v_fma_f32 v42, -v36, v39, 1.0
	v_fma_f32 v43, -v38, v40, 1.0
	v_fmac_f32_e32 v39, v42, v39
	v_div_scale_f32 v41, s[0:1], 1.0, v32, 1.0
	v_fmac_f32_e32 v40, v43, v40
	v_mul_f32_e32 v42, v37, v39
	v_mul_f32_e32 v43, v41, v40
	v_fma_f32 v45, -v36, v42, v37
	v_fma_f32 v46, -v38, v43, v41
	v_fmac_f32_e32 v42, v45, v39
	v_fmac_f32_e32 v43, v46, v40
	v_fma_f32 v36, -v36, v42, v37
	v_fma_f32 v37, -v38, v43, v41
	v_div_fmas_f32 v36, v36, v39, v42
	s_mov_b64 vcc, s[0:1]
	v_div_fixup_f32 v35, v36, v35, 1.0
	v_div_fmas_f32 v36, v37, v40, v43
	v_div_fixup_f32 v32, v36, v32, 1.0
	v_mul_f32_e32 v33, v33, v35
	v_mul_f32_e32 v32, v34, v32
	v_cvt_pk_bf16_f32 v32, v33, v32
	v_add_u32_e32 v33, v44, v112
	global_store_dword v33, v32, s[10:11]
	v_add_u32_e32 v182, 0x1a4000, v113
	v_add_lshl_u32 v183, v182, v129, 1
	global_load_dword v166, v183, s[8:9]
	v_add_u32_e32 v184, 0x1a6a00, v113
	v_add_lshl_u32 v185, v184, v129, 1
	global_load_dword v167, v185, s[8:9]
	v_add_lshl_u32 v186, v182, v126, 1
	global_load_dword v168, v186, s[8:9]
	v_add_lshl_u32 v187, v184, v126, 1
	global_load_dword v169, v187, s[8:9]
	v_add_lshl_u32 v188, v182, v122, 1
	global_load_dword v170, v188, s[8:9]
	v_add_lshl_u32 v190, v184, v122, 1
	global_load_dword v171, v190, s[8:9]
	v_add_lshl_u32 v191, v182, v116, 1
	global_load_dword v172, v191, s[8:9]
	v_add_lshl_u32 v192, v184, v116, 1
	global_load_dword v173, v192, s[8:9]
	v_add_u32_e32 v34, 0x17a000, v113
	v_add_lshl_u32 v32, v34, v129, 1
	s_nop 0
	v_cndmask_b32_e64 v36, v28, v30, s[6:7]
	v_add_u32_e32 v32, 0xa0000, v128
	v_add_u32_e32 v33, 0x17ca00, v113
	v_mov_b32_dpp v36, v36 quad_perm:[1,0,3,2] row_mask:0xf bank_mask:0xf bound_ctrl:1
	v_cndmask_b32_e64 v28, v36, v28, s[6:7]
	v_cndmask_b32_e64 v30, v30, v36, s[6:7]
	v_add_u32_e32 v37, v32, v124
	v_add_lshl_u32 v38, v33, v129, 1
	s_waitcnt vmcnt(23)
; DEVINL float bflo(unsigned u) { return __uint_as_float(u << 16); }
; DEVINL float bfhi(unsigned u) { return __uint_as_float(u & 0xffff0000u); }
; DEVINL float sigm(float x) { return 1.f / (1.f + __expf(-x)); }
; template <int EPI, bool GATHER>
; DEVINL void gemm_tile(const Params& p, const u16* __restrict__ A, int lda, const int* __restrict__ rowidx,
;                       const u16* __restrict__ Bt, int ldb, int K, int brow, int bcol, int orow, int ocol) {
;     ...
;           f32x4 v = acc[ai][bj][m][n];
;           if (EPI == EPI_HID) {
; #pragma unroll
;             for (int j = 0; j < 4; ++j) { const float a1 = acc[ai][0][m][n][j], a3 = acc[ai][1][m][n][j]; v[j] = a1 * sigm(a1) * a3; }
;           }
;           float lo[2], hi[2];
;           xchg_pairs(v, odd, lo, hi);
; #pragma unroll
;           for (int k = 0; k < 2; ++k) {
;             const unsigned row = (unsigned)(rA + k);
;             if (EPI == EPI_HID) {
;               *(unsigned*)(ws + O_HID + (row * 1024u + (unsigned)(colp + cc)) * 2u) = pk2(lo[k], hi[k]);
;             } else if (EPI == EPI_COLS) {
;               *(unsigned*)(ws + O_COLS + (row * (unsigned)NCP + (unsigned)(colp + cc)) * 2u) = pk2(lo[k], hi[k]);
;             } else if (EPI == EPI_MOE2) {
;               *(unsigned*)(ws + O_EO + (row * 2048u + (unsigned)(colp + cc)) * 2u) = pk2(gate[k] * lo[k], gate[k] * hi[k]);
;             } else if (EPI == EPI_M1) {
;               const unsigned g2 = *(const unsigned*)(ws + O_COLS + (row * (unsigned)NCP + (unsigned)(C_GG + colp + cc)) * 2u);
;               *(unsigned*)(ws + O_M1 + (row * 2048u + (unsigned)(colp + cc)) * 2u) = pk2(sigm(bflo(g2)) * lo[k], sigm(bfhi(g2)) * hi[k]);
	v_lshlrev_b32_e32 v39, 16, v150
	v_and_b32_e32 v35, 0xffff0000, v150
	v_mul_f32_e32 v39, 0xbfb8aa3b, v39
	v_mul_f32_e32 v35, 0xbfb8aa3b, v35
	v_exp_f32_e32 v39, v39
	v_exp_f32_e32 v35, v35
	v_add_f32_e32 v36, 1.0, v39
	v_add_f32_e32 v35, 1.0, v35
	v_div_scale_f32 v39, s[0:1], v36, v36, 1.0
	v_div_scale_f32 v41, s[0:1], v35, v35, 1.0
	v_rcp_f32_e32 v42, v39
	v_rcp_f32_e32 v43, v41
	v_div_scale_f32 v40, vcc, 1.0, v36, 1.0
	v_fma_f32 v45, -v39, v42, 1.0
	v_fma_f32 v46, -v41, v43, 1.0
	v_fmac_f32_e32 v42, v45, v42
	v_div_scale_f32 v44, s[0:1], 1.0, v35, 1.0
	v_fmac_f32_e32 v43, v46, v43
	v_mul_f32_e32 v45, v40, v42
	v_mul_f32_e32 v46, v44, v43
	v_fma_f32 v47, -v39, v45, v40
	v_fma_f32 v48, -v41, v46, v44
	v_fmac_f32_e32 v45, v47, v42
	v_fmac_f32_e32 v46, v48, v43
	v_fma_f32 v39, -v39, v45, v40
	v_fma_f32 v40, -v41, v46, v44
	v_div_fmas_f32 v39, v39, v42, v45
	s_mov_b64 vcc, s[0:1]
	v_div_fixup_f32 v36, v39, v36, 1.0
	v_div_fmas_f32 v39, v40, v43, v46
	v_div_fixup_f32 v35, v39, v35, 1.0
	v_mul_f32_e32 v28, v28, v36
	v_mul_f32_e32 v30, v30, v35
	v_cvt_pk_bf16_f32 v28, v28, v30
	global_store_dword v37, v28, s[10:11]
	s_nop 0
	v_cndmask_b32_e64 v35, v29, v31, s[6:7]
	v_add_u32_e32 v28, 0xa1000, v128
	v_add_u32_e32 v36, v28, v124
	v_mov_b32_dpp v35, v35 quad_perm:[1,0,3,2] row_mask:0xf bank_mask:0xf bound_ctrl:1
	v_cndmask_b32_e64 v29, v35, v29, s[6:7]
	v_cndmask_b32_e64 v31, v31, v35, s[6:7]
	v_add_lshl_u32 v37, v34, v126, 1
	s_waitcnt vmcnt(23)
	v_lshlrev_b32_e32 v38, 16, v151
	v_and_b32_e32 v30, 0xffff0000, v151
	v_mul_f32_e32 v38, 0xbfb8aa3b, v38
	v_mul_f32_e32 v30, 0xbfb8aa3b, v30
	v_exp_f32_e32 v38, v38
	v_exp_f32_e32 v30, v30
	v_add_f32_e32 v35, 1.0, v38
	v_add_f32_e32 v30, 1.0, v30
	v_div_scale_f32 v38, s[0:1], v35, v35, 1.0
	v_div_scale_f32 v40, s[0:1], v30, v30, 1.0
	v_rcp_f32_e32 v41, v38
	v_rcp_f32_e32 v42, v40
	v_div_scale_f32 v39, vcc, 1.0, v35, 1.0
	v_fma_f32 v44, -v38, v41, 1.0
	v_fma_f32 v45, -v40, v42, 1.0
	v_fmac_f32_e32 v41, v44, v41
	v_div_scale_f32 v43, s[0:1], 1.0, v30, 1.0
	v_fmac_f32_e32 v42, v45, v42
	v_mul_f32_e32 v44, v39, v41
	v_mul_f32_e32 v45, v43, v42
	v_fma_f32 v46, -v38, v44, v39
	v_fma_f32 v47, -v40, v45, v43
	v_fmac_f32_e32 v44, v46, v41
	v_fmac_f32_e32 v45, v47, v42
	v_fma_f32 v38, -v38, v44, v39
	v_fma_f32 v39, -v40, v45, v43
	v_div_fmas_f32 v38, v38, v41, v44
	s_mov_b64 vcc, s[0:1]
	v_div_fixup_f32 v35, v38, v35, 1.0
	v_div_fmas_f32 v38, v39, v42, v45
	v_div_fixup_f32 v30, v38, v30, 1.0
	v_mul_f32_e32 v29, v29, v35
	v_mul_f32_e32 v30, v31, v30
	v_cvt_pk_bf16_f32 v29, v29, v30
	global_store_dword v36, v29, s[10:11]
	s_nop 0
	v_cndmask_b32_e64 v30, v24, v26, s[6:7]
	v_add_u32_e32 v31, v32, v120
	v_add_lshl_u32 v35, v33, v126, 1
	v_mov_b32_dpp v30, v30 quad_perm:[1,0,3,2] row_mask:0xf bank_mask:0xf bound_ctrl:1
	v_cndmask_b32_e64 v24, v30, v24, s[6:7]
	v_cndmask_b32_e64 v26, v26, v30, s[6:7]
	s_waitcnt vmcnt(23)
	v_lshlrev_b32_e32 v36, 16, v152
	v_and_b32_e32 v29, 0xffff0000, v152
	v_mul_f32_e32 v36, 0xbfb8aa3b, v36
	v_mul_f32_e32 v29, 0xbfb8aa3b, v29
	v_exp_f32_e32 v36, v36
	v_exp_f32_e32 v29, v29
	v_add_f32_e32 v30, 1.0, v36
	v_add_f32_e32 v29, 1.0, v29
	v_div_scale_f32 v36, s[0:1], v30, v30, 1.0
	v_div_scale_f32 v38, s[0:1], v29, v29, 1.0
	v_rcp_f32_e32 v39, v36
	v_rcp_f32_e32 v40, v38
	v_div_scale_f32 v37, vcc, 1.0, v30, 1.0
	v_fma_f32 v42, -v36, v39, 1.0
	v_fma_f32 v43, -v38, v40, 1.0
	v_fmac_f32_e32 v39, v42, v39
	v_div_scale_f32 v41, s[0:1], 1.0, v29, 1.0
	v_fmac_f32_e32 v40, v43, v40
	v_mul_f32_e32 v42, v37, v39
	v_mul_f32_e32 v43, v41, v40
	v_fma_f32 v44, -v36, v42, v37
	v_fma_f32 v45, -v38, v43, v41
	v_fmac_f32_e32 v42, v44, v39
	v_fmac_f32_e32 v43, v45, v40
	v_fma_f32 v36, -v36, v42, v37
	v_fma_f32 v37, -v38, v43, v41
	v_div_fmas_f32 v36, v36, v39, v42
	s_mov_b64 vcc, s[0:1]
	v_div_fixup_f32 v30, v36, v30, 1.0
	v_div_fmas_f32 v36, v37, v40, v43
	v_div_fixup_f32 v29, v36, v29, 1.0
	v_mul_f32_e32 v24, v24, v30
	v_mul_f32_e32 v26, v26, v29
	v_cvt_pk_bf16_f32 v24, v24, v26
	global_store_dword v31, v24, s[10:11]
	s_nop 0
	v_cndmask_b32_e64 v26, v25, v27, s[6:7]
	v_add_u32_e32 v29, v28, v120
	v_add_lshl_u32 v30, v34, v122, 1
	v_mov_b32_dpp v26, v26 quad_perm:[1,0,3,2] row_mask:0xf bank_mask:0xf bound_ctrl:1
	v_cndmask_b32_e64 v25, v26, v25, s[6:7]
	v_cndmask_b32_e64 v26, v27, v26, s[6:7]
	s_waitcnt vmcnt(23)
	v_lshlrev_b32_e32 v31, 16, v153
	v_and_b32_e32 v24, 0xffff0000, v153
	v_mul_f32_e32 v31, 0xbfb8aa3b, v31
	v_mul_f32_e32 v24, 0xbfb8aa3b, v24
	v_exp_f32_e32 v31, v31
	v_exp_f32_e32 v24, v24
	v_add_f32_e32 v27, 1.0, v31
	v_add_f32_e32 v24, 1.0, v24
	v_div_scale_f32 v31, s[0:1], v27, v27, 1.0
	v_div_scale_f32 v36, s[0:1], v24, v24, 1.0
	v_rcp_f32_e32 v37, v31
	v_rcp_f32_e32 v38, v36
	v_div_scale_f32 v35, vcc, 1.0, v27, 1.0
	v_fma_f32 v40, -v31, v37, 1.0
	v_fma_f32 v41, -v36, v38, 1.0
	v_fmac_f32_e32 v37, v40, v37
	v_div_scale_f32 v39, s[0:1], 1.0, v24, 1.0
	v_fmac_f32_e32 v38, v41, v38
	v_mul_f32_e32 v40, v35, v37
	v_mul_f32_e32 v41, v39, v38
	v_fma_f32 v42, -v31, v40, v35
	v_fma_f32 v43, -v36, v41, v39
	v_fmac_f32_e32 v40, v42, v37
	v_fmac_f32_e32 v41, v43, v38
	v_fma_f32 v31, -v31, v40, v35
	v_fma_f32 v35, -v36, v41, v39
	v_div_fmas_f32 v31, v31, v37, v40
	s_mov_b64 vcc, s[0:1]
	v_div_fixup_f32 v27, v31, v27, 1.0
	v_div_fmas_f32 v31, v35, v38, v41
	v_div_fixup_f32 v24, v31, v24, 1.0
	v_mul_f32_e32 v25, v25, v27
	v_mul_f32_e32 v24, v26, v24
	v_cvt_pk_bf16_f32 v24, v25, v24
	global_store_dword v29, v24, s[10:11]
	s_nop 0
	v_cndmask_b32_e64 v25, v20, v22, s[6:7]
	v_add_u32_e32 v26, v32, v118
	v_add_lshl_u32 v27, v33, v122, 1
	v_mov_b32_dpp v25, v25 quad_perm:[1,0,3,2] row_mask:0xf bank_mask:0xf bound_ctrl:1
	v_cndmask_b32_e64 v20, v25, v20, s[6:7]
	v_cndmask_b32_e64 v22, v22, v25, s[6:7]
	s_waitcnt vmcnt(23)
; DEVINL float bflo(unsigned u) { return __uint_as_float(u << 16); }
; DEVINL float bfhi(unsigned u) { return __uint_as_float(u & 0xffff0000u); }
; DEVINL float sigm(float x) { return 1.f / (1.f + __expf(-x)); }
; template <int EPI, bool GATHER>
; DEVINL void gemm_tile(const Params& p, const u16* __restrict__ A, int lda, const int* __restrict__ rowidx,
;                       const u16* __restrict__ Bt, int ldb, int K, int brow, int bcol, int orow, int ocol) {
;     ...
;           f32x4 v = acc[ai][bj][m][n];
;           if (EPI == EPI_HID) {
; #pragma unroll
;             for (int j = 0; j < 4; ++j) { const float a1 = acc[ai][0][m][n][j], a3 = acc[ai][1][m][n][j]; v[j] = a1 * sigm(a1) * a3; }
;           }
;           float lo[2], hi[2];
;           xchg_pairs(v, odd, lo, hi);
; #pragma unroll
;           for (int k = 0; k < 2; ++k) {
;             const unsigned row = (unsigned)(rA + k);
;             if (EPI == EPI_HID) {
;               *(unsigned*)(ws + O_HID + (row * 1024u + (unsigned)(colp + cc)) * 2u) = pk2(lo[k], hi[k]);
;             } else if (EPI == EPI_COLS) {
;               *(unsigned*)(ws + O_COLS + (row * (unsigned)NCP + (unsigned)(colp + cc)) * 2u) = pk2(lo[k], hi[k]);
;             } else if (EPI == EPI_MOE2) {
;               *(unsigned*)(ws + O_EO + (row * 2048u + (unsigned)(colp + cc)) * 2u) = pk2(gate[k] * lo[k], gate[k] * hi[k]);
;             } else if (EPI == EPI_M1) {
;               const unsigned g2 = *(const unsigned*)(ws + O_COLS + (row * (unsigned)NCP + (unsigned)(C_GG + colp + cc)) * 2u);
;               *(unsigned*)(ws + O_M1 + (row * 2048u + (unsigned)(colp + cc)) * 2u) = pk2(sigm(bflo(g2)) * lo[k], sigm(bfhi(g2)) * hi[k]);
	v_lshlrev_b32_e32 v29, 16, v154
	v_and_b32_e32 v24, 0xffff0000, v154
	v_mul_f32_e32 v29, 0xbfb8aa3b, v29
	v_mul_f32_e32 v24, 0xbfb8aa3b, v24
	v_exp_f32_e32 v29, v29
	v_exp_f32_e32 v24, v24
	v_add_f32_e32 v25, 1.0, v29
	v_add_f32_e32 v24, 1.0, v24
	v_div_scale_f32 v29, s[0:1], v25, v25, 1.0
	v_div_scale_f32 v31, s[0:1], v24, v24, 1.0
	v_rcp_f32_e32 v35, v29
	v_rcp_f32_e32 v36, v31
	v_div_scale_f32 v30, vcc, 1.0, v25, 1.0
	v_fma_f32 v38, -v29, v35, 1.0
	v_fma_f32 v39, -v31, v36, 1.0
	v_fmac_f32_e32 v35, v38, v35
	v_div_scale_f32 v37, s[0:1], 1.0, v24, 1.0
	v_fmac_f32_e32 v36, v39, v36
	v_mul_f32_e32 v38, v30, v35
	v_mul_f32_e32 v39, v37, v36
	v_fma_f32 v40, -v29, v38, v30
	v_fma_f32 v41, -v31, v39, v37
	v_fmac_f32_e32 v38, v40, v35
	v_fmac_f32_e32 v39, v41, v36
	v_fma_f32 v29, -v29, v38, v30
	v_fma_f32 v30, -v31, v39, v37
	v_div_fmas_f32 v29, v29, v35, v38
	s_mov_b64 vcc, s[0:1]
	v_div_fixup_f32 v25, v29, v25, 1.0
	v_div_fmas_f32 v29, v30, v36, v39
	v_div_fixup_f32 v24, v29, v24, 1.0
	v_mul_f32_e32 v20, v20, v25
	v_mul_f32_e32 v22, v22, v24
	v_cvt_pk_bf16_f32 v20, v20, v22
	global_store_dword v26, v20, s[10:11]
	s_nop 0
	v_cndmask_b32_e64 v22, v21, v23, s[6:7]
	v_add_lshl_u32 v25, v34, v116, 1
	v_add_u32_e32 v24, v28, v118
	v_mov_b32_dpp v22, v22 quad_perm:[1,0,3,2] row_mask:0xf bank_mask:0xf bound_ctrl:1
	v_cndmask_b32_e64 v21, v22, v21, s[6:7]
	v_cndmask_b32_e64 v22, v23, v22, s[6:7]
	s_waitcnt vmcnt(23)
	v_lshlrev_b32_e32 v26, 16, v155
	v_and_b32_e32 v20, 0xffff0000, v155
	v_mul_f32_e32 v26, 0xbfb8aa3b, v26
	v_mul_f32_e32 v20, 0xbfb8aa3b, v20
	v_exp_f32_e32 v26, v26
	v_exp_f32_e32 v20, v20
	v_add_f32_e32 v23, 1.0, v26
	v_add_f32_e32 v20, 1.0, v20
	v_div_scale_f32 v26, s[0:1], v23, v23, 1.0
	v_div_scale_f32 v29, s[0:1], v20, v20, 1.0
	v_rcp_f32_e32 v30, v26
	v_rcp_f32_e32 v31, v29
	v_div_scale_f32 v27, vcc, 1.0, v23, 1.0
	v_fma_f32 v35, -v26, v30, 1.0
	v_fma_f32 v36, -v29, v31, 1.0
	v_fmac_f32_e32 v30, v35, v30
	v_div_scale_f32 v34, s[0:1], 1.0, v20, 1.0
	v_fmac_f32_e32 v31, v36, v31
	v_mul_f32_e32 v35, v27, v30
	v_mul_f32_e32 v36, v34, v31
	v_fma_f32 v37, -v26, v35, v27
	v_fma_f32 v38, -v29, v36, v34
	v_fmac_f32_e32 v35, v37, v30
	v_fmac_f32_e32 v36, v38, v31
	v_fma_f32 v26, -v26, v35, v27
	v_fma_f32 v27, -v29, v36, v34
	v_div_fmas_f32 v26, v26, v30, v35
	s_mov_b64 vcc, s[0:1]
	v_div_fixup_f32 v23, v26, v23, 1.0
	v_div_fmas_f32 v26, v27, v31, v36
	v_div_fixup_f32 v20, v26, v20, 1.0
	v_mul_f32_e32 v21, v21, v23
	v_mul_f32_e32 v20, v22, v20
	v_cvt_pk_bf16_f32 v20, v21, v20
	global_store_dword v24, v20, s[10:11]
	s_nop 0
	v_cndmask_b32_e64 v21, v16, v18, s[6:7]
	v_add_u32_e32 v22, v32, v112
	v_add_lshl_u32 v23, v33, v116, 1
	v_mov_b32_dpp v21, v21 quad_perm:[1,0,3,2] row_mask:0xf bank_mask:0xf bound_ctrl:1
	v_cndmask_b32_e64 v16, v21, v16, s[6:7]
	v_cndmask_b32_e64 v18, v18, v21, s[6:7]
	s_waitcnt vmcnt(23)
	v_lshlrev_b32_e32 v24, 16, v156
	v_and_b32_e32 v20, 0xffff0000, v156
	v_mul_f32_e32 v24, 0xbfb8aa3b, v24
	v_mul_f32_e32 v20, 0xbfb8aa3b, v20
	v_exp_f32_e32 v24, v24
	v_exp_f32_e32 v20, v20
	v_add_f32_e32 v21, 1.0, v24
	v_add_f32_e32 v20, 1.0, v20
	v_div_scale_f32 v24, s[0:1], v21, v21, 1.0
	v_div_scale_f32 v26, s[0:1], v20, v20, 1.0
	v_rcp_f32_e32 v27, v24
	v_rcp_f32_e32 v29, v26
	v_div_scale_f32 v25, vcc, 1.0, v21, 1.0
	v_fma_f32 v31, -v24, v27, 1.0
	v_fma_f32 v32, -v26, v29, 1.0
	v_fmac_f32_e32 v27, v31, v27
	v_div_scale_f32 v30, s[0:1], 1.0, v20, 1.0
	v_fmac_f32_e32 v29, v32, v29
	v_mul_f32_e32 v31, v25, v27
	v_mul_f32_e32 v32, v30, v29
	v_fma_f32 v33, -v24, v31, v25
	v_fma_f32 v34, -v26, v32, v30
	v_fmac_f32_e32 v31, v33, v27
	v_fmac_f32_e32 v32, v34, v29
	v_fma_f32 v24, -v24, v31, v25
	v_fma_f32 v25, -v26, v32, v30
	v_div_fmas_f32 v24, v24, v27, v31
	s_mov_b64 vcc, s[0:1]
	v_div_fixup_f32 v21, v24, v21, 1.0
	v_div_fmas_f32 v24, v25, v29, v32
	v_div_fixup_f32 v20, v24, v20, 1.0
	v_mul_f32_e32 v16, v16, v21
	v_mul_f32_e32 v18, v18, v20
	v_cvt_pk_bf16_f32 v16, v16, v18
	global_store_dword v22, v16, s[10:11]
	s_nop 0
	v_cndmask_b32_e64 v18, v17, v19, s[6:7]
	s_waitcnt vmcnt(23)
	v_lshlrev_b32_e32 v20, 16, v157
	v_and_b32_e32 v16, 0xffff0000, v157
	v_mul_f32_e32 v20, 0xbfb8aa3b, v20
	v_mul_f32_e32 v16, 0xbfb8aa3b, v16
	v_exp_f32_e32 v20, v20
	v_exp_f32_e32 v16, v16
	v_mov_b32_dpp v18, v18 quad_perm:[1,0,3,2] row_mask:0xf bank_mask:0xf bound_ctrl:1
	v_cndmask_b32_e64 v17, v18, v17, s[6:7]
	v_cndmask_b32_e64 v18, v19, v18, s[6:7]
	v_add_f32_e32 v19, 1.0, v20
	v_add_f32_e32 v16, 1.0, v16
	v_div_scale_f32 v20, s[0:1], v19, v19, 1.0
	v_div_scale_f32 v22, s[0:1], v16, v16, 1.0
	v_rcp_f32_e32 v23, v20
	v_rcp_f32_e32 v24, v22
	v_div_scale_f32 v21, vcc, 1.0, v19, 1.0
	v_fma_f32 v26, -v20, v23, 1.0
	v_fma_f32 v27, -v22, v24, 1.0
	v_fmac_f32_e32 v23, v26, v23
	v_div_scale_f32 v25, s[0:1], 1.0, v16, 1.0
	v_fmac_f32_e32 v24, v27, v24
	v_mul_f32_e32 v26, v21, v23
	v_mul_f32_e32 v27, v25, v24
	v_fma_f32 v29, -v20, v26, v21
	v_fma_f32 v30, -v22, v27, v25
	v_fmac_f32_e32 v26, v29, v23
	v_fmac_f32_e32 v27, v30, v24
	v_fma_f32 v20, -v20, v26, v21
	v_fma_f32 v21, -v22, v27, v25
	v_div_fmas_f32 v20, v20, v23, v26
	s_mov_b64 vcc, s[0:1]
	v_div_fixup_f32 v19, v20, v19, 1.0
	v_div_fmas_f32 v20, v21, v24, v27
	v_div_fixup_f32 v16, v20, v16, 1.0
	v_mul_f32_e32 v17, v17, v19
	v_mul_f32_e32 v16, v18, v16
	v_cvt_pk_bf16_f32 v16, v17, v16
	v_add_u32_e32 v17, v28, v112
	global_store_dword v17, v16, s[10:11]
	v_add_u32_e32 v18, 0x1a4000, v113
	v_add_lshl_u32 v16, v18, v129, 1
	s_nop 0
	v_cndmask_b32_e64 v20, v12, v14, s[6:7]
	v_add_u32_e32 v16, 0xb0000, v128
	v_add_u32_e32 v17, 0x1a6a00, v113
	v_mov_b32_dpp v20, v20 quad_perm:[1,0,3,2] row_mask:0xf bank_mask:0xf bound_ctrl:1
	v_cndmask_b32_e64 v12, v20, v12, s[6:7]
	v_cndmask_b32_e64 v14, v14, v20, s[6:7]
	v_add_u32_e32 v21, v16, v124
	v_add_lshl_u32 v22, v17, v129, 1
	s_waitcnt vmcnt(15)
; DEVINL float bflo(unsigned u) { return __uint_as_float(u << 16); }
; DEVINL float bfhi(unsigned u) { return __uint_as_float(u & 0xffff0000u); }
; DEVINL float sigm(float x) { return 1.f / (1.f + __expf(-x)); }
; template <int EPI, bool GATHER>
; DEVINL void gemm_tile(const Params& p, const u16* __restrict__ A, int lda, const int* __restrict__ rowidx,
;                       const u16* __restrict__ Bt, int ldb, int K, int brow, int bcol, int orow, int ocol) {
;     ...
;           f32x4 v = acc[ai][bj][m][n];
;           if (EPI == EPI_HID) {
; #pragma unroll
;             for (int j = 0; j < 4; ++j) { const float a1 = acc[ai][0][m][n][j], a3 = acc[ai][1][m][n][j]; v[j] = a1 * sigm(a1) * a3; }
;           }
;           float lo[2], hi[2];
;           xchg_pairs(v, odd, lo, hi);
; #pragma unroll
;           for (int k = 0; k < 2; ++k) {
;             const unsigned row = (unsigned)(rA + k);
;             if (EPI == EPI_HID) {
;               *(unsigned*)(ws + O_HID + (row * 1024u + (unsigned)(colp + cc)) * 2u) = pk2(lo[k], hi[k]);
;             } else if (EPI == EPI_COLS) {
;               *(unsigned*)(ws + O_COLS + (row * (unsigned)NCP + (unsigned)(colp + cc)) * 2u) = pk2(lo[k], hi[k]);
;             } else if (EPI == EPI_MOE2) {
;               *(unsigned*)(ws + O_EO + (row * 2048u + (unsigned)(colp + cc)) * 2u) = pk2(gate[k] * lo[k], gate[k] * hi[k]);
;             } else if (EPI == EPI_M1) {
;               const unsigned g2 = *(const unsigned*)(ws + O_COLS + (row * (unsigned)NCP + (unsigned)(C_GG + colp + cc)) * 2u);
;               *(unsigned*)(ws + O_M1 + (row * 2048u + (unsigned)(colp + cc)) * 2u) = pk2(sigm(bflo(g2)) * lo[k], sigm(bfhi(g2)) * hi[k]);
	v_lshlrev_b32_e32 v23, 16, v166
	v_and_b32_e32 v19, 0xffff0000, v166
	v_mul_f32_e32 v23, 0xbfb8aa3b, v23
	v_mul_f32_e32 v19, 0xbfb8aa3b, v19
	v_exp_f32_e32 v23, v23
	v_exp_f32_e32 v19, v19
	v_add_f32_e32 v20, 1.0, v23
	v_add_f32_e32 v19, 1.0, v19
	v_div_scale_f32 v23, s[0:1], v20, v20, 1.0
	v_div_scale_f32 v25, s[0:1], v19, v19, 1.0
	v_rcp_f32_e32 v26, v23
	v_rcp_f32_e32 v27, v25
	v_div_scale_f32 v24, vcc, 1.0, v20, 1.0
	v_fma_f32 v29, -v23, v26, 1.0
	v_fma_f32 v30, -v25, v27, 1.0
	v_fmac_f32_e32 v26, v29, v26
	v_div_scale_f32 v28, s[0:1], 1.0, v19, 1.0
	v_fmac_f32_e32 v27, v30, v27
	v_mul_f32_e32 v29, v24, v26
	v_mul_f32_e32 v30, v28, v27
	v_fma_f32 v31, -v23, v29, v24
	v_fma_f32 v32, -v25, v30, v28
	v_fmac_f32_e32 v29, v31, v26
	v_fmac_f32_e32 v30, v32, v27
	v_fma_f32 v23, -v23, v29, v24
	v_fma_f32 v24, -v25, v30, v28
	v_div_fmas_f32 v23, v23, v26, v29
	s_mov_b64 vcc, s[0:1]
	v_div_fixup_f32 v20, v23, v20, 1.0
	v_div_fmas_f32 v23, v24, v27, v30
	v_div_fixup_f32 v19, v23, v19, 1.0
	v_mul_f32_e32 v12, v12, v20
	v_mul_f32_e32 v14, v14, v19
	v_cvt_pk_bf16_f32 v12, v12, v14
	global_store_dword v21, v12, s[10:11]
	s_nop 0
	v_cndmask_b32_e64 v19, v13, v15, s[6:7]
	v_add_u32_e32 v12, 0xb1000, v128
	v_add_u32_e32 v20, v12, v124
	v_mov_b32_dpp v19, v19 quad_perm:[1,0,3,2] row_mask:0xf bank_mask:0xf bound_ctrl:1
	v_cndmask_b32_e64 v13, v19, v13, s[6:7]
	v_cndmask_b32_e64 v15, v15, v19, s[6:7]
	v_add_lshl_u32 v21, v18, v126, 1
	s_waitcnt vmcnt(15)
	v_lshlrev_b32_e32 v22, 16, v167
	v_and_b32_e32 v14, 0xffff0000, v167
	v_mul_f32_e32 v22, 0xbfb8aa3b, v22
	v_mul_f32_e32 v14, 0xbfb8aa3b, v14
	v_exp_f32_e32 v22, v22
	v_exp_f32_e32 v14, v14
	v_add_f32_e32 v19, 1.0, v22
	v_add_f32_e32 v14, 1.0, v14
	v_div_scale_f32 v22, s[0:1], v19, v19, 1.0
	v_div_scale_f32 v24, s[0:1], v14, v14, 1.0
	v_rcp_f32_e32 v25, v22
	v_rcp_f32_e32 v26, v24
	v_div_scale_f32 v23, vcc, 1.0, v19, 1.0
	v_fma_f32 v28, -v22, v25, 1.0
	v_fma_f32 v29, -v24, v26, 1.0
	v_fmac_f32_e32 v25, v28, v25
	v_div_scale_f32 v27, s[0:1], 1.0, v14, 1.0
	v_fmac_f32_e32 v26, v29, v26
	v_mul_f32_e32 v28, v23, v25
	v_mul_f32_e32 v29, v27, v26
	v_fma_f32 v30, -v22, v28, v23
	v_fma_f32 v31, -v24, v29, v27
	v_fmac_f32_e32 v28, v30, v25
	v_fmac_f32_e32 v29, v31, v26
	v_fma_f32 v22, -v22, v28, v23
	v_fma_f32 v23, -v24, v29, v27
	v_div_fmas_f32 v22, v22, v25, v28
	s_mov_b64 vcc, s[0:1]
	v_div_fixup_f32 v19, v22, v19, 1.0
	v_div_fmas_f32 v22, v23, v26, v29
	v_div_fixup_f32 v14, v22, v14, 1.0
	v_mul_f32_e32 v13, v13, v19
	v_mul_f32_e32 v14, v15, v14
	v_cvt_pk_bf16_f32 v13, v13, v14
	global_store_dword v20, v13, s[10:11]
	s_nop 0
	v_cndmask_b32_e64 v14, v8, v10, s[6:7]
	v_add_u32_e32 v15, v16, v120
	v_add_lshl_u32 v19, v17, v126, 1
	v_mov_b32_dpp v14, v14 quad_perm:[1,0,3,2] row_mask:0xf bank_mask:0xf bound_ctrl:1
	v_cndmask_b32_e64 v8, v14, v8, s[6:7]
	v_cndmask_b32_e64 v10, v10, v14, s[6:7]
	s_waitcnt vmcnt(15)
	v_lshlrev_b32_e32 v20, 16, v168
	v_and_b32_e32 v13, 0xffff0000, v168
	v_mul_f32_e32 v20, 0xbfb8aa3b, v20
	v_mul_f32_e32 v13, 0xbfb8aa3b, v13
	v_exp_f32_e32 v20, v20
	v_exp_f32_e32 v13, v13
	v_add_f32_e32 v14, 1.0, v20
	v_add_f32_e32 v13, 1.0, v13
	v_div_scale_f32 v20, s[0:1], v14, v14, 1.0
	v_div_scale_f32 v22, s[0:1], v13, v13, 1.0
	v_rcp_f32_e32 v23, v20
	v_rcp_f32_e32 v24, v22
	v_div_scale_f32 v21, vcc, 1.0, v14, 1.0
	v_fma_f32 v26, -v20, v23, 1.0
	v_fma_f32 v27, -v22, v24, 1.0
	v_fmac_f32_e32 v23, v26, v23
	v_div_scale_f32 v25, s[0:1], 1.0, v13, 1.0
	v_fmac_f32_e32 v24, v27, v24
	v_mul_f32_e32 v26, v21, v23
	v_mul_f32_e32 v27, v25, v24
	v_fma_f32 v28, -v20, v26, v21
	v_fma_f32 v29, -v22, v27, v25
	v_fmac_f32_e32 v26, v28, v23
	v_fmac_f32_e32 v27, v29, v24
	v_fma_f32 v20, -v20, v26, v21
	v_fma_f32 v21, -v22, v27, v25
	v_div_fmas_f32 v20, v20, v23, v26
	s_mov_b64 vcc, s[0:1]
	v_div_fixup_f32 v14, v20, v14, 1.0
	v_div_fmas_f32 v20, v21, v24, v27
	v_div_fixup_f32 v13, v20, v13, 1.0
	v_mul_f32_e32 v8, v8, v14
	v_mul_f32_e32 v10, v10, v13
	v_cvt_pk_bf16_f32 v8, v8, v10
	global_store_dword v15, v8, s[10:11]
	s_nop 0
	v_cndmask_b32_e64 v10, v9, v11, s[6:7]
	v_add_u32_e32 v13, v12, v120
	v_add_lshl_u32 v14, v18, v122, 1
	v_mov_b32_dpp v10, v10 quad_perm:[1,0,3,2] row_mask:0xf bank_mask:0xf bound_ctrl:1
	v_cndmask_b32_e64 v9, v10, v9, s[6:7]
	v_cndmask_b32_e64 v10, v11, v10, s[6:7]
	s_waitcnt vmcnt(15)
	v_lshlrev_b32_e32 v15, 16, v169
	v_and_b32_e32 v8, 0xffff0000, v169
	v_mul_f32_e32 v15, 0xbfb8aa3b, v15
	v_mul_f32_e32 v8, 0xbfb8aa3b, v8
	v_exp_f32_e32 v15, v15
	v_exp_f32_e32 v8, v8
	v_add_f32_e32 v11, 1.0, v15
	v_add_f32_e32 v8, 1.0, v8
	v_div_scale_f32 v15, s[0:1], v11, v11, 1.0
	v_div_scale_f32 v20, s[0:1], v8, v8, 1.0
	v_rcp_f32_e32 v21, v15
	v_rcp_f32_e32 v22, v20
	v_div_scale_f32 v19, vcc, 1.0, v11, 1.0
	v_fma_f32 v24, -v15, v21, 1.0
	v_fma_f32 v25, -v20, v22, 1.0
	v_fmac_f32_e32 v21, v24, v21
	v_div_scale_f32 v23, s[0:1], 1.0, v8, 1.0
	v_fmac_f32_e32 v22, v25, v22
	v_mul_f32_e32 v24, v19, v21
	v_mul_f32_e32 v25, v23, v22
	v_fma_f32 v26, -v15, v24, v19
	v_fma_f32 v27, -v20, v25, v23
	v_fmac_f32_e32 v24, v26, v21
	v_fmac_f32_e32 v25, v27, v22
	v_fma_f32 v15, -v15, v24, v19
	v_fma_f32 v19, -v20, v25, v23
	v_div_fmas_f32 v15, v15, v21, v24
	s_mov_b64 vcc, s[0:1]
	v_div_fixup_f32 v11, v15, v11, 1.0
	v_div_fmas_f32 v15, v19, v22, v25
	v_div_fixup_f32 v8, v15, v8, 1.0
	v_mul_f32_e32 v9, v9, v11
	v_mul_f32_e32 v8, v10, v8
	v_cvt_pk_bf16_f32 v8, v9, v8
	global_store_dword v13, v8, s[10:11]
	s_nop 0
	v_cndmask_b32_e64 v9, v4, v6, s[6:7]
	v_add_u32_e32 v10, v16, v118
	v_add_lshl_u32 v11, v17, v122, 1
	v_mov_b32_dpp v9, v9 quad_perm:[1,0,3,2] row_mask:0xf bank_mask:0xf bound_ctrl:1
	v_cndmask_b32_e64 v4, v9, v4, s[6:7]
	v_cndmask_b32_e64 v6, v6, v9, s[6:7]
	s_waitcnt vmcnt(15)
; DEVINL float bflo(unsigned u) { return __uint_as_float(u << 16); }
; DEVINL float bfhi(unsigned u) { return __uint_as_float(u & 0xffff0000u); }
; DEVINL float sigm(float x) { return 1.f / (1.f + __expf(-x)); }
; template <int EPI, bool GATHER>
; DEVINL void gemm_tile(const Params& p, const u16* __restrict__ A, int lda, const int* __restrict__ rowidx,
;                       const u16* __restrict__ Bt, int ldb, int K, int brow, int bcol, int orow, int ocol) {
;     ...
;           f32x4 v = acc[ai][bj][m][n];
;           if (EPI == EPI_HID) {
; #pragma unroll
;             for (int j = 0; j < 4; ++j) { const float a1 = acc[ai][0][m][n][j], a3 = acc[ai][1][m][n][j]; v[j] = a1 * sigm(a1) * a3; }
;           }
;           float lo[2], hi[2];
;           xchg_pairs(v, odd, lo, hi);
; #pragma unroll
;           for (int k = 0; k < 2; ++k) {
;             const unsigned row = (unsigned)(rA + k);
;             if (EPI == EPI_HID) {
;               *(unsigned*)(ws + O_HID + (row * 1024u + (unsigned)(colp + cc)) * 2u) = pk2(lo[k], hi[k]);
;             } else if (EPI == EPI_COLS) {
;               *(unsigned*)(ws + O_COLS + (row * (unsigned)NCP + (unsigned)(colp + cc)) * 2u) = pk2(lo[k], hi[k]);
;             } else if (EPI == EPI_MOE2) {
;               *(unsigned*)(ws + O_EO + (row * 2048u + (unsigned)(colp + cc)) * 2u) = pk2(gate[k] * lo[k], gate[k] * hi[k]);
;             } else if (EPI == EPI_M1) {
;               const unsigned g2 = *(const unsigned*)(ws + O_COLS + (row * (unsigned)NCP + (unsigned)(C_GG + colp + cc)) * 2u);
;               *(unsigned*)(ws + O_M1 + (row * 2048u + (unsigned)(colp + cc)) * 2u) = pk2(sigm(bflo(g2)) * lo[k], sigm(bfhi(g2)) * hi[k]);
; DEVINL void phase5(const Params& p) {
;     ...
;   for (int t = blockIdx.x; t < 256; t += gridDim.x) {
;     int pm = t & 31, pn = t >> 5;
;     gemm_tile<EPI_M1, false>(p, A1, 1024, nullptr, B1, 1024, 1024, pm * 256, pn * 256, pm * 256, pn * 256);
;   }
	v_lshlrev_b32_e32 v13, 16, v170
	v_and_b32_e32 v8, 0xffff0000, v170
	v_mul_f32_e32 v13, 0xbfb8aa3b, v13
	v_mul_f32_e32 v8, 0xbfb8aa3b, v8
	v_exp_f32_e32 v13, v13
	v_exp_f32_e32 v8, v8
	v_add_f32_e32 v9, 1.0, v13
	v_add_f32_e32 v8, 1.0, v8
	v_div_scale_f32 v13, s[0:1], v9, v9, 1.0
	v_div_scale_f32 v15, s[0:1], v8, v8, 1.0
	v_rcp_f32_e32 v19, v13
	v_rcp_f32_e32 v20, v15
	v_div_scale_f32 v14, vcc, 1.0, v9, 1.0
	v_fma_f32 v22, -v13, v19, 1.0
	v_fma_f32 v23, -v15, v20, 1.0
	v_fmac_f32_e32 v19, v22, v19
	v_div_scale_f32 v21, s[0:1], 1.0, v8, 1.0
	v_fmac_f32_e32 v20, v23, v20
	v_mul_f32_e32 v22, v14, v19
	v_mul_f32_e32 v23, v21, v20
	v_fma_f32 v24, -v13, v22, v14
	v_fma_f32 v25, -v15, v23, v21
	v_fmac_f32_e32 v22, v24, v19
	v_fmac_f32_e32 v23, v25, v20
	v_fma_f32 v13, -v13, v22, v14
	v_fma_f32 v14, -v15, v23, v21
	v_div_fmas_f32 v13, v13, v19, v22
	s_mov_b64 vcc, s[0:1]
	v_div_fixup_f32 v9, v13, v9, 1.0
	v_div_fmas_f32 v13, v14, v20, v23
	v_div_fixup_f32 v8, v13, v8, 1.0
	v_mul_f32_e32 v4, v4, v9
	v_mul_f32_e32 v6, v6, v8
	v_cvt_pk_bf16_f32 v4, v4, v6
	global_store_dword v10, v4, s[10:11]
	s_nop 0
	v_cndmask_b32_e64 v6, v5, v7, s[6:7]
	v_add_lshl_u32 v9, v18, v116, 1
	v_add_u32_e32 v8, v12, v118
	v_mov_b32_dpp v6, v6 quad_perm:[1,0,3,2] row_mask:0xf bank_mask:0xf bound_ctrl:1
	v_cndmask_b32_e64 v5, v6, v5, s[6:7]
	v_cndmask_b32_e64 v6, v7, v6, s[6:7]
	s_waitcnt vmcnt(15)
	v_lshlrev_b32_e32 v10, 16, v171
	v_and_b32_e32 v4, 0xffff0000, v171
	v_mul_f32_e32 v10, 0xbfb8aa3b, v10
	v_mul_f32_e32 v4, 0xbfb8aa3b, v4
	v_exp_f32_e32 v10, v10
	v_exp_f32_e32 v4, v4
	v_add_f32_e32 v7, 1.0, v10
	v_add_f32_e32 v4, 1.0, v4
	v_div_scale_f32 v10, s[0:1], v7, v7, 1.0
	v_div_scale_f32 v13, s[0:1], v4, v4, 1.0
	v_rcp_f32_e32 v14, v10
	v_rcp_f32_e32 v15, v13
	v_div_scale_f32 v11, vcc, 1.0, v7, 1.0
	v_fma_f32 v19, -v10, v14, 1.0
	v_fma_f32 v20, -v13, v15, 1.0
	v_fmac_f32_e32 v14, v19, v14
	v_div_scale_f32 v18, s[0:1], 1.0, v4, 1.0
	v_fmac_f32_e32 v15, v20, v15
	v_mul_f32_e32 v19, v11, v14
	v_mul_f32_e32 v20, v18, v15
	v_fma_f32 v21, -v10, v19, v11
	v_fma_f32 v22, -v13, v20, v18
	v_fmac_f32_e32 v19, v21, v14
	v_fmac_f32_e32 v20, v22, v15
	v_fma_f32 v10, -v10, v19, v11
	v_fma_f32 v11, -v13, v20, v18
	v_div_fmas_f32 v10, v10, v14, v19
	s_mov_b64 vcc, s[0:1]
	v_div_fixup_f32 v7, v10, v7, 1.0
	v_div_fmas_f32 v10, v11, v15, v20
	v_div_fixup_f32 v4, v10, v4, 1.0
	v_mul_f32_e32 v5, v5, v7
	v_mul_f32_e32 v4, v6, v4
	v_cvt_pk_bf16_f32 v4, v5, v4
	global_store_dword v8, v4, s[10:11]
	s_nop 0
	v_cndmask_b32_e64 v5, v0, v2, s[6:7]
	v_add_u32_e32 v6, v16, v112
	v_add_lshl_u32 v7, v17, v116, 1
	v_mov_b32_dpp v5, v5 quad_perm:[1,0,3,2] row_mask:0xf bank_mask:0xf bound_ctrl:1
	v_cndmask_b32_e64 v0, v5, v0, s[6:7]
	v_cndmask_b32_e64 v2, v2, v5, s[6:7]
	s_waitcnt vmcnt(15)
	v_lshlrev_b32_e32 v8, 16, v172
	v_and_b32_e32 v4, 0xffff0000, v172
	v_mul_f32_e32 v8, 0xbfb8aa3b, v8
	v_mul_f32_e32 v4, 0xbfb8aa3b, v4
	v_exp_f32_e32 v8, v8
	v_exp_f32_e32 v4, v4
	v_add_f32_e32 v5, 1.0, v8
	v_add_f32_e32 v4, 1.0, v4
	v_div_scale_f32 v8, s[0:1], v5, v5, 1.0
	v_div_scale_f32 v10, s[0:1], v4, v4, 1.0
	v_rcp_f32_e32 v11, v8
	v_rcp_f32_e32 v13, v10
	v_div_scale_f32 v9, vcc, 1.0, v5, 1.0
	v_fma_f32 v15, -v8, v11, 1.0
	v_fma_f32 v16, -v10, v13, 1.0
	v_fmac_f32_e32 v11, v15, v11
	v_div_scale_f32 v14, s[0:1], 1.0, v4, 1.0
	v_fmac_f32_e32 v13, v16, v13
	v_mul_f32_e32 v15, v9, v11
	v_mul_f32_e32 v16, v14, v13
	v_fma_f32 v17, -v8, v15, v9
	v_fma_f32 v18, -v10, v16, v14
	v_fmac_f32_e32 v15, v17, v11
	v_fmac_f32_e32 v16, v18, v13
	v_fma_f32 v8, -v8, v15, v9
	v_fma_f32 v9, -v10, v16, v14
	v_div_fmas_f32 v8, v8, v11, v15
	s_mov_b64 vcc, s[0:1]
	v_div_fixup_f32 v5, v8, v5, 1.0
	v_div_fmas_f32 v8, v9, v13, v16
	v_div_fixup_f32 v4, v8, v4, 1.0
	v_mul_f32_e32 v0, v0, v5
	v_mul_f32_e32 v2, v2, v4
	v_cvt_pk_bf16_f32 v0, v0, v2
	global_store_dword v6, v0, s[10:11]
	s_nop 0
	v_cndmask_b32_e64 v2, v1, v3, s[6:7]
	s_waitcnt vmcnt(15)
	v_lshlrev_b32_e32 v4, 16, v173
	v_and_b32_e32 v0, 0xffff0000, v173
	v_mul_f32_e32 v4, 0xbfb8aa3b, v4
	v_mul_f32_e32 v0, 0xbfb8aa3b, v0
	v_exp_f32_e32 v4, v4
	v_exp_f32_e32 v0, v0
	v_mov_b32_dpp v2, v2 quad_perm:[1,0,3,2] row_mask:0xf bank_mask:0xf bound_ctrl:1
	v_cndmask_b32_e64 v1, v2, v1, s[6:7]
	v_cndmask_b32_e64 v2, v3, v2, s[6:7]
	v_add_f32_e32 v3, 1.0, v4
	v_add_f32_e32 v0, 1.0, v0
	v_div_scale_f32 v4, s[0:1], v3, v3, 1.0
	v_div_scale_f32 v6, s[0:1], v0, v0, 1.0
	v_rcp_f32_e32 v7, v4
	v_rcp_f32_e32 v8, v6
	v_div_scale_f32 v5, vcc, 1.0, v3, 1.0
	v_fma_f32 v10, -v4, v7, 1.0
	v_fma_f32 v11, -v6, v8, 1.0
	v_fmac_f32_e32 v7, v10, v7
	v_div_scale_f32 v9, s[0:1], 1.0, v0, 1.0
	v_fmac_f32_e32 v8, v11, v8
	v_mul_f32_e32 v10, v5, v7
	v_mul_f32_e32 v11, v9, v8
	v_fma_f32 v13, -v4, v10, v5
	v_fma_f32 v14, -v6, v11, v9
	v_fmac_f32_e32 v10, v13, v7
	v_fmac_f32_e32 v11, v14, v8
	v_fma_f32 v4, -v4, v10, v5
	v_fma_f32 v5, -v6, v11, v9
	v_div_fmas_f32 v4, v4, v7, v10
	s_mov_b64 vcc, s[0:1]
	v_div_fixup_f32 v3, v4, v3, 1.0
	v_div_fmas_f32 v4, v5, v8, v11
	v_div_fixup_f32 v0, v4, v0, 1.0
	v_mul_f32_e32 v1, v1, v3
	v_mul_f32_e32 v0, v2, v0
	v_cvt_pk_bf16_f32 v0, v1, v0
	v_add_u32_e32 v1, v12, v112
	global_store_dword v1, v0, s[10:11]
	s_add_i32 s53, s53, s94
	s_add_i32 s51, s51, s40
	s_add_i32 s50, s50, s60
	s_cmpk_lt_i32 s53, 0x100
	s_barrier
	s_cbranch_scc0 .LBB0_616

; DEVINL float bflo(unsigned u) { return __uint_as_float(u << 16); }
; template <int EPI, bool GATHER>
; DEVINL void gemm_tile(const Params& p, const u16* __restrict__ A, int lda, const int* __restrict__ rowidx,
;                       const u16* __restrict__ Bt, int ldb, int K, int brow, int bcol, int orow, int ocol) {
;     ...
;   const int row0 = orow + wr * 64 + fq * 4;
;   const int col0 = ocol + wc * 32 + fr;
;   const bool odd = (fr & 1) != 0;
;   const int colp = col0 - (odd ? 1 : 0);
; #pragma unroll
;   for (int ai = 0; ai < 2; ++ai)
; #pragma unroll
;     for (int m = 0; m < 4; ++m) {
;       const int rA = row0 + ai * HALF + m * 16 + (odd ? 2 : 0);
;       float gate[2] = {0.f, 0.f};
;       if (EPI == EPI_MOE2) { gate[0] = ((const float*)(ws + O_SELG))[rA]; gate[1] = ((const float*)(ws + O_SELG))[rA + 1]; }
; #pragma unroll
;       for (int bj = 0; bj < (EPI == EPI_HID ? 1 : 2); ++bj)
; #pragma unroll
;         for (int n = 0; n < 2; ++n) {
;           const int cc = bj * HALF + n * 16;
;           f32x4 v = acc[ai][bj][m][n];
;           if (EPI == EPI_HID) {
; #pragma unroll
;             for (int j = 0; j < 4; ++j) { const float a1 = acc[ai][0][m][n][j], a3 = acc[ai][1][m][n][j]; v[j] = a1 * sigm(a1) * a3; }
;           }
;           float lo[2], hi[2];
;           xchg_pairs(v, odd, lo, hi);
; #pragma unroll
;           for (int k = 0; k < 2; ++k) {
;             const unsigned row = (unsigned)(rA + k);
;             if (EPI == EPI_HID) {
;               *(unsigned*)(ws + O_HID + (row * 1024u + (unsigned)(colp + cc)) * 2u) = pk2(lo[k], hi[k]);
;             } else if (EPI == EPI_COLS) {
;               *(unsigned*)(ws + O_COLS + (row * (unsigned)NCP + (unsigned)(colp + cc)) * 2u) = pk2(lo[k], hi[k]);
;             } else if (EPI == EPI_MOE2) {
;               *(unsigned*)(ws + O_EO + (row * 2048u + (unsigned)(colp + cc)) * 2u) = pk2(gate[k] * lo[k], gate[k] * hi[k]);
;             } else if (EPI == EPI_M1) {
;               const unsigned g2 = *(const unsigned*)(ws + O_COLS + (row * (unsigned)NCP + (unsigned)(C_GG + colp + cc)) * 2u);
;               *(unsigned*)(ws + O_M1 + (row * 2048u + (unsigned)(colp + cc)) * 2u) = pk2(sigm(bflo(g2)) * lo[k], sigm(bfhi(g2)) * hi[k]);
;             } else if (EPI == EPI_MERGED) {
;               const unsigned g2 = *(const unsigned*)(ws + O_COLS + (row * (unsigned)NCP + (unsigned)(C_GR + colp + cc)) * 2u);
.LBB0_617:
	s_or_b64 exec, exec, s[6:7]
	v_and_b32_e32 v184, 1, v141
	v_or_b32_e32 v185, s0, v143
	v_sub_u32_e32 v185, v185, v184
	v_add_u32_e32 v186, s56, v145
	v_lshlrev_b32_e32 v187, 2, v144
	v_lshl_add_u32 v188, v142, 5, v185
	v_lshlrev_b32_e32 v185, 1, v184
	v_or3_b32 v222, v186, v185, v187
	v_add_u32_e32 v185, 0x2160, v188
	v_mul_lo_u32 v223, v222, s51
	v_add_lshl_u32 v186, v223, v185, 1
	global_load_dword v152, v186, s[8:9]
	v_lshlrev_b32_e32 v186, 1, v188
	v_lshlrev_b32_e32 v187, 12, v222
	v_add_u32_e32 v224, v187, v186
	global_load_dword v153, v224, s[10:11]
	v_add_u32_e32 v225, 0x2a00, v223
	v_add_lshl_u32 v226, v225, v185, 1
	global_load_dword v154, v226, s[8:9]
	v_or_b32_e32 v184, 0x1000, v187
	v_add_u32_e32 v224, v184, v186
	global_load_dword v155, v224, s[10:11]
	v_add_u32_e32 v226, 0x2170, v188
	v_add_lshl_u32 v227, v223, v226, 1
	global_load_dword v156, v227, s[8:9]
	v_add_u32_e32 v227, 32, v186
	v_add_u32_e32 v224, v187, v227
	global_load_dword v157, v224, s[10:11]
	v_add_lshl_u32 v228, v225, v226, 1
	v_add_u32_e32 v229, v184, v227
	global_load_dword v158, v228, s[8:9]
	global_load_dword v159, v229, s[10:11]
	v_add_u32_e32 v228, 0x21e0, v188
	v_add_lshl_u32 v230, v223, v228, 1
	global_load_dword v160, v230, s[8:9]
	v_add_u32_e32 v230, 0x100, v186
	v_add_u32_e32 v229, v187, v230
	global_load_dword v161, v229, s[10:11]
	v_add_lshl_u32 v231, v225, v228, 1
	v_add_u32_e32 v232, v184, v230
	global_load_dword v162, v231, s[8:9]
	global_load_dword v163, v232, s[10:11]
	v_add_u32_e32 v231, 0x21f0, v188
	v_add_lshl_u32 v233, v223, v231, 1
	global_load_dword v164, v233, s[8:9]
	v_add_u32_e32 v233, 0x120, v186
	v_add_u32_e32 v234, v187, v233
	global_load_dword v165, v234, s[10:11]
	v_add_lshl_u32 v235, v225, v231, 1
	v_add_u32_e32 v236, v184, v233
	global_load_dword v166, v235, s[8:9]
	global_load_dword v167, v236, s[10:11]
	v_and_b32_e32 v184, 1, v141
	v_or_b32_e32 v185, s0, v143
	v_sub_u32_e32 v185, v185, v184
	v_add_u32_e32 v186, s56, v145
	v_lshlrev_b32_e32 v187, 2, v144
	v_lshl_add_u32 v188, v142, 5, v185
	v_lshlrev_b32_e32 v185, 1, v184
	v_or3_b32 v222, v186, v185, v187
	v_add_u32_e32 v185, 0x2160, v188
	v_lshlrev_b32_e32 v186, 1, v188
	v_lshlrev_b32_e32 v187, 12, v222
	v_add_u32_e32 v223, 0x2170, v188
	v_add_u32_e32 v224, 32, v186
	v_add_u32_e32 v225, 0x21e0, v188
	v_add_u32_e32 v226, 0x100, v186
	v_add_u32_e32 v227, 0x21f0, v188
	v_add_u32_e32 v228, 0x120, v186
	v_or_b32_e32 v229, 16, v222
	v_mul_lo_u32 v230, v229, s51
	v_add_lshl_u32 v231, v230, v185, 1
	global_load_dword v190, v231, s[8:9]
	v_lshlrev_b32_e32 v229, 12, v229
	v_add_u32_e32 v232, v229, v186
	global_load_dword v191, v232, s[10:11]
	v_add_u32_e32 v233, 0x2a00, v230
	v_add_lshl_u32 v234, v233, v185, 1
	global_load_dword v192, v234, s[8:9]
	v_or_b32_e32 v234, 0x11000, v187
	v_add_u32_e32 v232, v234, v186
	global_load_dword v193, v232, s[10:11]
	v_add_lshl_u32 v235, v230, v223, 1
	global_load_dword v194, v235, s[8:9]
	v_add_u32_e32 v236, v229, v224
	global_load_dword v195, v236, s[10:11]
	v_add_lshl_u32 v237, v233, v223, 1
	v_add_u32_e32 v235, v234, v224
	global_load_dword v196, v237, s[8:9]
	global_load_dword v197, v235, s[10:11]
	v_add_lshl_u32 v238, v230, v225, 1
	global_load_dword v198, v238, s[8:9]
	v_add_u32_e32 v235, v229, v226
	global_load_dword v199, v235, s[10:11]
	v_add_lshl_u32 v239, v233, v225, 1
	v_add_u32_e32 v240, v234, v226
	global_load_dword v200, v239, s[8:9]
	global_load_dword v201, v240, s[10:11]
	v_add_lshl_u32 v241, v230, v227, 1
	global_load_dword v202, v241, s[8:9]
	v_add_u32_e32 v240, v229, v228
	global_load_dword v203, v240, s[10:11]
	v_add_lshl_u32 v242, v233, v227, 1
	v_add_u32_e32 v243, v234, v228
	global_load_dword v204, v242, s[8:9]
	global_load_dword v205, v243, s[10:11]
	v_and_b32_e32 v133, 1, v141
	v_or_b32_e32 v130, s0, v143
	v_sub_u32_e32 v130, v130, v133
	v_add_u32_e32 v128, s56, v145
	v_lshlrev_b32_e32 v129, 2, v144
	v_lshl_add_u32 v141, v142, 5, v130
	v_lshlrev_b32_e32 v130, 1, v133
	v_or3_b32 v132, v128, v130, v129
	v_add_u32_e32 v130, 0x2160, v141
	v_mul_lo_u32 v131, v132, s51
	v_add_lshl_u32 v128, v131, v130, 1
	s_nop 0
	v_lshlrev_b32_e32 v128, 1, v141
	v_lshlrev_b32_e32 v129, 12, v132
	v_add_u32_e32 v142, v129, v128
	s_nop 0
	v_cmp_eq_u32_e64 s[6:7], 0, v133
	s_waitcnt vmcnt(30)
	v_lshlrev_b32_e32 v138, 16, v153
	v_cndmask_b32_e64 v133, v124, v126, s[6:7]
	v_and_b32_e32 v139, 0xffff0000, v153
	s_nop 0
	v_mov_b32_dpp v133, v133 quad_perm:[1,0,3,2] row_mask:0xf bank_mask:0xf bound_ctrl:1
	v_cndmask_b32_e64 v135, v126, v133, s[6:7]
	v_cndmask_b32_e64 v134, v133, v124, s[6:7]
	v_lshlrev_b32_e32 v124, 16, v152
	v_and_b32_e32 v133, 0xffff0000, v152
	v_mul_f32_e32 v124, 0xbfb8aa3b, v124
	v_mul_f32_e32 v133, 0xbfb8aa3b, v133
	v_exp_f32_e32 v136, v124
	v_exp_f32_e32 v137, v133
	v_add_u32_e32 v126, 0x2a00, v131
	v_add_lshl_u32 v124, v126, v130, 1
	v_pk_add_f32 v[136:137], v[136:137], 1.0 op_sel_hi:[1,0]
	s_nop 0
	v_div_scale_f32 v133, s[0:1], v137, v137, 1.0
	v_div_scale_f32 v144, s[0:1], v136, v136, 1.0
	v_rcp_f32_e32 v145, v133
	v_rcp_f32_e32 v146, v144
	v_div_scale_f32 v143, vcc, 1.0, v137, 1.0
	v_fma_f32 v148, -v133, v145, 1.0
	v_fma_f32 v149, -v144, v146, 1.0
	v_fmac_f32_e32 v145, v148, v145
	v_div_scale_f32 v147, s[0:1], 1.0, v136, 1.0
	v_fmac_f32_e32 v146, v149, v146
	v_mul_f32_e32 v148, v143, v145
	v_mul_f32_e32 v149, v147, v146
	v_fma_f32 v150, -v133, v148, v143
	v_fma_f32 v151, -v144, v149, v147
	v_fmac_f32_e32 v148, v150, v145
	v_fmac_f32_e32 v149, v151, v146
	v_fma_f32 v133, -v133, v148, v143
	v_fma_f32 v143, -v144, v149, v147
	v_div_fmas_f32 v133, v133, v145, v148
	s_mov_b64 vcc, s[0:1]
	v_div_fixup_f32 v137, v133, v137, 1.0
	v_div_fmas_f32 v133, v143, v146, v149
	v_div_fixup_f32 v136, v133, v136, 1.0
	v_pk_fma_f32 v[134:135], v[134:135], v[136:137], v[138:139]
	s_nop 0
	v_cvt_pk_bf16_f32 v133, v134, v135
	global_store_dword v142, v133, s[12:13]
	s_nop 0
	v_or_b32_e32 v133, 0x1000, v129
	v_add_u32_e32 v142, v133, v128
	s_nop 0
	v_cndmask_b32_e64 v124, v125, v127, s[6:7]
	s_waitcnt vmcnt(29)
; DEVINL float bflo(unsigned u) { return __uint_as_float(u << 16); }
; DEVINL float bfhi(unsigned u) { return __uint_as_float(u & 0xffff0000u); }
; DEVINL float sigm(float x) { return 1.f / (1.f + __expf(-x)); }
; template <int EPI, bool GATHER>
; DEVINL void gemm_tile(const Params& p, const u16* __restrict__ A, int lda, const int* __restrict__ rowidx,
;                       const u16* __restrict__ Bt, int ldb, int K, int brow, int bcol, int orow, int ocol) {
;     ...
;       for (int bj = 0; bj < (EPI == EPI_HID ? 1 : 2); ++bj)
; #pragma unroll
;         for (int n = 0; n < 2; ++n) {
;           const int cc = bj * HALF + n * 16;
;           f32x4 v = acc[ai][bj][m][n];
;           if (EPI == EPI_HID) {
; #pragma unroll
;             for (int j = 0; j < 4; ++j) { const float a1 = acc[ai][0][m][n][j], a3 = acc[ai][1][m][n][j]; v[j] = a1 * sigm(a1) * a3; }
;           }
;           float lo[2], hi[2];
;           xchg_pairs(v, odd, lo, hi);
; #pragma unroll
;           for (int k = 0; k < 2; ++k) {
;             const unsigned row = (unsigned)(rA + k);
;             if (EPI == EPI_HID) {
;               *(unsigned*)(ws + O_HID + (row * 1024u + (unsigned)(colp + cc)) * 2u) = pk2(lo[k], hi[k]);
;             } else if (EPI == EPI_COLS) {
;               *(unsigned*)(ws + O_COLS + (row * (unsigned)NCP + (unsigned)(colp + cc)) * 2u) = pk2(lo[k], hi[k]);
;             } else if (EPI == EPI_MOE2) {
;               *(unsigned*)(ws + O_EO + (row * 2048u + (unsigned)(colp + cc)) * 2u) = pk2(gate[k] * lo[k], gate[k] * hi[k]);
;             } else if (EPI == EPI_M1) {
;               const unsigned g2 = *(const unsigned*)(ws + O_COLS + (row * (unsigned)NCP + (unsigned)(C_GG + colp + cc)) * 2u);
;               *(unsigned*)(ws + O_M1 + (row * 2048u + (unsigned)(colp + cc)) * 2u) = pk2(sigm(bflo(g2)) * lo[k], sigm(bfhi(g2)) * hi[k]);
;             } else if (EPI == EPI_MERGED) {
;               const unsigned g2 = *(const unsigned*)(ws + O_COLS + (row * (unsigned)NCP + (unsigned)(C_GR + colp + cc)) * 2u);
;               const unsigned m1 = *(const unsigned*)(ws + O_M1 + (row * 2048u + (unsigned)(colp + cc)) * 2u);
;               *(unsigned*)(ws + O_MERGED + (row * 2048u + (unsigned)(colp + cc)) * 2u) =
;                   pk2(bflo(m1) + sigm(bflo(g2)) * lo[k], bfhi(m1) + sigm(bfhi(g2)) * hi[k]);
	v_lshlrev_b32_e32 v138, 16, v155
	v_mov_b32_dpp v134, v124 quad_perm:[1,0,3,2] row_mask:0xf bank_mask:0xf bound_ctrl:1
	v_cndmask_b32_e64 v135, v127, v134, s[6:7]
	v_cndmask_b32_e64 v134, v134, v125, s[6:7]
	v_lshlrev_b32_e32 v125, 16, v154
	v_and_b32_e32 v127, 0xffff0000, v154
	v_mul_f32_e32 v125, 0xbfb8aa3b, v125
	v_mul_f32_e32 v127, 0xbfb8aa3b, v127
	v_exp_f32_e32 v136, v125
	v_exp_f32_e32 v137, v127
	v_and_b32_e32 v139, 0xffff0000, v155
	v_add_u32_e32 v124, 0x2170, v141
	v_add_lshl_u32 v125, v131, v124, 1
	v_pk_add_f32 v[136:137], v[136:137], 1.0 op_sel_hi:[1,0]
	s_nop 0
	v_div_scale_f32 v127, s[0:1], v137, v137, 1.0
	v_div_scale_f32 v144, s[0:1], v136, v136, 1.0
	v_rcp_f32_e32 v145, v127
	v_rcp_f32_e32 v146, v144
	v_div_scale_f32 v143, vcc, 1.0, v137, 1.0
	v_fma_f32 v148, -v127, v145, 1.0
	v_fma_f32 v149, -v144, v146, 1.0
	v_fmac_f32_e32 v145, v148, v145
	v_div_scale_f32 v147, s[0:1], 1.0, v136, 1.0
	v_fmac_f32_e32 v146, v149, v146
	v_mul_f32_e32 v148, v143, v145
	v_mul_f32_e32 v149, v147, v146
	v_fma_f32 v150, -v127, v148, v143
	v_fma_f32 v151, -v144, v149, v147
	v_fmac_f32_e32 v148, v150, v145
	v_fmac_f32_e32 v149, v151, v146
	v_fma_f32 v127, -v127, v148, v143
	v_fma_f32 v143, -v144, v149, v147
	v_div_fmas_f32 v127, v127, v145, v148
	s_mov_b64 vcc, s[0:1]
	v_div_fixup_f32 v137, v127, v137, 1.0
	v_div_fmas_f32 v127, v143, v146, v149
	v_div_fixup_f32 v136, v127, v136, 1.0
	v_pk_fma_f32 v[134:135], v[134:135], v[136:137], v[138:139]
	s_nop 0
	v_cvt_pk_bf16_f32 v127, v134, v135
	global_store_dword v142, v127, s[12:13]
	s_nop 0
	v_add_u32_e32 v125, 32, v128
	v_add_u32_e32 v142, v129, v125
	s_nop 0
	v_cndmask_b32_e64 v134, v120, v122, s[6:7]
	s_waitcnt vmcnt(28)
	v_lshlrev_b32_e32 v138, 16, v157
	v_mov_b32_dpp v134, v134 quad_perm:[1,0,3,2] row_mask:0xf bank_mask:0xf bound_ctrl:1
	v_cndmask_b32_e64 v135, v122, v134, s[6:7]
	v_cndmask_b32_e64 v134, v134, v120, s[6:7]
	v_lshlrev_b32_e32 v120, 16, v156
	v_and_b32_e32 v122, 0xffff0000, v156
	v_mul_f32_e32 v120, 0xbfb8aa3b, v120
	v_mul_f32_e32 v122, 0xbfb8aa3b, v122
	v_exp_f32_e32 v136, v120
	v_exp_f32_e32 v137, v122
	v_and_b32_e32 v139, 0xffff0000, v157
	v_add_lshl_u32 v120, v126, v124, 1
	v_pk_add_f32 v[136:137], v[136:137], 1.0 op_sel_hi:[1,0]
	s_nop 0
	v_div_scale_f32 v122, s[0:1], v137, v137, 1.0
	v_div_scale_f32 v143, s[0:1], v136, v136, 1.0
	v_rcp_f32_e32 v144, v122
	v_rcp_f32_e32 v145, v143
	v_div_scale_f32 v127, vcc, 1.0, v137, 1.0
	v_fma_f32 v147, -v122, v144, 1.0
	v_fma_f32 v148, -v143, v145, 1.0
	v_fmac_f32_e32 v144, v147, v144
	v_div_scale_f32 v146, s[0:1], 1.0, v136, 1.0
	v_fmac_f32_e32 v145, v148, v145
	v_mul_f32_e32 v147, v127, v144
	v_mul_f32_e32 v148, v146, v145
	v_fma_f32 v149, -v122, v147, v127
	v_fma_f32 v150, -v143, v148, v146
	v_fmac_f32_e32 v147, v149, v144
	v_fmac_f32_e32 v148, v150, v145
	v_fma_f32 v122, -v122, v147, v127
	v_fma_f32 v127, -v143, v148, v146
	v_div_fmas_f32 v122, v122, v144, v147
	s_mov_b64 vcc, s[0:1]
	v_div_fixup_f32 v137, v122, v137, 1.0
	v_div_fmas_f32 v122, v127, v145, v148
	v_div_fixup_f32 v136, v122, v136, 1.0
	v_pk_fma_f32 v[134:135], v[134:135], v[136:137], v[138:139]
	v_add_u32_e32 v138, v133, v125
	v_cvt_pk_bf16_f32 v122, v134, v135
	global_store_dword v142, v122, s[12:13]
	s_nop 0
	s_nop 0
	v_cndmask_b32_e64 v120, v121, v123, s[6:7]
	s_waitcnt vmcnt(27)
	v_lshlrev_b32_e32 v136, 16, v159
	v_mov_b32_dpp v122, v120 quad_perm:[1,0,3,2] row_mask:0xf bank_mask:0xf bound_ctrl:1
	v_cndmask_b32_e64 v123, v123, v122, s[6:7]
	v_cndmask_b32_e64 v122, v122, v121, s[6:7]
	v_lshlrev_b32_e32 v121, 16, v158
	v_and_b32_e32 v127, 0xffff0000, v158
	v_mul_f32_e32 v121, 0xbfb8aa3b, v121
	v_mul_f32_e32 v127, 0xbfb8aa3b, v127
	v_exp_f32_e32 v134, v121
	v_exp_f32_e32 v135, v127
	v_and_b32_e32 v137, 0xffff0000, v159
	v_add_u32_e32 v120, 0x21e0, v141
	v_add_lshl_u32 v121, v131, v120, 1
	v_pk_add_f32 v[134:135], v[134:135], 1.0 op_sel_hi:[1,0]
	s_nop 0
	v_div_scale_f32 v127, s[0:1], v135, v135, 1.0
	v_div_scale_f32 v142, s[0:1], v134, v134, 1.0
	v_rcp_f32_e32 v143, v127
	v_rcp_f32_e32 v144, v142
	v_div_scale_f32 v139, vcc, 1.0, v135, 1.0
	v_fma_f32 v146, -v127, v143, 1.0
	v_fma_f32 v147, -v142, v144, 1.0
	v_fmac_f32_e32 v143, v146, v143
	v_div_scale_f32 v145, s[0:1], 1.0, v134, 1.0
	v_fmac_f32_e32 v144, v147, v144
	v_mul_f32_e32 v146, v139, v143
	v_mul_f32_e32 v147, v145, v144
	v_fma_f32 v148, -v127, v146, v139
	v_fma_f32 v149, -v142, v147, v145
	v_fmac_f32_e32 v146, v148, v143
	v_fmac_f32_e32 v147, v149, v144
	v_fma_f32 v127, -v127, v146, v139
	v_fma_f32 v139, -v142, v147, v145
	v_div_fmas_f32 v127, v127, v143, v146
	s_mov_b64 vcc, s[0:1]
	v_div_fixup_f32 v135, v127, v135, 1.0
	v_div_fmas_f32 v127, v139, v144, v147
	v_div_fixup_f32 v134, v127, v134, 1.0
	v_pk_fma_f32 v[122:123], v[122:123], v[134:135], v[136:137]
	s_nop 0
	v_cvt_pk_bf16_f32 v122, v122, v123
	global_store_dword v138, v122, s[12:13]
	s_nop 0
	v_add_u32_e32 v121, 0x100, v128
	v_add_u32_e32 v138, v129, v121
	s_nop 0
	v_cndmask_b32_e64 v122, v116, v118, s[6:7]
	s_waitcnt vmcnt(26)
; DEVINL float bflo(unsigned u) { return __uint_as_float(u << 16); }
; DEVINL float bfhi(unsigned u) { return __uint_as_float(u & 0xffff0000u); }
; DEVINL float sigm(float x) { return 1.f / (1.f + __expf(-x)); }
; template <int EPI, bool GATHER>
; DEVINL void gemm_tile(const Params& p, const u16* __restrict__ A, int lda, const int* __restrict__ rowidx,
;                       const u16* __restrict__ Bt, int ldb, int K, int brow, int bcol, int orow, int ocol) {
;     ...
;       for (int bj = 0; bj < (EPI == EPI_HID ? 1 : 2); ++bj)
; #pragma unroll
;         for (int n = 0; n < 2; ++n) {
;           const int cc = bj * HALF + n * 16;
;           f32x4 v = acc[ai][bj][m][n];
;           if (EPI == EPI_HID) {
; #pragma unroll
;             for (int j = 0; j < 4; ++j) { const float a1 = acc[ai][0][m][n][j], a3 = acc[ai][1][m][n][j]; v[j] = a1 * sigm(a1) * a3; }
;           }
;           float lo[2], hi[2];
;           xchg_pairs(v, odd, lo, hi);
; #pragma unroll
;           for (int k = 0; k < 2; ++k) {
;             const unsigned row = (unsigned)(rA + k);
;             if (EPI == EPI_HID) {
;               *(unsigned*)(ws + O_HID + (row * 1024u + (unsigned)(colp + cc)) * 2u) = pk2(lo[k], hi[k]);
;             } else if (EPI == EPI_COLS) {
;               *(unsigned*)(ws + O_COLS + (row * (unsigned)NCP + (unsigned)(colp + cc)) * 2u) = pk2(lo[k], hi[k]);
;             } else if (EPI == EPI_MOE2) {
;               *(unsigned*)(ws + O_EO + (row * 2048u + (unsigned)(colp + cc)) * 2u) = pk2(gate[k] * lo[k], gate[k] * hi[k]);
;             } else if (EPI == EPI_M1) {
;               const unsigned g2 = *(const unsigned*)(ws + O_COLS + (row * (unsigned)NCP + (unsigned)(C_GG + colp + cc)) * 2u);
;               *(unsigned*)(ws + O_M1 + (row * 2048u + (unsigned)(colp + cc)) * 2u) = pk2(sigm(bflo(g2)) * lo[k], sigm(bfhi(g2)) * hi[k]);
;             } else if (EPI == EPI_MERGED) {
;               const unsigned g2 = *(const unsigned*)(ws + O_COLS + (row * (unsigned)NCP + (unsigned)(C_GR + colp + cc)) * 2u);
;               const unsigned m1 = *(const unsigned*)(ws + O_M1 + (row * 2048u + (unsigned)(colp + cc)) * 2u);
;               *(unsigned*)(ws + O_MERGED + (row * 2048u + (unsigned)(colp + cc)) * 2u) =
;                   pk2(bflo(m1) + sigm(bflo(g2)) * lo[k], bfhi(m1) + sigm(bfhi(g2)) * hi[k]);
	v_lshlrev_b32_e32 v136, 16, v161
	v_mov_b32_dpp v122, v122 quad_perm:[1,0,3,2] row_mask:0xf bank_mask:0xf bound_ctrl:1
	v_cndmask_b32_e64 v123, v118, v122, s[6:7]
	v_cndmask_b32_e64 v122, v122, v116, s[6:7]
	v_lshlrev_b32_e32 v116, 16, v160
	v_and_b32_e32 v118, 0xffff0000, v160
	v_mul_f32_e32 v116, 0xbfb8aa3b, v116
	v_mul_f32_e32 v118, 0xbfb8aa3b, v118
	v_exp_f32_e32 v134, v116
	v_exp_f32_e32 v135, v118
	v_and_b32_e32 v137, 0xffff0000, v161
	v_add_lshl_u32 v116, v126, v120, 1
	v_pk_add_f32 v[134:135], v[134:135], 1.0 op_sel_hi:[1,0]
	s_nop 0
	v_div_scale_f32 v118, s[0:1], v135, v135, 1.0
	v_div_scale_f32 v139, s[0:1], v134, v134, 1.0
	v_rcp_f32_e32 v142, v118
	v_rcp_f32_e32 v143, v139
	v_div_scale_f32 v127, vcc, 1.0, v135, 1.0
	v_fma_f32 v145, -v118, v142, 1.0
	v_fma_f32 v146, -v139, v143, 1.0
	v_fmac_f32_e32 v142, v145, v142
	v_div_scale_f32 v144, s[0:1], 1.0, v134, 1.0
	v_fmac_f32_e32 v143, v146, v143
	v_mul_f32_e32 v145, v127, v142
	v_mul_f32_e32 v146, v144, v143
	v_fma_f32 v147, -v118, v145, v127
	v_fma_f32 v148, -v139, v146, v144
	v_fmac_f32_e32 v145, v147, v142
	v_fmac_f32_e32 v146, v148, v143
	v_fma_f32 v118, -v118, v145, v127
	v_fma_f32 v127, -v139, v146, v144
	v_div_fmas_f32 v118, v118, v142, v145
	s_mov_b64 vcc, s[0:1]
	v_div_fixup_f32 v135, v118, v135, 1.0
	v_div_fmas_f32 v118, v127, v143, v146
	v_div_fixup_f32 v134, v118, v134, 1.0
	v_pk_fma_f32 v[122:123], v[122:123], v[134:135], v[136:137]
	v_add_u32_e32 v127, v133, v121
	v_cvt_pk_bf16_f32 v118, v122, v123
	global_store_dword v138, v118, s[12:13]
	s_nop 0
	s_nop 0
	v_cndmask_b32_e64 v118, v117, v119, s[6:7]
	v_add_u32_e32 v116, 0x21f0, v141
	s_waitcnt vmcnt(25)
	v_lshlrev_b32_e32 v134, 16, v163
	v_mov_b32_dpp v118, v118 quad_perm:[1,0,3,2] row_mask:0xf bank_mask:0xf bound_ctrl:1
	v_cndmask_b32_e64 v119, v119, v118, s[6:7]
	v_cndmask_b32_e64 v118, v118, v117, s[6:7]
	v_lshlrev_b32_e32 v117, 16, v162
	v_and_b32_e32 v122, 0xffff0000, v162
	v_mul_f32_e32 v117, 0xbfb8aa3b, v117
	v_mul_f32_e32 v123, 0xbfb8aa3b, v122
	v_exp_f32_e32 v122, v117
	v_exp_f32_e32 v123, v123
	v_and_b32_e32 v135, 0xffff0000, v163
	v_add_lshl_u32 v117, v131, v116, 1
	v_pk_add_f32 v[122:123], v[122:123], 1.0 op_sel_hi:[1,0]
	s_nop 0
	v_div_scale_f32 v136, s[0:1], v123, v123, 1.0
	v_div_scale_f32 v138, s[0:1], v122, v122, 1.0
	v_rcp_f32_e32 v139, v136
	v_rcp_f32_e32 v141, v138
	v_div_scale_f32 v137, vcc, 1.0, v123, 1.0
	v_fma_f32 v143, -v136, v139, 1.0
	v_fma_f32 v144, -v138, v141, 1.0
	v_fmac_f32_e32 v139, v143, v139
	v_div_scale_f32 v142, s[0:1], 1.0, v122, 1.0
	v_fmac_f32_e32 v141, v144, v141
	v_mul_f32_e32 v143, v137, v139
	v_mul_f32_e32 v144, v142, v141
	v_fma_f32 v145, -v136, v143, v137
	v_fma_f32 v146, -v138, v144, v142
	v_fmac_f32_e32 v143, v145, v139
	v_fmac_f32_e32 v144, v146, v141
	v_fma_f32 v136, -v136, v143, v137
	v_fma_f32 v137, -v138, v144, v142
	v_div_fmas_f32 v136, v136, v139, v143
	s_mov_b64 vcc, s[0:1]
	v_div_fixup_f32 v123, v136, v123, 1.0
	v_div_fmas_f32 v136, v137, v141, v144
	v_div_fixup_f32 v122, v136, v122, 1.0
	v_pk_fma_f32 v[118:119], v[118:119], v[122:123], v[134:135]
	s_nop 0
	v_cvt_pk_bf16_f32 v118, v118, v119
	global_store_dword v127, v118, s[12:13]
	s_nop 0
	v_add_u32_e32 v117, 0x120, v128
	v_add_u32_e32 v134, v129, v117
	s_nop 0
	v_cndmask_b32_e64 v118, v112, v114, s[6:7]
	s_nop 1
	v_mov_b32_dpp v118, v118 quad_perm:[1,0,3,2] row_mask:0xf bank_mask:0xf bound_ctrl:1
	v_cndmask_b32_e64 v119, v114, v118, s[6:7]
	v_cndmask_b32_e64 v118, v118, v112, s[6:7]
	s_waitcnt vmcnt(24)
	v_lshlrev_b32_e32 v112, 16, v164
	v_and_b32_e32 v114, 0xffff0000, v164
	v_mul_f32_e32 v112, 0xbfb8aa3b, v112
	v_mul_f32_e32 v114, 0xbfb8aa3b, v114
	v_exp_f32_e32 v122, v112
	v_exp_f32_e32 v123, v114
	v_add_lshl_u32 v112, v126, v116, 1
	s_waitcnt vmcnt(24)
	v_lshlrev_b32_e32 v126, 16, v165
	v_and_b32_e32 v127, 0xffff0000, v165
	v_pk_add_f32 v[122:123], v[122:123], 1.0 op_sel_hi:[1,0]
	s_nop 0
	v_div_scale_f32 v114, s[0:1], v123, v123, 1.0
	v_div_scale_f32 v136, s[0:1], v122, v122, 1.0
	v_rcp_f32_e32 v137, v114
	v_rcp_f32_e32 v138, v136
	v_div_scale_f32 v135, vcc, 1.0, v123, 1.0
	v_fma_f32 v141, -v114, v137, 1.0
	v_fma_f32 v142, -v136, v138, 1.0
	v_fmac_f32_e32 v137, v141, v137
	v_div_scale_f32 v139, s[0:1], 1.0, v122, 1.0
	v_fmac_f32_e32 v138, v142, v138
	v_mul_f32_e32 v141, v135, v137
	v_mul_f32_e32 v142, v139, v138
	v_fma_f32 v143, -v114, v141, v135
	v_fma_f32 v144, -v136, v142, v139
	v_fmac_f32_e32 v141, v143, v137
	v_fmac_f32_e32 v142, v144, v138
	v_fma_f32 v114, -v114, v141, v135
	v_fma_f32 v135, -v136, v142, v139
	v_div_fmas_f32 v114, v114, v137, v141
	s_mov_b64 vcc, s[0:1]
	v_div_fixup_f32 v123, v114, v123, 1.0
	v_div_fmas_f32 v114, v135, v138, v142
	v_div_fixup_f32 v122, v114, v122, 1.0
	v_pk_fma_f32 v[118:119], v[118:119], v[122:123], v[126:127]
	v_add_u32_e32 v122, v133, v117
	v_cvt_pk_bf16_f32 v114, v118, v119
	global_store_dword v134, v114, s[12:13]
	s_nop 0
	v_cndmask_b32_e64 v114, v113, v115, s[6:7]
	s_nop 0
	s_waitcnt vmcnt(23)
	v_lshlrev_b32_e32 v118, 16, v166
	v_and_b32_e32 v112, 0xffff0000, v166
	v_mul_f32_e32 v118, 0xbfb8aa3b, v118
	v_mul_f32_e32 v112, 0xbfb8aa3b, v112
	v_exp_f32_e32 v118, v118
	v_exp_f32_e32 v119, v112
	v_mov_b32_dpp v114, v114 quad_perm:[1,0,3,2] row_mask:0xf bank_mask:0xf bound_ctrl:1
	v_cndmask_b32_e64 v115, v115, v114, s[6:7]
	v_cndmask_b32_e64 v114, v114, v113, s[6:7]
	v_pk_add_f32 v[118:119], v[118:119], 1.0 op_sel_hi:[1,0]
	s_waitcnt vmcnt(23)
; template <int EPI, bool GATHER>
; DEVINL void gemm_tile(const Params& p, const u16* __restrict__ A, int lda, const int* __restrict__ rowidx,
;                       const u16* __restrict__ Bt, int ldb, int K, int brow, int bcol, int orow, int ocol) {
;     ...
;     for (int m = 0; m < 4; ++m) {
;       const int rA = row0 + ai * HALF + m * 16 + (odd ? 2 : 0);
;       float gate[2] = {0.f, 0.f};
;       if (EPI == EPI_MOE2) { gate[0] = ((const float*)(ws + O_SELG))[rA]; gate[1] = ((const float*)(ws + O_SELG))[rA + 1]; }
; #pragma unroll
;       for (int bj = 0; bj < (EPI == EPI_HID ? 1 : 2); ++bj)
; #pragma unroll
;         for (int n = 0; n < 2; ++n) {
;           const int cc = bj * HALF + n * 16;
;           f32x4 v = acc[ai][bj][m][n];
;           if (EPI == EPI_HID) {
; #pragma unroll
;             for (int j = 0; j < 4; ++j) { const float a1 = acc[ai][0][m][n][j], a3 = acc[ai][1][m][n][j]; v[j] = a1 * sigm(a1) * a3; }
;           }
;           float lo[2], hi[2];
;           xchg_pairs(v, odd, lo, hi);
; #pragma unroll
;           for (int k = 0; k < 2; ++k) {
;             const unsigned row = (unsigned)(rA + k);
;             if (EPI == EPI_HID) {
;               *(unsigned*)(ws + O_HID + (row * 1024u + (unsigned)(colp + cc)) * 2u) = pk2(lo[k], hi[k]);
;             } else if (EPI == EPI_COLS) {
;               *(unsigned*)(ws + O_COLS + (row * (unsigned)NCP + (unsigned)(colp + cc)) * 2u) = pk2(lo[k], hi[k]);
;             } else if (EPI == EPI_MOE2) {
;               *(unsigned*)(ws + O_EO + (row * 2048u + (unsigned)(colp + cc)) * 2u) = pk2(gate[k] * lo[k], gate[k] * hi[k]);
;             } else if (EPI == EPI_M1) {
;               const unsigned g2 = *(const unsigned*)(ws + O_COLS + (row * (unsigned)NCP + (unsigned)(C_GG + colp + cc)) * 2u);
;               *(unsigned*)(ws + O_M1 + (row * 2048u + (unsigned)(colp + cc)) * 2u) = pk2(sigm(bflo(g2)) * lo[k], sigm(bfhi(g2)) * hi[k]);
;             } else if (EPI == EPI_MERGED) {
;               const unsigned g2 = *(const unsigned*)(ws + O_COLS + (row * (unsigned)NCP + (unsigned)(C_GR + colp + cc)) * 2u);
;               const unsigned m1 = *(const unsigned*)(ws + O_M1 + (row * 2048u + (unsigned)(colp + cc)) * 2u);
;               *(unsigned*)(ws + O_MERGED + (row * 2048u + (unsigned)(colp + cc)) * 2u) =
;                   pk2(bflo(m1) + sigm(bflo(g2)) * lo[k], bfhi(m1) + sigm(bfhi(g2)) * hi[k]);
	v_lshlrev_b32_e32 v112, 16, v167
	v_and_b32_e32 v113, 0xffff0000, v167
	v_div_scale_f32 v123, s[0:1], v119, v119, 1.0
	v_div_scale_f32 v127, s[0:1], v118, v118, 1.0
	v_rcp_f32_e32 v133, v123
	v_rcp_f32_e32 v134, v127
	v_div_scale_f32 v126, vcc, 1.0, v119, 1.0
	v_fma_f32 v136, -v123, v133, 1.0
	v_fma_f32 v137, -v127, v134, 1.0
	v_fmac_f32_e32 v133, v136, v133
	v_div_scale_f32 v135, s[0:1], 1.0, v118, 1.0
	v_fmac_f32_e32 v134, v137, v134
	v_mul_f32_e32 v136, v126, v133
	v_mul_f32_e32 v137, v135, v134
	v_fma_f32 v138, -v123, v136, v126
	v_fma_f32 v139, -v127, v137, v135
	v_fmac_f32_e32 v136, v138, v133
	v_fmac_f32_e32 v137, v139, v134
	v_fma_f32 v123, -v123, v136, v126
	v_fma_f32 v126, -v127, v137, v135
	v_div_fmas_f32 v123, v123, v133, v136
	s_mov_b64 vcc, s[0:1]
	v_div_fixup_f32 v119, v123, v119, 1.0
	v_div_fmas_f32 v123, v126, v134, v137
	v_div_fixup_f32 v118, v123, v118, 1.0
	v_pk_fma_f32 v[112:113], v[114:115], v[118:119], v[112:113]
	s_nop 0
	v_cvt_pk_bf16_f32 v112, v112, v113
	global_store_dword v122, v112, s[12:13]
	v_or_b32_e32 v184, 32, v132
	v_mul_lo_u32 v185, v184, s51
	v_add_lshl_u32 v186, v185, v130, 1
	global_load_dword v152, v186, s[8:9]
	v_lshlrev_b32_e32 v184, 12, v184
	v_add_u32_e32 v187, v184, v128
	global_load_dword v153, v187, s[10:11]
	v_add_u32_e32 v188, 0x2a00, v185
	v_add_lshl_u32 v222, v188, v130, 1
	global_load_dword v154, v222, s[8:9]
	v_or_b32_e32 v222, 0x21000, v129
	v_add_u32_e32 v187, v222, v128
	global_load_dword v155, v187, s[10:11]
	v_add_lshl_u32 v223, v185, v124, 1
	global_load_dword v156, v223, s[8:9]
	v_add_u32_e32 v224, v184, v125
	global_load_dword v157, v224, s[10:11]
	v_add_lshl_u32 v225, v188, v124, 1
	v_add_u32_e32 v223, v222, v125
	global_load_dword v158, v225, s[8:9]
	global_load_dword v159, v223, s[10:11]
	v_add_lshl_u32 v226, v185, v120, 1
	global_load_dword v160, v226, s[8:9]
	v_add_u32_e32 v223, v184, v121
	global_load_dword v161, v223, s[10:11]
	v_add_lshl_u32 v227, v188, v120, 1
	v_add_u32_e32 v228, v222, v121
	global_load_dword v162, v227, s[8:9]
	global_load_dword v163, v228, s[10:11]
	v_add_lshl_u32 v229, v185, v116, 1
	global_load_dword v164, v229, s[8:9]
	v_add_u32_e32 v228, v184, v117
	global_load_dword v165, v228, s[10:11]
	v_add_lshl_u32 v230, v188, v116, 1
	v_add_u32_e32 v231, v222, v117
	global_load_dword v166, v230, s[8:9]
	global_load_dword v167, v231, s[10:11]
	v_or_b32_e32 v112, 16, v132
	v_mul_lo_u32 v113, v112, s51
	v_add_lshl_u32 v114, v113, v130, 1
	s_nop 0
	v_lshlrev_b32_e32 v112, 12, v112
	v_add_u32_e32 v126, v112, v128
	s_nop 0
	v_cndmask_b32_e64 v114, v108, v110, s[6:7]
	s_waitcnt vmcnt(38)
	v_lshlrev_b32_e32 v122, 16, v191
	v_mov_b32_dpp v114, v114 quad_perm:[1,0,3,2] row_mask:0xf bank_mask:0xf bound_ctrl:1
	v_cndmask_b32_e64 v115, v110, v114, s[6:7]
	v_lshlrev_b32_e32 v110, 16, v190
	v_and_b32_e32 v118, 0xffff0000, v190
	v_mul_f32_e32 v110, 0xbfb8aa3b, v110
	v_mul_f32_e32 v119, 0xbfb8aa3b, v118
	v_exp_f32_e32 v118, v110
	v_exp_f32_e32 v119, v119
	v_cndmask_b32_e64 v114, v114, v108, s[6:7]
	v_and_b32_e32 v123, 0xffff0000, v191
	v_add_u32_e32 v108, 0x2a00, v113
	v_pk_add_f32 v[118:119], v[118:119], 1.0 op_sel_hi:[1,0]
	v_add_lshl_u32 v110, v108, v130, 1
	v_div_scale_f32 v127, s[0:1], v119, v119, 1.0
	v_div_scale_f32 v134, s[0:1], v118, v118, 1.0
	v_rcp_f32_e32 v135, v127
	v_rcp_f32_e32 v136, v134
	v_div_scale_f32 v133, vcc, 1.0, v119, 1.0
	v_fma_f32 v138, -v127, v135, 1.0
	v_fma_f32 v139, -v134, v136, 1.0
	v_fmac_f32_e32 v135, v138, v135
	v_div_scale_f32 v137, s[0:1], 1.0, v118, 1.0
	v_fmac_f32_e32 v136, v139, v136
	v_mul_f32_e32 v138, v133, v135
	v_mul_f32_e32 v139, v137, v136
	v_fma_f32 v141, -v127, v138, v133
	v_fma_f32 v142, -v134, v139, v137
	v_fmac_f32_e32 v138, v141, v135
	v_fmac_f32_e32 v139, v142, v136
	v_fma_f32 v127, -v127, v138, v133
	v_fma_f32 v133, -v134, v139, v137
	v_div_fmas_f32 v127, v127, v135, v138
	s_mov_b64 vcc, s[0:1]
	v_div_fixup_f32 v119, v127, v119, 1.0
	v_div_fmas_f32 v127, v133, v136, v139
	v_div_fixup_f32 v118, v127, v118, 1.0
	v_pk_fma_f32 v[114:115], v[114:115], v[118:119], v[122:123]
	s_nop 0
	v_cvt_pk_bf16_f32 v114, v114, v115
	global_store_dword v126, v114, s[12:13]
	s_nop 0
	v_or_b32_e32 v110, 0x11000, v129
	v_add_u32_e32 v126, v110, v128
	s_nop 0
	v_cndmask_b32_e64 v114, v109, v111, s[6:7]
	s_waitcnt vmcnt(37)
	v_lshlrev_b32_e32 v122, 16, v193
	v_mov_b32_dpp v114, v114 quad_perm:[1,0,3,2] row_mask:0xf bank_mask:0xf bound_ctrl:1
	v_cndmask_b32_e64 v115, v111, v114, s[6:7]
	v_cndmask_b32_e64 v114, v114, v109, s[6:7]
	v_lshlrev_b32_e32 v109, 16, v192
	v_and_b32_e32 v111, 0xffff0000, v192
	v_mul_f32_e32 v109, 0xbfb8aa3b, v109
	v_mul_f32_e32 v111, 0xbfb8aa3b, v111
	v_exp_f32_e32 v118, v109
	v_exp_f32_e32 v119, v111
	v_and_b32_e32 v123, 0xffff0000, v193
	v_add_lshl_u32 v109, v113, v124, 1
	v_pk_add_f32 v[118:119], v[118:119], 1.0 op_sel_hi:[1,0]
	s_nop 0
	v_div_scale_f32 v111, s[0:1], v119, v119, 1.0
	v_div_scale_f32 v133, s[0:1], v118, v118, 1.0
	v_rcp_f32_e32 v134, v111
	v_rcp_f32_e32 v135, v133
	v_div_scale_f32 v127, vcc, 1.0, v119, 1.0
	v_fma_f32 v137, -v111, v134, 1.0
	v_fma_f32 v138, -v133, v135, 1.0
	v_fmac_f32_e32 v134, v137, v134
	v_div_scale_f32 v136, s[0:1], 1.0, v118, 1.0
	v_fmac_f32_e32 v135, v138, v135
	v_mul_f32_e32 v137, v127, v134
	v_mul_f32_e32 v138, v136, v135
	v_fma_f32 v139, -v111, v137, v127
	v_fma_f32 v141, -v133, v138, v136
	v_fmac_f32_e32 v137, v139, v134
	v_fmac_f32_e32 v138, v141, v135
	v_fma_f32 v111, -v111, v137, v127
	v_fma_f32 v127, -v133, v138, v136
	v_div_fmas_f32 v111, v111, v134, v137
	s_mov_b64 vcc, s[0:1]
	v_div_fixup_f32 v119, v111, v119, 1.0
	v_div_fmas_f32 v111, v127, v135, v138
	v_div_fixup_f32 v118, v111, v118, 1.0
	v_pk_fma_f32 v[114:115], v[114:115], v[118:119], v[122:123]
	s_nop 0
	v_cvt_pk_bf16_f32 v111, v114, v115
	global_store_dword v126, v111, s[12:13]
	s_nop 0
	v_add_u32_e32 v111, v112, v125
	s_nop 0
	v_cndmask_b32_e64 v114, v104, v106, s[6:7]
	s_waitcnt vmcnt(36)
; DEVINL float bflo(unsigned u) { return __uint_as_float(u << 16); }
; DEVINL float bfhi(unsigned u) { return __uint_as_float(u & 0xffff0000u); }
; DEVINL float sigm(float x) { return 1.f / (1.f + __expf(-x)); }
; template <int EPI, bool GATHER>
; DEVINL void gemm_tile(const Params& p, const u16* __restrict__ A, int lda, const int* __restrict__ rowidx,
;                       const u16* __restrict__ Bt, int ldb, int K, int brow, int bcol, int orow, int ocol) {
;     ...
;       for (int bj = 0; bj < (EPI == EPI_HID ? 1 : 2); ++bj)
; #pragma unroll
;         for (int n = 0; n < 2; ++n) {
;           const int cc = bj * HALF + n * 16;
;           f32x4 v = acc[ai][bj][m][n];
;           if (EPI == EPI_HID) {
; #pragma unroll
;             for (int j = 0; j < 4; ++j) { const float a1 = acc[ai][0][m][n][j], a3 = acc[ai][1][m][n][j]; v[j] = a1 * sigm(a1) * a3; }
;           }
;           float lo[2], hi[2];
;           xchg_pairs(v, odd, lo, hi);
; #pragma unroll
;           for (int k = 0; k < 2; ++k) {
;             const unsigned row = (unsigned)(rA + k);
;             if (EPI == EPI_HID) {
;               *(unsigned*)(ws + O_HID + (row * 1024u + (unsigned)(colp + cc)) * 2u) = pk2(lo[k], hi[k]);
;             } else if (EPI == EPI_COLS) {
;               *(unsigned*)(ws + O_COLS + (row * (unsigned)NCP + (unsigned)(colp + cc)) * 2u) = pk2(lo[k], hi[k]);
;             } else if (EPI == EPI_MOE2) {
;               *(unsigned*)(ws + O_EO + (row * 2048u + (unsigned)(colp + cc)) * 2u) = pk2(gate[k] * lo[k], gate[k] * hi[k]);
;             } else if (EPI == EPI_M1) {
;               const unsigned g2 = *(const unsigned*)(ws + O_COLS + (row * (unsigned)NCP + (unsigned)(C_GG + colp + cc)) * 2u);
;               *(unsigned*)(ws + O_M1 + (row * 2048u + (unsigned)(colp + cc)) * 2u) = pk2(sigm(bflo(g2)) * lo[k], sigm(bfhi(g2)) * hi[k]);
;             } else if (EPI == EPI_MERGED) {
;               const unsigned g2 = *(const unsigned*)(ws + O_COLS + (row * (unsigned)NCP + (unsigned)(C_GR + colp + cc)) * 2u);
;               const unsigned m1 = *(const unsigned*)(ws + O_M1 + (row * 2048u + (unsigned)(colp + cc)) * 2u);
;               *(unsigned*)(ws + O_MERGED + (row * 2048u + (unsigned)(colp + cc)) * 2u) =
;                   pk2(bflo(m1) + sigm(bflo(g2)) * lo[k], bfhi(m1) + sigm(bfhi(g2)) * hi[k]);
	v_lshlrev_b32_e32 v122, 16, v195
	v_mov_b32_dpp v114, v114 quad_perm:[1,0,3,2] row_mask:0xf bank_mask:0xf bound_ctrl:1
	v_cndmask_b32_e64 v115, v106, v114, s[6:7]
	v_cndmask_b32_e64 v114, v114, v104, s[6:7]
	v_lshlrev_b32_e32 v104, 16, v194
	v_and_b32_e32 v106, 0xffff0000, v194
	v_mul_f32_e32 v104, 0xbfb8aa3b, v104
	v_mul_f32_e32 v106, 0xbfb8aa3b, v106
	v_exp_f32_e32 v118, v104
	v_exp_f32_e32 v119, v106
	v_and_b32_e32 v123, 0xffff0000, v195
	v_add_lshl_u32 v104, v108, v124, 1
	v_pk_add_f32 v[118:119], v[118:119], 1.0 op_sel_hi:[1,0]
	s_nop 0
	v_div_scale_f32 v106, s[0:1], v119, v119, 1.0
	v_div_scale_f32 v126, s[0:1], v118, v118, 1.0
	v_rcp_f32_e32 v127, v106
	v_rcp_f32_e32 v133, v126
	v_div_scale_f32 v109, vcc, 1.0, v119, 1.0
	v_fma_f32 v135, -v106, v127, 1.0
	v_fma_f32 v136, -v126, v133, 1.0
	v_fmac_f32_e32 v127, v135, v127
	v_div_scale_f32 v134, s[0:1], 1.0, v118, 1.0
	v_fmac_f32_e32 v133, v136, v133
	v_mul_f32_e32 v135, v109, v127
	v_mul_f32_e32 v136, v134, v133
	v_fma_f32 v137, -v106, v135, v109
	v_fma_f32 v138, -v126, v136, v134
	v_fmac_f32_e32 v135, v137, v127
	v_fmac_f32_e32 v136, v138, v133
	v_fma_f32 v106, -v106, v135, v109
	v_fma_f32 v109, -v126, v136, v134
	v_div_fmas_f32 v106, v106, v127, v135
	s_mov_b64 vcc, s[0:1]
	v_div_fixup_f32 v119, v106, v119, 1.0
	v_div_fmas_f32 v106, v109, v133, v136
	v_div_fixup_f32 v118, v106, v118, 1.0
	v_pk_fma_f32 v[114:115], v[114:115], v[118:119], v[122:123]
	v_add_u32_e32 v109, v110, v125
	v_cvt_pk_bf16_f32 v106, v114, v115
	global_store_dword v111, v106, s[12:13]
	s_nop 0
	v_cndmask_b32_e64 v106, v105, v107, s[6:7]
	s_nop 0
	v_add_lshl_u32 v118, v113, v120, 1
	v_mov_b32_dpp v106, v106 quad_perm:[1,0,3,2] row_mask:0xf bank_mask:0xf bound_ctrl:1
	v_cndmask_b32_e64 v107, v107, v106, s[6:7]
	v_cndmask_b32_e64 v106, v106, v105, s[6:7]
	s_waitcnt vmcnt(35)
	v_lshlrev_b32_e32 v105, 16, v196
	v_and_b32_e32 v104, 0xffff0000, v196
	v_mul_f32_e32 v105, 0xbfb8aa3b, v105
	v_mul_f32_e32 v114, 0xbfb8aa3b, v104
	v_exp_f32_e32 v104, v105
	v_exp_f32_e32 v105, v114
	s_waitcnt vmcnt(35)
	v_lshlrev_b32_e32 v114, 16, v197
	v_and_b32_e32 v115, 0xffff0000, v197
	v_pk_add_f32 v[104:105], v[104:105], 1.0 op_sel_hi:[1,0]
	s_nop 0
	v_div_scale_f32 v111, s[0:1], v105, v105, 1.0
	v_div_scale_f32 v122, s[0:1], v104, v104, 1.0
	v_rcp_f32_e32 v123, v111
	v_rcp_f32_e32 v126, v122
	v_div_scale_f32 v119, vcc, 1.0, v105, 1.0
	v_fma_f32 v133, -v111, v123, 1.0
	v_fma_f32 v134, -v122, v126, 1.0
	v_fmac_f32_e32 v123, v133, v123
	v_div_scale_f32 v127, s[0:1], 1.0, v104, 1.0
	v_fmac_f32_e32 v126, v134, v126
	v_mul_f32_e32 v133, v119, v123
	v_mul_f32_e32 v134, v127, v126
	v_fma_f32 v135, -v111, v133, v119
	v_fma_f32 v136, -v122, v134, v127
	v_fmac_f32_e32 v133, v135, v123
	v_fmac_f32_e32 v134, v136, v126
	v_fma_f32 v111, -v111, v133, v119
	v_fma_f32 v119, -v122, v134, v127
	v_div_fmas_f32 v111, v111, v123, v133
	s_mov_b64 vcc, s[0:1]
	v_div_fixup_f32 v105, v111, v105, 1.0
	v_div_fmas_f32 v111, v119, v126, v134
	v_div_fixup_f32 v104, v111, v104, 1.0
	v_pk_fma_f32 v[104:105], v[106:107], v[104:105], v[114:115]
	s_nop 0
	v_cvt_pk_bf16_f32 v104, v104, v105
	global_store_dword v109, v104, s[12:13]
	s_nop 0
	v_add_u32_e32 v109, v112, v121
	s_nop 0
	v_cndmask_b32_e64 v104, v100, v102, s[6:7]
	s_waitcnt vmcnt(34)
	v_lshlrev_b32_e32 v114, 16, v199
	v_mov_b32_dpp v104, v104 quad_perm:[1,0,3,2] row_mask:0xf bank_mask:0xf bound_ctrl:1
	v_cndmask_b32_e64 v105, v102, v104, s[6:7]
	v_cndmask_b32_e64 v104, v104, v100, s[6:7]
	v_lshlrev_b32_e32 v100, 16, v198
	v_and_b32_e32 v102, 0xffff0000, v198
	v_mul_f32_e32 v100, 0xbfb8aa3b, v100
	v_mul_f32_e32 v102, 0xbfb8aa3b, v102
	v_exp_f32_e32 v106, v100
	v_exp_f32_e32 v107, v102
	v_and_b32_e32 v115, 0xffff0000, v199
	v_add_lshl_u32 v100, v108, v120, 1
	v_pk_add_f32 v[106:107], v[106:107], 1.0 op_sel_hi:[1,0]
	s_nop 0
	v_div_scale_f32 v102, s[0:1], v107, v107, 1.0
	v_div_scale_f32 v118, s[0:1], v106, v106, 1.0
	v_rcp_f32_e32 v119, v102
	v_rcp_f32_e32 v122, v118
	v_div_scale_f32 v111, vcc, 1.0, v107, 1.0
	v_fma_f32 v126, -v102, v119, 1.0
	v_fma_f32 v127, -v118, v122, 1.0
	v_fmac_f32_e32 v119, v126, v119
	v_div_scale_f32 v123, s[0:1], 1.0, v106, 1.0
	v_fmac_f32_e32 v122, v127, v122
	v_mul_f32_e32 v126, v111, v119
	v_mul_f32_e32 v127, v123, v122
	v_fma_f32 v133, -v102, v126, v111
	v_fma_f32 v134, -v118, v127, v123
	v_fmac_f32_e32 v126, v133, v119
	v_fmac_f32_e32 v127, v134, v122
	v_fma_f32 v102, -v102, v126, v111
	v_fma_f32 v111, -v118, v127, v123
	v_div_fmas_f32 v102, v102, v119, v126
	s_mov_b64 vcc, s[0:1]
	v_div_fixup_f32 v107, v102, v107, 1.0
	v_div_fmas_f32 v102, v111, v122, v127
	v_div_fixup_f32 v106, v102, v106, 1.0
	v_pk_fma_f32 v[104:105], v[104:105], v[106:107], v[114:115]
	v_add_u32_e32 v106, v110, v121
	v_cvt_pk_bf16_f32 v102, v104, v105
	global_store_dword v109, v102, s[12:13]
	s_nop 0
	v_cndmask_b32_e64 v102, v101, v103, s[6:7]
	s_nop 0
	v_add_lshl_u32 v107, v113, v116, 1
	v_mov_b32_dpp v102, v102 quad_perm:[1,0,3,2] row_mask:0xf bank_mask:0xf bound_ctrl:1
	v_cndmask_b32_e64 v103, v103, v102, s[6:7]
	v_cndmask_b32_e64 v102, v102, v101, s[6:7]
	s_waitcnt vmcnt(33)
	v_lshlrev_b32_e32 v101, 16, v200
	v_and_b32_e32 v100, 0xffff0000, v200
	v_mul_f32_e32 v101, 0xbfb8aa3b, v101
	v_mul_f32_e32 v104, 0xbfb8aa3b, v100
	v_exp_f32_e32 v100, v101
	v_exp_f32_e32 v101, v104
	s_waitcnt vmcnt(33)
; template <int EPI, bool GATHER>
; DEVINL void gemm_tile(const Params& p, const u16* __restrict__ A, int lda, const int* __restrict__ rowidx,
;                       const u16* __restrict__ Bt, int ldb, int K, int brow, int bcol, int orow, int ocol) {
;     ...
;     for (int m = 0; m < 4; ++m) {
;       const int rA = row0 + ai * HALF + m * 16 + (odd ? 2 : 0);
;       float gate[2] = {0.f, 0.f};
;       if (EPI == EPI_MOE2) { gate[0] = ((const float*)(ws + O_SELG))[rA]; gate[1] = ((const float*)(ws + O_SELG))[rA + 1]; }
; #pragma unroll
;       for (int bj = 0; bj < (EPI == EPI_HID ? 1 : 2); ++bj)
; #pragma unroll
;         for (int n = 0; n < 2; ++n) {
;           const int cc = bj * HALF + n * 16;
;           f32x4 v = acc[ai][bj][m][n];
;           if (EPI == EPI_HID) {
; #pragma unroll
;             for (int j = 0; j < 4; ++j) { const float a1 = acc[ai][0][m][n][j], a3 = acc[ai][1][m][n][j]; v[j] = a1 * sigm(a1) * a3; }
;           }
;           float lo[2], hi[2];
;           xchg_pairs(v, odd, lo, hi);
; #pragma unroll
;           for (int k = 0; k < 2; ++k) {
;             const unsigned row = (unsigned)(rA + k);
;             if (EPI == EPI_HID) {
;               *(unsigned*)(ws + O_HID + (row * 1024u + (unsigned)(colp + cc)) * 2u) = pk2(lo[k], hi[k]);
;             } else if (EPI == EPI_COLS) {
;               *(unsigned*)(ws + O_COLS + (row * (unsigned)NCP + (unsigned)(colp + cc)) * 2u) = pk2(lo[k], hi[k]);
;             } else if (EPI == EPI_MOE2) {
;               *(unsigned*)(ws + O_EO + (row * 2048u + (unsigned)(colp + cc)) * 2u) = pk2(gate[k] * lo[k], gate[k] * hi[k]);
;             } else if (EPI == EPI_M1) {
;               const unsigned g2 = *(const unsigned*)(ws + O_COLS + (row * (unsigned)NCP + (unsigned)(C_GG + colp + cc)) * 2u);
;               *(unsigned*)(ws + O_M1 + (row * 2048u + (unsigned)(colp + cc)) * 2u) = pk2(sigm(bflo(g2)) * lo[k], sigm(bfhi(g2)) * hi[k]);
;             } else if (EPI == EPI_MERGED) {
;               const unsigned g2 = *(const unsigned*)(ws + O_COLS + (row * (unsigned)NCP + (unsigned)(C_GR + colp + cc)) * 2u);
;               const unsigned m1 = *(const unsigned*)(ws + O_M1 + (row * 2048u + (unsigned)(colp + cc)) * 2u);
;               *(unsigned*)(ws + O_MERGED + (row * 2048u + (unsigned)(colp + cc)) * 2u) =
;                   pk2(bflo(m1) + sigm(bflo(g2)) * lo[k], bfhi(m1) + sigm(bfhi(g2)) * hi[k]);
	v_lshlrev_b32_e32 v104, 16, v201
	v_and_b32_e32 v105, 0xffff0000, v201
	v_pk_add_f32 v[100:101], v[100:101], 1.0 op_sel_hi:[1,0]
	s_nop 0
	v_div_scale_f32 v109, s[0:1], v101, v101, 1.0
	v_div_scale_f32 v113, s[0:1], v100, v100, 1.0
	v_rcp_f32_e32 v114, v109
	v_rcp_f32_e32 v115, v113
	v_div_scale_f32 v111, vcc, 1.0, v101, 1.0
	v_fma_f32 v119, -v109, v114, 1.0
	v_fma_f32 v122, -v113, v115, 1.0
	v_fmac_f32_e32 v114, v119, v114
	v_div_scale_f32 v118, s[0:1], 1.0, v100, 1.0
	v_fmac_f32_e32 v115, v122, v115
	v_mul_f32_e32 v119, v111, v114
	v_mul_f32_e32 v122, v118, v115
	v_fma_f32 v123, -v109, v119, v111
	v_fma_f32 v126, -v113, v122, v118
	v_fmac_f32_e32 v119, v123, v114
	v_fmac_f32_e32 v122, v126, v115
	v_fma_f32 v109, -v109, v119, v111
	v_fma_f32 v111, -v113, v122, v118
	v_div_fmas_f32 v109, v109, v114, v119
	s_mov_b64 vcc, s[0:1]
	v_div_fixup_f32 v101, v109, v101, 1.0
	v_div_fmas_f32 v109, v111, v115, v122
	v_div_fixup_f32 v100, v109, v100, 1.0
	v_pk_fma_f32 v[100:101], v[102:103], v[100:101], v[104:105]
	s_nop 0
	v_cvt_pk_bf16_f32 v100, v100, v101
	global_store_dword v106, v100, s[12:13]
	s_nop 0
	v_add_u32_e32 v106, v112, v117
	s_nop 0
	v_cndmask_b32_e64 v100, v96, v98, s[6:7]
	s_waitcnt vmcnt(32)
	v_lshlrev_b32_e32 v104, 16, v203
	v_mov_b32_dpp v100, v100 quad_perm:[1,0,3,2] row_mask:0xf bank_mask:0xf bound_ctrl:1
	v_cndmask_b32_e64 v101, v98, v100, s[6:7]
	v_cndmask_b32_e64 v100, v100, v96, s[6:7]
	v_lshlrev_b32_e32 v96, 16, v202
	v_and_b32_e32 v98, 0xffff0000, v202
	v_mul_f32_e32 v96, 0xbfb8aa3b, v96
	v_mul_f32_e32 v98, 0xbfb8aa3b, v98
	v_exp_f32_e32 v102, v96
	v_exp_f32_e32 v103, v98
	v_add_lshl_u32 v96, v108, v116, 1
	v_and_b32_e32 v105, 0xffff0000, v203
	v_pk_add_f32 v[102:103], v[102:103], 1.0 op_sel_hi:[1,0]
	s_nop 0
	v_div_scale_f32 v98, s[0:1], v103, v103, 1.0
	v_div_scale_f32 v108, s[0:1], v102, v102, 1.0
	v_rcp_f32_e32 v109, v98
	v_rcp_f32_e32 v111, v108
	v_div_scale_f32 v107, vcc, 1.0, v103, 1.0
	v_fma_f32 v113, -v98, v109, 1.0
	v_fma_f32 v114, -v108, v111, 1.0
	v_fmac_f32_e32 v109, v113, v109
	v_div_scale_f32 v112, s[0:1], 1.0, v102, 1.0
	v_fmac_f32_e32 v111, v114, v111
	v_mul_f32_e32 v113, v107, v109
	v_mul_f32_e32 v114, v112, v111
	v_fma_f32 v115, -v98, v113, v107
	v_fma_f32 v118, -v108, v114, v112
	v_fmac_f32_e32 v113, v115, v109
	v_fmac_f32_e32 v114, v118, v111
	v_fma_f32 v98, -v98, v113, v107
	v_fma_f32 v107, -v108, v114, v112
	v_div_fmas_f32 v98, v98, v109, v113
	s_mov_b64 vcc, s[0:1]
	v_div_fixup_f32 v103, v98, v103, 1.0
	v_div_fmas_f32 v98, v107, v111, v114
	v_div_fixup_f32 v102, v98, v102, 1.0
	v_pk_fma_f32 v[100:101], v[100:101], v[102:103], v[104:105]
	v_add_u32_e32 v102, v110, v117
	v_cvt_pk_bf16_f32 v98, v100, v101
	global_store_dword v106, v98, s[12:13]
	s_nop 0
	v_cndmask_b32_e64 v98, v97, v99, s[6:7]
	s_nop 0
	s_waitcnt vmcnt(31)
	v_lshlrev_b32_e32 v100, 16, v204
	v_and_b32_e32 v96, 0xffff0000, v204
	v_mul_f32_e32 v100, 0xbfb8aa3b, v100
	v_mul_f32_e32 v96, 0xbfb8aa3b, v96
	v_exp_f32_e32 v100, v100
	v_exp_f32_e32 v101, v96
	v_mov_b32_dpp v98, v98 quad_perm:[1,0,3,2] row_mask:0xf bank_mask:0xf bound_ctrl:1
	v_cndmask_b32_e64 v99, v99, v98, s[6:7]
	v_cndmask_b32_e64 v98, v98, v97, s[6:7]
	v_pk_add_f32 v[100:101], v[100:101], 1.0 op_sel_hi:[1,0]
	s_waitcnt vmcnt(31)
	v_lshlrev_b32_e32 v96, 16, v205
	v_and_b32_e32 v97, 0xffff0000, v205
	v_div_scale_f32 v103, s[0:1], v101, v101, 1.0
	v_div_scale_f32 v105, s[0:1], v100, v100, 1.0
	v_rcp_f32_e32 v106, v103
	v_rcp_f32_e32 v107, v105
	v_div_scale_f32 v104, vcc, 1.0, v101, 1.0
	v_fma_f32 v109, -v103, v106, 1.0
	v_fma_f32 v110, -v105, v107, 1.0
	v_fmac_f32_e32 v106, v109, v106
	v_div_scale_f32 v108, s[0:1], 1.0, v100, 1.0
	v_fmac_f32_e32 v107, v110, v107
	v_mul_f32_e32 v109, v104, v106
	v_mul_f32_e32 v110, v108, v107
	v_fma_f32 v111, -v103, v109, v104
	v_fma_f32 v112, -v105, v110, v108
	v_fmac_f32_e32 v109, v111, v106
	v_fmac_f32_e32 v110, v112, v107
	v_fma_f32 v103, -v103, v109, v104
	v_fma_f32 v104, -v105, v110, v108
	v_div_fmas_f32 v103, v103, v106, v109
	s_mov_b64 vcc, s[0:1]
	v_div_fixup_f32 v101, v103, v101, 1.0
	v_div_fmas_f32 v103, v104, v107, v110
	v_div_fixup_f32 v100, v103, v100, 1.0
	v_pk_fma_f32 v[96:97], v[98:99], v[100:101], v[96:97]
	s_nop 0
	v_cvt_pk_bf16_f32 v96, v96, v97
	global_store_dword v102, v96, s[12:13]
	v_or_b32_e32 v184, 48, v132
	v_mul_lo_u32 v185, v184, s51
	v_add_lshl_u32 v186, v185, v130, 1
	global_load_dword v190, v186, s[8:9]
	v_lshlrev_b32_e32 v184, 12, v184
	v_add_u32_e32 v187, v184, v128
	global_load_dword v191, v187, s[10:11]
	v_add_u32_e32 v188, 0x2a00, v185
	v_add_lshl_u32 v222, v188, v130, 1
	global_load_dword v192, v222, s[8:9]
	v_or_b32_e32 v222, 0x31000, v129
	v_add_u32_e32 v187, v222, v128
	global_load_dword v193, v187, s[10:11]
	v_add_lshl_u32 v223, v185, v124, 1
	global_load_dword v194, v223, s[8:9]
	v_add_u32_e32 v224, v184, v125
	global_load_dword v195, v224, s[10:11]
	v_add_lshl_u32 v225, v188, v124, 1
	v_add_u32_e32 v223, v222, v125
	global_load_dword v196, v225, s[8:9]
	global_load_dword v197, v223, s[10:11]
	v_add_lshl_u32 v226, v185, v120, 1
	global_load_dword v198, v226, s[8:9]
	v_add_u32_e32 v223, v184, v121
	global_load_dword v199, v223, s[10:11]
	v_add_lshl_u32 v227, v188, v120, 1
	v_add_u32_e32 v228, v222, v121
	global_load_dword v200, v227, s[8:9]
	global_load_dword v201, v228, s[10:11]
	v_add_lshl_u32 v229, v185, v116, 1
	global_load_dword v202, v229, s[8:9]
	v_add_u32_e32 v228, v184, v117
	global_load_dword v203, v228, s[10:11]
	v_add_lshl_u32 v230, v188, v116, 1
	v_add_u32_e32 v231, v222, v117
	global_load_dword v204, v230, s[8:9]
	global_load_dword v205, v231, s[10:11]
	v_or_b32_e32 v96, 32, v132
	v_mul_lo_u32 v97, v96, s51
	v_add_lshl_u32 v98, v97, v130, 1
	s_nop 0
	v_lshlrev_b32_e32 v96, 12, v96
	v_add_u32_e32 v104, v96, v128
	s_nop 0
	v_cndmask_b32_e64 v98, v92, v94, s[6:7]
	s_waitcnt vmcnt(38)
; DEVINL float bflo(unsigned u) { return __uint_as_float(u << 16); }
; DEVINL float bfhi(unsigned u) { return __uint_as_float(u & 0xffff0000u); }
; DEVINL float sigm(float x) { return 1.f / (1.f + __expf(-x)); }
; template <int EPI, bool GATHER>
; DEVINL void gemm_tile(const Params& p, const u16* __restrict__ A, int lda, const int* __restrict__ rowidx,
;                       const u16* __restrict__ Bt, int ldb, int K, int brow, int bcol, int orow, int ocol) {
;     ...
;       for (int bj = 0; bj < (EPI == EPI_HID ? 1 : 2); ++bj)
; #pragma unroll
;         for (int n = 0; n < 2; ++n) {
;           const int cc = bj * HALF + n * 16;
;           f32x4 v = acc[ai][bj][m][n];
;           if (EPI == EPI_HID) {
; #pragma unroll
;             for (int j = 0; j < 4; ++j) { const float a1 = acc[ai][0][m][n][j], a3 = acc[ai][1][m][n][j]; v[j] = a1 * sigm(a1) * a3; }
;           }
;           float lo[2], hi[2];
;           xchg_pairs(v, odd, lo, hi);
; #pragma unroll
;           for (int k = 0; k < 2; ++k) {
;             const unsigned row = (unsigned)(rA + k);
;             if (EPI == EPI_HID) {
;               *(unsigned*)(ws + O_HID + (row * 1024u + (unsigned)(colp + cc)) * 2u) = pk2(lo[k], hi[k]);
;             } else if (EPI == EPI_COLS) {
;               *(unsigned*)(ws + O_COLS + (row * (unsigned)NCP + (unsigned)(colp + cc)) * 2u) = pk2(lo[k], hi[k]);
;             } else if (EPI == EPI_MOE2) {
;               *(unsigned*)(ws + O_EO + (row * 2048u + (unsigned)(colp + cc)) * 2u) = pk2(gate[k] * lo[k], gate[k] * hi[k]);
;             } else if (EPI == EPI_M1) {
;               const unsigned g2 = *(const unsigned*)(ws + O_COLS + (row * (unsigned)NCP + (unsigned)(C_GG + colp + cc)) * 2u);
;               *(unsigned*)(ws + O_M1 + (row * 2048u + (unsigned)(colp + cc)) * 2u) = pk2(sigm(bflo(g2)) * lo[k], sigm(bfhi(g2)) * hi[k]);
;             } else if (EPI == EPI_MERGED) {
;               const unsigned g2 = *(const unsigned*)(ws + O_COLS + (row * (unsigned)NCP + (unsigned)(C_GR + colp + cc)) * 2u);
;               const unsigned m1 = *(const unsigned*)(ws + O_M1 + (row * 2048u + (unsigned)(colp + cc)) * 2u);
;               *(unsigned*)(ws + O_MERGED + (row * 2048u + (unsigned)(colp + cc)) * 2u) =
;                   pk2(bflo(m1) + sigm(bflo(g2)) * lo[k], bfhi(m1) + sigm(bfhi(g2)) * hi[k]);
	v_lshlrev_b32_e32 v102, 16, v153
	v_mov_b32_dpp v98, v98 quad_perm:[1,0,3,2] row_mask:0xf bank_mask:0xf bound_ctrl:1
	v_cndmask_b32_e64 v99, v94, v98, s[6:7]
	v_lshlrev_b32_e32 v94, 16, v152
	v_and_b32_e32 v100, 0xffff0000, v152
	v_mul_f32_e32 v94, 0xbfb8aa3b, v94
	v_mul_f32_e32 v101, 0xbfb8aa3b, v100
	v_exp_f32_e32 v100, v94
	v_exp_f32_e32 v101, v101
	v_cndmask_b32_e64 v98, v98, v92, s[6:7]
	v_and_b32_e32 v103, 0xffff0000, v153
	v_add_u32_e32 v92, 0x2a00, v97
	v_pk_add_f32 v[100:101], v[100:101], 1.0 op_sel_hi:[1,0]
	v_add_lshl_u32 v94, v92, v130, 1
	v_div_scale_f32 v105, s[0:1], v101, v101, 1.0
	v_div_scale_f32 v107, s[0:1], v100, v100, 1.0
	v_rcp_f32_e32 v108, v105
	v_rcp_f32_e32 v109, v107
	v_div_scale_f32 v106, vcc, 1.0, v101, 1.0
	v_fma_f32 v111, -v105, v108, 1.0
	v_fma_f32 v112, -v107, v109, 1.0
	v_fmac_f32_e32 v108, v111, v108
	v_div_scale_f32 v110, s[0:1], 1.0, v100, 1.0
	v_fmac_f32_e32 v109, v112, v109
	v_mul_f32_e32 v111, v106, v108
	v_mul_f32_e32 v112, v110, v109
	v_fma_f32 v113, -v105, v111, v106
	v_fma_f32 v114, -v107, v112, v110
	v_fmac_f32_e32 v111, v113, v108
	v_fmac_f32_e32 v112, v114, v109
	v_fma_f32 v105, -v105, v111, v106
	v_fma_f32 v106, -v107, v112, v110
	v_div_fmas_f32 v105, v105, v108, v111
	s_mov_b64 vcc, s[0:1]
	v_div_fixup_f32 v101, v105, v101, 1.0
	v_div_fmas_f32 v105, v106, v109, v112
	v_div_fixup_f32 v100, v105, v100, 1.0
	v_pk_fma_f32 v[98:99], v[98:99], v[100:101], v[102:103]
	s_nop 0
	v_cvt_pk_bf16_f32 v98, v98, v99
	global_store_dword v104, v98, s[12:13]
	s_nop 0
	v_or_b32_e32 v94, 0x21000, v129
	v_add_u32_e32 v104, v94, v128
	s_nop 0
	v_cndmask_b32_e64 v98, v93, v95, s[6:7]
	s_waitcnt vmcnt(37)
	v_lshlrev_b32_e32 v102, 16, v155
	v_mov_b32_dpp v98, v98 quad_perm:[1,0,3,2] row_mask:0xf bank_mask:0xf bound_ctrl:1
	v_cndmask_b32_e64 v99, v95, v98, s[6:7]
	v_cndmask_b32_e64 v98, v98, v93, s[6:7]
	v_lshlrev_b32_e32 v93, 16, v154
	v_and_b32_e32 v95, 0xffff0000, v154
	v_mul_f32_e32 v93, 0xbfb8aa3b, v93
	v_mul_f32_e32 v95, 0xbfb8aa3b, v95
	v_exp_f32_e32 v100, v93
	v_exp_f32_e32 v101, v95
	v_and_b32_e32 v103, 0xffff0000, v155
	v_add_lshl_u32 v93, v97, v124, 1
	v_pk_add_f32 v[100:101], v[100:101], 1.0 op_sel_hi:[1,0]
	s_nop 0
	v_div_scale_f32 v95, s[0:1], v101, v101, 1.0
	v_div_scale_f32 v106, s[0:1], v100, v100, 1.0
	v_rcp_f32_e32 v107, v95
	v_rcp_f32_e32 v108, v106
	v_div_scale_f32 v105, vcc, 1.0, v101, 1.0
	v_fma_f32 v110, -v95, v107, 1.0
	v_fma_f32 v111, -v106, v108, 1.0
	v_fmac_f32_e32 v107, v110, v107
	v_div_scale_f32 v109, s[0:1], 1.0, v100, 1.0
	v_fmac_f32_e32 v108, v111, v108
	v_mul_f32_e32 v110, v105, v107
	v_mul_f32_e32 v111, v109, v108
	v_fma_f32 v112, -v95, v110, v105
	v_fma_f32 v113, -v106, v111, v109
	v_fmac_f32_e32 v110, v112, v107
	v_fmac_f32_e32 v111, v113, v108
	v_fma_f32 v95, -v95, v110, v105
	v_fma_f32 v105, -v106, v111, v109
	v_div_fmas_f32 v95, v95, v107, v110
	s_mov_b64 vcc, s[0:1]
	v_div_fixup_f32 v101, v95, v101, 1.0
	v_div_fmas_f32 v95, v105, v108, v111
	v_div_fixup_f32 v100, v95, v100, 1.0
	v_pk_fma_f32 v[98:99], v[98:99], v[100:101], v[102:103]
	s_nop 0
	v_cvt_pk_bf16_f32 v95, v98, v99
	global_store_dword v104, v95, s[12:13]
	s_nop 0
	v_add_u32_e32 v95, v96, v125
	s_nop 0
	v_cndmask_b32_e64 v98, v88, v90, s[6:7]
	s_waitcnt vmcnt(36)
	v_lshlrev_b32_e32 v102, 16, v157
	v_mov_b32_dpp v98, v98 quad_perm:[1,0,3,2] row_mask:0xf bank_mask:0xf bound_ctrl:1
	v_cndmask_b32_e64 v99, v90, v98, s[6:7]
	v_cndmask_b32_e64 v98, v98, v88, s[6:7]
	v_lshlrev_b32_e32 v88, 16, v156
	v_and_b32_e32 v90, 0xffff0000, v156
	v_mul_f32_e32 v88, 0xbfb8aa3b, v88
	v_mul_f32_e32 v90, 0xbfb8aa3b, v90
	v_exp_f32_e32 v100, v88
	v_exp_f32_e32 v101, v90
	v_and_b32_e32 v103, 0xffff0000, v157
	v_add_lshl_u32 v88, v92, v124, 1
	v_pk_add_f32 v[100:101], v[100:101], 1.0 op_sel_hi:[1,0]
	s_nop 0
	v_div_scale_f32 v90, s[0:1], v101, v101, 1.0
	v_div_scale_f32 v104, s[0:1], v100, v100, 1.0
	v_rcp_f32_e32 v105, v90
	v_rcp_f32_e32 v106, v104
	v_div_scale_f32 v93, vcc, 1.0, v101, 1.0
	v_fma_f32 v108, -v90, v105, 1.0
	v_fma_f32 v109, -v104, v106, 1.0
	v_fmac_f32_e32 v105, v108, v105
	v_div_scale_f32 v107, s[0:1], 1.0, v100, 1.0
	v_fmac_f32_e32 v106, v109, v106
	v_mul_f32_e32 v108, v93, v105
	v_mul_f32_e32 v109, v107, v106
	v_fma_f32 v110, -v90, v108, v93
	v_fma_f32 v111, -v104, v109, v107
	v_fmac_f32_e32 v108, v110, v105
	v_fmac_f32_e32 v109, v111, v106
	v_fma_f32 v90, -v90, v108, v93
	v_fma_f32 v93, -v104, v109, v107
	v_div_fmas_f32 v90, v90, v105, v108
	s_mov_b64 vcc, s[0:1]
	v_div_fixup_f32 v101, v90, v101, 1.0
	v_div_fmas_f32 v90, v93, v106, v109
	v_div_fixup_f32 v100, v90, v100, 1.0
	v_pk_fma_f32 v[98:99], v[98:99], v[100:101], v[102:103]
	v_add_u32_e32 v93, v94, v125
	v_cvt_pk_bf16_f32 v90, v98, v99
	global_store_dword v95, v90, s[12:13]
	s_nop 0
	v_cndmask_b32_e64 v90, v89, v91, s[6:7]
	s_nop 0
	v_add_lshl_u32 v100, v97, v120, 1
	v_mov_b32_dpp v90, v90 quad_perm:[1,0,3,2] row_mask:0xf bank_mask:0xf bound_ctrl:1
	v_cndmask_b32_e64 v91, v91, v90, s[6:7]
	v_cndmask_b32_e64 v90, v90, v89, s[6:7]
	s_waitcnt vmcnt(35)
	v_lshlrev_b32_e32 v89, 16, v158
	v_and_b32_e32 v88, 0xffff0000, v158
	v_mul_f32_e32 v89, 0xbfb8aa3b, v89
	v_mul_f32_e32 v98, 0xbfb8aa3b, v88
	v_exp_f32_e32 v88, v89
	v_exp_f32_e32 v89, v98
	s_waitcnt vmcnt(35)
; DEVINL float bflo(unsigned u) { return __uint_as_float(u << 16); }
; DEVINL float bfhi(unsigned u) { return __uint_as_float(u & 0xffff0000u); }
; DEVINL float sigm(float x) { return 1.f / (1.f + __expf(-x)); }
; template <int EPI, bool GATHER>
; DEVINL void gemm_tile(const Params& p, const u16* __restrict__ A, int lda, const int* __restrict__ rowidx,
;                       const u16* __restrict__ Bt, int ldb, int K, int brow, int bcol, int orow, int ocol) {
;     ...
;       for (int bj = 0; bj < (EPI == EPI_HID ? 1 : 2); ++bj)
; #pragma unroll
;         for (int n = 0; n < 2; ++n) {
;           const int cc = bj * HALF + n * 16;
;           f32x4 v = acc[ai][bj][m][n];
;           if (EPI == EPI_HID) {
; #pragma unroll
;             for (int j = 0; j < 4; ++j) { const float a1 = acc[ai][0][m][n][j], a3 = acc[ai][1][m][n][j]; v[j] = a1 * sigm(a1) * a3; }
;           }
;           float lo[2], hi[2];
;           xchg_pairs(v, odd, lo, hi);
; #pragma unroll
;           for (int k = 0; k < 2; ++k) {
;             const unsigned row = (unsigned)(rA + k);
;             if (EPI == EPI_HID) {
;               *(unsigned*)(ws + O_HID + (row * 1024u + (unsigned)(colp + cc)) * 2u) = pk2(lo[k], hi[k]);
;             } else if (EPI == EPI_COLS) {
;               *(unsigned*)(ws + O_COLS + (row * (unsigned)NCP + (unsigned)(colp + cc)) * 2u) = pk2(lo[k], hi[k]);
;             } else if (EPI == EPI_MOE2) {
;               *(unsigned*)(ws + O_EO + (row * 2048u + (unsigned)(colp + cc)) * 2u) = pk2(gate[k] * lo[k], gate[k] * hi[k]);
;             } else if (EPI == EPI_M1) {
;               const unsigned g2 = *(const unsigned*)(ws + O_COLS + (row * (unsigned)NCP + (unsigned)(C_GG + colp + cc)) * 2u);
;               *(unsigned*)(ws + O_M1 + (row * 2048u + (unsigned)(colp + cc)) * 2u) = pk2(sigm(bflo(g2)) * lo[k], sigm(bfhi(g2)) * hi[k]);
;             } else if (EPI == EPI_MERGED) {
;               const unsigned g2 = *(const unsigned*)(ws + O_COLS + (row * (unsigned)NCP + (unsigned)(C_GR + colp + cc)) * 2u);
;               const unsigned m1 = *(const unsigned*)(ws + O_M1 + (row * 2048u + (unsigned)(colp + cc)) * 2u);
;               *(unsigned*)(ws + O_MERGED + (row * 2048u + (unsigned)(colp + cc)) * 2u) =
;                   pk2(bflo(m1) + sigm(bflo(g2)) * lo[k], bfhi(m1) + sigm(bfhi(g2)) * hi[k]);
	v_lshlrev_b32_e32 v98, 16, v159
	v_and_b32_e32 v99, 0xffff0000, v159
	v_pk_add_f32 v[88:89], v[88:89], 1.0 op_sel_hi:[1,0]
	s_nop 0
	v_div_scale_f32 v95, s[0:1], v89, v89, 1.0
	v_div_scale_f32 v102, s[0:1], v88, v88, 1.0
	v_rcp_f32_e32 v103, v95
	v_rcp_f32_e32 v104, v102
	v_div_scale_f32 v101, vcc, 1.0, v89, 1.0
	v_fma_f32 v106, -v95, v103, 1.0
	v_fma_f32 v107, -v102, v104, 1.0
	v_fmac_f32_e32 v103, v106, v103
	v_div_scale_f32 v105, s[0:1], 1.0, v88, 1.0
	v_fmac_f32_e32 v104, v107, v104
	v_mul_f32_e32 v106, v101, v103
	v_mul_f32_e32 v107, v105, v104
	v_fma_f32 v108, -v95, v106, v101
	v_fma_f32 v109, -v102, v107, v105
	v_fmac_f32_e32 v106, v108, v103
	v_fmac_f32_e32 v107, v109, v104
	v_fma_f32 v95, -v95, v106, v101
	v_fma_f32 v101, -v102, v107, v105
	v_div_fmas_f32 v95, v95, v103, v106
	s_mov_b64 vcc, s[0:1]
	v_div_fixup_f32 v89, v95, v89, 1.0
	v_div_fmas_f32 v95, v101, v104, v107
	v_div_fixup_f32 v88, v95, v88, 1.0
	v_pk_fma_f32 v[88:89], v[90:91], v[88:89], v[98:99]
	s_nop 0
	v_cvt_pk_bf16_f32 v88, v88, v89
	global_store_dword v93, v88, s[12:13]
	s_nop 0
	v_add_u32_e32 v93, v96, v121
	s_nop 0
	v_cndmask_b32_e64 v88, v84, v86, s[6:7]
	s_waitcnt vmcnt(34)
	v_lshlrev_b32_e32 v98, 16, v161
	v_mov_b32_dpp v88, v88 quad_perm:[1,0,3,2] row_mask:0xf bank_mask:0xf bound_ctrl:1
	v_cndmask_b32_e64 v89, v86, v88, s[6:7]
	v_cndmask_b32_e64 v88, v88, v84, s[6:7]
	v_lshlrev_b32_e32 v84, 16, v160
	v_and_b32_e32 v86, 0xffff0000, v160
	v_mul_f32_e32 v84, 0xbfb8aa3b, v84
	v_mul_f32_e32 v86, 0xbfb8aa3b, v86
	v_exp_f32_e32 v90, v84
	v_exp_f32_e32 v91, v86
	v_and_b32_e32 v99, 0xffff0000, v161
	v_add_lshl_u32 v84, v92, v120, 1
	v_pk_add_f32 v[90:91], v[90:91], 1.0 op_sel_hi:[1,0]
	s_nop 0
	v_div_scale_f32 v86, s[0:1], v91, v91, 1.0
	v_div_scale_f32 v100, s[0:1], v90, v90, 1.0
	v_rcp_f32_e32 v101, v86
	v_rcp_f32_e32 v102, v100
	v_div_scale_f32 v95, vcc, 1.0, v91, 1.0
	v_fma_f32 v104, -v86, v101, 1.0
	v_fma_f32 v105, -v100, v102, 1.0
	v_fmac_f32_e32 v101, v104, v101
	v_div_scale_f32 v103, s[0:1], 1.0, v90, 1.0
	v_fmac_f32_e32 v102, v105, v102
	v_mul_f32_e32 v104, v95, v101
	v_mul_f32_e32 v105, v103, v102
	v_fma_f32 v106, -v86, v104, v95
	v_fma_f32 v107, -v100, v105, v103
	v_fmac_f32_e32 v104, v106, v101
	v_fmac_f32_e32 v105, v107, v102
	v_fma_f32 v86, -v86, v104, v95
	v_fma_f32 v95, -v100, v105, v103
	v_div_fmas_f32 v86, v86, v101, v104
	s_mov_b64 vcc, s[0:1]
	v_div_fixup_f32 v91, v86, v91, 1.0
	v_div_fmas_f32 v86, v95, v102, v105
	v_div_fixup_f32 v90, v86, v90, 1.0
	v_pk_fma_f32 v[88:89], v[88:89], v[90:91], v[98:99]
	v_add_u32_e32 v90, v94, v121
	v_cvt_pk_bf16_f32 v86, v88, v89
	global_store_dword v93, v86, s[12:13]
	s_nop 0
	v_cndmask_b32_e64 v86, v85, v87, s[6:7]
	s_nop 0
	v_add_lshl_u32 v91, v97, v116, 1
	v_mov_b32_dpp v86, v86 quad_perm:[1,0,3,2] row_mask:0xf bank_mask:0xf bound_ctrl:1
	v_cndmask_b32_e64 v87, v87, v86, s[6:7]
	v_cndmask_b32_e64 v86, v86, v85, s[6:7]
	s_waitcnt vmcnt(33)
	v_lshlrev_b32_e32 v85, 16, v162
	v_and_b32_e32 v84, 0xffff0000, v162
	v_mul_f32_e32 v85, 0xbfb8aa3b, v85
	v_mul_f32_e32 v88, 0xbfb8aa3b, v84
	v_exp_f32_e32 v84, v85
	v_exp_f32_e32 v85, v88
	s_waitcnt vmcnt(33)
	v_lshlrev_b32_e32 v88, 16, v163
	v_and_b32_e32 v89, 0xffff0000, v163
	v_pk_add_f32 v[84:85], v[84:85], 1.0 op_sel_hi:[1,0]
	s_nop 0
	v_div_scale_f32 v93, s[0:1], v85, v85, 1.0
	v_div_scale_f32 v97, s[0:1], v84, v84, 1.0
	v_rcp_f32_e32 v98, v93
	v_rcp_f32_e32 v99, v97
	v_div_scale_f32 v95, vcc, 1.0, v85, 1.0
	v_fma_f32 v101, -v93, v98, 1.0
	v_fma_f32 v102, -v97, v99, 1.0
	v_fmac_f32_e32 v98, v101, v98
	v_div_scale_f32 v100, s[0:1], 1.0, v84, 1.0
	v_fmac_f32_e32 v99, v102, v99
	v_mul_f32_e32 v101, v95, v98
	v_mul_f32_e32 v102, v100, v99
	v_fma_f32 v103, -v93, v101, v95
	v_fma_f32 v104, -v97, v102, v100
	v_fmac_f32_e32 v101, v103, v98
	v_fmac_f32_e32 v102, v104, v99
	v_fma_f32 v93, -v93, v101, v95
	v_fma_f32 v95, -v97, v102, v100
	v_div_fmas_f32 v93, v93, v98, v101
	s_mov_b64 vcc, s[0:1]
	v_div_fixup_f32 v85, v93, v85, 1.0
	v_div_fmas_f32 v93, v95, v99, v102
	v_div_fixup_f32 v84, v93, v84, 1.0
	v_pk_fma_f32 v[84:85], v[86:87], v[84:85], v[88:89]
	s_nop 0
	v_cvt_pk_bf16_f32 v84, v84, v85
	global_store_dword v90, v84, s[12:13]
	s_nop 0
	v_add_u32_e32 v90, v96, v117
	s_nop 0
	v_cndmask_b32_e64 v84, v80, v82, s[6:7]
	s_waitcnt vmcnt(32)
	v_lshlrev_b32_e32 v88, 16, v165
	v_mov_b32_dpp v84, v84 quad_perm:[1,0,3,2] row_mask:0xf bank_mask:0xf bound_ctrl:1
	v_cndmask_b32_e64 v85, v82, v84, s[6:7]
	v_cndmask_b32_e64 v84, v84, v80, s[6:7]
	v_lshlrev_b32_e32 v80, 16, v164
	v_and_b32_e32 v82, 0xffff0000, v164
	v_mul_f32_e32 v80, 0xbfb8aa3b, v80
	v_mul_f32_e32 v82, 0xbfb8aa3b, v82
	v_exp_f32_e32 v86, v80
	v_exp_f32_e32 v87, v82
	v_add_lshl_u32 v80, v92, v116, 1
	v_and_b32_e32 v89, 0xffff0000, v165
	v_pk_add_f32 v[86:87], v[86:87], 1.0 op_sel_hi:[1,0]
	s_nop 0
	v_div_scale_f32 v82, s[0:1], v87, v87, 1.0
	v_div_scale_f32 v92, s[0:1], v86, v86, 1.0
	v_rcp_f32_e32 v93, v82
	v_rcp_f32_e32 v95, v92
	v_div_scale_f32 v91, vcc, 1.0, v87, 1.0
	v_fma_f32 v97, -v82, v93, 1.0
	v_fma_f32 v98, -v92, v95, 1.0
	v_fmac_f32_e32 v93, v97, v93
	v_div_scale_f32 v96, s[0:1], 1.0, v86, 1.0
	v_fmac_f32_e32 v95, v98, v95
	v_mul_f32_e32 v97, v91, v93
	v_mul_f32_e32 v98, v96, v95
	v_fma_f32 v99, -v82, v97, v91
	v_fma_f32 v100, -v92, v98, v96
	v_fmac_f32_e32 v97, v99, v93
	v_fmac_f32_e32 v98, v100, v95
	v_fma_f32 v82, -v82, v97, v91
	v_fma_f32 v91, -v92, v98, v96
	v_div_fmas_f32 v82, v82, v93, v97
	s_mov_b64 vcc, s[0:1]
	v_div_fixup_f32 v87, v82, v87, 1.0
	v_div_fmas_f32 v82, v91, v95, v98
	v_div_fixup_f32 v86, v82, v86, 1.0
	v_pk_fma_f32 v[84:85], v[84:85], v[86:87], v[88:89]
	v_add_u32_e32 v86, v94, v117
	v_cvt_pk_bf16_f32 v82, v84, v85
	global_store_dword v90, v82, s[12:13]
	s_nop 0
	v_cndmask_b32_e64 v82, v81, v83, s[6:7]
	s_nop 0
	s_waitcnt vmcnt(31)
; template <int EPI, bool GATHER>
; DEVINL void gemm_tile(const Params& p, const u16* __restrict__ A, int lda, const int* __restrict__ rowidx,
;                       const u16* __restrict__ Bt, int ldb, int K, int brow, int bcol, int orow, int ocol) {
;     ...
;     for (int m = 0; m < 4; ++m) {
;       const int rA = row0 + ai * HALF + m * 16 + (odd ? 2 : 0);
;       float gate[2] = {0.f, 0.f};
;       if (EPI == EPI_MOE2) { gate[0] = ((const float*)(ws + O_SELG))[rA]; gate[1] = ((const float*)(ws + O_SELG))[rA + 1]; }
; #pragma unroll
;       for (int bj = 0; bj < (EPI == EPI_HID ? 1 : 2); ++bj)
; #pragma unroll
;         for (int n = 0; n < 2; ++n) {
;           const int cc = bj * HALF + n * 16;
;           f32x4 v = acc[ai][bj][m][n];
;           if (EPI == EPI_HID) {
; #pragma unroll
;             for (int j = 0; j < 4; ++j) { const float a1 = acc[ai][0][m][n][j], a3 = acc[ai][1][m][n][j]; v[j] = a1 * sigm(a1) * a3; }
;           }
;           float lo[2], hi[2];
;           xchg_pairs(v, odd, lo, hi);
; #pragma unroll
;           for (int k = 0; k < 2; ++k) {
;             const unsigned row = (unsigned)(rA + k);
;             if (EPI == EPI_HID) {
;               *(unsigned*)(ws + O_HID + (row * 1024u + (unsigned)(colp + cc)) * 2u) = pk2(lo[k], hi[k]);
;             } else if (EPI == EPI_COLS) {
;               *(unsigned*)(ws + O_COLS + (row * (unsigned)NCP + (unsigned)(colp + cc)) * 2u) = pk2(lo[k], hi[k]);
;             } else if (EPI == EPI_MOE2) {
;               *(unsigned*)(ws + O_EO + (row * 2048u + (unsigned)(colp + cc)) * 2u) = pk2(gate[k] * lo[k], gate[k] * hi[k]);
;             } else if (EPI == EPI_M1) {
;               const unsigned g2 = *(const unsigned*)(ws + O_COLS + (row * (unsigned)NCP + (unsigned)(C_GG + colp + cc)) * 2u);
;               *(unsigned*)(ws + O_M1 + (row * 2048u + (unsigned)(colp + cc)) * 2u) = pk2(sigm(bflo(g2)) * lo[k], sigm(bfhi(g2)) * hi[k]);
;             } else if (EPI == EPI_MERGED) {
;               const unsigned g2 = *(const unsigned*)(ws + O_COLS + (row * (unsigned)NCP + (unsigned)(C_GR + colp + cc)) * 2u);
;               const unsigned m1 = *(const unsigned*)(ws + O_M1 + (row * 2048u + (unsigned)(colp + cc)) * 2u);
;               *(unsigned*)(ws + O_MERGED + (row * 2048u + (unsigned)(colp + cc)) * 2u) =
;                   pk2(bflo(m1) + sigm(bflo(g2)) * lo[k], bfhi(m1) + sigm(bfhi(g2)) * hi[k]);
	v_lshlrev_b32_e32 v84, 16, v166
	v_and_b32_e32 v80, 0xffff0000, v166
	v_mul_f32_e32 v84, 0xbfb8aa3b, v84
	v_mul_f32_e32 v80, 0xbfb8aa3b, v80
	v_exp_f32_e32 v84, v84
	v_exp_f32_e32 v85, v80
	v_mov_b32_dpp v82, v82 quad_perm:[1,0,3,2] row_mask:0xf bank_mask:0xf bound_ctrl:1
	v_cndmask_b32_e64 v83, v83, v82, s[6:7]
	v_cndmask_b32_e64 v82, v82, v81, s[6:7]
	v_pk_add_f32 v[84:85], v[84:85], 1.0 op_sel_hi:[1,0]
	s_waitcnt vmcnt(31)
	v_lshlrev_b32_e32 v80, 16, v167
	v_and_b32_e32 v81, 0xffff0000, v167
	v_div_scale_f32 v87, s[0:1], v85, v85, 1.0
	v_div_scale_f32 v89, s[0:1], v84, v84, 1.0
	v_rcp_f32_e32 v90, v87
	v_rcp_f32_e32 v91, v89
	v_div_scale_f32 v88, vcc, 1.0, v85, 1.0
	v_fma_f32 v93, -v87, v90, 1.0
	v_fma_f32 v94, -v89, v91, 1.0
	v_fmac_f32_e32 v90, v93, v90
	v_div_scale_f32 v92, s[0:1], 1.0, v84, 1.0
	v_fmac_f32_e32 v91, v94, v91
	v_mul_f32_e32 v93, v88, v90
	v_mul_f32_e32 v94, v92, v91
	v_fma_f32 v95, -v87, v93, v88
	v_fma_f32 v96, -v89, v94, v92
	v_fmac_f32_e32 v93, v95, v90
	v_fmac_f32_e32 v94, v96, v91
	v_fma_f32 v87, -v87, v93, v88
	v_fma_f32 v88, -v89, v94, v92
	v_div_fmas_f32 v87, v87, v90, v93
	s_mov_b64 vcc, s[0:1]
	v_div_fixup_f32 v85, v87, v85, 1.0
	v_div_fmas_f32 v87, v88, v91, v94
	v_div_fixup_f32 v84, v87, v84, 1.0
	v_pk_fma_f32 v[80:81], v[82:83], v[84:85], v[80:81]
	s_nop 0
	v_cvt_pk_bf16_f32 v80, v80, v81
	global_store_dword v86, v80, s[12:13]
	v_add_u32_e32 v184, 0x150000, v131
	v_add_lshl_u32 v185, v184, v130, 1
	global_load_dword v152, v185, s[8:9]
	v_add_u32_e32 v185, 0x80000, v129
	v_add_u32_e32 v186, v185, v128
	global_load_dword v153, v186, s[10:11]
	v_add_u32_e32 v187, 0x152a00, v131
	v_add_lshl_u32 v188, v187, v130, 1
	global_load_dword v154, v188, s[8:9]
	v_add_u32_e32 v222, 0x81000, v129
	v_add_u32_e32 v223, v222, v128
	global_load_dword v155, v223, s[10:11]
	v_add_lshl_u32 v224, v184, v124, 1
	v_add_u32_e32 v225, v185, v125
	global_load_dword v156, v224, s[8:9]
	global_load_dword v157, v225, s[10:11]
	v_add_lshl_u32 v223, v187, v124, 1
	v_add_u32_e32 v226, v222, v125
	global_load_dword v158, v223, s[8:9]
	global_load_dword v159, v226, s[10:11]
	v_add_lshl_u32 v227, v184, v120, 1
	v_add_lshl_u32 v225, v187, v120, 1
	global_load_dword v160, v227, s[8:9]
	v_add_u32_e32 v226, v185, v121
	global_load_dword v161, v226, s[10:11]
	v_add_u32_e32 v228, v222, v121
	global_load_dword v162, v225, s[8:9]
	global_load_dword v163, v228, s[10:11]
	v_add_lshl_u32 v229, v184, v116, 1
	v_add_lshl_u32 v230, v187, v116, 1
	global_load_dword v164, v229, s[8:9]
	v_add_u32_e32 v228, v185, v117
	global_load_dword v165, v228, s[10:11]
	v_add_u32_e32 v231, v222, v117
	global_load_dword v166, v230, s[8:9]
	global_load_dword v167, v231, s[10:11]
	v_or_b32_e32 v80, 48, v132
	v_mul_lo_u32 v81, v80, s51
	v_add_lshl_u32 v82, v81, v130, 1
	s_nop 0
	v_lshlrev_b32_e32 v80, 12, v80
	v_add_u32_e32 v88, v80, v128
	s_nop 0
	v_cndmask_b32_e64 v82, v76, v78, s[6:7]
	s_waitcnt vmcnt(38)
	v_lshlrev_b32_e32 v86, 16, v191
	v_mov_b32_dpp v82, v82 quad_perm:[1,0,3,2] row_mask:0xf bank_mask:0xf bound_ctrl:1
	v_cndmask_b32_e64 v83, v78, v82, s[6:7]
	v_lshlrev_b32_e32 v78, 16, v190
	v_and_b32_e32 v84, 0xffff0000, v190
	v_mul_f32_e32 v78, 0xbfb8aa3b, v78
	v_mul_f32_e32 v85, 0xbfb8aa3b, v84
	v_exp_f32_e32 v84, v78
	v_exp_f32_e32 v85, v85
	v_cndmask_b32_e64 v82, v82, v76, s[6:7]
	v_and_b32_e32 v87, 0xffff0000, v191
	v_add_u32_e32 v76, 0x2a00, v81
	v_pk_add_f32 v[84:85], v[84:85], 1.0 op_sel_hi:[1,0]
	v_add_lshl_u32 v78, v76, v130, 1
	v_div_scale_f32 v89, s[0:1], v85, v85, 1.0
	v_div_scale_f32 v91, s[0:1], v84, v84, 1.0
	v_rcp_f32_e32 v92, v89
	v_rcp_f32_e32 v93, v91
	v_div_scale_f32 v90, vcc, 1.0, v85, 1.0
	v_fma_f32 v95, -v89, v92, 1.0
	v_fma_f32 v96, -v91, v93, 1.0
	v_fmac_f32_e32 v92, v95, v92
	v_div_scale_f32 v94, s[0:1], 1.0, v84, 1.0
	v_fmac_f32_e32 v93, v96, v93
	v_mul_f32_e32 v95, v90, v92
	v_mul_f32_e32 v96, v94, v93
	v_fma_f32 v97, -v89, v95, v90
	v_fma_f32 v98, -v91, v96, v94
	v_fmac_f32_e32 v95, v97, v92
	v_fmac_f32_e32 v96, v98, v93
	v_fma_f32 v89, -v89, v95, v90
	v_fma_f32 v90, -v91, v96, v94
	v_div_fmas_f32 v89, v89, v92, v95
	s_mov_b64 vcc, s[0:1]
	v_div_fixup_f32 v85, v89, v85, 1.0
	v_div_fmas_f32 v89, v90, v93, v96
	v_div_fixup_f32 v84, v89, v84, 1.0
	v_pk_fma_f32 v[82:83], v[82:83], v[84:85], v[86:87]
	s_nop 0
	v_cvt_pk_bf16_f32 v82, v82, v83
	global_store_dword v88, v82, s[12:13]
	s_nop 0
	v_or_b32_e32 v78, 0x31000, v129
	v_add_u32_e32 v88, v78, v128
	s_nop 0
	v_cndmask_b32_e64 v82, v77, v79, s[6:7]
	s_waitcnt vmcnt(37)
	v_lshlrev_b32_e32 v86, 16, v193
	v_mov_b32_dpp v82, v82 quad_perm:[1,0,3,2] row_mask:0xf bank_mask:0xf bound_ctrl:1
	v_cndmask_b32_e64 v83, v79, v82, s[6:7]
	v_cndmask_b32_e64 v82, v82, v77, s[6:7]
	v_lshlrev_b32_e32 v77, 16, v192
	v_and_b32_e32 v79, 0xffff0000, v192
	v_mul_f32_e32 v77, 0xbfb8aa3b, v77
	v_mul_f32_e32 v79, 0xbfb8aa3b, v79
	v_exp_f32_e32 v84, v77
	v_exp_f32_e32 v85, v79
	v_and_b32_e32 v87, 0xffff0000, v193
	v_add_lshl_u32 v77, v81, v124, 1
	v_pk_add_f32 v[84:85], v[84:85], 1.0 op_sel_hi:[1,0]
	s_nop 0
	v_div_scale_f32 v79, s[0:1], v85, v85, 1.0
	v_div_scale_f32 v90, s[0:1], v84, v84, 1.0
	v_rcp_f32_e32 v91, v79
	v_rcp_f32_e32 v92, v90
	v_div_scale_f32 v89, vcc, 1.0, v85, 1.0
	v_fma_f32 v94, -v79, v91, 1.0
	v_fma_f32 v95, -v90, v92, 1.0
	v_fmac_f32_e32 v91, v94, v91
	v_div_scale_f32 v93, s[0:1], 1.0, v84, 1.0
	v_fmac_f32_e32 v92, v95, v92
	v_mul_f32_e32 v94, v89, v91
	v_mul_f32_e32 v95, v93, v92
	v_fma_f32 v96, -v79, v94, v89
	v_fma_f32 v97, -v90, v95, v93
	v_fmac_f32_e32 v94, v96, v91
	v_fmac_f32_e32 v95, v97, v92
	v_fma_f32 v79, -v79, v94, v89
	v_fma_f32 v89, -v90, v95, v93
	v_div_fmas_f32 v79, v79, v91, v94
	s_mov_b64 vcc, s[0:1]
	v_div_fixup_f32 v85, v79, v85, 1.0
	v_div_fmas_f32 v79, v89, v92, v95
	v_div_fixup_f32 v84, v79, v84, 1.0
	v_pk_fma_f32 v[82:83], v[82:83], v[84:85], v[86:87]
	s_nop 0
	v_cvt_pk_bf16_f32 v79, v82, v83
	global_store_dword v88, v79, s[12:13]
	s_nop 0
	v_add_u32_e32 v79, v80, v125
	s_nop 0
	v_cndmask_b32_e64 v82, v72, v74, s[6:7]
	s_waitcnt vmcnt(36)
; DEVINL float bflo(unsigned u) { return __uint_as_float(u << 16); }
; DEVINL float bfhi(unsigned u) { return __uint_as_float(u & 0xffff0000u); }
; DEVINL float sigm(float x) { return 1.f / (1.f + __expf(-x)); }
; template <int EPI, bool GATHER>
; DEVINL void gemm_tile(const Params& p, const u16* __restrict__ A, int lda, const int* __restrict__ rowidx,
;                       const u16* __restrict__ Bt, int ldb, int K, int brow, int bcol, int orow, int ocol) {
;     ...
;       for (int bj = 0; bj < (EPI == EPI_HID ? 1 : 2); ++bj)
; #pragma unroll
;         for (int n = 0; n < 2; ++n) {
;           const int cc = bj * HALF + n * 16;
;           f32x4 v = acc[ai][bj][m][n];
;           if (EPI == EPI_HID) {
; #pragma unroll
;             for (int j = 0; j < 4; ++j) { const float a1 = acc[ai][0][m][n][j], a3 = acc[ai][1][m][n][j]; v[j] = a1 * sigm(a1) * a3; }
;           }
;           float lo[2], hi[2];
;           xchg_pairs(v, odd, lo, hi);
; #pragma unroll
;           for (int k = 0; k < 2; ++k) {
;             const unsigned row = (unsigned)(rA + k);
;             if (EPI == EPI_HID) {
;               *(unsigned*)(ws + O_HID + (row * 1024u + (unsigned)(colp + cc)) * 2u) = pk2(lo[k], hi[k]);
;             } else if (EPI == EPI_COLS) {
;               *(unsigned*)(ws + O_COLS + (row * (unsigned)NCP + (unsigned)(colp + cc)) * 2u) = pk2(lo[k], hi[k]);
;             } else if (EPI == EPI_MOE2) {
;               *(unsigned*)(ws + O_EO + (row * 2048u + (unsigned)(colp + cc)) * 2u) = pk2(gate[k] * lo[k], gate[k] * hi[k]);
;             } else if (EPI == EPI_M1) {
;               const unsigned g2 = *(const unsigned*)(ws + O_COLS + (row * (unsigned)NCP + (unsigned)(C_GG + colp + cc)) * 2u);
;               *(unsigned*)(ws + O_M1 + (row * 2048u + (unsigned)(colp + cc)) * 2u) = pk2(sigm(bflo(g2)) * lo[k], sigm(bfhi(g2)) * hi[k]);
;             } else if (EPI == EPI_MERGED) {
;               const unsigned g2 = *(const unsigned*)(ws + O_COLS + (row * (unsigned)NCP + (unsigned)(C_GR + colp + cc)) * 2u);
;               const unsigned m1 = *(const unsigned*)(ws + O_M1 + (row * 2048u + (unsigned)(colp + cc)) * 2u);
;               *(unsigned*)(ws + O_MERGED + (row * 2048u + (unsigned)(colp + cc)) * 2u) =
;                   pk2(bflo(m1) + sigm(bflo(g2)) * lo[k], bfhi(m1) + sigm(bfhi(g2)) * hi[k]);
	v_lshlrev_b32_e32 v86, 16, v195
	v_mov_b32_dpp v82, v82 quad_perm:[1,0,3,2] row_mask:0xf bank_mask:0xf bound_ctrl:1
	v_cndmask_b32_e64 v83, v74, v82, s[6:7]
	v_cndmask_b32_e64 v82, v82, v72, s[6:7]
	v_lshlrev_b32_e32 v72, 16, v194
	v_and_b32_e32 v74, 0xffff0000, v194
	v_mul_f32_e32 v72, 0xbfb8aa3b, v72
	v_mul_f32_e32 v74, 0xbfb8aa3b, v74
	v_exp_f32_e32 v84, v72
	v_exp_f32_e32 v85, v74
	v_and_b32_e32 v87, 0xffff0000, v195
	v_add_lshl_u32 v72, v76, v124, 1
	v_pk_add_f32 v[84:85], v[84:85], 1.0 op_sel_hi:[1,0]
	s_nop 0
	v_div_scale_f32 v74, s[0:1], v85, v85, 1.0
	v_div_scale_f32 v88, s[0:1], v84, v84, 1.0
	v_rcp_f32_e32 v89, v74
	v_rcp_f32_e32 v90, v88
	v_div_scale_f32 v77, vcc, 1.0, v85, 1.0
	v_fma_f32 v92, -v74, v89, 1.0
	v_fma_f32 v93, -v88, v90, 1.0
	v_fmac_f32_e32 v89, v92, v89
	v_div_scale_f32 v91, s[0:1], 1.0, v84, 1.0
	v_fmac_f32_e32 v90, v93, v90
	v_mul_f32_e32 v92, v77, v89
	v_mul_f32_e32 v93, v91, v90
	v_fma_f32 v94, -v74, v92, v77
	v_fma_f32 v95, -v88, v93, v91
	v_fmac_f32_e32 v92, v94, v89
	v_fmac_f32_e32 v93, v95, v90
	v_fma_f32 v74, -v74, v92, v77
	v_fma_f32 v77, -v88, v93, v91
	v_div_fmas_f32 v74, v74, v89, v92
	s_mov_b64 vcc, s[0:1]
	v_div_fixup_f32 v85, v74, v85, 1.0
	v_div_fmas_f32 v74, v77, v90, v93
	v_div_fixup_f32 v84, v74, v84, 1.0
	v_pk_fma_f32 v[82:83], v[82:83], v[84:85], v[86:87]
	v_add_u32_e32 v77, v78, v125
	v_cvt_pk_bf16_f32 v74, v82, v83
	global_store_dword v79, v74, s[12:13]
	s_nop 0
	v_cndmask_b32_e64 v74, v73, v75, s[6:7]
	s_nop 0
	v_add_lshl_u32 v84, v81, v120, 1
	v_mov_b32_dpp v74, v74 quad_perm:[1,0,3,2] row_mask:0xf bank_mask:0xf bound_ctrl:1
	v_cndmask_b32_e64 v75, v75, v74, s[6:7]
	v_cndmask_b32_e64 v74, v74, v73, s[6:7]
	s_waitcnt vmcnt(35)
	v_lshlrev_b32_e32 v73, 16, v196
	v_and_b32_e32 v72, 0xffff0000, v196
	v_mul_f32_e32 v73, 0xbfb8aa3b, v73
	v_mul_f32_e32 v82, 0xbfb8aa3b, v72
	v_exp_f32_e32 v72, v73
	v_exp_f32_e32 v73, v82
	s_waitcnt vmcnt(35)
	v_lshlrev_b32_e32 v82, 16, v197
	v_and_b32_e32 v83, 0xffff0000, v197
	v_pk_add_f32 v[72:73], v[72:73], 1.0 op_sel_hi:[1,0]
	s_nop 0
	v_div_scale_f32 v79, s[0:1], v73, v73, 1.0
	v_div_scale_f32 v86, s[0:1], v72, v72, 1.0
	v_rcp_f32_e32 v87, v79
	v_rcp_f32_e32 v88, v86
	v_div_scale_f32 v85, vcc, 1.0, v73, 1.0
	v_fma_f32 v90, -v79, v87, 1.0
	v_fma_f32 v91, -v86, v88, 1.0
	v_fmac_f32_e32 v87, v90, v87
	v_div_scale_f32 v89, s[0:1], 1.0, v72, 1.0
	v_fmac_f32_e32 v88, v91, v88
	v_mul_f32_e32 v90, v85, v87
	v_mul_f32_e32 v91, v89, v88
	v_fma_f32 v92, -v79, v90, v85
	v_fma_f32 v93, -v86, v91, v89
	v_fmac_f32_e32 v90, v92, v87
	v_fmac_f32_e32 v91, v93, v88
	v_fma_f32 v79, -v79, v90, v85
	v_fma_f32 v85, -v86, v91, v89
	v_div_fmas_f32 v79, v79, v87, v90
	s_mov_b64 vcc, s[0:1]
	v_div_fixup_f32 v73, v79, v73, 1.0
	v_div_fmas_f32 v79, v85, v88, v91
	v_div_fixup_f32 v72, v79, v72, 1.0
	v_pk_fma_f32 v[72:73], v[74:75], v[72:73], v[82:83]
	s_nop 0
	v_cvt_pk_bf16_f32 v72, v72, v73
	global_store_dword v77, v72, s[12:13]
	s_nop 0
	v_add_u32_e32 v77, v80, v121
	s_nop 0
	v_cndmask_b32_e64 v72, v68, v70, s[6:7]
	s_waitcnt vmcnt(34)
	v_lshlrev_b32_e32 v82, 16, v199
	v_mov_b32_dpp v72, v72 quad_perm:[1,0,3,2] row_mask:0xf bank_mask:0xf bound_ctrl:1
	v_cndmask_b32_e64 v73, v70, v72, s[6:7]
	v_cndmask_b32_e64 v72, v72, v68, s[6:7]
	v_lshlrev_b32_e32 v68, 16, v198
	v_and_b32_e32 v70, 0xffff0000, v198
	v_mul_f32_e32 v68, 0xbfb8aa3b, v68
	v_mul_f32_e32 v70, 0xbfb8aa3b, v70
	v_exp_f32_e32 v74, v68
	v_exp_f32_e32 v75, v70
	v_and_b32_e32 v83, 0xffff0000, v199
	v_add_lshl_u32 v68, v76, v120, 1
	v_pk_add_f32 v[74:75], v[74:75], 1.0 op_sel_hi:[1,0]
	s_nop 0
	v_div_scale_f32 v70, s[0:1], v75, v75, 1.0
	v_div_scale_f32 v84, s[0:1], v74, v74, 1.0
	v_rcp_f32_e32 v85, v70
	v_rcp_f32_e32 v86, v84
	v_div_scale_f32 v79, vcc, 1.0, v75, 1.0
	v_fma_f32 v88, -v70, v85, 1.0
	v_fma_f32 v89, -v84, v86, 1.0
	v_fmac_f32_e32 v85, v88, v85
	v_div_scale_f32 v87, s[0:1], 1.0, v74, 1.0
	v_fmac_f32_e32 v86, v89, v86
	v_mul_f32_e32 v88, v79, v85
	v_mul_f32_e32 v89, v87, v86
	v_fma_f32 v90, -v70, v88, v79
	v_fma_f32 v91, -v84, v89, v87
	v_fmac_f32_e32 v88, v90, v85
	v_fmac_f32_e32 v89, v91, v86
	v_fma_f32 v70, -v70, v88, v79
	v_fma_f32 v79, -v84, v89, v87
	v_div_fmas_f32 v70, v70, v85, v88
	s_mov_b64 vcc, s[0:1]
	v_div_fixup_f32 v75, v70, v75, 1.0
	v_div_fmas_f32 v70, v79, v86, v89
	v_div_fixup_f32 v74, v70, v74, 1.0
	v_pk_fma_f32 v[72:73], v[72:73], v[74:75], v[82:83]
	v_add_u32_e32 v74, v78, v121
	v_cvt_pk_bf16_f32 v70, v72, v73
	global_store_dword v77, v70, s[12:13]
	s_nop 0
	v_cndmask_b32_e64 v70, v69, v71, s[6:7]
	s_nop 0
	v_add_lshl_u32 v75, v81, v116, 1
	v_mov_b32_dpp v70, v70 quad_perm:[1,0,3,2] row_mask:0xf bank_mask:0xf bound_ctrl:1
	v_cndmask_b32_e64 v71, v71, v70, s[6:7]
	v_cndmask_b32_e64 v70, v70, v69, s[6:7]
	s_waitcnt vmcnt(33)
	v_lshlrev_b32_e32 v69, 16, v200
	v_and_b32_e32 v68, 0xffff0000, v200
	v_mul_f32_e32 v69, 0xbfb8aa3b, v69
	v_mul_f32_e32 v72, 0xbfb8aa3b, v68
	v_exp_f32_e32 v68, v69
	v_exp_f32_e32 v69, v72
	s_waitcnt vmcnt(33)
	v_lshlrev_b32_e32 v72, 16, v201
	v_and_b32_e32 v73, 0xffff0000, v201
	v_pk_add_f32 v[68:69], v[68:69], 1.0 op_sel_hi:[1,0]
	s_nop 0
	v_div_scale_f32 v77, s[0:1], v69, v69, 1.0
	v_div_scale_f32 v81, s[0:1], v68, v68, 1.0
	v_rcp_f32_e32 v82, v77
	v_rcp_f32_e32 v83, v81
	v_div_scale_f32 v79, vcc, 1.0, v69, 1.0
	v_fma_f32 v85, -v77, v82, 1.0
	v_fma_f32 v86, -v81, v83, 1.0
	v_fmac_f32_e32 v82, v85, v82
	v_div_scale_f32 v84, s[0:1], 1.0, v68, 1.0
	v_fmac_f32_e32 v83, v86, v83
	v_mul_f32_e32 v85, v79, v82
	v_mul_f32_e32 v86, v84, v83
	v_fma_f32 v87, -v77, v85, v79
	v_fma_f32 v88, -v81, v86, v84
	v_fmac_f32_e32 v85, v87, v82
	v_fmac_f32_e32 v86, v88, v83
	v_fma_f32 v77, -v77, v85, v79
	v_fma_f32 v79, -v81, v86, v84
	v_div_fmas_f32 v77, v77, v82, v85
	s_mov_b64 vcc, s[0:1]
	v_div_fixup_f32 v69, v77, v69, 1.0
	v_div_fmas_f32 v77, v79, v83, v86
	v_div_fixup_f32 v68, v77, v68, 1.0
	v_pk_fma_f32 v[68:69], v[70:71], v[68:69], v[72:73]
	s_nop 0
	v_cvt_pk_bf16_f32 v68, v68, v69
	global_store_dword v74, v68, s[12:13]
	s_nop 0
	v_add_u32_e32 v74, v80, v117
	s_nop 0
	v_cndmask_b32_e64 v68, v64, v66, s[6:7]
	s_waitcnt vmcnt(32)
; template <int EPI, bool GATHER>
; DEVINL void gemm_tile(const Params& p, const u16* __restrict__ A, int lda, const int* __restrict__ rowidx,
;                       const u16* __restrict__ Bt, int ldb, int K, int brow, int bcol, int orow, int ocol) {
;     ...
;     for (int m = 0; m < 4; ++m) {
;       const int rA = row0 + ai * HALF + m * 16 + (odd ? 2 : 0);
;       float gate[2] = {0.f, 0.f};
;       if (EPI == EPI_MOE2) { gate[0] = ((const float*)(ws + O_SELG))[rA]; gate[1] = ((const float*)(ws + O_SELG))[rA + 1]; }
; #pragma unroll
;       for (int bj = 0; bj < (EPI == EPI_HID ? 1 : 2); ++bj)
; #pragma unroll
;         for (int n = 0; n < 2; ++n) {
;           const int cc = bj * HALF + n * 16;
;           f32x4 v = acc[ai][bj][m][n];
;           if (EPI == EPI_HID) {
; #pragma unroll
;             for (int j = 0; j < 4; ++j) { const float a1 = acc[ai][0][m][n][j], a3 = acc[ai][1][m][n][j]; v[j] = a1 * sigm(a1) * a3; }
;           }
;           float lo[2], hi[2];
;           xchg_pairs(v, odd, lo, hi);
; #pragma unroll
;           for (int k = 0; k < 2; ++k) {
;             const unsigned row = (unsigned)(rA + k);
;             if (EPI == EPI_HID) {
;               *(unsigned*)(ws + O_HID + (row * 1024u + (unsigned)(colp + cc)) * 2u) = pk2(lo[k], hi[k]);
;             } else if (EPI == EPI_COLS) {
;               *(unsigned*)(ws + O_COLS + (row * (unsigned)NCP + (unsigned)(colp + cc)) * 2u) = pk2(lo[k], hi[k]);
;             } else if (EPI == EPI_MOE2) {
;               *(unsigned*)(ws + O_EO + (row * 2048u + (unsigned)(colp + cc)) * 2u) = pk2(gate[k] * lo[k], gate[k] * hi[k]);
;             } else if (EPI == EPI_M1) {
;               const unsigned g2 = *(const unsigned*)(ws + O_COLS + (row * (unsigned)NCP + (unsigned)(C_GG + colp + cc)) * 2u);
;               *(unsigned*)(ws + O_M1 + (row * 2048u + (unsigned)(colp + cc)) * 2u) = pk2(sigm(bflo(g2)) * lo[k], sigm(bfhi(g2)) * hi[k]);
;             } else if (EPI == EPI_MERGED) {
;               const unsigned g2 = *(const unsigned*)(ws + O_COLS + (row * (unsigned)NCP + (unsigned)(C_GR + colp + cc)) * 2u);
;               const unsigned m1 = *(const unsigned*)(ws + O_M1 + (row * 2048u + (unsigned)(colp + cc)) * 2u);
;               *(unsigned*)(ws + O_MERGED + (row * 2048u + (unsigned)(colp + cc)) * 2u) =
;                   pk2(bflo(m1) + sigm(bflo(g2)) * lo[k], bfhi(m1) + sigm(bfhi(g2)) * hi[k]);
	v_lshlrev_b32_e32 v72, 16, v203
	v_mov_b32_dpp v68, v68 quad_perm:[1,0,3,2] row_mask:0xf bank_mask:0xf bound_ctrl:1
	v_cndmask_b32_e64 v69, v66, v68, s[6:7]
	v_cndmask_b32_e64 v68, v68, v64, s[6:7]
	v_lshlrev_b32_e32 v64, 16, v202
	v_and_b32_e32 v66, 0xffff0000, v202
	v_mul_f32_e32 v64, 0xbfb8aa3b, v64
	v_mul_f32_e32 v66, 0xbfb8aa3b, v66
	v_exp_f32_e32 v70, v64
	v_exp_f32_e32 v71, v66
	v_add_lshl_u32 v64, v76, v116, 1
	v_and_b32_e32 v73, 0xffff0000, v203
	v_pk_add_f32 v[70:71], v[70:71], 1.0 op_sel_hi:[1,0]
	s_nop 0
	v_div_scale_f32 v66, s[0:1], v71, v71, 1.0
	v_div_scale_f32 v76, s[0:1], v70, v70, 1.0
	v_rcp_f32_e32 v77, v66
	v_rcp_f32_e32 v79, v76
	v_div_scale_f32 v75, vcc, 1.0, v71, 1.0
	v_fma_f32 v81, -v66, v77, 1.0
	v_fma_f32 v82, -v76, v79, 1.0
	v_fmac_f32_e32 v77, v81, v77
	v_div_scale_f32 v80, s[0:1], 1.0, v70, 1.0
	v_fmac_f32_e32 v79, v82, v79
	v_mul_f32_e32 v81, v75, v77
	v_mul_f32_e32 v82, v80, v79
	v_fma_f32 v83, -v66, v81, v75
	v_fma_f32 v84, -v76, v82, v80
	v_fmac_f32_e32 v81, v83, v77
	v_fmac_f32_e32 v82, v84, v79
	v_fma_f32 v66, -v66, v81, v75
	v_fma_f32 v75, -v76, v82, v80
	v_div_fmas_f32 v66, v66, v77, v81
	s_mov_b64 vcc, s[0:1]
	v_div_fixup_f32 v71, v66, v71, 1.0
	v_div_fmas_f32 v66, v75, v79, v82
	v_div_fixup_f32 v70, v66, v70, 1.0
	v_pk_fma_f32 v[68:69], v[68:69], v[70:71], v[72:73]
	v_add_u32_e32 v70, v78, v117
	v_cvt_pk_bf16_f32 v66, v68, v69
	global_store_dword v74, v66, s[12:13]
	s_nop 0
	s_nop 0
	s_nop 0
	v_cndmask_b32_e64 v64, v65, v67, s[6:7]
	s_nop 1
	v_mov_b32_dpp v72, v64 quad_perm:[1,0,3,2] row_mask:0xf bank_mask:0xf bound_ctrl:1
	v_cndmask_b32_e64 v64, v72, v65, s[6:7]
	s_waitcnt vmcnt(31)
	v_lshlrev_b32_e32 v65, 16, v204
	v_and_b32_e32 v66, 0xffff0000, v204
	v_mul_f32_e32 v65, 0xbfb8aa3b, v65
	v_mul_f32_e32 v66, 0xbfb8aa3b, v66
	v_exp_f32_e32 v68, v65
	v_exp_f32_e32 v69, v66
	v_cndmask_b32_e64 v65, v67, v72, s[6:7]
	s_waitcnt vmcnt(31)
	v_lshlrev_b32_e32 v66, 16, v205
	v_and_b32_e32 v67, 0xffff0000, v205
	v_pk_add_f32 v[68:69], v[68:69], 1.0 op_sel_hi:[1,0]
	s_nop 0
	v_div_scale_f32 v71, s[0:1], v69, v69, 1.0
	v_div_scale_f32 v73, s[0:1], v68, v68, 1.0
	v_rcp_f32_e32 v74, v71
	v_rcp_f32_e32 v75, v73
	v_div_scale_f32 v72, vcc, 1.0, v69, 1.0
	v_fma_f32 v77, -v71, v74, 1.0
	v_fma_f32 v78, -v73, v75, 1.0
	v_fmac_f32_e32 v74, v77, v74
	v_div_scale_f32 v76, s[0:1], 1.0, v68, 1.0
	v_fmac_f32_e32 v75, v78, v75
	v_mul_f32_e32 v77, v72, v74
	v_mul_f32_e32 v78, v76, v75
	v_fma_f32 v79, -v71, v77, v72
	v_fma_f32 v80, -v73, v78, v76
	v_fmac_f32_e32 v77, v79, v74
	v_fmac_f32_e32 v78, v80, v75
	v_fma_f32 v71, -v71, v77, v72
	v_fma_f32 v72, -v73, v78, v76
	v_div_fmas_f32 v71, v71, v74, v77
	s_mov_b64 vcc, s[0:1]
	v_div_fixup_f32 v69, v71, v69, 1.0
	v_div_fmas_f32 v71, v72, v75, v78
	v_div_fixup_f32 v68, v71, v68, 1.0
	v_pk_fma_f32 v[64:65], v[64:65], v[68:69], v[66:67]
	s_nop 0
	v_cvt_pk_bf16_f32 v64, v64, v65
	global_store_dword v70, v64, s[12:13]
	v_add_u32_e32 v184, 0x17a000, v131
	v_add_lshl_u32 v185, v184, v130, 1
	global_load_dword v190, v185, s[8:9]
	v_add_u32_e32 v185, 0x90000, v129
	v_add_u32_e32 v186, v185, v128
	global_load_dword v191, v186, s[10:11]
	v_add_u32_e32 v187, 0x17ca00, v131
	v_add_lshl_u32 v188, v187, v130, 1
	global_load_dword v192, v188, s[8:9]
	v_add_u32_e32 v222, 0x91000, v129
	v_add_u32_e32 v223, v222, v128
	global_load_dword v193, v223, s[10:11]
	v_add_lshl_u32 v224, v184, v124, 1
	v_add_u32_e32 v225, v185, v125
	global_load_dword v194, v224, s[8:9]
	global_load_dword v195, v225, s[10:11]
	v_add_lshl_u32 v223, v187, v124, 1
	v_add_u32_e32 v226, v222, v125
	global_load_dword v196, v223, s[8:9]
	global_load_dword v197, v226, s[10:11]
	v_add_lshl_u32 v227, v184, v120, 1
	v_add_lshl_u32 v225, v187, v120, 1
	global_load_dword v198, v227, s[8:9]
	v_add_u32_e32 v226, v185, v121
	global_load_dword v199, v226, s[10:11]
	v_add_u32_e32 v228, v222, v121
	global_load_dword v200, v225, s[8:9]
	global_load_dword v201, v228, s[10:11]
	v_add_lshl_u32 v229, v184, v116, 1
	v_add_lshl_u32 v230, v187, v116, 1
	global_load_dword v202, v229, s[8:9]
	v_add_u32_e32 v228, v185, v117
	global_load_dword v203, v228, s[10:11]
	v_add_u32_e32 v231, v222, v117
	global_load_dword v204, v230, s[8:9]
	global_load_dword v205, v231, s[10:11]
	v_add_u32_e32 v66, 0x150000, v131
	v_add_lshl_u32 v64, v66, v130, 1
	s_nop 0
	v_add_u32_e32 v64, 0x80000, v129
	v_add_u32_e32 v74, v64, v128
	s_nop 0
	v_cndmask_b32_e64 v68, v60, v62, s[6:7]
	v_add_u32_e32 v65, 0x152a00, v131
	v_add_lshl_u32 v75, v65, v130, 1
	v_mov_b32_dpp v69, v68 quad_perm:[1,0,3,2] row_mask:0xf bank_mask:0xf bound_ctrl:1
	v_cndmask_b32_e64 v68, v69, v60, s[6:7]
	v_cndmask_b32_e64 v69, v62, v69, s[6:7]
	s_waitcnt vmcnt(38)
	v_lshlrev_b32_e32 v60, 16, v152
	v_and_b32_e32 v67, 0xffff0000, v152
	v_mul_f32_e32 v60, 0xbfb8aa3b, v60
	v_mul_f32_e32 v67, 0xbfb8aa3b, v67
	v_exp_f32_e32 v70, v60
	v_exp_f32_e32 v71, v67
	s_waitcnt vmcnt(38)
	v_lshlrev_b32_e32 v72, 16, v153
	v_and_b32_e32 v73, 0xffff0000, v153
	v_pk_add_f32 v[70:71], v[70:71], 1.0 op_sel_hi:[1,0]
	s_nop 0
	v_div_scale_f32 v60, s[0:1], v71, v71, 1.0
	v_div_scale_f32 v67, s[0:1], v70, v70, 1.0
	v_rcp_f32_e32 v76, v60
	v_rcp_f32_e32 v77, v67
	v_div_scale_f32 v62, vcc, 1.0, v71, 1.0
	v_fma_f32 v79, -v60, v76, 1.0
	v_fma_f32 v80, -v67, v77, 1.0
	v_fmac_f32_e32 v76, v79, v76
	v_div_scale_f32 v78, s[0:1], 1.0, v70, 1.0
	v_fmac_f32_e32 v77, v80, v77
	v_mul_f32_e32 v79, v62, v76
	v_mul_f32_e32 v80, v78, v77
	v_fma_f32 v81, -v60, v79, v62
	v_fma_f32 v82, -v67, v80, v78
	v_fmac_f32_e32 v79, v81, v76
	v_fmac_f32_e32 v80, v82, v77
	v_fma_f32 v60, -v60, v79, v62
	v_fma_f32 v62, -v67, v80, v78
	v_div_fmas_f32 v60, v60, v76, v79
	s_mov_b64 vcc, s[0:1]
	v_div_fixup_f32 v71, v60, v71, 1.0
	v_div_fmas_f32 v60, v62, v77, v80
	v_div_fixup_f32 v70, v60, v70, 1.0
	v_pk_fma_f32 v[68:69], v[68:69], v[70:71], v[72:73]
	v_cndmask_b32_e64 v62, v61, v63, s[6:7]
	v_cvt_pk_bf16_f32 v60, v68, v69
	global_store_dword v74, v60, s[12:13]
	s_nop 0
	v_add_u32_e32 v60, 0x81000, v129
	v_add_u32_e32 v72, v60, v128
	s_nop 0
	v_mov_b32_dpp v70, v62 quad_perm:[1,0,3,2] row_mask:0xf bank_mask:0xf bound_ctrl:1
	v_cndmask_b32_e64 v62, v70, v61, s[6:7]
	v_cndmask_b32_e64 v63, v63, v70, s[6:7]
	v_add_lshl_u32 v73, v66, v124, 1
	s_waitcnt vmcnt(37)
; DEVINL float bflo(unsigned u) { return __uint_as_float(u << 16); }
; DEVINL float bfhi(unsigned u) { return __uint_as_float(u & 0xffff0000u); }
; DEVINL float sigm(float x) { return 1.f / (1.f + __expf(-x)); }
; template <int EPI, bool GATHER>
; DEVINL void gemm_tile(const Params& p, const u16* __restrict__ A, int lda, const int* __restrict__ rowidx,
;                       const u16* __restrict__ Bt, int ldb, int K, int brow, int bcol, int orow, int ocol) {
;     ...
;       for (int bj = 0; bj < (EPI == EPI_HID ? 1 : 2); ++bj)
; #pragma unroll
;         for (int n = 0; n < 2; ++n) {
;           const int cc = bj * HALF + n * 16;
;           f32x4 v = acc[ai][bj][m][n];
;           if (EPI == EPI_HID) {
; #pragma unroll
;             for (int j = 0; j < 4; ++j) { const float a1 = acc[ai][0][m][n][j], a3 = acc[ai][1][m][n][j]; v[j] = a1 * sigm(a1) * a3; }
;           }
;           float lo[2], hi[2];
;           xchg_pairs(v, odd, lo, hi);
; #pragma unroll
;           for (int k = 0; k < 2; ++k) {
;             const unsigned row = (unsigned)(rA + k);
;             if (EPI == EPI_HID) {
;               *(unsigned*)(ws + O_HID + (row * 1024u + (unsigned)(colp + cc)) * 2u) = pk2(lo[k], hi[k]);
;             } else if (EPI == EPI_COLS) {
;               *(unsigned*)(ws + O_COLS + (row * (unsigned)NCP + (unsigned)(colp + cc)) * 2u) = pk2(lo[k], hi[k]);
;             } else if (EPI == EPI_MOE2) {
;               *(unsigned*)(ws + O_EO + (row * 2048u + (unsigned)(colp + cc)) * 2u) = pk2(gate[k] * lo[k], gate[k] * hi[k]);
;             } else if (EPI == EPI_M1) {
;               const unsigned g2 = *(const unsigned*)(ws + O_COLS + (row * (unsigned)NCP + (unsigned)(C_GG + colp + cc)) * 2u);
;               *(unsigned*)(ws + O_M1 + (row * 2048u + (unsigned)(colp + cc)) * 2u) = pk2(sigm(bflo(g2)) * lo[k], sigm(bfhi(g2)) * hi[k]);
;             } else if (EPI == EPI_MERGED) {
;               const unsigned g2 = *(const unsigned*)(ws + O_COLS + (row * (unsigned)NCP + (unsigned)(C_GR + colp + cc)) * 2u);
;               const unsigned m1 = *(const unsigned*)(ws + O_M1 + (row * 2048u + (unsigned)(colp + cc)) * 2u);
;               *(unsigned*)(ws + O_MERGED + (row * 2048u + (unsigned)(colp + cc)) * 2u) =
;                   pk2(bflo(m1) + sigm(bflo(g2)) * lo[k], bfhi(m1) + sigm(bfhi(g2)) * hi[k]);
	v_lshlrev_b32_e32 v61, 16, v154
	v_and_b32_e32 v67, 0xffff0000, v154
	v_mul_f32_e32 v61, 0xbfb8aa3b, v61
	v_mul_f32_e32 v67, 0xbfb8aa3b, v67
	v_exp_f32_e32 v68, v61
	v_exp_f32_e32 v69, v67
	s_waitcnt vmcnt(37)
	v_lshlrev_b32_e32 v70, 16, v155
	v_and_b32_e32 v71, 0xffff0000, v155
	v_pk_add_f32 v[68:69], v[68:69], 1.0 op_sel_hi:[1,0]
	s_nop 0
	v_div_scale_f32 v61, s[0:1], v69, v69, 1.0
	v_div_scale_f32 v74, s[0:1], v68, v68, 1.0
	v_rcp_f32_e32 v75, v61
	v_rcp_f32_e32 v76, v74
	v_div_scale_f32 v67, vcc, 1.0, v69, 1.0
	v_fma_f32 v78, -v61, v75, 1.0
	v_fma_f32 v79, -v74, v76, 1.0
	v_fmac_f32_e32 v75, v78, v75
	v_div_scale_f32 v77, s[0:1], 1.0, v68, 1.0
	v_fmac_f32_e32 v76, v79, v76
	v_mul_f32_e32 v78, v67, v75
	v_mul_f32_e32 v79, v77, v76
	v_fma_f32 v80, -v61, v78, v67
	v_fma_f32 v81, -v74, v79, v77
	v_fmac_f32_e32 v78, v80, v75
	v_fmac_f32_e32 v79, v81, v76
	v_fma_f32 v61, -v61, v78, v67
	v_fma_f32 v67, -v74, v79, v77
	v_div_fmas_f32 v61, v61, v75, v78
	s_mov_b64 vcc, s[0:1]
	v_div_fixup_f32 v69, v61, v69, 1.0
	v_div_fmas_f32 v61, v67, v76, v79
	v_div_fixup_f32 v68, v61, v68, 1.0
	v_pk_fma_f32 v[62:63], v[62:63], v[68:69], v[70:71]
	v_add_u32_e32 v67, v64, v125
	v_cvt_pk_bf16_f32 v61, v62, v63
	global_store_dword v72, v61, s[12:13]
	s_nop 0
	v_cndmask_b32_e64 v62, v56, v58, s[6:7]
	s_nop 0
	v_add_lshl_u32 v72, v65, v124, 1
	v_mov_b32_dpp v63, v62 quad_perm:[1,0,3,2] row_mask:0xf bank_mask:0xf bound_ctrl:1
	v_cndmask_b32_e64 v62, v63, v56, s[6:7]
	v_cndmask_b32_e64 v63, v58, v63, s[6:7]
	s_waitcnt vmcnt(36)
	v_lshlrev_b32_e32 v56, 16, v156
	v_and_b32_e32 v61, 0xffff0000, v156
	v_mul_f32_e32 v56, 0xbfb8aa3b, v56
	v_mul_f32_e32 v61, 0xbfb8aa3b, v61
	v_exp_f32_e32 v68, v56
	v_exp_f32_e32 v69, v61
	s_waitcnt vmcnt(36)
	v_lshlrev_b32_e32 v70, 16, v157
	v_and_b32_e32 v71, 0xffff0000, v157
	v_pk_add_f32 v[68:69], v[68:69], 1.0 op_sel_hi:[1,0]
	s_nop 0
	v_div_scale_f32 v56, s[0:1], v69, v69, 1.0
	v_div_scale_f32 v61, s[0:1], v68, v68, 1.0
	v_rcp_f32_e32 v73, v56
	v_rcp_f32_e32 v74, v61
	v_div_scale_f32 v58, vcc, 1.0, v69, 1.0
	v_fma_f32 v76, -v56, v73, 1.0
	v_fma_f32 v77, -v61, v74, 1.0
	v_fmac_f32_e32 v73, v76, v73
	v_div_scale_f32 v75, s[0:1], 1.0, v68, 1.0
	v_fmac_f32_e32 v74, v77, v74
	v_mul_f32_e32 v76, v58, v73
	v_mul_f32_e32 v77, v75, v74
	v_fma_f32 v78, -v56, v76, v58
	v_fma_f32 v79, -v61, v77, v75
	v_fmac_f32_e32 v76, v78, v73
	v_fmac_f32_e32 v77, v79, v74
	v_fma_f32 v56, -v56, v76, v58
	v_fma_f32 v58, -v61, v77, v75
	v_div_fmas_f32 v56, v56, v73, v76
	s_mov_b64 vcc, s[0:1]
	v_div_fixup_f32 v69, v56, v69, 1.0
	v_div_fmas_f32 v56, v58, v74, v77
	v_div_fixup_f32 v68, v56, v68, 1.0
	v_pk_fma_f32 v[62:63], v[62:63], v[68:69], v[70:71]
	v_add_u32_e32 v61, v60, v125
	v_cvt_pk_bf16_f32 v56, v62, v63
	global_store_dword v67, v56, s[12:13]
	s_nop 0
	v_cndmask_b32_e64 v56, v57, v59, s[6:7]
	s_nop 0
	v_add_lshl_u32 v69, v66, v120, 1
	v_mov_b32_dpp v68, v56 quad_perm:[1,0,3,2] row_mask:0xf bank_mask:0xf bound_ctrl:1
	v_cndmask_b32_e64 v56, v68, v57, s[6:7]
	s_waitcnt vmcnt(35)
	v_lshlrev_b32_e32 v57, 16, v158
	v_and_b32_e32 v58, 0xffff0000, v158
	v_mul_f32_e32 v57, 0xbfb8aa3b, v57
	v_mul_f32_e32 v58, 0xbfb8aa3b, v58
	v_exp_f32_e32 v62, v57
	v_exp_f32_e32 v63, v58
	v_cndmask_b32_e64 v57, v59, v68, s[6:7]
	s_waitcnt vmcnt(35)
	v_lshlrev_b32_e32 v58, 16, v159
	v_and_b32_e32 v59, 0xffff0000, v159
	v_pk_add_f32 v[62:63], v[62:63], 1.0 op_sel_hi:[1,0]
	s_nop 0
	v_div_scale_f32 v67, s[0:1], v63, v63, 1.0
	v_div_scale_f32 v70, s[0:1], v62, v62, 1.0
	v_rcp_f32_e32 v71, v67
	v_rcp_f32_e32 v72, v70
	v_div_scale_f32 v68, vcc, 1.0, v63, 1.0
	v_fma_f32 v74, -v67, v71, 1.0
	v_fma_f32 v75, -v70, v72, 1.0
	v_fmac_f32_e32 v71, v74, v71
	v_div_scale_f32 v73, s[0:1], 1.0, v62, 1.0
	v_fmac_f32_e32 v72, v75, v72
	v_mul_f32_e32 v74, v68, v71
	v_mul_f32_e32 v75, v73, v72
	v_fma_f32 v76, -v67, v74, v68
	v_fma_f32 v77, -v70, v75, v73
	v_fmac_f32_e32 v74, v76, v71
	v_fmac_f32_e32 v75, v77, v72
	v_fma_f32 v67, -v67, v74, v68
	v_fma_f32 v68, -v70, v75, v73
	v_div_fmas_f32 v67, v67, v71, v74
	s_mov_b64 vcc, s[0:1]
	v_div_fixup_f32 v63, v67, v63, 1.0
	v_div_fmas_f32 v67, v68, v72, v75
	v_div_fixup_f32 v62, v67, v62, 1.0
	v_pk_fma_f32 v[56:57], v[56:57], v[62:63], v[58:59]
	v_add_lshl_u32 v67, v65, v120, 1
	v_cvt_pk_bf16_f32 v56, v56, v57
	global_store_dword v61, v56, s[12:13]
	s_nop 0
	v_add_u32_e32 v61, v64, v121
	s_nop 0
	v_cndmask_b32_e64 v56, v52, v54, s[6:7]
	s_nop 1
	v_mov_b32_dpp v62, v56 quad_perm:[1,0,3,2] row_mask:0xf bank_mask:0xf bound_ctrl:1
	v_cndmask_b32_e64 v56, v62, v52, s[6:7]
	s_waitcnt vmcnt(34)
	v_lshlrev_b32_e32 v52, 16, v160
	v_and_b32_e32 v57, 0xffff0000, v160
	v_mul_f32_e32 v52, 0xbfb8aa3b, v52
	v_mul_f32_e32 v57, 0xbfb8aa3b, v57
	v_exp_f32_e32 v58, v52
	v_exp_f32_e32 v59, v57
	v_cndmask_b32_e64 v57, v54, v62, s[6:7]
	s_waitcnt vmcnt(34)
	v_lshlrev_b32_e32 v62, 16, v161
	v_and_b32_e32 v63, 0xffff0000, v161
	v_pk_add_f32 v[58:59], v[58:59], 1.0 op_sel_hi:[1,0]
	s_nop 0
	v_div_scale_f32 v52, s[0:1], v59, v59, 1.0
	v_div_scale_f32 v68, s[0:1], v58, v58, 1.0
	v_rcp_f32_e32 v69, v52
	v_rcp_f32_e32 v70, v68
	v_div_scale_f32 v54, vcc, 1.0, v59, 1.0
	v_fma_f32 v72, -v52, v69, 1.0
	v_fma_f32 v73, -v68, v70, 1.0
	v_fmac_f32_e32 v69, v72, v69
	v_div_scale_f32 v71, s[0:1], 1.0, v58, 1.0
	v_fmac_f32_e32 v70, v73, v70
	v_mul_f32_e32 v72, v54, v69
	v_mul_f32_e32 v73, v71, v70
	v_fma_f32 v74, -v52, v72, v54
	v_fma_f32 v75, -v68, v73, v71
	v_fmac_f32_e32 v72, v74, v69
	v_fmac_f32_e32 v73, v75, v70
	v_fma_f32 v52, -v52, v72, v54
	v_fma_f32 v54, -v68, v73, v71
	v_div_fmas_f32 v52, v52, v69, v72
	s_mov_b64 vcc, s[0:1]
	v_div_fixup_f32 v59, v52, v59, 1.0
	v_div_fmas_f32 v52, v54, v70, v73
	v_div_fixup_f32 v58, v52, v58, 1.0
	v_pk_fma_f32 v[56:57], v[56:57], v[58:59], v[62:63]
	v_add_u32_e32 v58, v60, v121
	v_cvt_pk_bf16_f32 v52, v56, v57
	global_store_dword v61, v52, s[12:13]
	s_nop 0
	s_nop 0
	v_cndmask_b32_e64 v52, v53, v55, s[6:7]
	v_add_lshl_u32 v62, v66, v116, 1
	s_nop 0
	v_mov_b32_dpp v61, v52 quad_perm:[1,0,3,2] row_mask:0xf bank_mask:0xf bound_ctrl:1
	v_cndmask_b32_e64 v52, v61, v53, s[6:7]
	s_waitcnt vmcnt(33)
; template <int EPI, bool GATHER>
; DEVINL void gemm_tile(const Params& p, const u16* __restrict__ A, int lda, const int* __restrict__ rowidx,
;                       const u16* __restrict__ Bt, int ldb, int K, int brow, int bcol, int orow, int ocol) {
;     ...
;     for (int m = 0; m < 4; ++m) {
;       const int rA = row0 + ai * HALF + m * 16 + (odd ? 2 : 0);
;       float gate[2] = {0.f, 0.f};
;       if (EPI == EPI_MOE2) { gate[0] = ((const float*)(ws + O_SELG))[rA]; gate[1] = ((const float*)(ws + O_SELG))[rA + 1]; }
; #pragma unroll
;       for (int bj = 0; bj < (EPI == EPI_HID ? 1 : 2); ++bj)
; #pragma unroll
;         for (int n = 0; n < 2; ++n) {
;           const int cc = bj * HALF + n * 16;
;           f32x4 v = acc[ai][bj][m][n];
;           if (EPI == EPI_HID) {
; #pragma unroll
;             for (int j = 0; j < 4; ++j) { const float a1 = acc[ai][0][m][n][j], a3 = acc[ai][1][m][n][j]; v[j] = a1 * sigm(a1) * a3; }
;           }
;           float lo[2], hi[2];
;           xchg_pairs(v, odd, lo, hi);
; #pragma unroll
;           for (int k = 0; k < 2; ++k) {
;             const unsigned row = (unsigned)(rA + k);
;             if (EPI == EPI_HID) {
;               *(unsigned*)(ws + O_HID + (row * 1024u + (unsigned)(colp + cc)) * 2u) = pk2(lo[k], hi[k]);
;             } else if (EPI == EPI_COLS) {
;               *(unsigned*)(ws + O_COLS + (row * (unsigned)NCP + (unsigned)(colp + cc)) * 2u) = pk2(lo[k], hi[k]);
;             } else if (EPI == EPI_MOE2) {
;               *(unsigned*)(ws + O_EO + (row * 2048u + (unsigned)(colp + cc)) * 2u) = pk2(gate[k] * lo[k], gate[k] * hi[k]);
;             } else if (EPI == EPI_M1) {
;               const unsigned g2 = *(const unsigned*)(ws + O_COLS + (row * (unsigned)NCP + (unsigned)(C_GG + colp + cc)) * 2u);
;               *(unsigned*)(ws + O_M1 + (row * 2048u + (unsigned)(colp + cc)) * 2u) = pk2(sigm(bflo(g2)) * lo[k], sigm(bfhi(g2)) * hi[k]);
;             } else if (EPI == EPI_MERGED) {
;               const unsigned g2 = *(const unsigned*)(ws + O_COLS + (row * (unsigned)NCP + (unsigned)(C_GR + colp + cc)) * 2u);
;               const unsigned m1 = *(const unsigned*)(ws + O_M1 + (row * 2048u + (unsigned)(colp + cc)) * 2u);
;               *(unsigned*)(ws + O_MERGED + (row * 2048u + (unsigned)(colp + cc)) * 2u) =
;                   pk2(bflo(m1) + sigm(bflo(g2)) * lo[k], bfhi(m1) + sigm(bfhi(g2)) * hi[k]);
	v_lshlrev_b32_e32 v53, 16, v162
	v_and_b32_e32 v54, 0xffff0000, v162
	v_mul_f32_e32 v53, 0xbfb8aa3b, v53
	v_mul_f32_e32 v54, 0xbfb8aa3b, v54
	v_exp_f32_e32 v56, v53
	v_exp_f32_e32 v57, v54
	v_cndmask_b32_e64 v53, v55, v61, s[6:7]
	s_waitcnt vmcnt(33)
	v_lshlrev_b32_e32 v54, 16, v163
	v_and_b32_e32 v55, 0xffff0000, v163
	v_pk_add_f32 v[56:57], v[56:57], 1.0 op_sel_hi:[1,0]
	s_nop 0
	v_div_scale_f32 v59, s[0:1], v57, v57, 1.0
	v_div_scale_f32 v63, s[0:1], v56, v56, 1.0
	v_rcp_f32_e32 v66, v59
	v_rcp_f32_e32 v67, v63
	v_div_scale_f32 v61, vcc, 1.0, v57, 1.0
	v_fma_f32 v69, -v59, v66, 1.0
	v_fma_f32 v70, -v63, v67, 1.0
	v_fmac_f32_e32 v66, v69, v66
	v_div_scale_f32 v68, s[0:1], 1.0, v56, 1.0
	v_fmac_f32_e32 v67, v70, v67
	v_mul_f32_e32 v69, v61, v66
	v_mul_f32_e32 v70, v68, v67
	v_fma_f32 v71, -v59, v69, v61
	v_fma_f32 v72, -v63, v70, v68
	v_fmac_f32_e32 v69, v71, v66
	v_fmac_f32_e32 v70, v72, v67
	v_fma_f32 v59, -v59, v69, v61
	v_fma_f32 v61, -v63, v70, v68
	v_div_fmas_f32 v59, v59, v66, v69
	s_mov_b64 vcc, s[0:1]
	v_div_fixup_f32 v57, v59, v57, 1.0
	v_div_fmas_f32 v59, v61, v67, v70
	v_div_fixup_f32 v56, v59, v56, 1.0
	v_pk_fma_f32 v[52:53], v[52:53], v[56:57], v[54:55]
	v_add_lshl_u32 v59, v65, v116, 1
	v_cvt_pk_bf16_f32 v52, v52, v53
	global_store_dword v58, v52, s[12:13]
	s_nop 0
	v_add_u32_e32 v58, v64, v117
	s_nop 0
	v_cndmask_b32_e64 v52, v48, v50, s[6:7]
	s_nop 1
	v_mov_b32_dpp v56, v52 quad_perm:[1,0,3,2] row_mask:0xf bank_mask:0xf bound_ctrl:1
	v_cndmask_b32_e64 v52, v56, v48, s[6:7]
	s_waitcnt vmcnt(32)
	v_lshlrev_b32_e32 v48, 16, v164
	v_and_b32_e32 v53, 0xffff0000, v164
	v_mul_f32_e32 v48, 0xbfb8aa3b, v48
	v_mul_f32_e32 v53, 0xbfb8aa3b, v53
	v_exp_f32_e32 v54, v48
	v_exp_f32_e32 v55, v53
	v_cndmask_b32_e64 v53, v50, v56, s[6:7]
	s_waitcnt vmcnt(32)
	v_lshlrev_b32_e32 v56, 16, v165
	v_and_b32_e32 v57, 0xffff0000, v165
	v_pk_add_f32 v[54:55], v[54:55], 1.0 op_sel_hi:[1,0]
	s_nop 0
	v_div_scale_f32 v48, s[0:1], v55, v55, 1.0
	v_div_scale_f32 v61, s[0:1], v54, v54, 1.0
	v_rcp_f32_e32 v62, v48
	v_rcp_f32_e32 v63, v61
	v_div_scale_f32 v50, vcc, 1.0, v55, 1.0
	v_fma_f32 v65, -v48, v62, 1.0
	v_fma_f32 v66, -v61, v63, 1.0
	v_fmac_f32_e32 v62, v65, v62
	v_div_scale_f32 v64, s[0:1], 1.0, v54, 1.0
	v_fmac_f32_e32 v63, v66, v63
	v_mul_f32_e32 v65, v50, v62
	v_mul_f32_e32 v66, v64, v63
	v_fma_f32 v67, -v48, v65, v50
	v_fma_f32 v68, -v61, v66, v64
	v_fmac_f32_e32 v65, v67, v62
	v_fmac_f32_e32 v66, v68, v63
	v_fma_f32 v48, -v48, v65, v50
	v_fma_f32 v50, -v61, v66, v64
	v_div_fmas_f32 v48, v48, v62, v65
	s_mov_b64 vcc, s[0:1]
	v_div_fixup_f32 v55, v48, v55, 1.0
	v_div_fmas_f32 v48, v50, v63, v66
	v_div_fixup_f32 v54, v48, v54, 1.0
	v_pk_fma_f32 v[52:53], v[52:53], v[54:55], v[56:57]
	v_add_u32_e32 v54, v60, v117
	v_cvt_pk_bf16_f32 v48, v52, v53
	global_store_dword v58, v48, s[12:13]
	s_nop 0
	s_nop 0
	v_cndmask_b32_e64 v48, v49, v51, s[6:7]
	s_nop 1
	v_mov_b32_dpp v56, v48 quad_perm:[1,0,3,2] row_mask:0xf bank_mask:0xf bound_ctrl:1
	v_cndmask_b32_e64 v48, v56, v49, s[6:7]
	s_waitcnt vmcnt(31)
	v_lshlrev_b32_e32 v49, 16, v166
	v_and_b32_e32 v50, 0xffff0000, v166
	v_mul_f32_e32 v49, 0xbfb8aa3b, v49
	v_mul_f32_e32 v50, 0xbfb8aa3b, v50
	v_exp_f32_e32 v52, v49
	v_exp_f32_e32 v53, v50
	v_cndmask_b32_e64 v49, v51, v56, s[6:7]
	s_waitcnt vmcnt(31)
	v_lshlrev_b32_e32 v50, 16, v167
	v_and_b32_e32 v51, 0xffff0000, v167
	v_pk_add_f32 v[52:53], v[52:53], 1.0 op_sel_hi:[1,0]
	s_nop 0
	v_div_scale_f32 v55, s[0:1], v53, v53, 1.0
	v_div_scale_f32 v57, s[0:1], v52, v52, 1.0
	v_rcp_f32_e32 v58, v55
	v_rcp_f32_e32 v59, v57
	v_div_scale_f32 v56, vcc, 1.0, v53, 1.0
	v_fma_f32 v61, -v55, v58, 1.0
	v_fma_f32 v62, -v57, v59, 1.0
	v_fmac_f32_e32 v58, v61, v58
	v_div_scale_f32 v60, s[0:1], 1.0, v52, 1.0
	v_fmac_f32_e32 v59, v62, v59
	v_mul_f32_e32 v61, v56, v58
	v_mul_f32_e32 v62, v60, v59
	v_fma_f32 v63, -v55, v61, v56
	v_fma_f32 v64, -v57, v62, v60
	v_fmac_f32_e32 v61, v63, v58
	v_fmac_f32_e32 v62, v64, v59
	v_fma_f32 v55, -v55, v61, v56
	v_fma_f32 v56, -v57, v62, v60
	v_div_fmas_f32 v55, v55, v58, v61
	s_mov_b64 vcc, s[0:1]
	v_div_fixup_f32 v53, v55, v53, 1.0
	v_div_fmas_f32 v55, v56, v59, v62
	v_div_fixup_f32 v52, v55, v52, 1.0
	v_pk_fma_f32 v[48:49], v[48:49], v[52:53], v[50:51]
	s_nop 0
	v_cvt_pk_bf16_f32 v48, v48, v49
	global_store_dword v54, v48, s[12:13]
	v_add_u32_e32 v184, 0x1a4000, v131
	v_add_lshl_u32 v185, v184, v130, 1
	global_load_dword v152, v185, s[8:9]
	v_add_u32_e32 v185, 0xa0000, v129
	v_add_u32_e32 v186, v185, v128
	global_load_dword v153, v186, s[10:11]
	v_add_u32_e32 v187, 0x1a6a00, v131
	v_add_lshl_u32 v188, v187, v130, 1
	global_load_dword v154, v188, s[8:9]
	v_add_u32_e32 v222, 0xa1000, v129
	v_add_u32_e32 v223, v222, v128
	global_load_dword v155, v223, s[10:11]
	v_add_lshl_u32 v224, v184, v124, 1
	v_add_u32_e32 v225, v185, v125
	global_load_dword v156, v224, s[8:9]
	global_load_dword v157, v225, s[10:11]
	v_add_lshl_u32 v223, v187, v124, 1
	v_add_u32_e32 v226, v222, v125
	global_load_dword v158, v223, s[8:9]
	global_load_dword v159, v226, s[10:11]
	v_add_lshl_u32 v227, v184, v120, 1
	v_add_lshl_u32 v225, v187, v120, 1
	global_load_dword v160, v227, s[8:9]
	v_add_u32_e32 v226, v185, v121
	global_load_dword v161, v226, s[10:11]
	v_add_u32_e32 v228, v222, v121
	global_load_dword v162, v225, s[8:9]
	global_load_dword v163, v228, s[10:11]
	v_add_lshl_u32 v229, v184, v116, 1
	v_add_lshl_u32 v230, v187, v116, 1
	global_load_dword v164, v229, s[8:9]
	v_add_u32_e32 v228, v185, v117
	global_load_dword v165, v228, s[10:11]
	v_add_u32_e32 v231, v222, v117
	global_load_dword v166, v230, s[8:9]
	global_load_dword v167, v231, s[10:11]
	v_add_u32_e32 v50, 0x17a000, v131
	v_add_lshl_u32 v48, v50, v130, 1
	s_nop 0
	v_add_u32_e32 v48, 0x90000, v129
	v_add_u32_e32 v58, v48, v128
	s_nop 0
	v_cndmask_b32_e64 v52, v44, v46, s[6:7]
	v_add_u32_e32 v49, 0x17ca00, v131
	v_add_lshl_u32 v59, v49, v130, 1
	v_mov_b32_dpp v53, v52 quad_perm:[1,0,3,2] row_mask:0xf bank_mask:0xf bound_ctrl:1
	v_cndmask_b32_e64 v52, v53, v44, s[6:7]
	v_cndmask_b32_e64 v53, v46, v53, s[6:7]
	s_waitcnt vmcnt(38)
; DEVINL float bflo(unsigned u) { return __uint_as_float(u << 16); }
; DEVINL float bfhi(unsigned u) { return __uint_as_float(u & 0xffff0000u); }
; DEVINL float sigm(float x) { return 1.f / (1.f + __expf(-x)); }
; template <int EPI, bool GATHER>
; DEVINL void gemm_tile(const Params& p, const u16* __restrict__ A, int lda, const int* __restrict__ rowidx,
;                       const u16* __restrict__ Bt, int ldb, int K, int brow, int bcol, int orow, int ocol) {
;     ...
;       for (int bj = 0; bj < (EPI == EPI_HID ? 1 : 2); ++bj)
; #pragma unroll
;         for (int n = 0; n < 2; ++n) {
;           const int cc = bj * HALF + n * 16;
;           f32x4 v = acc[ai][bj][m][n];
;           if (EPI == EPI_HID) {
; #pragma unroll
;             for (int j = 0; j < 4; ++j) { const float a1 = acc[ai][0][m][n][j], a3 = acc[ai][1][m][n][j]; v[j] = a1 * sigm(a1) * a3; }
;           }
;           float lo[2], hi[2];
;           xchg_pairs(v, odd, lo, hi);
; #pragma unroll
;           for (int k = 0; k < 2; ++k) {
;             const unsigned row = (unsigned)(rA + k);
;             if (EPI == EPI_HID) {
;               *(unsigned*)(ws + O_HID + (row * 1024u + (unsigned)(colp + cc)) * 2u) = pk2(lo[k], hi[k]);
;             } else if (EPI == EPI_COLS) {
;               *(unsigned*)(ws + O_COLS + (row * (unsigned)NCP + (unsigned)(colp + cc)) * 2u) = pk2(lo[k], hi[k]);
;             } else if (EPI == EPI_MOE2) {
;               *(unsigned*)(ws + O_EO + (row * 2048u + (unsigned)(colp + cc)) * 2u) = pk2(gate[k] * lo[k], gate[k] * hi[k]);
;             } else if (EPI == EPI_M1) {
;               const unsigned g2 = *(const unsigned*)(ws + O_COLS + (row * (unsigned)NCP + (unsigned)(C_GG + colp + cc)) * 2u);
;               *(unsigned*)(ws + O_M1 + (row * 2048u + (unsigned)(colp + cc)) * 2u) = pk2(sigm(bflo(g2)) * lo[k], sigm(bfhi(g2)) * hi[k]);
;             } else if (EPI == EPI_MERGED) {
;               const unsigned g2 = *(const unsigned*)(ws + O_COLS + (row * (unsigned)NCP + (unsigned)(C_GR + colp + cc)) * 2u);
;               const unsigned m1 = *(const unsigned*)(ws + O_M1 + (row * 2048u + (unsigned)(colp + cc)) * 2u);
;               *(unsigned*)(ws + O_MERGED + (row * 2048u + (unsigned)(colp + cc)) * 2u) =
;                   pk2(bflo(m1) + sigm(bflo(g2)) * lo[k], bfhi(m1) + sigm(bfhi(g2)) * hi[k]);
	v_lshlrev_b32_e32 v44, 16, v190
	v_and_b32_e32 v51, 0xffff0000, v190
	v_mul_f32_e32 v44, 0xbfb8aa3b, v44
	v_mul_f32_e32 v51, 0xbfb8aa3b, v51
	v_exp_f32_e32 v54, v44
	v_exp_f32_e32 v55, v51
	s_waitcnt vmcnt(38)
	v_lshlrev_b32_e32 v56, 16, v191
	v_and_b32_e32 v57, 0xffff0000, v191
	v_pk_add_f32 v[54:55], v[54:55], 1.0 op_sel_hi:[1,0]
	s_nop 0
	v_div_scale_f32 v44, s[0:1], v55, v55, 1.0
	v_div_scale_f32 v51, s[0:1], v54, v54, 1.0
	v_rcp_f32_e32 v60, v44
	v_rcp_f32_e32 v61, v51
	v_div_scale_f32 v46, vcc, 1.0, v55, 1.0
	v_fma_f32 v63, -v44, v60, 1.0
	v_fma_f32 v64, -v51, v61, 1.0
	v_fmac_f32_e32 v60, v63, v60
	v_div_scale_f32 v62, s[0:1], 1.0, v54, 1.0
	v_fmac_f32_e32 v61, v64, v61
	v_mul_f32_e32 v63, v46, v60
	v_mul_f32_e32 v64, v62, v61
	v_fma_f32 v65, -v44, v63, v46
	v_fma_f32 v66, -v51, v64, v62
	v_fmac_f32_e32 v63, v65, v60
	v_fmac_f32_e32 v64, v66, v61
	v_fma_f32 v44, -v44, v63, v46
	v_fma_f32 v46, -v51, v64, v62
	v_div_fmas_f32 v44, v44, v60, v63
	s_mov_b64 vcc, s[0:1]
	v_div_fixup_f32 v55, v44, v55, 1.0
	v_div_fmas_f32 v44, v46, v61, v64
	v_div_fixup_f32 v54, v44, v54, 1.0
	v_pk_fma_f32 v[52:53], v[52:53], v[54:55], v[56:57]
	v_cndmask_b32_e64 v46, v45, v47, s[6:7]
	v_cvt_pk_bf16_f32 v44, v52, v53
	global_store_dword v58, v44, s[12:13]
	s_nop 0
	v_add_u32_e32 v44, 0x91000, v129
	v_add_u32_e32 v56, v44, v128
	s_nop 0
	v_mov_b32_dpp v54, v46 quad_perm:[1,0,3,2] row_mask:0xf bank_mask:0xf bound_ctrl:1
	v_cndmask_b32_e64 v46, v54, v45, s[6:7]
	v_cndmask_b32_e64 v47, v47, v54, s[6:7]
	v_add_lshl_u32 v57, v50, v124, 1
	s_waitcnt vmcnt(37)
	v_lshlrev_b32_e32 v45, 16, v192
	v_and_b32_e32 v51, 0xffff0000, v192
	v_mul_f32_e32 v45, 0xbfb8aa3b, v45
	v_mul_f32_e32 v51, 0xbfb8aa3b, v51
	v_exp_f32_e32 v52, v45
	v_exp_f32_e32 v53, v51
	s_waitcnt vmcnt(37)
	v_lshlrev_b32_e32 v54, 16, v193
	v_and_b32_e32 v55, 0xffff0000, v193
	v_pk_add_f32 v[52:53], v[52:53], 1.0 op_sel_hi:[1,0]
	s_nop 0
	v_div_scale_f32 v45, s[0:1], v53, v53, 1.0
	v_div_scale_f32 v58, s[0:1], v52, v52, 1.0
	v_rcp_f32_e32 v59, v45
	v_rcp_f32_e32 v60, v58
	v_div_scale_f32 v51, vcc, 1.0, v53, 1.0
	v_fma_f32 v62, -v45, v59, 1.0
	v_fma_f32 v63, -v58, v60, 1.0
	v_fmac_f32_e32 v59, v62, v59
	v_div_scale_f32 v61, s[0:1], 1.0, v52, 1.0
	v_fmac_f32_e32 v60, v63, v60
	v_mul_f32_e32 v62, v51, v59
	v_mul_f32_e32 v63, v61, v60
	v_fma_f32 v64, -v45, v62, v51
	v_fma_f32 v65, -v58, v63, v61
	v_fmac_f32_e32 v62, v64, v59
	v_fmac_f32_e32 v63, v65, v60
	v_fma_f32 v45, -v45, v62, v51
	v_fma_f32 v51, -v58, v63, v61
	v_div_fmas_f32 v45, v45, v59, v62
	s_mov_b64 vcc, s[0:1]
	v_div_fixup_f32 v53, v45, v53, 1.0
	v_div_fmas_f32 v45, v51, v60, v63
	v_div_fixup_f32 v52, v45, v52, 1.0
	v_pk_fma_f32 v[46:47], v[46:47], v[52:53], v[54:55]
	v_add_u32_e32 v51, v48, v125
	v_cvt_pk_bf16_f32 v45, v46, v47
	global_store_dword v56, v45, s[12:13]
	s_nop 0
	v_cndmask_b32_e64 v46, v40, v42, s[6:7]
	s_nop 0
	v_add_lshl_u32 v56, v49, v124, 1
	v_mov_b32_dpp v47, v46 quad_perm:[1,0,3,2] row_mask:0xf bank_mask:0xf bound_ctrl:1
	v_cndmask_b32_e64 v46, v47, v40, s[6:7]
	v_cndmask_b32_e64 v47, v42, v47, s[6:7]
	s_waitcnt vmcnt(36)
	v_lshlrev_b32_e32 v40, 16, v194
	v_and_b32_e32 v45, 0xffff0000, v194
	v_mul_f32_e32 v40, 0xbfb8aa3b, v40
	v_mul_f32_e32 v45, 0xbfb8aa3b, v45
	v_exp_f32_e32 v52, v40
	v_exp_f32_e32 v53, v45
	s_waitcnt vmcnt(36)
	v_lshlrev_b32_e32 v54, 16, v195
	v_and_b32_e32 v55, 0xffff0000, v195
	v_pk_add_f32 v[52:53], v[52:53], 1.0 op_sel_hi:[1,0]
	s_nop 0
	v_div_scale_f32 v40, s[0:1], v53, v53, 1.0
	v_div_scale_f32 v45, s[0:1], v52, v52, 1.0
	v_rcp_f32_e32 v57, v40
	v_rcp_f32_e32 v58, v45
	v_div_scale_f32 v42, vcc, 1.0, v53, 1.0
	v_fma_f32 v60, -v40, v57, 1.0
	v_fma_f32 v61, -v45, v58, 1.0
	v_fmac_f32_e32 v57, v60, v57
	v_div_scale_f32 v59, s[0:1], 1.0, v52, 1.0
	v_fmac_f32_e32 v58, v61, v58
	v_mul_f32_e32 v60, v42, v57
	v_mul_f32_e32 v61, v59, v58
	v_fma_f32 v62, -v40, v60, v42
	v_fma_f32 v63, -v45, v61, v59
	v_fmac_f32_e32 v60, v62, v57
	v_fmac_f32_e32 v61, v63, v58
	v_fma_f32 v40, -v40, v60, v42
	v_fma_f32 v42, -v45, v61, v59
	v_div_fmas_f32 v40, v40, v57, v60
	s_mov_b64 vcc, s[0:1]
	v_div_fixup_f32 v53, v40, v53, 1.0
	v_div_fmas_f32 v40, v42, v58, v61
	v_div_fixup_f32 v52, v40, v52, 1.0
	v_pk_fma_f32 v[46:47], v[46:47], v[52:53], v[54:55]
	v_add_u32_e32 v45, v44, v125
	v_cvt_pk_bf16_f32 v40, v46, v47
	global_store_dword v51, v40, s[12:13]
	s_nop 0
	v_cndmask_b32_e64 v40, v41, v43, s[6:7]
	s_nop 0
	v_add_lshl_u32 v53, v50, v120, 1
	v_mov_b32_dpp v52, v40 quad_perm:[1,0,3,2] row_mask:0xf bank_mask:0xf bound_ctrl:1
	v_cndmask_b32_e64 v40, v52, v41, s[6:7]
	s_waitcnt vmcnt(35)
	v_lshlrev_b32_e32 v41, 16, v196
	v_and_b32_e32 v42, 0xffff0000, v196
	v_mul_f32_e32 v41, 0xbfb8aa3b, v41
	v_mul_f32_e32 v42, 0xbfb8aa3b, v42
	v_exp_f32_e32 v46, v41
	v_exp_f32_e32 v47, v42
	v_cndmask_b32_e64 v41, v43, v52, s[6:7]
	s_waitcnt vmcnt(35)
	v_lshlrev_b32_e32 v42, 16, v197
	v_and_b32_e32 v43, 0xffff0000, v197
	v_pk_add_f32 v[46:47], v[46:47], 1.0 op_sel_hi:[1,0]
	s_nop 0
	v_div_scale_f32 v51, s[0:1], v47, v47, 1.0
	v_div_scale_f32 v54, s[0:1], v46, v46, 1.0
	v_rcp_f32_e32 v55, v51
	v_rcp_f32_e32 v56, v54
	v_div_scale_f32 v52, vcc, 1.0, v47, 1.0
	v_fma_f32 v58, -v51, v55, 1.0
	v_fma_f32 v59, -v54, v56, 1.0
	v_fmac_f32_e32 v55, v58, v55
	v_div_scale_f32 v57, s[0:1], 1.0, v46, 1.0
	v_fmac_f32_e32 v56, v59, v56
	v_mul_f32_e32 v58, v52, v55
	v_mul_f32_e32 v59, v57, v56
	v_fma_f32 v60, -v51, v58, v52
	v_fma_f32 v61, -v54, v59, v57
	v_fmac_f32_e32 v58, v60, v55
	v_fmac_f32_e32 v59, v61, v56
	v_fma_f32 v51, -v51, v58, v52
	v_fma_f32 v52, -v54, v59, v57
	v_div_fmas_f32 v51, v51, v55, v58
	s_mov_b64 vcc, s[0:1]
	v_div_fixup_f32 v47, v51, v47, 1.0
	v_div_fmas_f32 v51, v52, v56, v59
	v_div_fixup_f32 v46, v51, v46, 1.0
	v_pk_fma_f32 v[40:41], v[40:41], v[46:47], v[42:43]
	v_add_lshl_u32 v51, v49, v120, 1
	v_cvt_pk_bf16_f32 v40, v40, v41
	global_store_dword v45, v40, s[12:13]
	s_nop 0
	v_add_u32_e32 v45, v48, v121
	s_nop 0
	v_cndmask_b32_e64 v40, v36, v38, s[6:7]
	s_nop 1
	v_mov_b32_dpp v46, v40 quad_perm:[1,0,3,2] row_mask:0xf bank_mask:0xf bound_ctrl:1
	v_cndmask_b32_e64 v40, v46, v36, s[6:7]
	s_waitcnt vmcnt(34)
; DEVINL float bflo(unsigned u) { return __uint_as_float(u << 16); }
; DEVINL float bfhi(unsigned u) { return __uint_as_float(u & 0xffff0000u); }
; DEVINL float sigm(float x) { return 1.f / (1.f + __expf(-x)); }
; template <int EPI, bool GATHER>
; DEVINL void gemm_tile(const Params& p, const u16* __restrict__ A, int lda, const int* __restrict__ rowidx,
;                       const u16* __restrict__ Bt, int ldb, int K, int brow, int bcol, int orow, int ocol) {
;     ...
;       for (int bj = 0; bj < (EPI == EPI_HID ? 1 : 2); ++bj)
; #pragma unroll
;         for (int n = 0; n < 2; ++n) {
;           const int cc = bj * HALF + n * 16;
;           f32x4 v = acc[ai][bj][m][n];
;           if (EPI == EPI_HID) {
; #pragma unroll
;             for (int j = 0; j < 4; ++j) { const float a1 = acc[ai][0][m][n][j], a3 = acc[ai][1][m][n][j]; v[j] = a1 * sigm(a1) * a3; }
;           }
;           float lo[2], hi[2];
;           xchg_pairs(v, odd, lo, hi);
; #pragma unroll
;           for (int k = 0; k < 2; ++k) {
;             const unsigned row = (unsigned)(rA + k);
;             if (EPI == EPI_HID) {
;               *(unsigned*)(ws + O_HID + (row * 1024u + (unsigned)(colp + cc)) * 2u) = pk2(lo[k], hi[k]);
;             } else if (EPI == EPI_COLS) {
;               *(unsigned*)(ws + O_COLS + (row * (unsigned)NCP + (unsigned)(colp + cc)) * 2u) = pk2(lo[k], hi[k]);
;             } else if (EPI == EPI_MOE2) {
;               *(unsigned*)(ws + O_EO + (row * 2048u + (unsigned)(colp + cc)) * 2u) = pk2(gate[k] * lo[k], gate[k] * hi[k]);
;             } else if (EPI == EPI_M1) {
;               const unsigned g2 = *(const unsigned*)(ws + O_COLS + (row * (unsigned)NCP + (unsigned)(C_GG + colp + cc)) * 2u);
;               *(unsigned*)(ws + O_M1 + (row * 2048u + (unsigned)(colp + cc)) * 2u) = pk2(sigm(bflo(g2)) * lo[k], sigm(bfhi(g2)) * hi[k]);
;             } else if (EPI == EPI_MERGED) {
;               const unsigned g2 = *(const unsigned*)(ws + O_COLS + (row * (unsigned)NCP + (unsigned)(C_GR + colp + cc)) * 2u);
;               const unsigned m1 = *(const unsigned*)(ws + O_M1 + (row * 2048u + (unsigned)(colp + cc)) * 2u);
;               *(unsigned*)(ws + O_MERGED + (row * 2048u + (unsigned)(colp + cc)) * 2u) =
;                   pk2(bflo(m1) + sigm(bflo(g2)) * lo[k], bfhi(m1) + sigm(bfhi(g2)) * hi[k]);
	v_lshlrev_b32_e32 v36, 16, v198
	v_and_b32_e32 v41, 0xffff0000, v198
	v_mul_f32_e32 v36, 0xbfb8aa3b, v36
	v_mul_f32_e32 v41, 0xbfb8aa3b, v41
	v_exp_f32_e32 v42, v36
	v_exp_f32_e32 v43, v41
	v_cndmask_b32_e64 v41, v38, v46, s[6:7]
	s_waitcnt vmcnt(34)
	v_lshlrev_b32_e32 v46, 16, v199
	v_and_b32_e32 v47, 0xffff0000, v199
	v_pk_add_f32 v[42:43], v[42:43], 1.0 op_sel_hi:[1,0]
	s_nop 0
	v_div_scale_f32 v36, s[0:1], v43, v43, 1.0
	v_div_scale_f32 v52, s[0:1], v42, v42, 1.0
	v_rcp_f32_e32 v53, v36
	v_rcp_f32_e32 v54, v52
	v_div_scale_f32 v38, vcc, 1.0, v43, 1.0
	v_fma_f32 v56, -v36, v53, 1.0
	v_fma_f32 v57, -v52, v54, 1.0
	v_fmac_f32_e32 v53, v56, v53
	v_div_scale_f32 v55, s[0:1], 1.0, v42, 1.0
	v_fmac_f32_e32 v54, v57, v54
	v_mul_f32_e32 v56, v38, v53
	v_mul_f32_e32 v57, v55, v54
	v_fma_f32 v58, -v36, v56, v38
	v_fma_f32 v59, -v52, v57, v55
	v_fmac_f32_e32 v56, v58, v53
	v_fmac_f32_e32 v57, v59, v54
	v_fma_f32 v36, -v36, v56, v38
	v_fma_f32 v38, -v52, v57, v55
	v_div_fmas_f32 v36, v36, v53, v56
	s_mov_b64 vcc, s[0:1]
	v_div_fixup_f32 v43, v36, v43, 1.0
	v_div_fmas_f32 v36, v38, v54, v57
	v_div_fixup_f32 v42, v36, v42, 1.0
	v_pk_fma_f32 v[40:41], v[40:41], v[42:43], v[46:47]
	v_add_u32_e32 v42, v44, v121
	v_cvt_pk_bf16_f32 v36, v40, v41
	global_store_dword v45, v36, s[12:13]
	s_nop 0
	s_nop 0
	v_cndmask_b32_e64 v36, v37, v39, s[6:7]
	v_add_lshl_u32 v46, v50, v116, 1
	s_nop 0
	v_mov_b32_dpp v45, v36 quad_perm:[1,0,3,2] row_mask:0xf bank_mask:0xf bound_ctrl:1
	v_cndmask_b32_e64 v36, v45, v37, s[6:7]
	s_waitcnt vmcnt(33)
	v_lshlrev_b32_e32 v37, 16, v200
	v_and_b32_e32 v38, 0xffff0000, v200
	v_mul_f32_e32 v37, 0xbfb8aa3b, v37
	v_mul_f32_e32 v38, 0xbfb8aa3b, v38
	v_exp_f32_e32 v40, v37
	v_exp_f32_e32 v41, v38
	v_cndmask_b32_e64 v37, v39, v45, s[6:7]
	s_waitcnt vmcnt(33)
	v_lshlrev_b32_e32 v38, 16, v201
	v_and_b32_e32 v39, 0xffff0000, v201
	v_pk_add_f32 v[40:41], v[40:41], 1.0 op_sel_hi:[1,0]
	s_nop 0
	v_div_scale_f32 v43, s[0:1], v41, v41, 1.0
	v_div_scale_f32 v47, s[0:1], v40, v40, 1.0
	v_rcp_f32_e32 v50, v43
	v_rcp_f32_e32 v51, v47
	v_div_scale_f32 v45, vcc, 1.0, v41, 1.0
	v_fma_f32 v53, -v43, v50, 1.0
	v_fma_f32 v54, -v47, v51, 1.0
	v_fmac_f32_e32 v50, v53, v50
	v_div_scale_f32 v52, s[0:1], 1.0, v40, 1.0
	v_fmac_f32_e32 v51, v54, v51
	v_mul_f32_e32 v53, v45, v50
	v_mul_f32_e32 v54, v52, v51
	v_fma_f32 v55, -v43, v53, v45
	v_fma_f32 v56, -v47, v54, v52
	v_fmac_f32_e32 v53, v55, v50
	v_fmac_f32_e32 v54, v56, v51
	v_fma_f32 v43, -v43, v53, v45
	v_fma_f32 v45, -v47, v54, v52
	v_div_fmas_f32 v43, v43, v50, v53
	s_mov_b64 vcc, s[0:1]
	v_div_fixup_f32 v41, v43, v41, 1.0
	v_div_fmas_f32 v43, v45, v51, v54
	v_div_fixup_f32 v40, v43, v40, 1.0
	v_pk_fma_f32 v[36:37], v[36:37], v[40:41], v[38:39]
	v_add_lshl_u32 v43, v49, v116, 1
	v_cvt_pk_bf16_f32 v36, v36, v37
	global_store_dword v42, v36, s[12:13]
	s_nop 0
	v_add_u32_e32 v42, v48, v117
	s_nop 0
	v_cndmask_b32_e64 v36, v32, v34, s[6:7]
	s_nop 1
	v_mov_b32_dpp v40, v36 quad_perm:[1,0,3,2] row_mask:0xf bank_mask:0xf bound_ctrl:1
	v_cndmask_b32_e64 v36, v40, v32, s[6:7]
	s_waitcnt vmcnt(32)
	v_lshlrev_b32_e32 v32, 16, v202
	v_and_b32_e32 v37, 0xffff0000, v202
	v_mul_f32_e32 v32, 0xbfb8aa3b, v32
	v_mul_f32_e32 v37, 0xbfb8aa3b, v37
	v_exp_f32_e32 v38, v32
	v_exp_f32_e32 v39, v37
	v_cndmask_b32_e64 v37, v34, v40, s[6:7]
	s_waitcnt vmcnt(32)
	v_lshlrev_b32_e32 v40, 16, v203
	v_and_b32_e32 v41, 0xffff0000, v203
	v_pk_add_f32 v[38:39], v[38:39], 1.0 op_sel_hi:[1,0]
	s_nop 0
	v_div_scale_f32 v32, s[0:1], v39, v39, 1.0
	v_div_scale_f32 v45, s[0:1], v38, v38, 1.0
	v_rcp_f32_e32 v46, v32
	v_rcp_f32_e32 v47, v45
	v_div_scale_f32 v34, vcc, 1.0, v39, 1.0
	v_fma_f32 v49, -v32, v46, 1.0
	v_fma_f32 v50, -v45, v47, 1.0
	v_fmac_f32_e32 v46, v49, v46
	v_div_scale_f32 v48, s[0:1], 1.0, v38, 1.0
	v_fmac_f32_e32 v47, v50, v47
	v_mul_f32_e32 v49, v34, v46
	v_mul_f32_e32 v50, v48, v47
	v_fma_f32 v51, -v32, v49, v34
	v_fma_f32 v52, -v45, v50, v48
	v_fmac_f32_e32 v49, v51, v46
	v_fmac_f32_e32 v50, v52, v47
	v_fma_f32 v32, -v32, v49, v34
	v_fma_f32 v34, -v45, v50, v48
	v_div_fmas_f32 v32, v32, v46, v49
	s_mov_b64 vcc, s[0:1]
	v_div_fixup_f32 v39, v32, v39, 1.0
	v_div_fmas_f32 v32, v34, v47, v50
	v_div_fixup_f32 v38, v32, v38, 1.0
	v_pk_fma_f32 v[36:37], v[36:37], v[38:39], v[40:41]
	v_add_u32_e32 v38, v44, v117
	v_cvt_pk_bf16_f32 v32, v36, v37
	global_store_dword v42, v32, s[12:13]
	s_nop 0
	s_nop 0
	v_cndmask_b32_e64 v32, v33, v35, s[6:7]
	s_nop 1
	v_mov_b32_dpp v40, v32 quad_perm:[1,0,3,2] row_mask:0xf bank_mask:0xf bound_ctrl:1
	v_cndmask_b32_e64 v32, v40, v33, s[6:7]
	s_waitcnt vmcnt(31)
	v_lshlrev_b32_e32 v33, 16, v204
	v_and_b32_e32 v34, 0xffff0000, v204
	v_mul_f32_e32 v33, 0xbfb8aa3b, v33
	v_mul_f32_e32 v34, 0xbfb8aa3b, v34
	v_exp_f32_e32 v36, v33
	v_exp_f32_e32 v37, v34
	v_cndmask_b32_e64 v33, v35, v40, s[6:7]
	s_waitcnt vmcnt(31)
; template <int EPI, bool GATHER>
; DEVINL void gemm_tile(const Params& p, const u16* __restrict__ A, int lda, const int* __restrict__ rowidx,
;                       const u16* __restrict__ Bt, int ldb, int K, int brow, int bcol, int orow, int ocol) {
;     ...
;     for (int m = 0; m < 4; ++m) {
;       const int rA = row0 + ai * HALF + m * 16 + (odd ? 2 : 0);
;       float gate[2] = {0.f, 0.f};
;       if (EPI == EPI_MOE2) { gate[0] = ((const float*)(ws + O_SELG))[rA]; gate[1] = ((const float*)(ws + O_SELG))[rA + 1]; }
; #pragma unroll
;       for (int bj = 0; bj < (EPI == EPI_HID ? 1 : 2); ++bj)
; #pragma unroll
;         for (int n = 0; n < 2; ++n) {
;           const int cc = bj * HALF + n * 16;
;           f32x4 v = acc[ai][bj][m][n];
;           if (EPI == EPI_HID) {
; #pragma unroll
;             for (int j = 0; j < 4; ++j) { const float a1 = acc[ai][0][m][n][j], a3 = acc[ai][1][m][n][j]; v[j] = a1 * sigm(a1) * a3; }
;           }
;           float lo[2], hi[2];
;           xchg_pairs(v, odd, lo, hi);
; #pragma unroll
;           for (int k = 0; k < 2; ++k) {
;             const unsigned row = (unsigned)(rA + k);
;             if (EPI == EPI_HID) {
;               *(unsigned*)(ws + O_HID + (row * 1024u + (unsigned)(colp + cc)) * 2u) = pk2(lo[k], hi[k]);
;             } else if (EPI == EPI_COLS) {
;               *(unsigned*)(ws + O_COLS + (row * (unsigned)NCP + (unsigned)(colp + cc)) * 2u) = pk2(lo[k], hi[k]);
;             } else if (EPI == EPI_MOE2) {
;               *(unsigned*)(ws + O_EO + (row * 2048u + (unsigned)(colp + cc)) * 2u) = pk2(gate[k] * lo[k], gate[k] * hi[k]);
;             } else if (EPI == EPI_M1) {
;               const unsigned g2 = *(const unsigned*)(ws + O_COLS + (row * (unsigned)NCP + (unsigned)(C_GG + colp + cc)) * 2u);
;               *(unsigned*)(ws + O_M1 + (row * 2048u + (unsigned)(colp + cc)) * 2u) = pk2(sigm(bflo(g2)) * lo[k], sigm(bfhi(g2)) * hi[k]);
;             } else if (EPI == EPI_MERGED) {
;               const unsigned g2 = *(const unsigned*)(ws + O_COLS + (row * (unsigned)NCP + (unsigned)(C_GR + colp + cc)) * 2u);
;               const unsigned m1 = *(const unsigned*)(ws + O_M1 + (row * 2048u + (unsigned)(colp + cc)) * 2u);
;               *(unsigned*)(ws + O_MERGED + (row * 2048u + (unsigned)(colp + cc)) * 2u) =
;                   pk2(bflo(m1) + sigm(bflo(g2)) * lo[k], bfhi(m1) + sigm(bfhi(g2)) * hi[k]);
	v_lshlrev_b32_e32 v34, 16, v205
	v_and_b32_e32 v35, 0xffff0000, v205
	v_pk_add_f32 v[36:37], v[36:37], 1.0 op_sel_hi:[1,0]
	s_nop 0
	v_div_scale_f32 v39, s[0:1], v37, v37, 1.0
	v_div_scale_f32 v41, s[0:1], v36, v36, 1.0
	v_rcp_f32_e32 v42, v39
	v_rcp_f32_e32 v43, v41
	v_div_scale_f32 v40, vcc, 1.0, v37, 1.0
	v_fma_f32 v45, -v39, v42, 1.0
	v_fma_f32 v46, -v41, v43, 1.0
	v_fmac_f32_e32 v42, v45, v42
	v_div_scale_f32 v44, s[0:1], 1.0, v36, 1.0
	v_fmac_f32_e32 v43, v46, v43
	v_mul_f32_e32 v45, v40, v42
	v_mul_f32_e32 v46, v44, v43
	v_fma_f32 v47, -v39, v45, v40
	v_fma_f32 v48, -v41, v46, v44
	v_fmac_f32_e32 v45, v47, v42
	v_fmac_f32_e32 v46, v48, v43
	v_fma_f32 v39, -v39, v45, v40
	v_fma_f32 v40, -v41, v46, v44
	v_div_fmas_f32 v39, v39, v42, v45
	s_mov_b64 vcc, s[0:1]
	v_div_fixup_f32 v37, v39, v37, 1.0
	v_div_fmas_f32 v39, v40, v43, v46
	v_div_fixup_f32 v36, v39, v36, 1.0
	v_pk_fma_f32 v[32:33], v[32:33], v[36:37], v[34:35]
	s_nop 0
	v_cvt_pk_bf16_f32 v32, v32, v33
	global_store_dword v38, v32, s[12:13]
	v_add_u32_e32 v184, 0x1ce000, v131
	v_add_lshl_u32 v185, v184, v130, 1
	global_load_dword v190, v185, s[8:9]
	v_add_u32_e32 v185, 0xb0000, v129
	v_add_u32_e32 v186, v185, v128
	global_load_dword v191, v186, s[10:11]
	v_add_u32_e32 v187, 0x1d0a00, v131
	v_add_lshl_u32 v188, v187, v130, 1
	global_load_dword v192, v188, s[8:9]
	v_add_u32_e32 v222, 0xb1000, v129
	v_add_u32_e32 v223, v222, v128
	global_load_dword v193, v223, s[10:11]
	v_add_lshl_u32 v224, v184, v124, 1
	v_add_u32_e32 v225, v185, v125
	global_load_dword v194, v224, s[8:9]
	global_load_dword v195, v225, s[10:11]
	v_add_lshl_u32 v223, v187, v124, 1
	v_add_u32_e32 v226, v222, v125
	global_load_dword v196, v223, s[8:9]
	global_load_dword v197, v226, s[10:11]
	v_add_lshl_u32 v227, v184, v120, 1
	v_add_lshl_u32 v225, v187, v120, 1
	global_load_dword v198, v227, s[8:9]
	v_add_u32_e32 v226, v185, v121
	global_load_dword v199, v226, s[10:11]
	v_add_u32_e32 v228, v222, v121
	global_load_dword v200, v225, s[8:9]
	global_load_dword v201, v228, s[10:11]
	v_add_lshl_u32 v229, v184, v116, 1
	v_add_lshl_u32 v230, v187, v116, 1
	global_load_dword v202, v229, s[8:9]
	v_add_u32_e32 v228, v185, v117
	global_load_dword v203, v228, s[10:11]
	v_add_u32_e32 v231, v222, v117
	global_load_dword v204, v230, s[8:9]
	global_load_dword v205, v231, s[10:11]
	v_add_u32_e32 v34, 0x1a4000, v131
	v_add_lshl_u32 v32, v34, v130, 1
	s_nop 0
	v_add_u32_e32 v32, 0xa0000, v129
	v_add_u32_e32 v42, v32, v128
	s_nop 0
	v_cndmask_b32_e64 v36, v28, v30, s[6:7]
	v_add_u32_e32 v33, 0x1a6a00, v131
	v_add_lshl_u32 v43, v33, v130, 1
	v_mov_b32_dpp v37, v36 quad_perm:[1,0,3,2] row_mask:0xf bank_mask:0xf bound_ctrl:1
	v_cndmask_b32_e64 v36, v37, v28, s[6:7]
	v_cndmask_b32_e64 v37, v30, v37, s[6:7]
	s_waitcnt vmcnt(38)
	v_lshlrev_b32_e32 v28, 16, v152
	v_and_b32_e32 v35, 0xffff0000, v152
	v_mul_f32_e32 v28, 0xbfb8aa3b, v28
	v_mul_f32_e32 v35, 0xbfb8aa3b, v35
	v_exp_f32_e32 v38, v28
	v_exp_f32_e32 v39, v35
	s_waitcnt vmcnt(38)
	v_lshlrev_b32_e32 v40, 16, v153
	v_and_b32_e32 v41, 0xffff0000, v153
	v_pk_add_f32 v[38:39], v[38:39], 1.0 op_sel_hi:[1,0]
	s_nop 0
	v_div_scale_f32 v28, s[0:1], v39, v39, 1.0
	v_div_scale_f32 v35, s[0:1], v38, v38, 1.0
	v_rcp_f32_e32 v44, v28
	v_rcp_f32_e32 v45, v35
	v_div_scale_f32 v30, vcc, 1.0, v39, 1.0
	v_fma_f32 v47, -v28, v44, 1.0
	v_fma_f32 v48, -v35, v45, 1.0
	v_fmac_f32_e32 v44, v47, v44
	v_div_scale_f32 v46, s[0:1], 1.0, v38, 1.0
	v_fmac_f32_e32 v45, v48, v45
	v_mul_f32_e32 v47, v30, v44
	v_mul_f32_e32 v48, v46, v45
	v_fma_f32 v49, -v28, v47, v30
	v_fma_f32 v50, -v35, v48, v46
	v_fmac_f32_e32 v47, v49, v44
	v_fmac_f32_e32 v48, v50, v45
	v_fma_f32 v28, -v28, v47, v30
	v_fma_f32 v30, -v35, v48, v46
	v_div_fmas_f32 v28, v28, v44, v47
	s_mov_b64 vcc, s[0:1]
	v_div_fixup_f32 v39, v28, v39, 1.0
	v_div_fmas_f32 v28, v30, v45, v48
	v_div_fixup_f32 v38, v28, v38, 1.0
	v_pk_fma_f32 v[36:37], v[36:37], v[38:39], v[40:41]
	v_cndmask_b32_e64 v30, v29, v31, s[6:7]
	v_cvt_pk_bf16_f32 v28, v36, v37
	global_store_dword v42, v28, s[12:13]
	s_nop 0
	v_add_u32_e32 v28, 0xa1000, v129
	v_add_u32_e32 v40, v28, v128
	s_nop 0
	v_mov_b32_dpp v38, v30 quad_perm:[1,0,3,2] row_mask:0xf bank_mask:0xf bound_ctrl:1
	v_cndmask_b32_e64 v30, v38, v29, s[6:7]
	v_cndmask_b32_e64 v31, v31, v38, s[6:7]
	v_add_lshl_u32 v41, v34, v124, 1
	s_waitcnt vmcnt(37)
	v_lshlrev_b32_e32 v29, 16, v154
	v_and_b32_e32 v35, 0xffff0000, v154
	v_mul_f32_e32 v29, 0xbfb8aa3b, v29
	v_mul_f32_e32 v35, 0xbfb8aa3b, v35
	v_exp_f32_e32 v36, v29
	v_exp_f32_e32 v37, v35
	s_waitcnt vmcnt(37)
	v_lshlrev_b32_e32 v38, 16, v155
	v_and_b32_e32 v39, 0xffff0000, v155
	v_pk_add_f32 v[36:37], v[36:37], 1.0 op_sel_hi:[1,0]
	s_nop 0
	v_div_scale_f32 v29, s[0:1], v37, v37, 1.0
	v_div_scale_f32 v42, s[0:1], v36, v36, 1.0
	v_rcp_f32_e32 v43, v29
	v_rcp_f32_e32 v44, v42
	v_div_scale_f32 v35, vcc, 1.0, v37, 1.0
	v_fma_f32 v46, -v29, v43, 1.0
	v_fma_f32 v47, -v42, v44, 1.0
	v_fmac_f32_e32 v43, v46, v43
	v_div_scale_f32 v45, s[0:1], 1.0, v36, 1.0
	v_fmac_f32_e32 v44, v47, v44
	v_mul_f32_e32 v46, v35, v43
	v_mul_f32_e32 v47, v45, v44
	v_fma_f32 v48, -v29, v46, v35
	v_fma_f32 v49, -v42, v47, v45
	v_fmac_f32_e32 v46, v48, v43
	v_fmac_f32_e32 v47, v49, v44
	v_fma_f32 v29, -v29, v46, v35
	v_fma_f32 v35, -v42, v47, v45
	v_div_fmas_f32 v29, v29, v43, v46
	s_mov_b64 vcc, s[0:1]
	v_div_fixup_f32 v37, v29, v37, 1.0
	v_div_fmas_f32 v29, v35, v44, v47
	v_div_fixup_f32 v36, v29, v36, 1.0
	v_pk_fma_f32 v[30:31], v[30:31], v[36:37], v[38:39]
	v_add_u32_e32 v35, v32, v125
	v_cvt_pk_bf16_f32 v29, v30, v31
	global_store_dword v40, v29, s[12:13]
	s_nop 0
	v_cndmask_b32_e64 v30, v24, v26, s[6:7]
	s_nop 0
	v_add_lshl_u32 v40, v33, v124, 1
	v_mov_b32_dpp v31, v30 quad_perm:[1,0,3,2] row_mask:0xf bank_mask:0xf bound_ctrl:1
	v_cndmask_b32_e64 v30, v31, v24, s[6:7]
	v_cndmask_b32_e64 v31, v26, v31, s[6:7]
	s_waitcnt vmcnt(36)
; DEVINL float bflo(unsigned u) { return __uint_as_float(u << 16); }
; DEVINL float bfhi(unsigned u) { return __uint_as_float(u & 0xffff0000u); }
; DEVINL float sigm(float x) { return 1.f / (1.f + __expf(-x)); }
; template <int EPI, bool GATHER>
; DEVINL void gemm_tile(const Params& p, const u16* __restrict__ A, int lda, const int* __restrict__ rowidx,
;                       const u16* __restrict__ Bt, int ldb, int K, int brow, int bcol, int orow, int ocol) {
;     ...
;       for (int bj = 0; bj < (EPI == EPI_HID ? 1 : 2); ++bj)
; #pragma unroll
;         for (int n = 0; n < 2; ++n) {
;           const int cc = bj * HALF + n * 16;
;           f32x4 v = acc[ai][bj][m][n];
;           if (EPI == EPI_HID) {
; #pragma unroll
;             for (int j = 0; j < 4; ++j) { const float a1 = acc[ai][0][m][n][j], a3 = acc[ai][1][m][n][j]; v[j] = a1 * sigm(a1) * a3; }
;           }
;           float lo[2], hi[2];
;           xchg_pairs(v, odd, lo, hi);
; #pragma unroll
;           for (int k = 0; k < 2; ++k) {
;             const unsigned row = (unsigned)(rA + k);
;             if (EPI == EPI_HID) {
;               *(unsigned*)(ws + O_HID + (row * 1024u + (unsigned)(colp + cc)) * 2u) = pk2(lo[k], hi[k]);
;             } else if (EPI == EPI_COLS) {
;               *(unsigned*)(ws + O_COLS + (row * (unsigned)NCP + (unsigned)(colp + cc)) * 2u) = pk2(lo[k], hi[k]);
;             } else if (EPI == EPI_MOE2) {
;               *(unsigned*)(ws + O_EO + (row * 2048u + (unsigned)(colp + cc)) * 2u) = pk2(gate[k] * lo[k], gate[k] * hi[k]);
;             } else if (EPI == EPI_M1) {
;               const unsigned g2 = *(const unsigned*)(ws + O_COLS + (row * (unsigned)NCP + (unsigned)(C_GG + colp + cc)) * 2u);
;               *(unsigned*)(ws + O_M1 + (row * 2048u + (unsigned)(colp + cc)) * 2u) = pk2(sigm(bflo(g2)) * lo[k], sigm(bfhi(g2)) * hi[k]);
;             } else if (EPI == EPI_MERGED) {
;               const unsigned g2 = *(const unsigned*)(ws + O_COLS + (row * (unsigned)NCP + (unsigned)(C_GR + colp + cc)) * 2u);
;               const unsigned m1 = *(const unsigned*)(ws + O_M1 + (row * 2048u + (unsigned)(colp + cc)) * 2u);
;               *(unsigned*)(ws + O_MERGED + (row * 2048u + (unsigned)(colp + cc)) * 2u) =
;                   pk2(bflo(m1) + sigm(bflo(g2)) * lo[k], bfhi(m1) + sigm(bfhi(g2)) * hi[k]);
	v_lshlrev_b32_e32 v24, 16, v156
	v_and_b32_e32 v29, 0xffff0000, v156
	v_mul_f32_e32 v24, 0xbfb8aa3b, v24
	v_mul_f32_e32 v29, 0xbfb8aa3b, v29
	v_exp_f32_e32 v36, v24
	v_exp_f32_e32 v37, v29
	s_waitcnt vmcnt(36)
	v_lshlrev_b32_e32 v38, 16, v157
	v_and_b32_e32 v39, 0xffff0000, v157
	v_pk_add_f32 v[36:37], v[36:37], 1.0 op_sel_hi:[1,0]
	s_nop 0
	v_div_scale_f32 v24, s[0:1], v37, v37, 1.0
	v_div_scale_f32 v29, s[0:1], v36, v36, 1.0
	v_rcp_f32_e32 v41, v24
	v_rcp_f32_e32 v42, v29
	v_div_scale_f32 v26, vcc, 1.0, v37, 1.0
	v_fma_f32 v44, -v24, v41, 1.0
	v_fma_f32 v45, -v29, v42, 1.0
	v_fmac_f32_e32 v41, v44, v41
	v_div_scale_f32 v43, s[0:1], 1.0, v36, 1.0
	v_fmac_f32_e32 v42, v45, v42
	v_mul_f32_e32 v44, v26, v41
	v_mul_f32_e32 v45, v43, v42
	v_fma_f32 v46, -v24, v44, v26
	v_fma_f32 v47, -v29, v45, v43
	v_fmac_f32_e32 v44, v46, v41
	v_fmac_f32_e32 v45, v47, v42
	v_fma_f32 v24, -v24, v44, v26
	v_fma_f32 v26, -v29, v45, v43
	v_div_fmas_f32 v24, v24, v41, v44
	s_mov_b64 vcc, s[0:1]
	v_div_fixup_f32 v37, v24, v37, 1.0
	v_div_fmas_f32 v24, v26, v42, v45
	v_div_fixup_f32 v36, v24, v36, 1.0
	v_pk_fma_f32 v[30:31], v[30:31], v[36:37], v[38:39]
	v_add_u32_e32 v29, v28, v125
	v_cvt_pk_bf16_f32 v24, v30, v31
	global_store_dword v35, v24, s[12:13]
	s_nop 0
	v_cndmask_b32_e64 v24, v25, v27, s[6:7]
	s_nop 0
	v_add_lshl_u32 v37, v34, v120, 1
	v_mov_b32_dpp v36, v24 quad_perm:[1,0,3,2] row_mask:0xf bank_mask:0xf bound_ctrl:1
	v_cndmask_b32_e64 v24, v36, v25, s[6:7]
	s_waitcnt vmcnt(35)
	v_lshlrev_b32_e32 v25, 16, v158
	v_and_b32_e32 v26, 0xffff0000, v158
	v_mul_f32_e32 v25, 0xbfb8aa3b, v25
	v_mul_f32_e32 v26, 0xbfb8aa3b, v26
	v_exp_f32_e32 v30, v25
	v_exp_f32_e32 v31, v26
	v_cndmask_b32_e64 v25, v27, v36, s[6:7]
	s_waitcnt vmcnt(35)
	v_lshlrev_b32_e32 v26, 16, v159
	v_and_b32_e32 v27, 0xffff0000, v159
	v_pk_add_f32 v[30:31], v[30:31], 1.0 op_sel_hi:[1,0]
	s_nop 0
	v_div_scale_f32 v35, s[0:1], v31, v31, 1.0
	v_div_scale_f32 v38, s[0:1], v30, v30, 1.0
	v_rcp_f32_e32 v39, v35
	v_rcp_f32_e32 v40, v38
	v_div_scale_f32 v36, vcc, 1.0, v31, 1.0
	v_fma_f32 v42, -v35, v39, 1.0
	v_fma_f32 v43, -v38, v40, 1.0
	v_fmac_f32_e32 v39, v42, v39
	v_div_scale_f32 v41, s[0:1], 1.0, v30, 1.0
	v_fmac_f32_e32 v40, v43, v40
	v_mul_f32_e32 v42, v36, v39
	v_mul_f32_e32 v43, v41, v40
	v_fma_f32 v44, -v35, v42, v36
	v_fma_f32 v45, -v38, v43, v41
	v_fmac_f32_e32 v42, v44, v39
	v_fmac_f32_e32 v43, v45, v40
	v_fma_f32 v35, -v35, v42, v36
	v_fma_f32 v36, -v38, v43, v41
	v_div_fmas_f32 v35, v35, v39, v42
	s_mov_b64 vcc, s[0:1]
	v_div_fixup_f32 v31, v35, v31, 1.0
	v_div_fmas_f32 v35, v36, v40, v43
	v_div_fixup_f32 v30, v35, v30, 1.0
	v_pk_fma_f32 v[24:25], v[24:25], v[30:31], v[26:27]
	v_add_lshl_u32 v35, v33, v120, 1
	v_cvt_pk_bf16_f32 v24, v24, v25
	global_store_dword v29, v24, s[12:13]
	s_nop 0
	v_add_u32_e32 v29, v32, v121
	s_nop 0
	v_cndmask_b32_e64 v24, v20, v22, s[6:7]
	s_nop 1
	v_mov_b32_dpp v30, v24 quad_perm:[1,0,3,2] row_mask:0xf bank_mask:0xf bound_ctrl:1
	v_cndmask_b32_e64 v24, v30, v20, s[6:7]
	s_waitcnt vmcnt(34)
	v_lshlrev_b32_e32 v20, 16, v160
	v_and_b32_e32 v25, 0xffff0000, v160
	v_mul_f32_e32 v20, 0xbfb8aa3b, v20
	v_mul_f32_e32 v25, 0xbfb8aa3b, v25
	v_exp_f32_e32 v26, v20
	v_exp_f32_e32 v27, v25
	v_cndmask_b32_e64 v25, v22, v30, s[6:7]
	s_waitcnt vmcnt(34)
	v_lshlrev_b32_e32 v30, 16, v161
	v_and_b32_e32 v31, 0xffff0000, v161
	v_pk_add_f32 v[26:27], v[26:27], 1.0 op_sel_hi:[1,0]
	s_nop 0
	v_div_scale_f32 v20, s[0:1], v27, v27, 1.0
	v_div_scale_f32 v36, s[0:1], v26, v26, 1.0
	v_rcp_f32_e32 v37, v20
	v_rcp_f32_e32 v38, v36
	v_div_scale_f32 v22, vcc, 1.0, v27, 1.0
	v_fma_f32 v40, -v20, v37, 1.0
	v_fma_f32 v41, -v36, v38, 1.0
	v_fmac_f32_e32 v37, v40, v37
	v_div_scale_f32 v39, s[0:1], 1.0, v26, 1.0
	v_fmac_f32_e32 v38, v41, v38
	v_mul_f32_e32 v40, v22, v37
	v_mul_f32_e32 v41, v39, v38
	v_fma_f32 v42, -v20, v40, v22
	v_fma_f32 v43, -v36, v41, v39
	v_fmac_f32_e32 v40, v42, v37
	v_fmac_f32_e32 v41, v43, v38
	v_fma_f32 v20, -v20, v40, v22
	v_fma_f32 v22, -v36, v41, v39
	v_div_fmas_f32 v20, v20, v37, v40
	s_mov_b64 vcc, s[0:1]
	v_div_fixup_f32 v27, v20, v27, 1.0
	v_div_fmas_f32 v20, v22, v38, v41
	v_div_fixup_f32 v26, v20, v26, 1.0
	v_pk_fma_f32 v[24:25], v[24:25], v[26:27], v[30:31]
	v_add_u32_e32 v26, v28, v121
	v_cvt_pk_bf16_f32 v20, v24, v25
	global_store_dword v29, v20, s[12:13]
	s_nop 0
	s_nop 0
	v_cndmask_b32_e64 v20, v21, v23, s[6:7]
	v_add_lshl_u32 v30, v34, v116, 1
	s_nop 0
	v_mov_b32_dpp v29, v20 quad_perm:[1,0,3,2] row_mask:0xf bank_mask:0xf bound_ctrl:1
	v_cndmask_b32_e64 v20, v29, v21, s[6:7]
	s_waitcnt vmcnt(33)
	v_lshlrev_b32_e32 v21, 16, v162
	v_and_b32_e32 v22, 0xffff0000, v162
	v_mul_f32_e32 v21, 0xbfb8aa3b, v21
	v_mul_f32_e32 v22, 0xbfb8aa3b, v22
	v_exp_f32_e32 v24, v21
	v_exp_f32_e32 v25, v22
	v_cndmask_b32_e64 v21, v23, v29, s[6:7]
	s_waitcnt vmcnt(33)
	v_lshlrev_b32_e32 v22, 16, v163
	v_and_b32_e32 v23, 0xffff0000, v163
	v_pk_add_f32 v[24:25], v[24:25], 1.0 op_sel_hi:[1,0]
	s_nop 0
	v_div_scale_f32 v27, s[0:1], v25, v25, 1.0
	v_div_scale_f32 v31, s[0:1], v24, v24, 1.0
	v_rcp_f32_e32 v34, v27
	v_rcp_f32_e32 v35, v31
	v_div_scale_f32 v29, vcc, 1.0, v25, 1.0
	v_fma_f32 v37, -v27, v34, 1.0
	v_fma_f32 v38, -v31, v35, 1.0
	v_fmac_f32_e32 v34, v37, v34
	v_div_scale_f32 v36, s[0:1], 1.0, v24, 1.0
	v_fmac_f32_e32 v35, v38, v35
	v_mul_f32_e32 v37, v29, v34
	v_mul_f32_e32 v38, v36, v35
	v_fma_f32 v39, -v27, v37, v29
	v_fma_f32 v40, -v31, v38, v36
	v_fmac_f32_e32 v37, v39, v34
	v_fmac_f32_e32 v38, v40, v35
	v_fma_f32 v27, -v27, v37, v29
	v_fma_f32 v29, -v31, v38, v36
	v_div_fmas_f32 v27, v27, v34, v37
	s_mov_b64 vcc, s[0:1]
	v_div_fixup_f32 v25, v27, v25, 1.0
	v_div_fmas_f32 v27, v29, v35, v38
	v_div_fixup_f32 v24, v27, v24, 1.0
	v_pk_fma_f32 v[20:21], v[20:21], v[24:25], v[22:23]
	v_add_lshl_u32 v27, v33, v116, 1
	v_cvt_pk_bf16_f32 v20, v20, v21
	global_store_dword v26, v20, s[12:13]
	s_nop 0
	v_add_u32_e32 v26, v32, v117
	s_nop 0
	v_cndmask_b32_e64 v20, v16, v18, s[6:7]
	s_nop 1
	v_mov_b32_dpp v24, v20 quad_perm:[1,0,3,2] row_mask:0xf bank_mask:0xf bound_ctrl:1
	v_cndmask_b32_e64 v20, v24, v16, s[6:7]
	s_waitcnt vmcnt(32)
; DEVINL float bflo(unsigned u) { return __uint_as_float(u << 16); }
; DEVINL float bfhi(unsigned u) { return __uint_as_float(u & 0xffff0000u); }
; DEVINL float sigm(float x) { return 1.f / (1.f + __expf(-x)); }
; template <int EPI, bool GATHER>
; DEVINL void gemm_tile(const Params& p, const u16* __restrict__ A, int lda, const int* __restrict__ rowidx,
;                       const u16* __restrict__ Bt, int ldb, int K, int brow, int bcol, int orow, int ocol) {
;     ...
;       for (int bj = 0; bj < (EPI == EPI_HID ? 1 : 2); ++bj)
; #pragma unroll
;         for (int n = 0; n < 2; ++n) {
;           const int cc = bj * HALF + n * 16;
;           f32x4 v = acc[ai][bj][m][n];
;           if (EPI == EPI_HID) {
; #pragma unroll
;             for (int j = 0; j < 4; ++j) { const float a1 = acc[ai][0][m][n][j], a3 = acc[ai][1][m][n][j]; v[j] = a1 * sigm(a1) * a3; }
;           }
;           float lo[2], hi[2];
;           xchg_pairs(v, odd, lo, hi);
; #pragma unroll
;           for (int k = 0; k < 2; ++k) {
;             const unsigned row = (unsigned)(rA + k);
;             if (EPI == EPI_HID) {
;               *(unsigned*)(ws + O_HID + (row * 1024u + (unsigned)(colp + cc)) * 2u) = pk2(lo[k], hi[k]);
;             } else if (EPI == EPI_COLS) {
;               *(unsigned*)(ws + O_COLS + (row * (unsigned)NCP + (unsigned)(colp + cc)) * 2u) = pk2(lo[k], hi[k]);
;             } else if (EPI == EPI_MOE2) {
;               *(unsigned*)(ws + O_EO + (row * 2048u + (unsigned)(colp + cc)) * 2u) = pk2(gate[k] * lo[k], gate[k] * hi[k]);
;             } else if (EPI == EPI_M1) {
;               const unsigned g2 = *(const unsigned*)(ws + O_COLS + (row * (unsigned)NCP + (unsigned)(C_GG + colp + cc)) * 2u);
;               *(unsigned*)(ws + O_M1 + (row * 2048u + (unsigned)(colp + cc)) * 2u) = pk2(sigm(bflo(g2)) * lo[k], sigm(bfhi(g2)) * hi[k]);
;             } else if (EPI == EPI_MERGED) {
;               const unsigned g2 = *(const unsigned*)(ws + O_COLS + (row * (unsigned)NCP + (unsigned)(C_GR + colp + cc)) * 2u);
;               const unsigned m1 = *(const unsigned*)(ws + O_M1 + (row * 2048u + (unsigned)(colp + cc)) * 2u);
;               *(unsigned*)(ws + O_MERGED + (row * 2048u + (unsigned)(colp + cc)) * 2u) =
;                   pk2(bflo(m1) + sigm(bflo(g2)) * lo[k], bfhi(m1) + sigm(bfhi(g2)) * hi[k]);
	v_lshlrev_b32_e32 v16, 16, v164
	v_and_b32_e32 v21, 0xffff0000, v164
	v_mul_f32_e32 v16, 0xbfb8aa3b, v16
	v_mul_f32_e32 v21, 0xbfb8aa3b, v21
	v_exp_f32_e32 v22, v16
	v_exp_f32_e32 v23, v21
	v_cndmask_b32_e64 v21, v18, v24, s[6:7]
	s_waitcnt vmcnt(32)
	v_lshlrev_b32_e32 v24, 16, v165
	v_and_b32_e32 v25, 0xffff0000, v165
	v_pk_add_f32 v[22:23], v[22:23], 1.0 op_sel_hi:[1,0]
	s_nop 0
	v_div_scale_f32 v16, s[0:1], v23, v23, 1.0
	v_div_scale_f32 v29, s[0:1], v22, v22, 1.0
	v_rcp_f32_e32 v30, v16
	v_rcp_f32_e32 v31, v29
	v_div_scale_f32 v18, vcc, 1.0, v23, 1.0
	v_fma_f32 v33, -v16, v30, 1.0
	v_fma_f32 v34, -v29, v31, 1.0
	v_fmac_f32_e32 v30, v33, v30
	v_div_scale_f32 v32, s[0:1], 1.0, v22, 1.0
	v_fmac_f32_e32 v31, v34, v31
	v_mul_f32_e32 v33, v18, v30
	v_mul_f32_e32 v34, v32, v31
	v_fma_f32 v35, -v16, v33, v18
	v_fma_f32 v36, -v29, v34, v32
	v_fmac_f32_e32 v33, v35, v30
	v_fmac_f32_e32 v34, v36, v31
	v_fma_f32 v16, -v16, v33, v18
	v_fma_f32 v18, -v29, v34, v32
	v_div_fmas_f32 v16, v16, v30, v33
	s_mov_b64 vcc, s[0:1]
	v_div_fixup_f32 v23, v16, v23, 1.0
	v_div_fmas_f32 v16, v18, v31, v34
	v_div_fixup_f32 v22, v16, v22, 1.0
	v_pk_fma_f32 v[20:21], v[20:21], v[22:23], v[24:25]
	v_add_u32_e32 v22, v28, v117
	v_cvt_pk_bf16_f32 v16, v20, v21
	global_store_dword v26, v16, s[12:13]
	s_nop 0
	s_nop 0
	v_cndmask_b32_e64 v16, v17, v19, s[6:7]
	s_nop 1
	v_mov_b32_dpp v24, v16 quad_perm:[1,0,3,2] row_mask:0xf bank_mask:0xf bound_ctrl:1
	v_cndmask_b32_e64 v16, v24, v17, s[6:7]
	s_waitcnt vmcnt(31)
	v_lshlrev_b32_e32 v17, 16, v166
	v_and_b32_e32 v18, 0xffff0000, v166
	v_mul_f32_e32 v17, 0xbfb8aa3b, v17
	v_mul_f32_e32 v18, 0xbfb8aa3b, v18
	v_exp_f32_e32 v20, v17
	v_exp_f32_e32 v21, v18
	v_cndmask_b32_e64 v17, v19, v24, s[6:7]
	s_waitcnt vmcnt(31)
	v_lshlrev_b32_e32 v18, 16, v167
	v_and_b32_e32 v19, 0xffff0000, v167
	v_pk_add_f32 v[20:21], v[20:21], 1.0 op_sel_hi:[1,0]
	s_nop 0
	v_div_scale_f32 v23, s[0:1], v21, v21, 1.0
	v_div_scale_f32 v25, s[0:1], v20, v20, 1.0
	v_rcp_f32_e32 v26, v23
	v_rcp_f32_e32 v27, v25
	v_div_scale_f32 v24, vcc, 1.0, v21, 1.0
	v_fma_f32 v29, -v23, v26, 1.0
	v_fma_f32 v30, -v25, v27, 1.0
	v_fmac_f32_e32 v26, v29, v26
	v_div_scale_f32 v28, s[0:1], 1.0, v20, 1.0
	v_fmac_f32_e32 v27, v30, v27
	v_mul_f32_e32 v29, v24, v26
	v_mul_f32_e32 v30, v28, v27
	v_fma_f32 v31, -v23, v29, v24
	v_fma_f32 v32, -v25, v30, v28
	v_fmac_f32_e32 v29, v31, v26
	v_fmac_f32_e32 v30, v32, v27
	v_fma_f32 v23, -v23, v29, v24
	v_fma_f32 v24, -v25, v30, v28
	v_div_fmas_f32 v23, v23, v26, v29
	s_mov_b64 vcc, s[0:1]
	v_div_fixup_f32 v21, v23, v21, 1.0
	v_div_fmas_f32 v23, v24, v27, v30
	v_div_fixup_f32 v20, v23, v20, 1.0
	v_pk_fma_f32 v[16:17], v[16:17], v[20:21], v[18:19]
	s_nop 0
	v_cvt_pk_bf16_f32 v16, v16, v17
	global_store_dword v22, v16, s[12:13]
	v_add_u32_e32 v18, 0x1ce000, v131
	v_add_lshl_u32 v16, v18, v130, 1
	s_nop 0
	v_add_u32_e32 v16, 0xb0000, v129
	v_add_u32_e32 v26, v16, v128
	s_nop 0
	v_cndmask_b32_e64 v20, v12, v14, s[6:7]
	v_add_u32_e32 v17, 0x1d0a00, v131
	v_add_lshl_u32 v27, v17, v130, 1
	v_mov_b32_dpp v21, v20 quad_perm:[1,0,3,2] row_mask:0xf bank_mask:0xf bound_ctrl:1
	v_cndmask_b32_e64 v20, v21, v12, s[6:7]
	v_cndmask_b32_e64 v21, v14, v21, s[6:7]
	s_waitcnt vmcnt(22)
	v_lshlrev_b32_e32 v12, 16, v190
	v_and_b32_e32 v19, 0xffff0000, v190
	v_mul_f32_e32 v12, 0xbfb8aa3b, v12
	v_mul_f32_e32 v19, 0xbfb8aa3b, v19
	v_exp_f32_e32 v22, v12
	v_exp_f32_e32 v23, v19
	s_waitcnt vmcnt(22)
	v_lshlrev_b32_e32 v24, 16, v191
	v_and_b32_e32 v25, 0xffff0000, v191
	v_pk_add_f32 v[22:23], v[22:23], 1.0 op_sel_hi:[1,0]
	s_nop 0
	v_div_scale_f32 v12, s[0:1], v23, v23, 1.0
	v_div_scale_f32 v19, s[0:1], v22, v22, 1.0
	v_rcp_f32_e32 v28, v12
	v_rcp_f32_e32 v29, v19
	v_div_scale_f32 v14, vcc, 1.0, v23, 1.0
	v_fma_f32 v31, -v12, v28, 1.0
	v_fma_f32 v32, -v19, v29, 1.0
	v_fmac_f32_e32 v28, v31, v28
	v_div_scale_f32 v30, s[0:1], 1.0, v22, 1.0
	v_fmac_f32_e32 v29, v32, v29
	v_mul_f32_e32 v31, v14, v28
	v_mul_f32_e32 v32, v30, v29
	v_fma_f32 v33, -v12, v31, v14
	v_fma_f32 v34, -v19, v32, v30
	v_fmac_f32_e32 v31, v33, v28
	v_fmac_f32_e32 v32, v34, v29
	v_fma_f32 v12, -v12, v31, v14
	v_fma_f32 v14, -v19, v32, v30
	v_div_fmas_f32 v12, v12, v28, v31
	s_mov_b64 vcc, s[0:1]
	v_div_fixup_f32 v23, v12, v23, 1.0
	v_div_fmas_f32 v12, v14, v29, v32
	v_div_fixup_f32 v22, v12, v22, 1.0
	v_pk_fma_f32 v[20:21], v[20:21], v[22:23], v[24:25]
	v_cndmask_b32_e64 v14, v13, v15, s[6:7]
	v_cvt_pk_bf16_f32 v12, v20, v21
	global_store_dword v26, v12, s[12:13]
	s_nop 0
	v_add_u32_e32 v12, 0xb1000, v129
	v_add_u32_e32 v24, v12, v128
	s_nop 0
	v_mov_b32_dpp v22, v14 quad_perm:[1,0,3,2] row_mask:0xf bank_mask:0xf bound_ctrl:1
	v_cndmask_b32_e64 v14, v22, v13, s[6:7]
	v_cndmask_b32_e64 v15, v15, v22, s[6:7]
	v_add_lshl_u32 v25, v18, v124, 1
	s_waitcnt vmcnt(21)
	v_lshlrev_b32_e32 v13, 16, v192
	v_and_b32_e32 v19, 0xffff0000, v192
	v_mul_f32_e32 v13, 0xbfb8aa3b, v13
	v_mul_f32_e32 v19, 0xbfb8aa3b, v19
	v_exp_f32_e32 v20, v13
	v_exp_f32_e32 v21, v19
	s_waitcnt vmcnt(21)
; DEVINL float bflo(unsigned u) { return __uint_as_float(u << 16); }
; DEVINL float bfhi(unsigned u) { return __uint_as_float(u & 0xffff0000u); }
; DEVINL float sigm(float x) { return 1.f / (1.f + __expf(-x)); }
; template <int EPI, bool GATHER>
; DEVINL void gemm_tile(const Params& p, const u16* __restrict__ A, int lda, const int* __restrict__ rowidx,
;                       const u16* __restrict__ Bt, int ldb, int K, int brow, int bcol, int orow, int ocol) {
;     ...
;       for (int bj = 0; bj < (EPI == EPI_HID ? 1 : 2); ++bj)
; #pragma unroll
;         for (int n = 0; n < 2; ++n) {
;           const int cc = bj * HALF + n * 16;
;           f32x4 v = acc[ai][bj][m][n];
;           if (EPI == EPI_HID) {
; #pragma unroll
;             for (int j = 0; j < 4; ++j) { const float a1 = acc[ai][0][m][n][j], a3 = acc[ai][1][m][n][j]; v[j] = a1 * sigm(a1) * a3; }
;           }
;           float lo[2], hi[2];
;           xchg_pairs(v, odd, lo, hi);
; #pragma unroll
;           for (int k = 0; k < 2; ++k) {
;             const unsigned row = (unsigned)(rA + k);
;             if (EPI == EPI_HID) {
;               *(unsigned*)(ws + O_HID + (row * 1024u + (unsigned)(colp + cc)) * 2u) = pk2(lo[k], hi[k]);
;             } else if (EPI == EPI_COLS) {
;               *(unsigned*)(ws + O_COLS + (row * (unsigned)NCP + (unsigned)(colp + cc)) * 2u) = pk2(lo[k], hi[k]);
;             } else if (EPI == EPI_MOE2) {
;               *(unsigned*)(ws + O_EO + (row * 2048u + (unsigned)(colp + cc)) * 2u) = pk2(gate[k] * lo[k], gate[k] * hi[k]);
;             } else if (EPI == EPI_M1) {
;               const unsigned g2 = *(const unsigned*)(ws + O_COLS + (row * (unsigned)NCP + (unsigned)(C_GG + colp + cc)) * 2u);
;               *(unsigned*)(ws + O_M1 + (row * 2048u + (unsigned)(colp + cc)) * 2u) = pk2(sigm(bflo(g2)) * lo[k], sigm(bfhi(g2)) * hi[k]);
;             } else if (EPI == EPI_MERGED) {
;               const unsigned g2 = *(const unsigned*)(ws + O_COLS + (row * (unsigned)NCP + (unsigned)(C_GR + colp + cc)) * 2u);
;               const unsigned m1 = *(const unsigned*)(ws + O_M1 + (row * 2048u + (unsigned)(colp + cc)) * 2u);
;               *(unsigned*)(ws + O_MERGED + (row * 2048u + (unsigned)(colp + cc)) * 2u) =
;                   pk2(bflo(m1) + sigm(bflo(g2)) * lo[k], bfhi(m1) + sigm(bfhi(g2)) * hi[k]);
	v_lshlrev_b32_e32 v22, 16, v193
	v_and_b32_e32 v23, 0xffff0000, v193
	v_pk_add_f32 v[20:21], v[20:21], 1.0 op_sel_hi:[1,0]
	s_nop 0
	v_div_scale_f32 v13, s[0:1], v21, v21, 1.0
	v_div_scale_f32 v26, s[0:1], v20, v20, 1.0
	v_rcp_f32_e32 v27, v13
	v_rcp_f32_e32 v28, v26
	v_div_scale_f32 v19, vcc, 1.0, v21, 1.0
	v_fma_f32 v30, -v13, v27, 1.0
	v_fma_f32 v31, -v26, v28, 1.0
	v_fmac_f32_e32 v27, v30, v27
	v_div_scale_f32 v29, s[0:1], 1.0, v20, 1.0
	v_fmac_f32_e32 v28, v31, v28
	v_mul_f32_e32 v30, v19, v27
	v_mul_f32_e32 v31, v29, v28
	v_fma_f32 v32, -v13, v30, v19
	v_fma_f32 v33, -v26, v31, v29
	v_fmac_f32_e32 v30, v32, v27
	v_fmac_f32_e32 v31, v33, v28
	v_fma_f32 v13, -v13, v30, v19
	v_fma_f32 v19, -v26, v31, v29
	v_div_fmas_f32 v13, v13, v27, v30
	s_mov_b64 vcc, s[0:1]
	v_div_fixup_f32 v21, v13, v21, 1.0
	v_div_fmas_f32 v13, v19, v28, v31
	v_div_fixup_f32 v20, v13, v20, 1.0
	v_pk_fma_f32 v[14:15], v[14:15], v[20:21], v[22:23]
	v_add_u32_e32 v19, v16, v125
	v_cvt_pk_bf16_f32 v13, v14, v15
	global_store_dword v24, v13, s[12:13]
	s_nop 0
	v_cndmask_b32_e64 v14, v8, v10, s[6:7]
	s_nop 0
	v_add_lshl_u32 v24, v17, v124, 1
	v_mov_b32_dpp v15, v14 quad_perm:[1,0,3,2] row_mask:0xf bank_mask:0xf bound_ctrl:1
	v_cndmask_b32_e64 v14, v15, v8, s[6:7]
	v_cndmask_b32_e64 v15, v10, v15, s[6:7]
	s_waitcnt vmcnt(20)
	v_lshlrev_b32_e32 v8, 16, v194
	v_and_b32_e32 v13, 0xffff0000, v194
	v_mul_f32_e32 v8, 0xbfb8aa3b, v8
	v_mul_f32_e32 v13, 0xbfb8aa3b, v13
	v_exp_f32_e32 v20, v8
	v_exp_f32_e32 v21, v13
	s_waitcnt vmcnt(20)
	v_lshlrev_b32_e32 v22, 16, v195
	v_and_b32_e32 v23, 0xffff0000, v195
	v_pk_add_f32 v[20:21], v[20:21], 1.0 op_sel_hi:[1,0]
	s_nop 0
	v_div_scale_f32 v8, s[0:1], v21, v21, 1.0
	v_div_scale_f32 v13, s[0:1], v20, v20, 1.0
	v_rcp_f32_e32 v25, v8
	v_rcp_f32_e32 v26, v13
	v_div_scale_f32 v10, vcc, 1.0, v21, 1.0
	v_fma_f32 v28, -v8, v25, 1.0
	v_fma_f32 v29, -v13, v26, 1.0
	v_fmac_f32_e32 v25, v28, v25
	v_div_scale_f32 v27, s[0:1], 1.0, v20, 1.0
	v_fmac_f32_e32 v26, v29, v26
	v_mul_f32_e32 v28, v10, v25
	v_mul_f32_e32 v29, v27, v26
	v_fma_f32 v30, -v8, v28, v10
	v_fma_f32 v31, -v13, v29, v27
	v_fmac_f32_e32 v28, v30, v25
	v_fmac_f32_e32 v29, v31, v26
	v_fma_f32 v8, -v8, v28, v10
	v_fma_f32 v10, -v13, v29, v27
	v_div_fmas_f32 v8, v8, v25, v28
	s_mov_b64 vcc, s[0:1]
	v_div_fixup_f32 v21, v8, v21, 1.0
	v_div_fmas_f32 v8, v10, v26, v29
	v_div_fixup_f32 v20, v8, v20, 1.0
	v_pk_fma_f32 v[14:15], v[14:15], v[20:21], v[22:23]
	v_add_u32_e32 v13, v12, v125
	v_cvt_pk_bf16_f32 v8, v14, v15
	global_store_dword v19, v8, s[12:13]
	s_nop 0
	v_cndmask_b32_e64 v8, v9, v11, s[6:7]
	s_nop 0
	v_add_lshl_u32 v21, v18, v120, 1
	v_mov_b32_dpp v20, v8 quad_perm:[1,0,3,2] row_mask:0xf bank_mask:0xf bound_ctrl:1
	v_cndmask_b32_e64 v8, v20, v9, s[6:7]
	s_waitcnt vmcnt(19)
	v_lshlrev_b32_e32 v9, 16, v196
	v_and_b32_e32 v10, 0xffff0000, v196
	v_mul_f32_e32 v9, 0xbfb8aa3b, v9
	v_mul_f32_e32 v10, 0xbfb8aa3b, v10
	v_exp_f32_e32 v14, v9
	v_exp_f32_e32 v15, v10
	v_cndmask_b32_e64 v9, v11, v20, s[6:7]
	s_waitcnt vmcnt(19)
	v_lshlrev_b32_e32 v10, 16, v197
	v_and_b32_e32 v11, 0xffff0000, v197
	v_pk_add_f32 v[14:15], v[14:15], 1.0 op_sel_hi:[1,0]
	s_nop 0
	v_div_scale_f32 v19, s[0:1], v15, v15, 1.0
	v_div_scale_f32 v22, s[0:1], v14, v14, 1.0
	v_rcp_f32_e32 v23, v19
	v_rcp_f32_e32 v24, v22
	v_div_scale_f32 v20, vcc, 1.0, v15, 1.0
	v_fma_f32 v26, -v19, v23, 1.0
	v_fma_f32 v27, -v22, v24, 1.0
	v_fmac_f32_e32 v23, v26, v23
	v_div_scale_f32 v25, s[0:1], 1.0, v14, 1.0
	v_fmac_f32_e32 v24, v27, v24
	v_mul_f32_e32 v26, v20, v23
	v_mul_f32_e32 v27, v25, v24
	v_fma_f32 v28, -v19, v26, v20
	v_fma_f32 v29, -v22, v27, v25
	v_fmac_f32_e32 v26, v28, v23
	v_fmac_f32_e32 v27, v29, v24
	v_fma_f32 v19, -v19, v26, v20
	v_fma_f32 v20, -v22, v27, v25
	v_div_fmas_f32 v19, v19, v23, v26
	s_mov_b64 vcc, s[0:1]
	v_div_fixup_f32 v15, v19, v15, 1.0
	v_div_fmas_f32 v19, v20, v24, v27
	v_div_fixup_f32 v14, v19, v14, 1.0
	v_pk_fma_f32 v[8:9], v[8:9], v[14:15], v[10:11]
	v_add_lshl_u32 v19, v17, v120, 1
	v_cvt_pk_bf16_f32 v8, v8, v9
	global_store_dword v13, v8, s[12:13]
	s_nop 0
	v_add_u32_e32 v13, v16, v121
	s_nop 0
	v_cndmask_b32_e64 v8, v4, v6, s[6:7]
	s_nop 1
	v_mov_b32_dpp v14, v8 quad_perm:[1,0,3,2] row_mask:0xf bank_mask:0xf bound_ctrl:1
	v_cndmask_b32_e64 v8, v14, v4, s[6:7]
	s_waitcnt vmcnt(18)
	v_lshlrev_b32_e32 v4, 16, v198
	v_and_b32_e32 v9, 0xffff0000, v198
	v_mul_f32_e32 v4, 0xbfb8aa3b, v4
	v_mul_f32_e32 v9, 0xbfb8aa3b, v9
	v_exp_f32_e32 v10, v4
	v_exp_f32_e32 v11, v9
	v_cndmask_b32_e64 v9, v6, v14, s[6:7]
	s_waitcnt vmcnt(18)
; DEVINL float bflo(unsigned u) { return __uint_as_float(u << 16); }
; DEVINL float bfhi(unsigned u) { return __uint_as_float(u & 0xffff0000u); }
; DEVINL float sigm(float x) { return 1.f / (1.f + __expf(-x)); }
; template <int EPI, bool GATHER>
; DEVINL void gemm_tile(const Params& p, const u16* __restrict__ A, int lda, const int* __restrict__ rowidx,
;                       const u16* __restrict__ Bt, int ldb, int K, int brow, int bcol, int orow, int ocol) {
;     ...
;             } else if (EPI == EPI_MERGED) {
;               const unsigned g2 = *(const unsigned*)(ws + O_COLS + (row * (unsigned)NCP + (unsigned)(C_GR + colp + cc)) * 2u);
;               const unsigned m1 = *(const unsigned*)(ws + O_M1 + (row * 2048u + (unsigned)(colp + cc)) * 2u);
;               *(unsigned*)(ws + O_MERGED + (row * 2048u + (unsigned)(colp + cc)) * 2u) =
;                   pk2(bflo(m1) + sigm(bflo(g2)) * lo[k], bfhi(m1) + sigm(bfhi(g2)) * hi[k]);
	v_lshlrev_b32_e32 v14, 16, v199
	v_and_b32_e32 v15, 0xffff0000, v199
	v_pk_add_f32 v[10:11], v[10:11], 1.0 op_sel_hi:[1,0]
	s_nop 0
	v_div_scale_f32 v4, s[0:1], v11, v11, 1.0
	v_div_scale_f32 v20, s[0:1], v10, v10, 1.0
	v_rcp_f32_e32 v21, v4
	v_rcp_f32_e32 v22, v20
	v_div_scale_f32 v6, vcc, 1.0, v11, 1.0
	v_fma_f32 v24, -v4, v21, 1.0
	v_fma_f32 v25, -v20, v22, 1.0
	v_fmac_f32_e32 v21, v24, v21
	v_div_scale_f32 v23, s[0:1], 1.0, v10, 1.0
	v_fmac_f32_e32 v22, v25, v22
	v_mul_f32_e32 v24, v6, v21
	v_mul_f32_e32 v25, v23, v22
	v_fma_f32 v26, -v4, v24, v6
	v_fma_f32 v27, -v20, v25, v23
	v_fmac_f32_e32 v24, v26, v21
	v_fmac_f32_e32 v25, v27, v22
	v_fma_f32 v4, -v4, v24, v6
	v_fma_f32 v6, -v20, v25, v23
	v_div_fmas_f32 v4, v4, v21, v24
	s_mov_b64 vcc, s[0:1]
	v_div_fixup_f32 v11, v4, v11, 1.0
	v_div_fmas_f32 v4, v6, v22, v25
	v_div_fixup_f32 v10, v4, v10, 1.0
	v_pk_fma_f32 v[8:9], v[8:9], v[10:11], v[14:15]
	v_add_u32_e32 v10, v12, v121
	v_cvt_pk_bf16_f32 v4, v8, v9
	global_store_dword v13, v4, s[12:13]
	s_nop 0
	s_nop 0
	v_cndmask_b32_e64 v4, v5, v7, s[6:7]
	v_add_lshl_u32 v14, v18, v116, 1
	s_nop 0
	v_mov_b32_dpp v13, v4 quad_perm:[1,0,3,2] row_mask:0xf bank_mask:0xf bound_ctrl:1
	v_cndmask_b32_e64 v4, v13, v5, s[6:7]
	s_waitcnt vmcnt(17)
	v_lshlrev_b32_e32 v5, 16, v200
	v_and_b32_e32 v6, 0xffff0000, v200
	v_mul_f32_e32 v5, 0xbfb8aa3b, v5
	v_mul_f32_e32 v6, 0xbfb8aa3b, v6
	v_exp_f32_e32 v8, v5
	v_exp_f32_e32 v9, v6
	v_cndmask_b32_e64 v5, v7, v13, s[6:7]
	s_waitcnt vmcnt(17)
	v_lshlrev_b32_e32 v6, 16, v201
	v_and_b32_e32 v7, 0xffff0000, v201
	v_pk_add_f32 v[8:9], v[8:9], 1.0 op_sel_hi:[1,0]
	s_nop 0
	v_div_scale_f32 v11, s[0:1], v9, v9, 1.0
	v_div_scale_f32 v15, s[0:1], v8, v8, 1.0
	v_rcp_f32_e32 v18, v11
	v_rcp_f32_e32 v19, v15
	v_div_scale_f32 v13, vcc, 1.0, v9, 1.0
	v_fma_f32 v21, -v11, v18, 1.0
	v_fma_f32 v22, -v15, v19, 1.0
	v_fmac_f32_e32 v18, v21, v18
	v_div_scale_f32 v20, s[0:1], 1.0, v8, 1.0
	v_fmac_f32_e32 v19, v22, v19
	v_mul_f32_e32 v21, v13, v18
	v_mul_f32_e32 v22, v20, v19
	v_fma_f32 v23, -v11, v21, v13
	v_fma_f32 v24, -v15, v22, v20
	v_fmac_f32_e32 v21, v23, v18
	v_fmac_f32_e32 v22, v24, v19
	v_fma_f32 v11, -v11, v21, v13
	v_fma_f32 v13, -v15, v22, v20
	v_div_fmas_f32 v11, v11, v18, v21
	s_mov_b64 vcc, s[0:1]
	v_div_fixup_f32 v9, v11, v9, 1.0
	v_div_fmas_f32 v11, v13, v19, v22
	v_div_fixup_f32 v8, v11, v8, 1.0
	v_pk_fma_f32 v[4:5], v[4:5], v[8:9], v[6:7]
	v_add_lshl_u32 v11, v17, v116, 1
	v_cvt_pk_bf16_f32 v4, v4, v5
	global_store_dword v10, v4, s[12:13]
	s_nop 0
	v_add_u32_e32 v10, v16, v117
	s_nop 0
	v_cndmask_b32_e64 v4, v0, v2, s[6:7]
	s_nop 1
	v_mov_b32_dpp v8, v4 quad_perm:[1,0,3,2] row_mask:0xf bank_mask:0xf bound_ctrl:1
	v_cndmask_b32_e64 v4, v8, v0, s[6:7]
	s_waitcnt vmcnt(16)
	v_lshlrev_b32_e32 v0, 16, v202
	v_and_b32_e32 v5, 0xffff0000, v202
	v_mul_f32_e32 v0, 0xbfb8aa3b, v0
	v_mul_f32_e32 v5, 0xbfb8aa3b, v5
	v_exp_f32_e32 v6, v0
	v_exp_f32_e32 v7, v5
	v_cndmask_b32_e64 v5, v2, v8, s[6:7]
	s_waitcnt vmcnt(16)
	v_lshlrev_b32_e32 v8, 16, v203
	v_and_b32_e32 v9, 0xffff0000, v203
	v_pk_add_f32 v[6:7], v[6:7], 1.0 op_sel_hi:[1,0]
	s_nop 0
	v_div_scale_f32 v0, s[0:1], v7, v7, 1.0
	v_div_scale_f32 v13, s[0:1], v6, v6, 1.0
	v_rcp_f32_e32 v14, v0
	v_rcp_f32_e32 v15, v13
	v_div_scale_f32 v2, vcc, 1.0, v7, 1.0
	v_fma_f32 v17, -v0, v14, 1.0
	v_fma_f32 v18, -v13, v15, 1.0
	v_fmac_f32_e32 v14, v17, v14
	v_div_scale_f32 v16, s[0:1], 1.0, v6, 1.0
	v_fmac_f32_e32 v15, v18, v15
	v_mul_f32_e32 v17, v2, v14
	v_mul_f32_e32 v18, v16, v15
	v_fma_f32 v19, -v0, v17, v2
	v_fma_f32 v20, -v13, v18, v16
	v_fmac_f32_e32 v17, v19, v14
	v_fmac_f32_e32 v18, v20, v15
	v_fma_f32 v0, -v0, v17, v2
	v_fma_f32 v2, -v13, v18, v16
	v_div_fmas_f32 v0, v0, v14, v17
	s_mov_b64 vcc, s[0:1]
	v_div_fixup_f32 v7, v0, v7, 1.0
	v_div_fmas_f32 v0, v2, v15, v18
	v_div_fixup_f32 v6, v0, v6, 1.0
	v_pk_fma_f32 v[4:5], v[4:5], v[6:7], v[8:9]
	v_add_u32_e32 v6, v12, v117
	v_cvt_pk_bf16_f32 v0, v4, v5
	global_store_dword v10, v0, s[12:13]
	s_nop 0
	s_nop 0
	v_cndmask_b32_e64 v0, v1, v3, s[6:7]
	s_nop 1
	v_mov_b32_dpp v8, v0 quad_perm:[1,0,3,2] row_mask:0xf bank_mask:0xf bound_ctrl:1
	v_cndmask_b32_e64 v0, v8, v1, s[6:7]
	s_waitcnt vmcnt(15)
	v_lshlrev_b32_e32 v1, 16, v204
	v_and_b32_e32 v2, 0xffff0000, v204
	v_mul_f32_e32 v1, 0xbfb8aa3b, v1
	v_mul_f32_e32 v2, 0xbfb8aa3b, v2
	v_exp_f32_e32 v4, v1
	v_exp_f32_e32 v5, v2
	v_cndmask_b32_e64 v1, v3, v8, s[6:7]
	s_waitcnt vmcnt(15)
	v_lshlrev_b32_e32 v2, 16, v205
	v_and_b32_e32 v3, 0xffff0000, v205
	v_pk_add_f32 v[4:5], v[4:5], 1.0 op_sel_hi:[1,0]
	s_nop 0
	v_div_scale_f32 v7, s[0:1], v5, v5, 1.0
	v_div_scale_f32 v9, s[0:1], v4, v4, 1.0
	v_rcp_f32_e32 v10, v7
	v_rcp_f32_e32 v11, v9
	v_div_scale_f32 v8, vcc, 1.0, v5, 1.0
	v_fma_f32 v13, -v7, v10, 1.0
	v_fma_f32 v14, -v9, v11, 1.0
	v_fmac_f32_e32 v10, v13, v10
	v_div_scale_f32 v12, s[0:1], 1.0, v4, 1.0
	v_fmac_f32_e32 v11, v14, v11
	v_mul_f32_e32 v13, v8, v10
	v_mul_f32_e32 v14, v12, v11
	v_fma_f32 v15, -v7, v13, v8
	v_fma_f32 v16, -v9, v14, v12
	v_fmac_f32_e32 v13, v15, v10
	v_fmac_f32_e32 v14, v16, v11
	v_fma_f32 v7, -v7, v13, v8
	v_fma_f32 v8, -v9, v14, v12
	v_div_fmas_f32 v7, v7, v10, v13
	s_mov_b64 vcc, s[0:1]
	v_div_fixup_f32 v5, v7, v5, 1.0
	v_div_fmas_f32 v7, v8, v11, v14
	v_div_fixup_f32 v4, v7, v4, 1.0
	v_pk_fma_f32 v[0:1], v[0:1], v[4:5], v[2:3]
	s_nop 0
	v_cvt_pk_bf16_f32 v0, v0, v1
	global_store_dword v6, v0, s[12:13]
	s_add_i32 s55, s55, s94
	s_add_i32 s3, s3, s40
	s_add_i32 s53, s53, s60
	s_cmpk_lt_i32 s55, 0x100
	s_barrier
	s_cbranch_scc0 .LBB0_624

; template <int EPI, bool GATHER>
; DEVINL void gemm_tile(const Params& p, const u16* __restrict__ A, int lda, const int* __restrict__ rowidx,
;                       const u16* __restrict__ Bt, int ldb, int K, int brow, int bcol, int orow, int ocol) {
;     ...
;     for (int m = 0; m < 4; ++m) {
;       const int rA = row0 + ai * HALF + m * 16 + (odd ? 2 : 0);
;       float gate[2] = {0.f, 0.f};
;       if (EPI == EPI_MOE2) { gate[0] = ((const float*)(ws + O_SELG))[rA]; gate[1] = ((const float*)(ws + O_SELG))[rA + 1]; }
; #pragma unroll
;       for (int bj = 0; bj < (EPI == EPI_HID ? 1 : 2); ++bj)
; #pragma unroll
;         for (int n = 0; n < 2; ++n) {
;           const int cc = bj * HALF + n * 16;
;           f32x4 v = acc[ai][bj][m][n];
;           if (EPI == EPI_HID) {
; #pragma unroll
;             for (int j = 0; j < 4; ++j) { const float a1 = acc[ai][0][m][n][j], a3 = acc[ai][1][m][n][j]; v[j] = a1 * sigm(a1) * a3; }
;           }
;           float lo[2], hi[2];
;           xchg_pairs(v, odd, lo, hi);
; #pragma unroll
;           for (int k = 0; k < 2; ++k) {
;             const unsigned row = (unsigned)(rA + k);
;             if (EPI == EPI_HID) {
;               *(unsigned*)(ws + O_HID + (row * 1024u + (unsigned)(colp + cc)) * 2u) = pk2(lo[k], hi[k]);
;             } else if (EPI == EPI_COLS) {
;               *(unsigned*)(ws + O_COLS + (row * (unsigned)NCP + (unsigned)(colp + cc)) * 2u) = pk2(lo[k], hi[k]);
;             } else if (EPI == EPI_MOE2) {
;               *(unsigned*)(ws + O_EO + (row * 2048u + (unsigned)(colp + cc)) * 2u) = pk2(gate[k] * lo[k], gate[k] * hi[k]);
;             } else if (EPI == EPI_M1) {
;               const unsigned g2 = *(const unsigned*)(ws + O_COLS + (row * (unsigned)NCP + (unsigned)(C_GG + colp + cc)) * 2u);
;               *(unsigned*)(ws + O_M1 + (row * 2048u + (unsigned)(colp + cc)) * 2u) = pk2(sigm(bflo(g2)) * lo[k], sigm(bfhi(g2)) * hi[k]);
;             } else if (EPI == EPI_MERGED) {
;               const unsigned g2 = *(const unsigned*)(ws + O_COLS + (row * (unsigned)NCP + (unsigned)(C_GR + colp + cc)) * 2u);
;               const unsigned m1 = *(const unsigned*)(ws + O_M1 + (row * 2048u + (unsigned)(colp + cc)) * 2u);
;               *(unsigned*)(ws + O_MERGED + (row * 2048u + (unsigned)(colp + cc)) * 2u) =
;                   pk2(bflo(m1) + sigm(bflo(g2)) * lo[k], bfhi(m1) + sigm(bfhi(g2)) * hi[k]);
.LBB0_678:
	s_or_b64 exec, exec, s[24:25]
	v_and_b32_e32 v135, 1, v141
	v_or_b32_e32 v136, s22, v144
	v_sub_u32_e32 v137, v136, v135
	v_lshlrev_b32_e32 v136, 15, v143
	v_lshlrev_b32_e32 v138, 14, v135
	v_add_lshl_u32 v139, v145, s43, 13
	v_or3_b32 v136, v139, v138, v136
	v_lshlrev_b32_e32 v138, 7, v142
	v_lshl_add_u32 v137, v137, 2, v138
	v_add_u32_e32 v170, v136, v137
	global_load_dwordx2 v[146:147], v170, s[76:77]
	v_or_b32_e32 v135, 0x2000, v136
	v_add_u32_e32 v171, v135, v137
	global_load_dwordx2 v[148:149], v171, s[76:77]
	v_add_u32_e32 v172, 64, v137
	v_add_u32_e32 v170, v136, v172
	global_load_dwordx2 v[150:151], v170, s[76:77]
	v_add_u32_e32 v173, v135, v172
	global_load_dwordx2 v[152:153], v173, s[76:77]
	v_add_u32_e32 v174, 0x200, v137
	v_add_u32_e32 v138, v136, v174
	global_load_dwordx2 v[154:155], v138, s[76:77]
	v_add_u32_e32 v175, v135, v174
	global_load_dwordx2 v[156:157], v175, s[76:77]
	v_add_u32_e32 v176, 0x240, v137
	v_add_u32_e32 v173, v136, v176
	global_load_dwordx2 v[158:159], v173, s[76:77]
	v_add_u32_e32 v177, v135, v176
	global_load_dwordx2 v[160:161], v177, s[76:77]
	v_and_b32_e32 v135, 1, v141
	v_or_b32_e32 v136, s22, v144
	v_sub_u32_e32 v137, v136, v135
	v_lshlrev_b32_e32 v136, 15, v143
	v_lshlrev_b32_e32 v138, 14, v135
	v_add_lshl_u32 v139, v145, s43, 13
	v_or3_b32 v136, v139, v138, v136
	v_lshlrev_b32_e32 v138, 7, v142
	v_lshl_add_u32 v137, v137, 2, v138
	v_add_u32_e32 v170, 64, v137
	v_add_u32_e32 v171, 0x200, v137
	v_add_u32_e32 v172, 0x240, v137
	v_or_b32_e32 v173, 0x20000, v136
	v_add_u32_e32 v174, v173, v137
	global_load_dwordx2 v[190:191], v174, s[76:77]
	v_or_b32_e32 v175, 0x22000, v136
	v_add_u32_e32 v176, v175, v137
	global_load_dwordx2 v[192:193], v176, s[76:77]
	v_add_u32_e32 v177, v173, v170
	global_load_dwordx2 v[194:195], v177, s[76:77]
	v_add_u32_e32 v178, v175, v170
	global_load_dwordx2 v[196:197], v178, s[76:77]
	v_add_u32_e32 v179, v173, v171
	global_load_dwordx2 v[198:199], v179, s[76:77]
	v_add_u32_e32 v180, v175, v171
	global_load_dwordx2 v[200:201], v180, s[76:77]
	v_add_u32_e32 v181, v173, v172
	global_load_dwordx2 v[202:203], v181, s[76:77]
	v_add_u32_e32 v182, v175, v172
	global_load_dwordx2 v[204:205], v182, s[76:77]
	v_and_b32_e32 v132, 1, v141
	v_or_b32_e32 v128, s22, v144
	v_sub_u32_e32 v129, v128, v132
	v_lshlrev_b32_e32 v128, 15, v143
	v_lshlrev_b32_e32 v130, 14, v132
	v_add_lshl_u32 v131, v145, s43, 13
	v_or3_b32 v128, v131, v130, v128
	v_lshlrev_b32_e32 v130, 7, v142
	v_lshl_add_u32 v129, v129, 2, v130
	v_add_u32_e32 v133, v128, v129
	s_nop 0
	v_cmp_eq_u32_e32 vcc, 0, v132
	v_lshrrev_b32_e32 v133, 1, v133
	s_nop 0
	v_cndmask_b32_e32 v132, v124, v126, vcc
	s_nop 1
	v_mov_b32_dpp v132, v132 quad_perm:[1,0,3,2] row_mask:0xf bank_mask:0xf bound_ctrl:1
	v_cndmask_b32_e32 v124, v132, v124, vcc
	v_cndmask_b32_e32 v126, v126, v132, vcc
	v_or_b32_e32 v132, 0x2000, v128
	v_add_u32_e32 v134, v132, v129
	s_waitcnt vmcnt(15)
	v_fmac_f32_e32 v124, 0x3f9837f0, v146
	v_fmac_f32_e32 v126, 0x3f9837f0, v147
	v_cvt_pk_bf16_f32 v124, v124, v126
	global_store_dword v133, v124, s[92:93]
	s_nop 0
	v_cndmask_b32_e32 v124, v125, v127, vcc
	s_nop 1
	v_mov_b32_dpp v126, v124 quad_perm:[1,0,3,2] row_mask:0xf bank_mask:0xf bound_ctrl:1
	v_cndmask_b32_e32 v125, v126, v125, vcc
	v_cndmask_b32_e32 v126, v127, v126, vcc
	v_add_u32_e32 v124, 64, v129
	v_lshrrev_b32_e32 v127, 1, v134
	v_add_u32_e32 v133, v128, v124
	s_waitcnt vmcnt(15)
	v_fmac_f32_e32 v125, 0x3f9837f0, v148
	v_fmac_f32_e32 v126, 0x3f9837f0, v149
	v_cvt_pk_bf16_f32 v125, v125, v126
	global_store_dword v127, v125, s[92:93]
	s_nop 0
	v_cndmask_b32_e32 v125, v120, v122, vcc
	v_lshrrev_b32_e32 v130, 1, v133
	s_nop 0
	v_mov_b32_dpp v125, v125 quad_perm:[1,0,3,2] row_mask:0xf bank_mask:0xf bound_ctrl:1
	v_cndmask_b32_e32 v120, v125, v120, vcc
	v_cndmask_b32_e32 v122, v122, v125, vcc
	v_add_u32_e32 v125, v132, v124
	s_waitcnt vmcnt(15)
	v_fmac_f32_e32 v120, 0x3f9837f0, v150
	v_fmac_f32_e32 v122, 0x3f9837f0, v151
	v_cvt_pk_bf16_f32 v120, v120, v122
	global_store_dword v130, v120, s[92:93]
	s_nop 0
	v_cndmask_b32_e32 v120, v121, v123, vcc
	s_nop 1
	v_mov_b32_dpp v122, v120 quad_perm:[1,0,3,2] row_mask:0xf bank_mask:0xf bound_ctrl:1
	v_cndmask_b32_e32 v121, v122, v121, vcc
	v_cndmask_b32_e32 v122, v123, v122, vcc
	v_add_u32_e32 v120, 0x200, v129
	v_lshrrev_b32_e32 v123, 1, v125
	v_add_u32_e32 v130, v128, v120
	v_lshrrev_b32_e32 v125, 1, v130
	s_waitcnt vmcnt(15)
	v_fmac_f32_e32 v121, 0x3f9837f0, v152
	v_fmac_f32_e32 v122, 0x3f9837f0, v153
	v_cvt_pk_bf16_f32 v121, v121, v122
	global_store_dword v123, v121, s[92:93]
	s_nop 0
	v_cndmask_b32_e32 v121, v116, v118, vcc
	s_nop 1
	v_mov_b32_dpp v121, v121 quad_perm:[1,0,3,2] row_mask:0xf bank_mask:0xf bound_ctrl:1
	v_cndmask_b32_e32 v116, v121, v116, vcc
	v_cndmask_b32_e32 v118, v118, v121, vcc
	v_add_u32_e32 v121, v132, v120
	s_waitcnt vmcnt(15)
	v_fmac_f32_e32 v116, 0x3f9837f0, v154
	v_fmac_f32_e32 v118, 0x3f9837f0, v155
	v_cvt_pk_bf16_f32 v116, v116, v118
	global_store_dword v125, v116, s[92:93]
	s_nop 0
	v_cndmask_b32_e32 v116, v117, v119, vcc
	s_nop 1
	v_mov_b32_dpp v118, v116 quad_perm:[1,0,3,2] row_mask:0xf bank_mask:0xf bound_ctrl:1
	v_cndmask_b32_e32 v117, v118, v117, vcc
	v_cndmask_b32_e32 v118, v119, v118, vcc
	v_add_u32_e32 v116, 0x240, v129
	v_lshrrev_b32_e32 v119, 1, v121
	v_add_u32_e32 v125, v128, v116
	v_lshrrev_b32_e32 v121, 1, v125
	s_waitcnt vmcnt(15)
	v_fmac_f32_e32 v117, 0x3f9837f0, v156
	v_fmac_f32_e32 v118, 0x3f9837f0, v157
	v_cvt_pk_bf16_f32 v117, v117, v118
	global_store_dword v119, v117, s[92:93]
	s_nop 0
	v_cndmask_b32_e32 v117, v112, v114, vcc
	s_nop 1
	v_mov_b32_dpp v117, v117 quad_perm:[1,0,3,2] row_mask:0xf bank_mask:0xf bound_ctrl:1
	v_cndmask_b32_e32 v112, v117, v112, vcc
	v_cndmask_b32_e32 v114, v114, v117, vcc
	v_add_u32_e32 v117, v132, v116
	s_waitcnt vmcnt(15)
; template <int EPI, bool GATHER>
; DEVINL void gemm_tile(const Params& p, const u16* __restrict__ A, int lda, const int* __restrict__ rowidx,
;                       const u16* __restrict__ Bt, int ldb, int K, int brow, int bcol, int orow, int ocol) {
;     ...
;     for (int m = 0; m < 4; ++m) {
;       const int rA = row0 + ai * HALF + m * 16 + (odd ? 2 : 0);
;       float gate[2] = {0.f, 0.f};
;       if (EPI == EPI_MOE2) { gate[0] = ((const float*)(ws + O_SELG))[rA]; gate[1] = ((const float*)(ws + O_SELG))[rA + 1]; }
; #pragma unroll
;       for (int bj = 0; bj < (EPI == EPI_HID ? 1 : 2); ++bj)
; #pragma unroll
;         for (int n = 0; n < 2; ++n) {
;           const int cc = bj * HALF + n * 16;
;           f32x4 v = acc[ai][bj][m][n];
;           if (EPI == EPI_HID) {
; #pragma unroll
;             for (int j = 0; j < 4; ++j) { const float a1 = acc[ai][0][m][n][j], a3 = acc[ai][1][m][n][j]; v[j] = a1 * sigm(a1) * a3; }
;           }
;           float lo[2], hi[2];
;           xchg_pairs(v, odd, lo, hi);
; #pragma unroll
;           for (int k = 0; k < 2; ++k) {
;             const unsigned row = (unsigned)(rA + k);
;             if (EPI == EPI_HID) {
;               *(unsigned*)(ws + O_HID + (row * 1024u + (unsigned)(colp + cc)) * 2u) = pk2(lo[k], hi[k]);
;             } else if (EPI == EPI_COLS) {
;               *(unsigned*)(ws + O_COLS + (row * (unsigned)NCP + (unsigned)(colp + cc)) * 2u) = pk2(lo[k], hi[k]);
;             } else if (EPI == EPI_MOE2) {
;               *(unsigned*)(ws + O_EO + (row * 2048u + (unsigned)(colp + cc)) * 2u) = pk2(gate[k] * lo[k], gate[k] * hi[k]);
;             } else if (EPI == EPI_M1) {
;               const unsigned g2 = *(const unsigned*)(ws + O_COLS + (row * (unsigned)NCP + (unsigned)(C_GG + colp + cc)) * 2u);
;               *(unsigned*)(ws + O_M1 + (row * 2048u + (unsigned)(colp + cc)) * 2u) = pk2(sigm(bflo(g2)) * lo[k], sigm(bfhi(g2)) * hi[k]);
;             } else if (EPI == EPI_MERGED) {
;               const unsigned g2 = *(const unsigned*)(ws + O_COLS + (row * (unsigned)NCP + (unsigned)(C_GR + colp + cc)) * 2u);
;               const unsigned m1 = *(const unsigned*)(ws + O_M1 + (row * 2048u + (unsigned)(colp + cc)) * 2u);
;               *(unsigned*)(ws + O_MERGED + (row * 2048u + (unsigned)(colp + cc)) * 2u) =
;                   pk2(bflo(m1) + sigm(bflo(g2)) * lo[k], bfhi(m1) + sigm(bfhi(g2)) * hi[k]);
	v_fmac_f32_e32 v112, 0x3f9837f0, v158
	v_fmac_f32_e32 v114, 0x3f9837f0, v159
	v_cvt_pk_bf16_f32 v112, v112, v114
	global_store_dword v121, v112, s[92:93]
	s_nop 0
	v_cndmask_b32_e32 v112, v113, v115, vcc
	s_nop 1
	v_mov_b32_dpp v112, v112 quad_perm:[1,0,3,2] row_mask:0xf bank_mask:0xf bound_ctrl:1
	v_cndmask_b32_e32 v113, v112, v113, vcc
	v_cndmask_b32_e32 v112, v115, v112, vcc
	s_waitcnt vmcnt(15)
	v_fmac_f32_e32 v113, 0x3f9837f0, v160
	v_fmac_f32_e32 v112, 0x3f9837f0, v161
	v_cvt_pk_bf16_f32 v112, v113, v112
	v_lshrrev_b32_e32 v113, 1, v117
	global_store_dword v113, v112, s[92:93]
	v_or_b32_e32 v135, 0x40000, v128
	v_add_u32_e32 v136, v135, v129
	global_load_dwordx2 v[146:147], v136, s[76:77]
	v_or_b32_e32 v137, 0x42000, v128
	v_add_u32_e32 v138, v137, v129
	global_load_dwordx2 v[148:149], v138, s[76:77]
	v_add_u32_e32 v139, v135, v124
	global_load_dwordx2 v[150:151], v139, s[76:77]
	v_add_u32_e32 v170, v137, v124
	global_load_dwordx2 v[152:153], v170, s[76:77]
	v_add_u32_e32 v171, v135, v120
	global_load_dwordx2 v[154:155], v171, s[76:77]
	v_add_u32_e32 v172, v137, v120
	global_load_dwordx2 v[156:157], v172, s[76:77]
	v_add_u32_e32 v173, v135, v116
	global_load_dwordx2 v[158:159], v173, s[76:77]
	v_add_u32_e32 v174, v137, v116
	global_load_dwordx2 v[160:161], v174, s[76:77]
	v_or_b32_e32 v114, 0x20000, v128
	v_add_u32_e32 v115, v114, v129
	s_nop 0
	v_cndmask_b32_e32 v117, v108, v110, vcc
	v_or_b32_e32 v118, 0x22000, v128
	v_lshrrev_b32_e32 v115, 1, v115
	v_mov_b32_dpp v117, v117 quad_perm:[1,0,3,2] row_mask:0xf bank_mask:0xf bound_ctrl:1
	v_cndmask_b32_e32 v108, v117, v108, vcc
	v_cndmask_b32_e32 v110, v110, v117, vcc
	v_add_u32_e32 v119, v118, v129
	s_waitcnt vmcnt(23)
	v_fmac_f32_e32 v108, 0x3f9837f0, v190
	v_fmac_f32_e32 v110, 0x3f9837f0, v191
	v_cvt_pk_bf16_f32 v108, v108, v110
	global_store_dword v115, v108, s[92:93]
	s_nop 0
	v_cndmask_b32_e32 v108, v109, v111, vcc
	v_add_u32_e32 v110, v114, v124
	s_nop 0
	v_mov_b32_dpp v108, v108 quad_perm:[1,0,3,2] row_mask:0xf bank_mask:0xf bound_ctrl:1
	v_cndmask_b32_e32 v109, v108, v109, vcc
	v_cndmask_b32_e32 v108, v111, v108, vcc
	v_lshrrev_b32_e32 v111, 1, v119
	s_waitcnt vmcnt(23)
	v_fmac_f32_e32 v109, 0x3f9837f0, v192
	v_fmac_f32_e32 v108, 0x3f9837f0, v193
	v_cvt_pk_bf16_f32 v108, v109, v108
	global_store_dword v111, v108, s[92:93]
	s_nop 0
	v_cndmask_b32_e32 v111, v104, v106, vcc
	v_lshrrev_b32_e32 v110, 1, v110
	v_add_u32_e32 v112, v118, v124
	v_mov_b32_dpp v111, v111 quad_perm:[1,0,3,2] row_mask:0xf bank_mask:0xf bound_ctrl:1
	v_cndmask_b32_e32 v104, v111, v104, vcc
	v_cndmask_b32_e32 v106, v106, v111, vcc
	s_waitcnt vmcnt(23)
	v_fmac_f32_e32 v104, 0x3f9837f0, v194
	v_fmac_f32_e32 v106, 0x3f9837f0, v195
	v_cvt_pk_bf16_f32 v104, v104, v106
	global_store_dword v110, v104, s[92:93]
	s_nop 0
	v_cndmask_b32_e32 v104, v105, v107, vcc
	v_add_u32_e32 v106, v114, v120
	s_nop 0
	v_mov_b32_dpp v104, v104 quad_perm:[1,0,3,2] row_mask:0xf bank_mask:0xf bound_ctrl:1
	v_cndmask_b32_e32 v105, v104, v105, vcc
	v_cndmask_b32_e32 v104, v107, v104, vcc
	v_lshrrev_b32_e32 v107, 1, v112
	s_waitcnt vmcnt(23)
	v_fmac_f32_e32 v105, 0x3f9837f0, v196
	v_fmac_f32_e32 v104, 0x3f9837f0, v197
	v_cvt_pk_bf16_f32 v104, v105, v104
	global_store_dword v107, v104, s[92:93]
	s_nop 0
	v_cndmask_b32_e32 v107, v100, v102, vcc
	v_lshrrev_b32_e32 v106, 1, v106
	v_add_u32_e32 v108, v118, v120
	v_mov_b32_dpp v107, v107 quad_perm:[1,0,3,2] row_mask:0xf bank_mask:0xf bound_ctrl:1
	v_cndmask_b32_e32 v100, v107, v100, vcc
	v_cndmask_b32_e32 v102, v102, v107, vcc
	s_waitcnt vmcnt(23)
	v_fmac_f32_e32 v100, 0x3f9837f0, v198
	v_fmac_f32_e32 v102, 0x3f9837f0, v199
	v_cvt_pk_bf16_f32 v100, v100, v102
	global_store_dword v106, v100, s[92:93]
	s_nop 0
	v_cndmask_b32_e32 v100, v101, v103, vcc
	v_add_u32_e32 v102, v114, v116
	s_nop 0
	v_mov_b32_dpp v100, v100 quad_perm:[1,0,3,2] row_mask:0xf bank_mask:0xf bound_ctrl:1
	v_cndmask_b32_e32 v101, v100, v101, vcc
	v_cndmask_b32_e32 v100, v103, v100, vcc
	v_lshrrev_b32_e32 v103, 1, v108
	s_waitcnt vmcnt(23)
	v_fmac_f32_e32 v101, 0x3f9837f0, v200
	v_fmac_f32_e32 v100, 0x3f9837f0, v201
	v_cvt_pk_bf16_f32 v100, v101, v100
	global_store_dword v103, v100, s[92:93]
	s_nop 0
	v_cndmask_b32_e32 v103, v96, v98, vcc
	v_lshrrev_b32_e32 v102, 1, v102
	v_add_u32_e32 v104, v118, v116
	v_mov_b32_dpp v103, v103 quad_perm:[1,0,3,2] row_mask:0xf bank_mask:0xf bound_ctrl:1
	v_cndmask_b32_e32 v96, v103, v96, vcc
	v_cndmask_b32_e32 v98, v98, v103, vcc
	s_waitcnt vmcnt(23)
	v_fmac_f32_e32 v96, 0x3f9837f0, v202
	v_fmac_f32_e32 v98, 0x3f9837f0, v203
	v_cvt_pk_bf16_f32 v96, v96, v98
	global_store_dword v102, v96, s[92:93]
	s_nop 0
	v_cndmask_b32_e32 v96, v97, v99, vcc
	s_nop 1
	v_mov_b32_dpp v96, v96 quad_perm:[1,0,3,2] row_mask:0xf bank_mask:0xf bound_ctrl:1
	v_cndmask_b32_e32 v97, v96, v97, vcc
	v_cndmask_b32_e32 v96, v99, v96, vcc
	s_waitcnt vmcnt(23)
	v_fmac_f32_e32 v97, 0x3f9837f0, v204
	v_fmac_f32_e32 v96, 0x3f9837f0, v205
	v_cvt_pk_bf16_f32 v96, v97, v96
	v_lshrrev_b32_e32 v97, 1, v104
	global_store_dword v97, v96, s[92:93]
	v_or_b32_e32 v135, 0x60000, v128
	v_add_u32_e32 v136, v135, v129
	global_load_dwordx2 v[190:191], v136, s[76:77]
	v_or_b32_e32 v137, 0x62000, v128
	v_add_u32_e32 v138, v137, v129
	global_load_dwordx2 v[192:193], v138, s[76:77]
	v_add_u32_e32 v139, v135, v124
	global_load_dwordx2 v[194:195], v139, s[76:77]
	v_add_u32_e32 v170, v137, v124
	global_load_dwordx2 v[196:197], v170, s[76:77]
	v_add_u32_e32 v171, v135, v120
	global_load_dwordx2 v[198:199], v171, s[76:77]
	v_add_u32_e32 v172, v137, v120
	global_load_dwordx2 v[200:201], v172, s[76:77]
	v_add_u32_e32 v173, v135, v116
	global_load_dwordx2 v[202:203], v173, s[76:77]
	v_add_u32_e32 v174, v137, v116
	global_load_dwordx2 v[204:205], v174, s[76:77]
	v_or_b32_e32 v98, 0x40000, v128
	v_add_u32_e32 v99, v98, v129
	s_nop 0
	v_cndmask_b32_e32 v100, v92, v94, vcc
	v_or_b32_e32 v101, 0x42000, v128
	v_lshrrev_b32_e32 v99, 1, v99
	v_mov_b32_dpp v100, v100 quad_perm:[1,0,3,2] row_mask:0xf bank_mask:0xf bound_ctrl:1
	v_cndmask_b32_e32 v92, v100, v92, vcc
	v_cndmask_b32_e32 v94, v94, v100, vcc
	v_add_u32_e32 v102, v101, v129
	s_waitcnt vmcnt(23)
; template <int EPI, bool GATHER>
; DEVINL void gemm_tile(const Params& p, const u16* __restrict__ A, int lda, const int* __restrict__ rowidx,
;                       const u16* __restrict__ Bt, int ldb, int K, int brow, int bcol, int orow, int ocol) {
;     ...
;     for (int m = 0; m < 4; ++m) {
;       const int rA = row0 + ai * HALF + m * 16 + (odd ? 2 : 0);
;       float gate[2] = {0.f, 0.f};
;       if (EPI == EPI_MOE2) { gate[0] = ((const float*)(ws + O_SELG))[rA]; gate[1] = ((const float*)(ws + O_SELG))[rA + 1]; }
; #pragma unroll
;       for (int bj = 0; bj < (EPI == EPI_HID ? 1 : 2); ++bj)
; #pragma unroll
;         for (int n = 0; n < 2; ++n) {
;           const int cc = bj * HALF + n * 16;
;           f32x4 v = acc[ai][bj][m][n];
;           if (EPI == EPI_HID) {
; #pragma unroll
;             for (int j = 0; j < 4; ++j) { const float a1 = acc[ai][0][m][n][j], a3 = acc[ai][1][m][n][j]; v[j] = a1 * sigm(a1) * a3; }
;           }
;           float lo[2], hi[2];
;           xchg_pairs(v, odd, lo, hi);
; #pragma unroll
;           for (int k = 0; k < 2; ++k) {
;             const unsigned row = (unsigned)(rA + k);
;             if (EPI == EPI_HID) {
;               *(unsigned*)(ws + O_HID + (row * 1024u + (unsigned)(colp + cc)) * 2u) = pk2(lo[k], hi[k]);
;             } else if (EPI == EPI_COLS) {
;               *(unsigned*)(ws + O_COLS + (row * (unsigned)NCP + (unsigned)(colp + cc)) * 2u) = pk2(lo[k], hi[k]);
;             } else if (EPI == EPI_MOE2) {
;               *(unsigned*)(ws + O_EO + (row * 2048u + (unsigned)(colp + cc)) * 2u) = pk2(gate[k] * lo[k], gate[k] * hi[k]);
;             } else if (EPI == EPI_M1) {
;               const unsigned g2 = *(const unsigned*)(ws + O_COLS + (row * (unsigned)NCP + (unsigned)(C_GG + colp + cc)) * 2u);
;               *(unsigned*)(ws + O_M1 + (row * 2048u + (unsigned)(colp + cc)) * 2u) = pk2(sigm(bflo(g2)) * lo[k], sigm(bfhi(g2)) * hi[k]);
;             } else if (EPI == EPI_MERGED) {
;               const unsigned g2 = *(const unsigned*)(ws + O_COLS + (row * (unsigned)NCP + (unsigned)(C_GR + colp + cc)) * 2u);
;               const unsigned m1 = *(const unsigned*)(ws + O_M1 + (row * 2048u + (unsigned)(colp + cc)) * 2u);
;               *(unsigned*)(ws + O_MERGED + (row * 2048u + (unsigned)(colp + cc)) * 2u) =
;                   pk2(bflo(m1) + sigm(bflo(g2)) * lo[k], bfhi(m1) + sigm(bfhi(g2)) * hi[k]);
	v_fmac_f32_e32 v92, 0x3f9837f0, v146
	v_fmac_f32_e32 v94, 0x3f9837f0, v147
	v_cvt_pk_bf16_f32 v92, v92, v94
	global_store_dword v99, v92, s[92:93]
	s_nop 0
	v_cndmask_b32_e32 v92, v93, v95, vcc
	v_add_u32_e32 v94, v98, v124
	s_nop 0
	v_mov_b32_dpp v92, v92 quad_perm:[1,0,3,2] row_mask:0xf bank_mask:0xf bound_ctrl:1
	v_cndmask_b32_e32 v93, v92, v93, vcc
	v_cndmask_b32_e32 v92, v95, v92, vcc
	v_lshrrev_b32_e32 v95, 1, v102
	s_waitcnt vmcnt(23)
	v_fmac_f32_e32 v93, 0x3f9837f0, v148
	v_fmac_f32_e32 v92, 0x3f9837f0, v149
	v_cvt_pk_bf16_f32 v92, v93, v92
	global_store_dword v95, v92, s[92:93]
	s_nop 0
	v_cndmask_b32_e32 v95, v88, v90, vcc
	v_lshrrev_b32_e32 v94, 1, v94
	v_add_u32_e32 v96, v101, v124
	v_mov_b32_dpp v95, v95 quad_perm:[1,0,3,2] row_mask:0xf bank_mask:0xf bound_ctrl:1
	v_cndmask_b32_e32 v88, v95, v88, vcc
	v_cndmask_b32_e32 v90, v90, v95, vcc
	s_waitcnt vmcnt(23)
	v_fmac_f32_e32 v88, 0x3f9837f0, v150
	v_fmac_f32_e32 v90, 0x3f9837f0, v151
	v_cvt_pk_bf16_f32 v88, v88, v90
	global_store_dword v94, v88, s[92:93]
	s_nop 0
	v_cndmask_b32_e32 v88, v89, v91, vcc
	v_add_u32_e32 v90, v98, v120
	s_nop 0
	v_mov_b32_dpp v88, v88 quad_perm:[1,0,3,2] row_mask:0xf bank_mask:0xf bound_ctrl:1
	v_cndmask_b32_e32 v89, v88, v89, vcc
	v_cndmask_b32_e32 v88, v91, v88, vcc
	v_lshrrev_b32_e32 v91, 1, v96
	s_waitcnt vmcnt(23)
	v_fmac_f32_e32 v89, 0x3f9837f0, v152
	v_fmac_f32_e32 v88, 0x3f9837f0, v153
	v_cvt_pk_bf16_f32 v88, v89, v88
	global_store_dword v91, v88, s[92:93]
	s_nop 0
	v_cndmask_b32_e32 v91, v84, v86, vcc
	v_lshrrev_b32_e32 v90, 1, v90
	v_add_u32_e32 v92, v101, v120
	v_mov_b32_dpp v91, v91 quad_perm:[1,0,3,2] row_mask:0xf bank_mask:0xf bound_ctrl:1
	v_cndmask_b32_e32 v84, v91, v84, vcc
	v_cndmask_b32_e32 v86, v86, v91, vcc
	s_waitcnt vmcnt(23)
	v_fmac_f32_e32 v84, 0x3f9837f0, v154
	v_fmac_f32_e32 v86, 0x3f9837f0, v155
	v_cvt_pk_bf16_f32 v84, v84, v86
	global_store_dword v90, v84, s[92:93]
	s_nop 0
	v_cndmask_b32_e32 v84, v85, v87, vcc
	v_add_u32_e32 v86, v98, v116
	s_nop 0
	v_mov_b32_dpp v84, v84 quad_perm:[1,0,3,2] row_mask:0xf bank_mask:0xf bound_ctrl:1
	v_cndmask_b32_e32 v85, v84, v85, vcc
	v_cndmask_b32_e32 v84, v87, v84, vcc
	v_lshrrev_b32_e32 v87, 1, v92
	s_waitcnt vmcnt(23)
	v_fmac_f32_e32 v85, 0x3f9837f0, v156
	v_fmac_f32_e32 v84, 0x3f9837f0, v157
	v_cvt_pk_bf16_f32 v84, v85, v84
	global_store_dword v87, v84, s[92:93]
	s_nop 0
	v_cndmask_b32_e32 v87, v80, v82, vcc
	v_lshrrev_b32_e32 v86, 1, v86
	v_add_u32_e32 v88, v101, v116
	v_mov_b32_dpp v87, v87 quad_perm:[1,0,3,2] row_mask:0xf bank_mask:0xf bound_ctrl:1
	v_cndmask_b32_e32 v80, v87, v80, vcc
	v_cndmask_b32_e32 v82, v82, v87, vcc
	s_waitcnt vmcnt(23)
	v_fmac_f32_e32 v80, 0x3f9837f0, v158
	v_fmac_f32_e32 v82, 0x3f9837f0, v159
	v_cvt_pk_bf16_f32 v80, v80, v82
	global_store_dword v86, v80, s[92:93]
	s_nop 0
	v_cndmask_b32_e32 v80, v81, v83, vcc
	s_nop 1
	v_mov_b32_dpp v80, v80 quad_perm:[1,0,3,2] row_mask:0xf bank_mask:0xf bound_ctrl:1
	v_cndmask_b32_e32 v81, v80, v81, vcc
	v_cndmask_b32_e32 v80, v83, v80, vcc
	s_waitcnt vmcnt(23)
	v_fmac_f32_e32 v81, 0x3f9837f0, v160
	v_fmac_f32_e32 v80, 0x3f9837f0, v161
	v_cvt_pk_bf16_f32 v80, v81, v80
	v_lshrrev_b32_e32 v81, 1, v88
	global_store_dword v81, v80, s[92:93]
	v_add_u32_e32 v135, 0x100000, v128
	v_add_u32_e32 v136, v135, v129
	global_load_dwordx2 v[146:147], v136, s[76:77]
	v_add_u32_e32 v137, 0x102000, v128
	v_add_u32_e32 v138, v137, v129
	global_load_dwordx2 v[148:149], v138, s[76:77]
	v_add_u32_e32 v139, v135, v124
	global_load_dwordx2 v[150:151], v139, s[76:77]
	v_add_u32_e32 v170, v137, v124
	global_load_dwordx2 v[152:153], v170, s[76:77]
	v_add_u32_e32 v171, v135, v120
	global_load_dwordx2 v[154:155], v171, s[76:77]
	v_add_u32_e32 v172, v137, v120
	global_load_dwordx2 v[156:157], v172, s[76:77]
	v_add_u32_e32 v173, v135, v116
	global_load_dwordx2 v[158:159], v173, s[76:77]
	v_add_u32_e32 v174, v137, v116
	global_load_dwordx2 v[160:161], v174, s[76:77]
	v_or_b32_e32 v82, 0x60000, v128
	v_add_u32_e32 v83, v82, v129
	s_nop 0
	v_cndmask_b32_e32 v84, v76, v78, vcc
	v_or_b32_e32 v85, 0x62000, v128
	v_lshrrev_b32_e32 v83, 1, v83
	v_mov_b32_dpp v84, v84 quad_perm:[1,0,3,2] row_mask:0xf bank_mask:0xf bound_ctrl:1
	v_cndmask_b32_e32 v76, v84, v76, vcc
	v_cndmask_b32_e32 v78, v78, v84, vcc
	v_add_u32_e32 v86, v85, v129
	s_waitcnt vmcnt(23)
	v_fmac_f32_e32 v76, 0x3f9837f0, v190
	v_fmac_f32_e32 v78, 0x3f9837f0, v191
	v_cvt_pk_bf16_f32 v76, v76, v78
	global_store_dword v83, v76, s[92:93]
	s_nop 0
	v_cndmask_b32_e32 v76, v77, v79, vcc
	v_add_u32_e32 v78, v82, v124
	s_nop 0
	v_mov_b32_dpp v76, v76 quad_perm:[1,0,3,2] row_mask:0xf bank_mask:0xf bound_ctrl:1
	v_cndmask_b32_e32 v77, v76, v77, vcc
	v_cndmask_b32_e32 v76, v79, v76, vcc
	v_lshrrev_b32_e32 v79, 1, v86
	s_waitcnt vmcnt(23)
	v_fmac_f32_e32 v77, 0x3f9837f0, v192
	v_fmac_f32_e32 v76, 0x3f9837f0, v193
	v_cvt_pk_bf16_f32 v76, v77, v76
	global_store_dword v79, v76, s[92:93]
	s_nop 0
	v_cndmask_b32_e32 v79, v72, v74, vcc
	v_lshrrev_b32_e32 v78, 1, v78
	v_add_u32_e32 v80, v85, v124
	v_mov_b32_dpp v79, v79 quad_perm:[1,0,3,2] row_mask:0xf bank_mask:0xf bound_ctrl:1
	v_cndmask_b32_e32 v72, v79, v72, vcc
	v_cndmask_b32_e32 v74, v74, v79, vcc
	s_waitcnt vmcnt(23)
	v_fmac_f32_e32 v72, 0x3f9837f0, v194
	v_fmac_f32_e32 v74, 0x3f9837f0, v195
	v_cvt_pk_bf16_f32 v72, v72, v74
	global_store_dword v78, v72, s[92:93]
	s_nop 0
	v_cndmask_b32_e32 v72, v73, v75, vcc
	v_add_u32_e32 v74, v82, v120
	s_nop 0
	v_mov_b32_dpp v72, v72 quad_perm:[1,0,3,2] row_mask:0xf bank_mask:0xf bound_ctrl:1
	v_cndmask_b32_e32 v73, v72, v73, vcc
	v_cndmask_b32_e32 v72, v75, v72, vcc
	v_lshrrev_b32_e32 v75, 1, v80
	s_waitcnt vmcnt(23)
; template <int EPI, bool GATHER>
; DEVINL void gemm_tile(const Params& p, const u16* __restrict__ A, int lda, const int* __restrict__ rowidx,
;                       const u16* __restrict__ Bt, int ldb, int K, int brow, int bcol, int orow, int ocol) {
;     ...
;     for (int m = 0; m < 4; ++m) {
;       const int rA = row0 + ai * HALF + m * 16 + (odd ? 2 : 0);
;       float gate[2] = {0.f, 0.f};
;       if (EPI == EPI_MOE2) { gate[0] = ((const float*)(ws + O_SELG))[rA]; gate[1] = ((const float*)(ws + O_SELG))[rA + 1]; }
; #pragma unroll
;       for (int bj = 0; bj < (EPI == EPI_HID ? 1 : 2); ++bj)
; #pragma unroll
;         for (int n = 0; n < 2; ++n) {
;           const int cc = bj * HALF + n * 16;
;           f32x4 v = acc[ai][bj][m][n];
;           if (EPI == EPI_HID) {
; #pragma unroll
;             for (int j = 0; j < 4; ++j) { const float a1 = acc[ai][0][m][n][j], a3 = acc[ai][1][m][n][j]; v[j] = a1 * sigm(a1) * a3; }
;           }
;           float lo[2], hi[2];
;           xchg_pairs(v, odd, lo, hi);
; #pragma unroll
;           for (int k = 0; k < 2; ++k) {
;             const unsigned row = (unsigned)(rA + k);
;             if (EPI == EPI_HID) {
;               *(unsigned*)(ws + O_HID + (row * 1024u + (unsigned)(colp + cc)) * 2u) = pk2(lo[k], hi[k]);
;             } else if (EPI == EPI_COLS) {
;               *(unsigned*)(ws + O_COLS + (row * (unsigned)NCP + (unsigned)(colp + cc)) * 2u) = pk2(lo[k], hi[k]);
;             } else if (EPI == EPI_MOE2) {
;               *(unsigned*)(ws + O_EO + (row * 2048u + (unsigned)(colp + cc)) * 2u) = pk2(gate[k] * lo[k], gate[k] * hi[k]);
;             } else if (EPI == EPI_M1) {
;               const unsigned g2 = *(const unsigned*)(ws + O_COLS + (row * (unsigned)NCP + (unsigned)(C_GG + colp + cc)) * 2u);
;               *(unsigned*)(ws + O_M1 + (row * 2048u + (unsigned)(colp + cc)) * 2u) = pk2(sigm(bflo(g2)) * lo[k], sigm(bfhi(g2)) * hi[k]);
;             } else if (EPI == EPI_MERGED) {
;               const unsigned g2 = *(const unsigned*)(ws + O_COLS + (row * (unsigned)NCP + (unsigned)(C_GR + colp + cc)) * 2u);
;               const unsigned m1 = *(const unsigned*)(ws + O_M1 + (row * 2048u + (unsigned)(colp + cc)) * 2u);
;               *(unsigned*)(ws + O_MERGED + (row * 2048u + (unsigned)(colp + cc)) * 2u) =
;                   pk2(bflo(m1) + sigm(bflo(g2)) * lo[k], bfhi(m1) + sigm(bfhi(g2)) * hi[k]);
	v_fmac_f32_e32 v73, 0x3f9837f0, v196
	v_fmac_f32_e32 v72, 0x3f9837f0, v197
	v_cvt_pk_bf16_f32 v72, v73, v72
	global_store_dword v75, v72, s[92:93]
	s_nop 0
	v_cndmask_b32_e32 v75, v68, v70, vcc
	v_lshrrev_b32_e32 v74, 1, v74
	v_add_u32_e32 v76, v85, v120
	v_mov_b32_dpp v75, v75 quad_perm:[1,0,3,2] row_mask:0xf bank_mask:0xf bound_ctrl:1
	v_cndmask_b32_e32 v68, v75, v68, vcc
	v_cndmask_b32_e32 v70, v70, v75, vcc
	s_waitcnt vmcnt(23)
	v_fmac_f32_e32 v68, 0x3f9837f0, v198
	v_fmac_f32_e32 v70, 0x3f9837f0, v199
	v_cvt_pk_bf16_f32 v68, v68, v70
	global_store_dword v74, v68, s[92:93]
	s_nop 0
	v_cndmask_b32_e32 v68, v69, v71, vcc
	v_add_u32_e32 v70, v82, v116
	s_nop 0
	v_mov_b32_dpp v68, v68 quad_perm:[1,0,3,2] row_mask:0xf bank_mask:0xf bound_ctrl:1
	v_cndmask_b32_e32 v69, v68, v69, vcc
	v_cndmask_b32_e32 v68, v71, v68, vcc
	v_lshrrev_b32_e32 v71, 1, v76
	s_waitcnt vmcnt(23)
	v_fmac_f32_e32 v69, 0x3f9837f0, v200
	v_fmac_f32_e32 v68, 0x3f9837f0, v201
	v_cvt_pk_bf16_f32 v68, v69, v68
	global_store_dword v71, v68, s[92:93]
	s_nop 0
	v_cndmask_b32_e32 v71, v64, v66, vcc
	v_lshrrev_b32_e32 v70, 1, v70
	v_add_u32_e32 v72, v85, v116
	v_mov_b32_dpp v71, v71 quad_perm:[1,0,3,2] row_mask:0xf bank_mask:0xf bound_ctrl:1
	v_cndmask_b32_e32 v64, v71, v64, vcc
	v_cndmask_b32_e32 v66, v66, v71, vcc
	s_waitcnt vmcnt(23)
	v_fmac_f32_e32 v64, 0x3f9837f0, v202
	v_fmac_f32_e32 v66, 0x3f9837f0, v203
	v_cvt_pk_bf16_f32 v64, v64, v66
	global_store_dword v70, v64, s[92:93]
	s_nop 0
	v_cndmask_b32_e32 v64, v65, v67, vcc
	s_nop 1
	v_mov_b32_dpp v64, v64 quad_perm:[1,0,3,2] row_mask:0xf bank_mask:0xf bound_ctrl:1
	v_cndmask_b32_e32 v65, v64, v65, vcc
	v_cndmask_b32_e32 v64, v67, v64, vcc
	s_waitcnt vmcnt(23)
	v_fmac_f32_e32 v65, 0x3f9837f0, v204
	v_fmac_f32_e32 v64, 0x3f9837f0, v205
	v_cvt_pk_bf16_f32 v64, v65, v64
	v_lshrrev_b32_e32 v65, 1, v72
	global_store_dword v65, v64, s[92:93]
	v_add_u32_e32 v135, 0x120000, v128
	v_add_u32_e32 v136, v135, v129
	global_load_dwordx2 v[190:191], v136, s[76:77]
	v_add_u32_e32 v137, 0x122000, v128
	v_add_u32_e32 v138, v137, v129
	global_load_dwordx2 v[192:193], v138, s[76:77]
	v_add_u32_e32 v139, v135, v124
	global_load_dwordx2 v[194:195], v139, s[76:77]
	v_add_u32_e32 v170, v137, v124
	global_load_dwordx2 v[196:197], v170, s[76:77]
	v_add_u32_e32 v171, v135, v120
	global_load_dwordx2 v[198:199], v171, s[76:77]
	v_add_u32_e32 v172, v137, v120
	global_load_dwordx2 v[200:201], v172, s[76:77]
	v_add_u32_e32 v173, v135, v116
	global_load_dwordx2 v[202:203], v173, s[76:77]
	v_add_u32_e32 v174, v137, v116
	global_load_dwordx2 v[204:205], v174, s[76:77]
	v_add_u32_e32 v66, 0x100000, v128
	v_add_u32_e32 v67, v66, v129
	s_nop 0
	v_cndmask_b32_e32 v68, v60, v62, vcc
	v_add_u32_e32 v69, 0x102000, v128
	v_lshrrev_b32_e32 v67, 1, v67
	v_mov_b32_dpp v68, v68 quad_perm:[1,0,3,2] row_mask:0xf bank_mask:0xf bound_ctrl:1
	v_cndmask_b32_e32 v60, v68, v60, vcc
	v_cndmask_b32_e32 v62, v62, v68, vcc
	v_add_u32_e32 v70, v69, v129
	s_waitcnt vmcnt(23)
	v_fmac_f32_e32 v60, 0x3f9837f0, v146
	v_fmac_f32_e32 v62, 0x3f9837f0, v147
	v_cvt_pk_bf16_f32 v60, v60, v62
	global_store_dword v67, v60, s[92:93]
	s_nop 0
	v_cndmask_b32_e32 v60, v61, v63, vcc
	v_add_u32_e32 v62, v66, v124
	s_nop 0
	v_mov_b32_dpp v60, v60 quad_perm:[1,0,3,2] row_mask:0xf bank_mask:0xf bound_ctrl:1
	v_cndmask_b32_e32 v61, v60, v61, vcc
	v_cndmask_b32_e32 v60, v63, v60, vcc
	v_lshrrev_b32_e32 v63, 1, v70
	s_waitcnt vmcnt(23)
	v_fmac_f32_e32 v61, 0x3f9837f0, v148
	v_fmac_f32_e32 v60, 0x3f9837f0, v149
	v_cvt_pk_bf16_f32 v60, v61, v60
	global_store_dword v63, v60, s[92:93]
	s_nop 0
	v_cndmask_b32_e32 v63, v56, v58, vcc
	v_lshrrev_b32_e32 v62, 1, v62
	v_add_u32_e32 v64, v69, v124
	v_mov_b32_dpp v63, v63 quad_perm:[1,0,3,2] row_mask:0xf bank_mask:0xf bound_ctrl:1
	v_cndmask_b32_e32 v56, v63, v56, vcc
	v_cndmask_b32_e32 v58, v58, v63, vcc
	s_waitcnt vmcnt(23)
	v_fmac_f32_e32 v56, 0x3f9837f0, v150
	v_fmac_f32_e32 v58, 0x3f9837f0, v151
	v_cvt_pk_bf16_f32 v56, v56, v58
	global_store_dword v62, v56, s[92:93]
	s_nop 0
	v_cndmask_b32_e32 v56, v57, v59, vcc
	v_add_u32_e32 v58, v66, v120
	s_nop 0
	v_mov_b32_dpp v56, v56 quad_perm:[1,0,3,2] row_mask:0xf bank_mask:0xf bound_ctrl:1
	v_cndmask_b32_e32 v57, v56, v57, vcc
	v_cndmask_b32_e32 v56, v59, v56, vcc
	v_lshrrev_b32_e32 v59, 1, v64
	s_waitcnt vmcnt(23)
	v_fmac_f32_e32 v57, 0x3f9837f0, v152
	v_fmac_f32_e32 v56, 0x3f9837f0, v153
	v_cvt_pk_bf16_f32 v56, v57, v56
	global_store_dword v59, v56, s[92:93]
	s_nop 0
	v_cndmask_b32_e32 v59, v52, v54, vcc
	v_lshrrev_b32_e32 v58, 1, v58
	v_add_u32_e32 v60, v69, v120
	v_mov_b32_dpp v59, v59 quad_perm:[1,0,3,2] row_mask:0xf bank_mask:0xf bound_ctrl:1
	v_cndmask_b32_e32 v52, v59, v52, vcc
	v_cndmask_b32_e32 v54, v54, v59, vcc
	s_waitcnt vmcnt(23)
	v_fmac_f32_e32 v52, 0x3f9837f0, v154
	v_fmac_f32_e32 v54, 0x3f9837f0, v155
	v_cvt_pk_bf16_f32 v52, v52, v54
	global_store_dword v58, v52, s[92:93]
	s_nop 0
	v_cndmask_b32_e32 v52, v53, v55, vcc
	v_add_u32_e32 v54, v66, v116
	s_nop 0
	v_mov_b32_dpp v52, v52 quad_perm:[1,0,3,2] row_mask:0xf bank_mask:0xf bound_ctrl:1
	v_cndmask_b32_e32 v53, v52, v53, vcc
	v_cndmask_b32_e32 v52, v55, v52, vcc
	v_lshrrev_b32_e32 v55, 1, v60
	s_waitcnt vmcnt(23)
	v_fmac_f32_e32 v53, 0x3f9837f0, v156
	v_fmac_f32_e32 v52, 0x3f9837f0, v157
	v_cvt_pk_bf16_f32 v52, v53, v52
	global_store_dword v55, v52, s[92:93]
	s_nop 0
	v_cndmask_b32_e32 v55, v48, v50, vcc
	v_lshrrev_b32_e32 v54, 1, v54
	v_add_u32_e32 v56, v69, v116
	v_mov_b32_dpp v55, v55 quad_perm:[1,0,3,2] row_mask:0xf bank_mask:0xf bound_ctrl:1
	v_cndmask_b32_e32 v48, v55, v48, vcc
	v_cndmask_b32_e32 v50, v50, v55, vcc
	s_waitcnt vmcnt(23)
; template <int EPI, bool GATHER>
; DEVINL void gemm_tile(const Params& p, const u16* __restrict__ A, int lda, const int* __restrict__ rowidx,
;                       const u16* __restrict__ Bt, int ldb, int K, int brow, int bcol, int orow, int ocol) {
;     ...
;     for (int m = 0; m < 4; ++m) {
;       const int rA = row0 + ai * HALF + m * 16 + (odd ? 2 : 0);
;       float gate[2] = {0.f, 0.f};
;       if (EPI == EPI_MOE2) { gate[0] = ((const float*)(ws + O_SELG))[rA]; gate[1] = ((const float*)(ws + O_SELG))[rA + 1]; }
; #pragma unroll
;       for (int bj = 0; bj < (EPI == EPI_HID ? 1 : 2); ++bj)
; #pragma unroll
;         for (int n = 0; n < 2; ++n) {
;           const int cc = bj * HALF + n * 16;
;           f32x4 v = acc[ai][bj][m][n];
;           if (EPI == EPI_HID) {
; #pragma unroll
;             for (int j = 0; j < 4; ++j) { const float a1 = acc[ai][0][m][n][j], a3 = acc[ai][1][m][n][j]; v[j] = a1 * sigm(a1) * a3; }
;           }
;           float lo[2], hi[2];
;           xchg_pairs(v, odd, lo, hi);
; #pragma unroll
;           for (int k = 0; k < 2; ++k) {
;             const unsigned row = (unsigned)(rA + k);
;             if (EPI == EPI_HID) {
;               *(unsigned*)(ws + O_HID + (row * 1024u + (unsigned)(colp + cc)) * 2u) = pk2(lo[k], hi[k]);
;             } else if (EPI == EPI_COLS) {
;               *(unsigned*)(ws + O_COLS + (row * (unsigned)NCP + (unsigned)(colp + cc)) * 2u) = pk2(lo[k], hi[k]);
;             } else if (EPI == EPI_MOE2) {
;               *(unsigned*)(ws + O_EO + (row * 2048u + (unsigned)(colp + cc)) * 2u) = pk2(gate[k] * lo[k], gate[k] * hi[k]);
;             } else if (EPI == EPI_M1) {
;               const unsigned g2 = *(const unsigned*)(ws + O_COLS + (row * (unsigned)NCP + (unsigned)(C_GG + colp + cc)) * 2u);
;               *(unsigned*)(ws + O_M1 + (row * 2048u + (unsigned)(colp + cc)) * 2u) = pk2(sigm(bflo(g2)) * lo[k], sigm(bfhi(g2)) * hi[k]);
;             } else if (EPI == EPI_MERGED) {
;               const unsigned g2 = *(const unsigned*)(ws + O_COLS + (row * (unsigned)NCP + (unsigned)(C_GR + colp + cc)) * 2u);
;               const unsigned m1 = *(const unsigned*)(ws + O_M1 + (row * 2048u + (unsigned)(colp + cc)) * 2u);
;               *(unsigned*)(ws + O_MERGED + (row * 2048u + (unsigned)(colp + cc)) * 2u) =
;                   pk2(bflo(m1) + sigm(bflo(g2)) * lo[k], bfhi(m1) + sigm(bfhi(g2)) * hi[k]);
	v_fmac_f32_e32 v48, 0x3f9837f0, v158
	v_fmac_f32_e32 v50, 0x3f9837f0, v159
	v_cvt_pk_bf16_f32 v48, v48, v50
	global_store_dword v54, v48, s[92:93]
	s_nop 0
	v_cndmask_b32_e32 v48, v49, v51, vcc
	s_nop 1
	v_mov_b32_dpp v48, v48 quad_perm:[1,0,3,2] row_mask:0xf bank_mask:0xf bound_ctrl:1
	v_cndmask_b32_e32 v49, v48, v49, vcc
	v_cndmask_b32_e32 v48, v51, v48, vcc
	s_waitcnt vmcnt(23)
	v_fmac_f32_e32 v49, 0x3f9837f0, v160
	v_fmac_f32_e32 v48, 0x3f9837f0, v161
	v_cvt_pk_bf16_f32 v48, v49, v48
	v_lshrrev_b32_e32 v49, 1, v56
	global_store_dword v49, v48, s[92:93]
	v_add_u32_e32 v135, 0x140000, v128
	v_add_u32_e32 v136, v135, v129
	global_load_dwordx2 v[146:147], v136, s[76:77]
	v_add_u32_e32 v137, 0x142000, v128
	v_add_u32_e32 v138, v137, v129
	global_load_dwordx2 v[148:149], v138, s[76:77]
	v_add_u32_e32 v139, v135, v124
	global_load_dwordx2 v[150:151], v139, s[76:77]
	v_add_u32_e32 v170, v137, v124
	global_load_dwordx2 v[152:153], v170, s[76:77]
	v_add_u32_e32 v171, v135, v120
	global_load_dwordx2 v[154:155], v171, s[76:77]
	v_add_u32_e32 v172, v137, v120
	global_load_dwordx2 v[156:157], v172, s[76:77]
	v_add_u32_e32 v173, v135, v116
	global_load_dwordx2 v[158:159], v173, s[76:77]
	v_add_u32_e32 v174, v137, v116
	global_load_dwordx2 v[160:161], v174, s[76:77]
	v_add_u32_e32 v50, 0x120000, v128
	v_add_u32_e32 v51, v50, v129
	s_nop 0
	v_cndmask_b32_e32 v52, v44, v46, vcc
	v_add_u32_e32 v53, 0x122000, v128
	v_lshrrev_b32_e32 v51, 1, v51
	v_mov_b32_dpp v52, v52 quad_perm:[1,0,3,2] row_mask:0xf bank_mask:0xf bound_ctrl:1
	v_cndmask_b32_e32 v44, v52, v44, vcc
	v_cndmask_b32_e32 v46, v46, v52, vcc
	v_add_u32_e32 v54, v53, v129
	s_waitcnt vmcnt(23)
	v_fmac_f32_e32 v44, 0x3f9837f0, v190
	v_fmac_f32_e32 v46, 0x3f9837f0, v191
	v_cvt_pk_bf16_f32 v44, v44, v46
	global_store_dword v51, v44, s[92:93]
	s_nop 0
	v_cndmask_b32_e32 v44, v45, v47, vcc
	v_add_u32_e32 v46, v50, v124
	s_nop 0
	v_mov_b32_dpp v44, v44 quad_perm:[1,0,3,2] row_mask:0xf bank_mask:0xf bound_ctrl:1
	v_cndmask_b32_e32 v45, v44, v45, vcc
	v_cndmask_b32_e32 v44, v47, v44, vcc
	v_lshrrev_b32_e32 v47, 1, v54
	s_waitcnt vmcnt(23)
	v_fmac_f32_e32 v45, 0x3f9837f0, v192
	v_fmac_f32_e32 v44, 0x3f9837f0, v193
	v_cvt_pk_bf16_f32 v44, v45, v44
	global_store_dword v47, v44, s[92:93]
	s_nop 0
	v_cndmask_b32_e32 v47, v40, v42, vcc
	v_lshrrev_b32_e32 v46, 1, v46
	v_add_u32_e32 v48, v53, v124
	v_mov_b32_dpp v47, v47 quad_perm:[1,0,3,2] row_mask:0xf bank_mask:0xf bound_ctrl:1
	v_cndmask_b32_e32 v40, v47, v40, vcc
	v_cndmask_b32_e32 v42, v42, v47, vcc
	s_waitcnt vmcnt(23)
	v_fmac_f32_e32 v40, 0x3f9837f0, v194
	v_fmac_f32_e32 v42, 0x3f9837f0, v195
	v_cvt_pk_bf16_f32 v40, v40, v42
	global_store_dword v46, v40, s[92:93]
	s_nop 0
	v_cndmask_b32_e32 v40, v41, v43, vcc
	v_add_u32_e32 v42, v50, v120
	s_nop 0
	v_mov_b32_dpp v40, v40 quad_perm:[1,0,3,2] row_mask:0xf bank_mask:0xf bound_ctrl:1
	v_cndmask_b32_e32 v41, v40, v41, vcc
	v_cndmask_b32_e32 v40, v43, v40, vcc
	v_lshrrev_b32_e32 v43, 1, v48
	s_waitcnt vmcnt(23)
	v_fmac_f32_e32 v41, 0x3f9837f0, v196
	v_fmac_f32_e32 v40, 0x3f9837f0, v197
	v_cvt_pk_bf16_f32 v40, v41, v40
	global_store_dword v43, v40, s[92:93]
	s_nop 0
	v_cndmask_b32_e32 v43, v36, v38, vcc
	v_lshrrev_b32_e32 v42, 1, v42
	v_add_u32_e32 v44, v53, v120
	v_mov_b32_dpp v43, v43 quad_perm:[1,0,3,2] row_mask:0xf bank_mask:0xf bound_ctrl:1
	v_cndmask_b32_e32 v36, v43, v36, vcc
	v_cndmask_b32_e32 v38, v38, v43, vcc
	s_waitcnt vmcnt(23)
	v_fmac_f32_e32 v36, 0x3f9837f0, v198
	v_fmac_f32_e32 v38, 0x3f9837f0, v199
	v_cvt_pk_bf16_f32 v36, v36, v38
	global_store_dword v42, v36, s[92:93]
	s_nop 0
	v_cndmask_b32_e32 v36, v37, v39, vcc
	v_add_u32_e32 v38, v50, v116
	s_nop 0
	v_mov_b32_dpp v36, v36 quad_perm:[1,0,3,2] row_mask:0xf bank_mask:0xf bound_ctrl:1
	v_cndmask_b32_e32 v37, v36, v37, vcc
	v_cndmask_b32_e32 v36, v39, v36, vcc
	v_lshrrev_b32_e32 v39, 1, v44
	s_waitcnt vmcnt(23)
	v_fmac_f32_e32 v37, 0x3f9837f0, v200
	v_fmac_f32_e32 v36, 0x3f9837f0, v201
	v_cvt_pk_bf16_f32 v36, v37, v36
	global_store_dword v39, v36, s[92:93]
	s_nop 0
	v_cndmask_b32_e32 v39, v32, v34, vcc
	v_lshrrev_b32_e32 v38, 1, v38
	v_add_u32_e32 v40, v53, v116
	v_mov_b32_dpp v39, v39 quad_perm:[1,0,3,2] row_mask:0xf bank_mask:0xf bound_ctrl:1
	v_cndmask_b32_e32 v32, v39, v32, vcc
	v_cndmask_b32_e32 v34, v34, v39, vcc
	s_waitcnt vmcnt(23)
	v_fmac_f32_e32 v32, 0x3f9837f0, v202
	v_fmac_f32_e32 v34, 0x3f9837f0, v203
	v_cvt_pk_bf16_f32 v32, v32, v34
	global_store_dword v38, v32, s[92:93]
	s_nop 0
	v_cndmask_b32_e32 v32, v33, v35, vcc
	s_nop 1
	v_mov_b32_dpp v32, v32 quad_perm:[1,0,3,2] row_mask:0xf bank_mask:0xf bound_ctrl:1
	v_cndmask_b32_e32 v33, v32, v33, vcc
	v_cndmask_b32_e32 v32, v35, v32, vcc
	s_waitcnt vmcnt(23)
	v_fmac_f32_e32 v33, 0x3f9837f0, v204
	v_fmac_f32_e32 v32, 0x3f9837f0, v205
	v_cvt_pk_bf16_f32 v32, v33, v32
	v_lshrrev_b32_e32 v33, 1, v40
	global_store_dword v33, v32, s[92:93]
	v_add_u32_e32 v135, 0x160000, v128
	v_add_u32_e32 v136, v135, v129
	global_load_dwordx2 v[190:191], v136, s[76:77]
	v_add_u32_e32 v137, 0x162000, v128
	v_add_u32_e32 v138, v137, v129
	global_load_dwordx2 v[192:193], v138, s[76:77]
	v_add_u32_e32 v139, v135, v124
	global_load_dwordx2 v[194:195], v139, s[76:77]
	v_add_u32_e32 v170, v137, v124
	global_load_dwordx2 v[196:197], v170, s[76:77]
	v_add_u32_e32 v171, v135, v120
	global_load_dwordx2 v[198:199], v171, s[76:77]
	v_add_u32_e32 v172, v137, v120
	global_load_dwordx2 v[200:201], v172, s[76:77]
	v_add_u32_e32 v173, v135, v116
	global_load_dwordx2 v[202:203], v173, s[76:77]
	v_add_u32_e32 v174, v137, v116
	global_load_dwordx2 v[204:205], v174, s[76:77]
	v_add_u32_e32 v34, 0x140000, v128
	v_add_u32_e32 v35, v34, v129
	s_nop 0
	v_cndmask_b32_e32 v36, v28, v30, vcc
	v_add_u32_e32 v37, 0x142000, v128
	v_lshrrev_b32_e32 v35, 1, v35
	v_mov_b32_dpp v36, v36 quad_perm:[1,0,3,2] row_mask:0xf bank_mask:0xf bound_ctrl:1
	v_cndmask_b32_e32 v28, v36, v28, vcc
	v_cndmask_b32_e32 v30, v30, v36, vcc
	v_add_u32_e32 v38, v37, v129
	s_waitcnt vmcnt(23)
; template <int EPI, bool GATHER>
; DEVINL void gemm_tile(const Params& p, const u16* __restrict__ A, int lda, const int* __restrict__ rowidx,
;                       const u16* __restrict__ Bt, int ldb, int K, int brow, int bcol, int orow, int ocol) {
;     ...
;     for (int m = 0; m < 4; ++m) {
;       const int rA = row0 + ai * HALF + m * 16 + (odd ? 2 : 0);
;       float gate[2] = {0.f, 0.f};
;       if (EPI == EPI_MOE2) { gate[0] = ((const float*)(ws + O_SELG))[rA]; gate[1] = ((const float*)(ws + O_SELG))[rA + 1]; }
; #pragma unroll
;       for (int bj = 0; bj < (EPI == EPI_HID ? 1 : 2); ++bj)
; #pragma unroll
;         for (int n = 0; n < 2; ++n) {
;           const int cc = bj * HALF + n * 16;
;           f32x4 v = acc[ai][bj][m][n];
;           if (EPI == EPI_HID) {
; #pragma unroll
;             for (int j = 0; j < 4; ++j) { const float a1 = acc[ai][0][m][n][j], a3 = acc[ai][1][m][n][j]; v[j] = a1 * sigm(a1) * a3; }
;           }
;           float lo[2], hi[2];
;           xchg_pairs(v, odd, lo, hi);
; #pragma unroll
;           for (int k = 0; k < 2; ++k) {
;             const unsigned row = (unsigned)(rA + k);
;             if (EPI == EPI_HID) {
;               *(unsigned*)(ws + O_HID + (row * 1024u + (unsigned)(colp + cc)) * 2u) = pk2(lo[k], hi[k]);
;             } else if (EPI == EPI_COLS) {
;               *(unsigned*)(ws + O_COLS + (row * (unsigned)NCP + (unsigned)(colp + cc)) * 2u) = pk2(lo[k], hi[k]);
;             } else if (EPI == EPI_MOE2) {
;               *(unsigned*)(ws + O_EO + (row * 2048u + (unsigned)(colp + cc)) * 2u) = pk2(gate[k] * lo[k], gate[k] * hi[k]);
;             } else if (EPI == EPI_M1) {
;               const unsigned g2 = *(const unsigned*)(ws + O_COLS + (row * (unsigned)NCP + (unsigned)(C_GG + colp + cc)) * 2u);
;               *(unsigned*)(ws + O_M1 + (row * 2048u + (unsigned)(colp + cc)) * 2u) = pk2(sigm(bflo(g2)) * lo[k], sigm(bfhi(g2)) * hi[k]);
;             } else if (EPI == EPI_MERGED) {
;               const unsigned g2 = *(const unsigned*)(ws + O_COLS + (row * (unsigned)NCP + (unsigned)(C_GR + colp + cc)) * 2u);
;               const unsigned m1 = *(const unsigned*)(ws + O_M1 + (row * 2048u + (unsigned)(colp + cc)) * 2u);
;               *(unsigned*)(ws + O_MERGED + (row * 2048u + (unsigned)(colp + cc)) * 2u) =
;                   pk2(bflo(m1) + sigm(bflo(g2)) * lo[k], bfhi(m1) + sigm(bfhi(g2)) * hi[k]);
	v_fmac_f32_e32 v28, 0x3f9837f0, v146
	v_fmac_f32_e32 v30, 0x3f9837f0, v147
	v_cvt_pk_bf16_f32 v28, v28, v30
	global_store_dword v35, v28, s[92:93]
	s_nop 0
	v_cndmask_b32_e32 v28, v29, v31, vcc
	v_add_u32_e32 v30, v34, v124
	s_nop 0
	v_mov_b32_dpp v28, v28 quad_perm:[1,0,3,2] row_mask:0xf bank_mask:0xf bound_ctrl:1
	v_cndmask_b32_e32 v29, v28, v29, vcc
	v_cndmask_b32_e32 v28, v31, v28, vcc
	v_lshrrev_b32_e32 v31, 1, v38
	s_waitcnt vmcnt(23)
	v_fmac_f32_e32 v29, 0x3f9837f0, v148
	v_fmac_f32_e32 v28, 0x3f9837f0, v149
	v_cvt_pk_bf16_f32 v28, v29, v28
	global_store_dword v31, v28, s[92:93]
	s_nop 0
	v_cndmask_b32_e32 v31, v24, v26, vcc
	v_lshrrev_b32_e32 v30, 1, v30
	v_add_u32_e32 v32, v37, v124
	v_mov_b32_dpp v31, v31 quad_perm:[1,0,3,2] row_mask:0xf bank_mask:0xf bound_ctrl:1
	v_cndmask_b32_e32 v24, v31, v24, vcc
	v_cndmask_b32_e32 v26, v26, v31, vcc
	s_waitcnt vmcnt(23)
	v_fmac_f32_e32 v24, 0x3f9837f0, v150
	v_fmac_f32_e32 v26, 0x3f9837f0, v151
	v_cvt_pk_bf16_f32 v24, v24, v26
	global_store_dword v30, v24, s[92:93]
	s_nop 0
	v_cndmask_b32_e32 v24, v25, v27, vcc
	v_add_u32_e32 v26, v34, v120
	s_nop 0
	v_mov_b32_dpp v24, v24 quad_perm:[1,0,3,2] row_mask:0xf bank_mask:0xf bound_ctrl:1
	v_cndmask_b32_e32 v25, v24, v25, vcc
	v_cndmask_b32_e32 v24, v27, v24, vcc
	v_lshrrev_b32_e32 v27, 1, v32
	s_waitcnt vmcnt(23)
	v_fmac_f32_e32 v25, 0x3f9837f0, v152
	v_fmac_f32_e32 v24, 0x3f9837f0, v153
	v_cvt_pk_bf16_f32 v24, v25, v24
	global_store_dword v27, v24, s[92:93]
	s_nop 0
	v_cndmask_b32_e32 v27, v20, v22, vcc
	v_lshrrev_b32_e32 v26, 1, v26
	v_add_u32_e32 v28, v37, v120
	v_mov_b32_dpp v27, v27 quad_perm:[1,0,3,2] row_mask:0xf bank_mask:0xf bound_ctrl:1
	v_cndmask_b32_e32 v20, v27, v20, vcc
	v_cndmask_b32_e32 v22, v22, v27, vcc
	s_waitcnt vmcnt(23)
	v_fmac_f32_e32 v20, 0x3f9837f0, v154
	v_fmac_f32_e32 v22, 0x3f9837f0, v155
	v_cvt_pk_bf16_f32 v20, v20, v22
	global_store_dword v26, v20, s[92:93]
	s_nop 0
	v_cndmask_b32_e32 v20, v21, v23, vcc
	v_add_u32_e32 v22, v34, v116
	s_nop 0
	v_mov_b32_dpp v20, v20 quad_perm:[1,0,3,2] row_mask:0xf bank_mask:0xf bound_ctrl:1
	v_cndmask_b32_e32 v21, v20, v21, vcc
	v_cndmask_b32_e32 v20, v23, v20, vcc
	v_lshrrev_b32_e32 v23, 1, v28
	s_waitcnt vmcnt(23)
	v_fmac_f32_e32 v21, 0x3f9837f0, v156
	v_fmac_f32_e32 v20, 0x3f9837f0, v157
	v_cvt_pk_bf16_f32 v20, v21, v20
	global_store_dword v23, v20, s[92:93]
	s_nop 0
	v_cndmask_b32_e32 v23, v16, v18, vcc
	v_lshrrev_b32_e32 v22, 1, v22
	v_add_u32_e32 v24, v37, v116
	v_mov_b32_dpp v23, v23 quad_perm:[1,0,3,2] row_mask:0xf bank_mask:0xf bound_ctrl:1
	v_cndmask_b32_e32 v16, v23, v16, vcc
	v_cndmask_b32_e32 v18, v18, v23, vcc
	s_waitcnt vmcnt(23)
	v_fmac_f32_e32 v16, 0x3f9837f0, v158
	v_fmac_f32_e32 v18, 0x3f9837f0, v159
	v_cvt_pk_bf16_f32 v16, v16, v18
	global_store_dword v22, v16, s[92:93]
	s_nop 0
	v_cndmask_b32_e32 v16, v17, v19, vcc
	s_nop 1
	v_mov_b32_dpp v16, v16 quad_perm:[1,0,3,2] row_mask:0xf bank_mask:0xf bound_ctrl:1
	v_cndmask_b32_e32 v17, v16, v17, vcc
	v_cndmask_b32_e32 v16, v19, v16, vcc
	s_waitcnt vmcnt(23)
	v_fmac_f32_e32 v17, 0x3f9837f0, v160
	v_fmac_f32_e32 v16, 0x3f9837f0, v161
	v_cvt_pk_bf16_f32 v16, v17, v16
	v_lshrrev_b32_e32 v17, 1, v24
	global_store_dword v17, v16, s[92:93]
	v_add_u32_e32 v18, 0x160000, v128
	v_add_u32_e32 v19, v18, v129
	s_nop 0
	v_cndmask_b32_e32 v20, v12, v14, vcc
	v_add_u32_e32 v21, 0x162000, v128
	v_lshrrev_b32_e32 v19, 1, v19
	v_mov_b32_dpp v20, v20 quad_perm:[1,0,3,2] row_mask:0xf bank_mask:0xf bound_ctrl:1
	v_cndmask_b32_e32 v12, v20, v12, vcc
	v_cndmask_b32_e32 v14, v14, v20, vcc
	v_add_u32_e32 v22, v21, v129
	s_waitcnt vmcnt(15)
	v_fmac_f32_e32 v12, 0x3f9837f0, v190
	v_fmac_f32_e32 v14, 0x3f9837f0, v191
	v_cvt_pk_bf16_f32 v12, v12, v14
	global_store_dword v19, v12, s[92:93]
	s_nop 0
	v_cndmask_b32_e32 v12, v13, v15, vcc
	v_add_u32_e32 v14, v18, v124
	s_nop 0
	v_mov_b32_dpp v12, v12 quad_perm:[1,0,3,2] row_mask:0xf bank_mask:0xf bound_ctrl:1
	v_cndmask_b32_e32 v13, v12, v13, vcc
	v_cndmask_b32_e32 v12, v15, v12, vcc
	v_lshrrev_b32_e32 v15, 1, v22
	s_waitcnt vmcnt(15)
	v_fmac_f32_e32 v13, 0x3f9837f0, v192
	v_fmac_f32_e32 v12, 0x3f9837f0, v193
	v_cvt_pk_bf16_f32 v12, v13, v12
	global_store_dword v15, v12, s[92:93]
	s_nop 0
	v_cndmask_b32_e32 v15, v8, v10, vcc
	v_lshrrev_b32_e32 v14, 1, v14
	v_add_u32_e32 v16, v21, v124
	v_mov_b32_dpp v15, v15 quad_perm:[1,0,3,2] row_mask:0xf bank_mask:0xf bound_ctrl:1
	v_cndmask_b32_e32 v8, v15, v8, vcc
	v_cndmask_b32_e32 v10, v10, v15, vcc
	s_waitcnt vmcnt(15)
	v_fmac_f32_e32 v8, 0x3f9837f0, v194
	v_fmac_f32_e32 v10, 0x3f9837f0, v195
	v_cvt_pk_bf16_f32 v8, v8, v10
	global_store_dword v14, v8, s[92:93]
	s_nop 0
	v_cndmask_b32_e32 v8, v9, v11, vcc
	v_add_u32_e32 v10, v18, v120
	s_nop 0
	v_mov_b32_dpp v8, v8 quad_perm:[1,0,3,2] row_mask:0xf bank_mask:0xf bound_ctrl:1
	v_cndmask_b32_e32 v9, v8, v9, vcc
	v_cndmask_b32_e32 v8, v11, v8, vcc
	v_lshrrev_b32_e32 v11, 1, v16
	s_waitcnt vmcnt(15)
	v_fmac_f32_e32 v9, 0x3f9837f0, v196
	v_fmac_f32_e32 v8, 0x3f9837f0, v197
	v_cvt_pk_bf16_f32 v8, v9, v8
	global_store_dword v11, v8, s[92:93]
	s_nop 0
	v_cndmask_b32_e32 v11, v4, v6, vcc
	v_lshrrev_b32_e32 v10, 1, v10
	v_add_u32_e32 v12, v21, v120
	v_mov_b32_dpp v11, v11 quad_perm:[1,0,3,2] row_mask:0xf bank_mask:0xf bound_ctrl:1
	v_cndmask_b32_e32 v4, v11, v4, vcc
	v_cndmask_b32_e32 v6, v6, v11, vcc
	s_waitcnt vmcnt(15)
	v_fmac_f32_e32 v4, 0x3f9837f0, v198
	v_fmac_f32_e32 v6, 0x3f9837f0, v199
	v_cvt_pk_bf16_f32 v4, v4, v6
	global_store_dword v10, v4, s[92:93]
	s_nop 0
	v_cndmask_b32_e32 v4, v5, v7, vcc
	v_add_u32_e32 v6, v18, v116
	s_nop 0
	v_mov_b32_dpp v4, v4 quad_perm:[1,0,3,2] row_mask:0xf bank_mask:0xf bound_ctrl:1
	v_cndmask_b32_e32 v5, v4, v5, vcc
	v_cndmask_b32_e32 v4, v7, v4, vcc
	v_lshrrev_b32_e32 v7, 1, v12
	s_waitcnt vmcnt(15)
	v_fmac_f32_e32 v5, 0x3f9837f0, v200
	v_fmac_f32_e32 v4, 0x3f9837f0, v201
	v_cvt_pk_bf16_f32 v4, v5, v4
	global_store_dword v7, v4, s[92:93]
	s_nop 0
	v_cndmask_b32_e32 v7, v0, v2, vcc
	v_lshrrev_b32_e32 v6, 1, v6
	v_add_u32_e32 v8, v21, v116
	v_mov_b32_dpp v7, v7 quad_perm:[1,0,3,2] row_mask:0xf bank_mask:0xf bound_ctrl:1
	v_cndmask_b32_e32 v0, v7, v0, vcc
	v_cndmask_b32_e32 v2, v2, v7, vcc
	s_waitcnt vmcnt(15)
	v_fmac_f32_e32 v0, 0x3f9837f0, v202
	v_fmac_f32_e32 v2, 0x3f9837f0, v203
	v_cvt_pk_bf16_f32 v0, v0, v2
	global_store_dword v6, v0, s[92:93]
	s_nop 0
	v_cndmask_b32_e32 v0, v1, v3, vcc
	s_nop 1
	v_mov_b32_dpp v0, v0 quad_perm:[1,0,3,2] row_mask:0xf bank_mask:0xf bound_ctrl:1
	v_cndmask_b32_e32 v1, v0, v1, vcc
	v_cndmask_b32_e32 v0, v3, v0, vcc
	s_waitcnt vmcnt(15)
	v_fmac_f32_e32 v1, 0x3f9837f0, v204
	v_fmac_f32_e32 v0, 0x3f9837f0, v205
	v_cvt_pk_bf16_f32 v0, v1, v0
	v_lshrrev_b32_e32 v1, 1, v8
	global_store_dword v1, v0, s[92:93]
	s_add_i32 s42, s42, s94
	s_add_i32 s31, s31, s34
	s_add_i32 s41, s41, s60
	s_cmpk_lt_i32 s42, 0x100
	s_barrier
	s_cbranch_scc0 .LBB0_685

; DEVINL float sigm(float x) { return 1.f / (1.f + __expf(-x)); }
; template <int EPI, bool GATHER>
; DEVINL void gemm_tile(const Params& p, const u16* __restrict__ A, int lda, const int* __restrict__ rowidx,
;                       const u16* __restrict__ Bt, int ldb, int K, int brow, int bcol, int orow, int ocol) {
;     ...
;     for (int m = 0; m < 4; ++m) {
;       const int rA = row0 + ai * HALF + m * 16 + (odd ? 2 : 0);
;       float gate[2] = {0.f, 0.f};
;       if (EPI == EPI_MOE2) { gate[0] = ((const float*)(ws + O_SELG))[rA]; gate[1] = ((const float*)(ws + O_SELG))[rA + 1]; }
; #pragma unroll
;       for (int bj = 0; bj < (EPI == EPI_HID ? 1 : 2); ++bj)
; #pragma unroll
;         for (int n = 0; n < 2; ++n) {
;           const int cc = bj * HALF + n * 16;
;           f32x4 v = acc[ai][bj][m][n];
;           if (EPI == EPI_HID) {
; #pragma unroll
;             for (int j = 0; j < 4; ++j) { const float a1 = acc[ai][0][m][n][j], a3 = acc[ai][1][m][n][j]; v[j] = a1 * sigm(a1) * a3; }
;           }
;           float lo[2], hi[2];
;           xchg_pairs(v, odd, lo, hi);
; #pragma unroll
;           for (int k = 0; k < 2; ++k) {
;             const unsigned row = (unsigned)(rA + k);
;             if (EPI == EPI_HID) {
;               *(unsigned*)(ws + O_HID + (row * 1024u + (unsigned)(colp + cc)) * 2u) = pk2(lo[k], hi[k]);
;             } else if (EPI == EPI_COLS) {
;               *(unsigned*)(ws + O_COLS + (row * (unsigned)NCP + (unsigned)(colp + cc)) * 2u) = pk2(lo[k], hi[k]);
;             } else if (EPI == EPI_MOE2) {
;               *(unsigned*)(ws + O_EO + (row * 2048u + (unsigned)(colp + cc)) * 2u) = pk2(gate[k] * lo[k], gate[k] * hi[k]);
.LBB0_1030:
	s_or_b64 exec, exec, s[34:35]
	v_and_b32_e32 v149, 1, v141
	v_add_u32_e32 v153, s30, v145
	v_lshlrev_b32_e32 v154, 2, v144
	v_lshlrev_b32_e32 v155, 1, v149
	v_or3_b32 v153, v153, v155, v154
	v_ashrrev_i32_e32 v154, 31, v153
	v_mov_b32_e32 v156, v153
	v_mov_b32_e32 v157, v154
	v_lshl_add_u64 v[158:159], v[156:157], 2, s[0:1]
	global_load_dwordx2 v[146:147], v[158:159], off
	v_and_b32_e32 v149, 1, v141
	v_add_u32_e32 v153, s30, v145
	v_lshlrev_b32_e32 v154, 2, v144
	v_lshlrev_b32_e32 v155, 1, v149
	v_or3_b32 v153, v153, v155, v154
	v_or_b32_e32 v156, 16, v153
	v_ashrrev_i32_e32 v157, 31, v156
	v_lshl_add_u64 v[158:159], v[156:157], 2, s[0:1]
	global_load_dwordx2 v[150:151], v[158:159], off
	v_and_b32_e32 v134, 1, v141
	v_add_u32_e32 v128, s30, v145
	v_lshlrev_b32_e32 v129, 2, v144
	v_lshlrev_b32_e32 v130, 1, v134
	v_or3_b32 v128, v128, v130, v129
	v_ashrrev_i32_e32 v129, 31, v128
	v_lshl_add_u64 v[130:131], v[128:129], 2, s[0:1]
	s_nop 0
	v_or_b32_e32 v129, s49, v143
	v_lshlrev_b32_e32 v130, 6, v142
	v_sub_u32_e32 v129, v129, v134
	v_cmp_eq_u32_e32 vcc, 0, v134
	v_lshl_add_u32 v129, v129, 1, v130
	s_nop 0
	v_cndmask_b32_e32 v131, v116, v118, vcc
	v_cndmask_b32_e32 v130, v112, v114, vcc
	v_cndmask_b32_e32 v134, v117, v119, vcc
	v_mov_b32_dpp v131, v131 quad_perm:[1,0,3,2] row_mask:0xf bank_mask:0xf bound_ctrl:1
	v_cndmask_b32_e32 v135, v113, v115, vcc
	v_cndmask_b32_e32 v136, v124, v126, vcc
	v_cndmask_b32_e32 v137, v125, v127, vcc
	v_cndmask_b32_e32 v138, v120, v122, vcc
	v_cndmask_b32_e32 v139, v121, v123, vcc
	v_mov_b32_dpp v143, v130 quad_perm:[1,0,3,2] row_mask:0xf bank_mask:0xf bound_ctrl:1
	v_mov_b32_dpp v134, v134 quad_perm:[1,0,3,2] row_mask:0xf bank_mask:0xf bound_ctrl:1
	v_cndmask_b32_e32 v141, v131, v116, vcc
	v_cndmask_b32_e32 v142, v118, v131, vcc
	v_mov_b32_dpp v135, v135 quad_perm:[1,0,3,2] row_mask:0xf bank_mask:0xf bound_ctrl:1
	v_mov_b32_dpp v136, v136 quad_perm:[1,0,3,2] row_mask:0xf bank_mask:0xf bound_ctrl:1
	v_mov_b32_dpp v137, v137 quad_perm:[1,0,3,2] row_mask:0xf bank_mask:0xf bound_ctrl:1
	v_mov_b32_dpp v138, v138 quad_perm:[1,0,3,2] row_mask:0xf bank_mask:0xf bound_ctrl:1
	v_mov_b32_dpp v139, v139 quad_perm:[1,0,3,2] row_mask:0xf bank_mask:0xf bound_ctrl:1
	v_cndmask_b32_e32 v112, v143, v112, vcc
	v_cndmask_b32_e32 v114, v114, v143, vcc
	v_lshlrev_b32_e32 v131, 12, v128
	v_cndmask_b32_e32 v117, v134, v117, vcc
	v_cndmask_b32_e32 v119, v119, v134, vcc
	v_cndmask_b32_e32 v113, v135, v113, vcc
	v_cndmask_b32_e32 v115, v115, v135, vcc
	v_cndmask_b32_e32 v124, v136, v124, vcc
	v_cndmask_b32_e32 v126, v126, v136, vcc
	v_cndmask_b32_e32 v125, v137, v125, vcc
	v_cndmask_b32_e32 v127, v127, v137, vcc
	v_cndmask_b32_e32 v120, v138, v120, vcc
	v_cndmask_b32_e32 v122, v122, v138, vcc
	v_cndmask_b32_e32 v121, v139, v121, vcc
	v_cndmask_b32_e32 v123, v123, v139, vcc
	v_add_u32_e32 v118, 32, v129
	v_add_u32_e32 v116, 0x100, v129
	v_add_u32_e32 v130, 0x120, v129
	v_add_u32_e32 v134, v131, v129
	v_or_b32_e32 v144, 0x1000, v131
	v_add_u32_e32 v135, v131, v118
	v_add_u32_e32 v136, v131, v116
	v_add_u32_e32 v137, v131, v130
	v_add_u32_e32 v138, v144, v129
	v_add_u32_e32 v139, v144, v118
	v_add_u32_e32 v143, v144, v116
	s_waitcnt vmcnt(1)
	v_mul_f32_e32 v141, v146, v141
	v_mul_f32_e32 v142, v146, v142
	v_mul_f32_e32 v112, v146, v112
	v_mul_f32_e32 v114, v146, v114
	v_mul_f32_e32 v117, v147, v117
	v_mul_f32_e32 v119, v147, v119
	v_mul_f32_e32 v113, v147, v113
	v_mul_f32_e32 v115, v147, v115
	v_mul_f32_e32 v124, v146, v124
	v_mul_f32_e32 v126, v146, v126
	v_mul_f32_e32 v125, v147, v125
	v_mul_f32_e32 v127, v147, v127
	v_mul_f32_e32 v120, v146, v120
	v_mul_f32_e32 v122, v146, v122
	v_mul_f32_e32 v121, v147, v121
	v_mul_f32_e32 v123, v147, v123
	v_cvt_pk_bf16_f32 v132, v141, v142
	v_cvt_pk_bf16_f32 v112, v112, v114
	v_cvt_pk_bf16_f32 v117, v117, v119
	v_cvt_pk_bf16_f32 v113, v113, v115
	v_cvt_pk_bf16_f32 v114, v124, v126
	v_cvt_pk_bf16_f32 v115, v125, v127
	v_cvt_pk_bf16_f32 v119, v120, v122
	v_cvt_pk_bf16_f32 v120, v121, v123
	global_store_dword v134, v132, s[8:9]
	global_store_dword v138, v117, s[8:9]
	global_store_dword v135, v112, s[8:9]
	global_store_dword v139, v113, s[8:9]
	global_store_dword v136, v114, s[8:9]
	global_store_dword v143, v115, s[8:9]
	global_store_dword v137, v119, s[8:9]
	v_add_u32_e32 v112, v144, v130
	global_store_dword v112, v120, s[8:9]
	v_or_b32_e32 v149, 32, v128
	v_ashrrev_i32_e32 v153, 31, v149
	v_mov_b32_e32 v154, v149
	v_mov_b32_e32 v155, v153
	v_lshl_add_u64 v[156:157], v[154:155], 2, s[0:1]
	global_load_dwordx2 v[146:147], v[156:157], off
	v_or_b32_e32 v112, 16, v128
	v_ashrrev_i32_e32 v113, 31, v112
	v_lshl_add_u64 v[114:115], v[112:113], 2, s[0:1]
	s_nop 0
	v_cndmask_b32_e32 v113, v100, v102, vcc
	v_cndmask_b32_e32 v117, v101, v103, vcc
	v_cndmask_b32_e32 v120, v96, v98, vcc
	v_cndmask_b32_e32 v121, v97, v99, vcc
	v_cndmask_b32_e32 v122, v108, v110, vcc
	v_cndmask_b32_e32 v123, v109, v111, vcc
	v_cndmask_b32_e32 v124, v104, v106, vcc
	v_cndmask_b32_e32 v125, v105, v107, vcc
	v_mov_b32_dpp v113, v113 quad_perm:[1,0,3,2] row_mask:0xf bank_mask:0xf bound_ctrl:1
	v_mov_b32_dpp v117, v117 quad_perm:[1,0,3,2] row_mask:0xf bank_mask:0xf bound_ctrl:1
	v_mov_b32_dpp v120, v120 quad_perm:[1,0,3,2] row_mask:0xf bank_mask:0xf bound_ctrl:1
	v_mov_b32_dpp v121, v121 quad_perm:[1,0,3,2] row_mask:0xf bank_mask:0xf bound_ctrl:1
	v_mov_b32_dpp v122, v122 quad_perm:[1,0,3,2] row_mask:0xf bank_mask:0xf bound_ctrl:1
	v_mov_b32_dpp v123, v123 quad_perm:[1,0,3,2] row_mask:0xf bank_mask:0xf bound_ctrl:1
	v_mov_b32_dpp v124, v124 quad_perm:[1,0,3,2] row_mask:0xf bank_mask:0xf bound_ctrl:1
	v_mov_b32_dpp v125, v125 quad_perm:[1,0,3,2] row_mask:0xf bank_mask:0xf bound_ctrl:1
	v_cndmask_b32_e32 v100, v113, v100, vcc
	v_cndmask_b32_e32 v102, v102, v113, vcc
	v_lshlrev_b32_e32 v112, 12, v112
	v_cndmask_b32_e32 v101, v117, v101, vcc
	v_cndmask_b32_e32 v103, v103, v117, vcc
	v_cndmask_b32_e32 v96, v120, v96, vcc
	v_cndmask_b32_e32 v98, v98, v120, vcc
	v_cndmask_b32_e32 v97, v121, v97, vcc
	v_cndmask_b32_e32 v99, v99, v121, vcc
	v_cndmask_b32_e32 v108, v122, v108, vcc
	v_cndmask_b32_e32 v110, v110, v122, vcc
	v_cndmask_b32_e32 v109, v123, v109, vcc
	v_cndmask_b32_e32 v111, v111, v123, vcc
	v_cndmask_b32_e32 v104, v124, v104, vcc
	v_cndmask_b32_e32 v106, v106, v124, vcc
	v_cndmask_b32_e32 v105, v125, v105, vcc
	v_cndmask_b32_e32 v107, v107, v125, vcc
	v_or_b32_e32 v119, 0x11000, v131
	v_add_u32_e32 v113, v112, v129
	v_add_u32_e32 v126, v119, v129
	v_add_u32_e32 v127, v119, v118
	v_add_u32_e32 v132, v119, v116
	v_add_u32_e32 v119, v119, v130
	v_add_u32_e32 v117, v112, v118
	v_add_u32_e32 v120, v112, v116
	v_add_u32_e32 v112, v112, v130
	s_waitcnt vmcnt(9)
; DEVINL float sigm(float x) { return 1.f / (1.f + __expf(-x)); }
; template <int EPI, bool GATHER>
; DEVINL void gemm_tile(const Params& p, const u16* __restrict__ A, int lda, const int* __restrict__ rowidx,
;                       const u16* __restrict__ Bt, int ldb, int K, int brow, int bcol, int orow, int ocol) {
;     ...
;     for (int m = 0; m < 4; ++m) {
;       const int rA = row0 + ai * HALF + m * 16 + (odd ? 2 : 0);
;       float gate[2] = {0.f, 0.f};
;       if (EPI == EPI_MOE2) { gate[0] = ((const float*)(ws + O_SELG))[rA]; gate[1] = ((const float*)(ws + O_SELG))[rA + 1]; }
; #pragma unroll
;       for (int bj = 0; bj < (EPI == EPI_HID ? 1 : 2); ++bj)
; #pragma unroll
;         for (int n = 0; n < 2; ++n) {
;           const int cc = bj * HALF + n * 16;
;           f32x4 v = acc[ai][bj][m][n];
;           if (EPI == EPI_HID) {
; #pragma unroll
;             for (int j = 0; j < 4; ++j) { const float a1 = acc[ai][0][m][n][j], a3 = acc[ai][1][m][n][j]; v[j] = a1 * sigm(a1) * a3; }
;           }
;           float lo[2], hi[2];
;           xchg_pairs(v, odd, lo, hi);
; #pragma unroll
;           for (int k = 0; k < 2; ++k) {
;             const unsigned row = (unsigned)(rA + k);
;             if (EPI == EPI_HID) {
;               *(unsigned*)(ws + O_HID + (row * 1024u + (unsigned)(colp + cc)) * 2u) = pk2(lo[k], hi[k]);
;             } else if (EPI == EPI_COLS) {
;               *(unsigned*)(ws + O_COLS + (row * (unsigned)NCP + (unsigned)(colp + cc)) * 2u) = pk2(lo[k], hi[k]);
;             } else if (EPI == EPI_MOE2) {
;               *(unsigned*)(ws + O_EO + (row * 2048u + (unsigned)(colp + cc)) * 2u) = pk2(gate[k] * lo[k], gate[k] * hi[k]);
	v_mul_f32_e32 v100, v150, v100
	v_mul_f32_e32 v102, v150, v102
	v_mul_f32_e32 v101, v151, v101
	v_mul_f32_e32 v103, v151, v103
	v_mul_f32_e32 v96, v150, v96
	v_mul_f32_e32 v98, v150, v98
	v_mul_f32_e32 v97, v151, v97
	v_mul_f32_e32 v99, v151, v99
	v_mul_f32_e32 v108, v150, v108
	v_mul_f32_e32 v110, v150, v110
	v_mul_f32_e32 v109, v151, v109
	v_mul_f32_e32 v111, v151, v111
	v_mul_f32_e32 v104, v150, v104
	v_mul_f32_e32 v106, v150, v106
	v_mul_f32_e32 v105, v151, v105
	v_mul_f32_e32 v107, v151, v107
	v_cvt_pk_bf16_f32 v100, v100, v102
	v_cvt_pk_bf16_f32 v101, v101, v103
	v_cvt_pk_bf16_f32 v96, v96, v98
	v_cvt_pk_bf16_f32 v97, v97, v99
	v_cvt_pk_bf16_f32 v98, v108, v110
	v_cvt_pk_bf16_f32 v99, v109, v111
	v_cvt_pk_bf16_f32 v102, v104, v106
	v_cvt_pk_bf16_f32 v103, v105, v107
	global_store_dword v113, v100, s[8:9]
	global_store_dword v126, v101, s[8:9]
	global_store_dword v117, v96, s[8:9]
	global_store_dword v127, v97, s[8:9]
	global_store_dword v120, v98, s[8:9]
	global_store_dword v132, v99, s[8:9]
	global_store_dword v112, v102, s[8:9]
	global_store_dword v119, v103, s[8:9]
	v_or_b32_e32 v149, 48, v128
	v_ashrrev_i32_e32 v153, 31, v149
	v_mov_b32_e32 v154, v149
	v_mov_b32_e32 v155, v153
	v_lshl_add_u64 v[156:157], v[154:155], 2, s[0:1]
	global_load_dwordx2 v[150:151], v[156:157], off
	v_or_b32_e32 v96, 32, v128
	v_ashrrev_i32_e32 v97, 31, v96
	v_lshl_add_u64 v[98:99], v[96:97], 2, s[0:1]
	s_nop 0
	v_cndmask_b32_e32 v97, v84, v86, vcc
	v_cndmask_b32_e32 v100, v85, v87, vcc
	v_cndmask_b32_e32 v102, v80, v82, vcc
	v_cndmask_b32_e32 v103, v81, v83, vcc
	v_cndmask_b32_e32 v104, v92, v94, vcc
	v_cndmask_b32_e32 v105, v93, v95, vcc
	v_cndmask_b32_e32 v106, v88, v90, vcc
	v_cndmask_b32_e32 v107, v89, v91, vcc
	v_mov_b32_dpp v97, v97 quad_perm:[1,0,3,2] row_mask:0xf bank_mask:0xf bound_ctrl:1
	v_mov_b32_dpp v100, v100 quad_perm:[1,0,3,2] row_mask:0xf bank_mask:0xf bound_ctrl:1
	v_mov_b32_dpp v102, v102 quad_perm:[1,0,3,2] row_mask:0xf bank_mask:0xf bound_ctrl:1
	v_mov_b32_dpp v103, v103 quad_perm:[1,0,3,2] row_mask:0xf bank_mask:0xf bound_ctrl:1
	v_mov_b32_dpp v104, v104 quad_perm:[1,0,3,2] row_mask:0xf bank_mask:0xf bound_ctrl:1
	v_mov_b32_dpp v105, v105 quad_perm:[1,0,3,2] row_mask:0xf bank_mask:0xf bound_ctrl:1
	v_mov_b32_dpp v106, v106 quad_perm:[1,0,3,2] row_mask:0xf bank_mask:0xf bound_ctrl:1
	v_mov_b32_dpp v107, v107 quad_perm:[1,0,3,2] row_mask:0xf bank_mask:0xf bound_ctrl:1
	v_cndmask_b32_e32 v84, v97, v84, vcc
	v_cndmask_b32_e32 v86, v86, v97, vcc
	v_lshlrev_b32_e32 v96, 12, v96
	v_cndmask_b32_e32 v85, v100, v85, vcc
	v_cndmask_b32_e32 v87, v87, v100, vcc
	v_cndmask_b32_e32 v80, v102, v80, vcc
	v_cndmask_b32_e32 v82, v82, v102, vcc
	v_cndmask_b32_e32 v81, v103, v81, vcc
	v_cndmask_b32_e32 v83, v83, v103, vcc
	v_cndmask_b32_e32 v92, v104, v92, vcc
	v_cndmask_b32_e32 v94, v94, v104, vcc
	v_cndmask_b32_e32 v93, v105, v93, vcc
	v_cndmask_b32_e32 v95, v95, v105, vcc
	v_cndmask_b32_e32 v88, v106, v88, vcc
	v_cndmask_b32_e32 v90, v90, v106, vcc
	v_cndmask_b32_e32 v89, v107, v89, vcc
	v_cndmask_b32_e32 v91, v91, v107, vcc
	v_or_b32_e32 v101, 0x21000, v131
	v_add_u32_e32 v97, v96, v129
	v_add_u32_e32 v108, v101, v129
	v_add_u32_e32 v109, v101, v118
	v_add_u32_e32 v110, v101, v116
	v_add_u32_e32 v101, v101, v130
	v_add_u32_e32 v100, v96, v118
	v_add_u32_e32 v102, v96, v116
	v_add_u32_e32 v96, v96, v130
	s_waitcnt vmcnt(9)
	v_mul_f32_e32 v84, v146, v84
	v_mul_f32_e32 v86, v146, v86
	v_mul_f32_e32 v85, v147, v85
	v_mul_f32_e32 v87, v147, v87
	v_mul_f32_e32 v80, v146, v80
	v_mul_f32_e32 v82, v146, v82
	v_mul_f32_e32 v81, v147, v81
	v_mul_f32_e32 v83, v147, v83
	v_mul_f32_e32 v92, v146, v92
	v_mul_f32_e32 v94, v146, v94
	v_mul_f32_e32 v93, v147, v93
	v_mul_f32_e32 v95, v147, v95
	v_mul_f32_e32 v88, v146, v88
	v_mul_f32_e32 v90, v146, v90
	v_mul_f32_e32 v89, v147, v89
	v_mul_f32_e32 v91, v147, v91
	v_cvt_pk_bf16_f32 v84, v84, v86
	v_cvt_pk_bf16_f32 v85, v85, v87
	v_cvt_pk_bf16_f32 v80, v80, v82
	v_cvt_pk_bf16_f32 v81, v81, v83
	v_cvt_pk_bf16_f32 v82, v92, v94
	v_cvt_pk_bf16_f32 v83, v93, v95
	v_cvt_pk_bf16_f32 v86, v88, v90
	v_cvt_pk_bf16_f32 v87, v89, v91
	global_store_dword v97, v84, s[8:9]
	global_store_dword v108, v85, s[8:9]
	global_store_dword v100, v80, s[8:9]
	global_store_dword v109, v81, s[8:9]
	global_store_dword v102, v82, s[8:9]
	global_store_dword v110, v83, s[8:9]
	global_store_dword v96, v86, s[8:9]
	global_store_dword v101, v87, s[8:9]
	v_add_u32_e32 v149, 0x80, v128
	v_ashrrev_i32_e32 v153, 31, v149
	v_mov_b32_e32 v154, v149
	v_mov_b32_e32 v155, v153
	v_lshl_add_u64 v[156:157], v[154:155], 2, s[0:1]
	global_load_dwordx2 v[146:147], v[156:157], off
	v_or_b32_e32 v80, 48, v128
	v_ashrrev_i32_e32 v81, 31, v80
	v_lshl_add_u64 v[82:83], v[80:81], 2, s[0:1]
	s_nop 0
	v_cndmask_b32_e32 v81, v68, v70, vcc
	v_cndmask_b32_e32 v84, v69, v71, vcc
	v_cndmask_b32_e32 v86, v64, v66, vcc
	v_cndmask_b32_e32 v87, v65, v67, vcc
	v_cndmask_b32_e32 v88, v76, v78, vcc
	v_cndmask_b32_e32 v89, v77, v79, vcc
	v_cndmask_b32_e32 v90, v72, v74, vcc
	v_cndmask_b32_e32 v91, v73, v75, vcc
	v_mov_b32_dpp v81, v81 quad_perm:[1,0,3,2] row_mask:0xf bank_mask:0xf bound_ctrl:1
	v_mov_b32_dpp v84, v84 quad_perm:[1,0,3,2] row_mask:0xf bank_mask:0xf bound_ctrl:1
	v_mov_b32_dpp v86, v86 quad_perm:[1,0,3,2] row_mask:0xf bank_mask:0xf bound_ctrl:1
	v_mov_b32_dpp v87, v87 quad_perm:[1,0,3,2] row_mask:0xf bank_mask:0xf bound_ctrl:1
	v_mov_b32_dpp v88, v88 quad_perm:[1,0,3,2] row_mask:0xf bank_mask:0xf bound_ctrl:1
	v_mov_b32_dpp v89, v89 quad_perm:[1,0,3,2] row_mask:0xf bank_mask:0xf bound_ctrl:1
	v_mov_b32_dpp v90, v90 quad_perm:[1,0,3,2] row_mask:0xf bank_mask:0xf bound_ctrl:1
	v_mov_b32_dpp v91, v91 quad_perm:[1,0,3,2] row_mask:0xf bank_mask:0xf bound_ctrl:1
	v_cndmask_b32_e32 v68, v81, v68, vcc
	v_cndmask_b32_e32 v70, v70, v81, vcc
	v_lshlrev_b32_e32 v80, 12, v80
	v_cndmask_b32_e32 v69, v84, v69, vcc
	v_cndmask_b32_e32 v71, v71, v84, vcc
	v_cndmask_b32_e32 v64, v86, v64, vcc
	v_cndmask_b32_e32 v66, v66, v86, vcc
	v_cndmask_b32_e32 v65, v87, v65, vcc
	v_cndmask_b32_e32 v67, v67, v87, vcc
	v_cndmask_b32_e32 v76, v88, v76, vcc
	v_cndmask_b32_e32 v78, v78, v88, vcc
	v_cndmask_b32_e32 v77, v89, v77, vcc
	v_cndmask_b32_e32 v79, v79, v89, vcc
	v_cndmask_b32_e32 v72, v90, v72, vcc
	v_cndmask_b32_e32 v74, v74, v90, vcc
	v_cndmask_b32_e32 v73, v91, v73, vcc
	v_cndmask_b32_e32 v75, v75, v91, vcc
	v_or_b32_e32 v85, 0x31000, v131
	v_add_u32_e32 v81, v80, v129
	v_add_u32_e32 v92, v85, v129
	v_add_u32_e32 v93, v85, v118
	v_add_u32_e32 v94, v85, v116
	v_add_u32_e32 v85, v85, v130
	v_add_u32_e32 v84, v80, v118
	v_add_u32_e32 v86, v80, v116
	v_add_u32_e32 v80, v80, v130
	s_waitcnt vmcnt(9)
; DEVINL float sigm(float x) { return 1.f / (1.f + __expf(-x)); }
; template <int EPI, bool GATHER>
; DEVINL void gemm_tile(const Params& p, const u16* __restrict__ A, int lda, const int* __restrict__ rowidx,
;                       const u16* __restrict__ Bt, int ldb, int K, int brow, int bcol, int orow, int ocol) {
;     ...
;     for (int m = 0; m < 4; ++m) {
;       const int rA = row0 + ai * HALF + m * 16 + (odd ? 2 : 0);
;       float gate[2] = {0.f, 0.f};
;       if (EPI == EPI_MOE2) { gate[0] = ((const float*)(ws + O_SELG))[rA]; gate[1] = ((const float*)(ws + O_SELG))[rA + 1]; }
; #pragma unroll
;       for (int bj = 0; bj < (EPI == EPI_HID ? 1 : 2); ++bj)
; #pragma unroll
;         for (int n = 0; n < 2; ++n) {
;           const int cc = bj * HALF + n * 16;
;           f32x4 v = acc[ai][bj][m][n];
;           if (EPI == EPI_HID) {
; #pragma unroll
;             for (int j = 0; j < 4; ++j) { const float a1 = acc[ai][0][m][n][j], a3 = acc[ai][1][m][n][j]; v[j] = a1 * sigm(a1) * a3; }
;           }
;           float lo[2], hi[2];
;           xchg_pairs(v, odd, lo, hi);
; #pragma unroll
;           for (int k = 0; k < 2; ++k) {
;             const unsigned row = (unsigned)(rA + k);
;             if (EPI == EPI_HID) {
;               *(unsigned*)(ws + O_HID + (row * 1024u + (unsigned)(colp + cc)) * 2u) = pk2(lo[k], hi[k]);
;             } else if (EPI == EPI_COLS) {
;               *(unsigned*)(ws + O_COLS + (row * (unsigned)NCP + (unsigned)(colp + cc)) * 2u) = pk2(lo[k], hi[k]);
;             } else if (EPI == EPI_MOE2) {
;               *(unsigned*)(ws + O_EO + (row * 2048u + (unsigned)(colp + cc)) * 2u) = pk2(gate[k] * lo[k], gate[k] * hi[k]);
	v_mul_f32_e32 v68, v150, v68
	v_mul_f32_e32 v70, v150, v70
	v_mul_f32_e32 v69, v151, v69
	v_mul_f32_e32 v71, v151, v71
	v_mul_f32_e32 v64, v150, v64
	v_mul_f32_e32 v66, v150, v66
	v_mul_f32_e32 v65, v151, v65
	v_mul_f32_e32 v67, v151, v67
	v_mul_f32_e32 v76, v150, v76
	v_mul_f32_e32 v78, v150, v78
	v_mul_f32_e32 v77, v151, v77
	v_mul_f32_e32 v79, v151, v79
	v_mul_f32_e32 v72, v150, v72
	v_mul_f32_e32 v74, v150, v74
	v_mul_f32_e32 v73, v151, v73
	v_mul_f32_e32 v75, v151, v75
	v_cvt_pk_bf16_f32 v68, v68, v70
	v_cvt_pk_bf16_f32 v69, v69, v71
	v_cvt_pk_bf16_f32 v64, v64, v66
	v_cvt_pk_bf16_f32 v65, v65, v67
	v_cvt_pk_bf16_f32 v66, v76, v78
	v_cvt_pk_bf16_f32 v67, v77, v79
	v_cvt_pk_bf16_f32 v70, v72, v74
	v_cvt_pk_bf16_f32 v71, v73, v75
	global_store_dword v81, v68, s[8:9]
	global_store_dword v92, v69, s[8:9]
	global_store_dword v84, v64, s[8:9]
	global_store_dword v93, v65, s[8:9]
	global_store_dword v86, v66, s[8:9]
	global_store_dword v94, v67, s[8:9]
	global_store_dword v80, v70, s[8:9]
	global_store_dword v85, v71, s[8:9]
	v_add_u32_e32 v149, 0x90, v128
	v_ashrrev_i32_e32 v153, 31, v149
	v_mov_b32_e32 v154, v149
	v_mov_b32_e32 v155, v153
	v_lshl_add_u64 v[156:157], v[154:155], 2, s[0:1]
	global_load_dwordx2 v[150:151], v[156:157], off
	v_add_u32_e32 v64, 0x80, v128
	v_ashrrev_i32_e32 v65, 31, v64
	v_lshl_add_u64 v[66:67], v[64:65], 2, s[0:1]
	s_nop 0
	v_cndmask_b32_e32 v65, v52, v54, vcc
	v_cndmask_b32_e32 v68, v53, v55, vcc
	v_cndmask_b32_e32 v70, v48, v50, vcc
	v_cndmask_b32_e32 v71, v49, v51, vcc
	v_cndmask_b32_e32 v72, v60, v62, vcc
	v_cndmask_b32_e32 v73, v61, v63, vcc
	v_cndmask_b32_e32 v74, v56, v58, vcc
	v_cndmask_b32_e32 v75, v57, v59, vcc
	v_mov_b32_dpp v65, v65 quad_perm:[1,0,3,2] row_mask:0xf bank_mask:0xf bound_ctrl:1
	v_mov_b32_dpp v68, v68 quad_perm:[1,0,3,2] row_mask:0xf bank_mask:0xf bound_ctrl:1
	v_mov_b32_dpp v70, v70 quad_perm:[1,0,3,2] row_mask:0xf bank_mask:0xf bound_ctrl:1
	v_mov_b32_dpp v71, v71 quad_perm:[1,0,3,2] row_mask:0xf bank_mask:0xf bound_ctrl:1
	v_mov_b32_dpp v72, v72 quad_perm:[1,0,3,2] row_mask:0xf bank_mask:0xf bound_ctrl:1
	v_mov_b32_dpp v73, v73 quad_perm:[1,0,3,2] row_mask:0xf bank_mask:0xf bound_ctrl:1
	v_mov_b32_dpp v74, v74 quad_perm:[1,0,3,2] row_mask:0xf bank_mask:0xf bound_ctrl:1
	v_mov_b32_dpp v75, v75 quad_perm:[1,0,3,2] row_mask:0xf bank_mask:0xf bound_ctrl:1
	v_cndmask_b32_e32 v52, v65, v52, vcc
	v_cndmask_b32_e32 v54, v54, v65, vcc
	v_lshlrev_b32_e32 v64, 12, v64
	v_cndmask_b32_e32 v53, v68, v53, vcc
	v_cndmask_b32_e32 v55, v55, v68, vcc
	v_cndmask_b32_e32 v48, v70, v48, vcc
	v_cndmask_b32_e32 v50, v50, v70, vcc
	v_cndmask_b32_e32 v49, v71, v49, vcc
	v_cndmask_b32_e32 v51, v51, v71, vcc
	v_cndmask_b32_e32 v60, v72, v60, vcc
	v_cndmask_b32_e32 v62, v62, v72, vcc
	v_cndmask_b32_e32 v61, v73, v61, vcc
	v_cndmask_b32_e32 v63, v63, v73, vcc
	v_cndmask_b32_e32 v56, v74, v56, vcc
	v_cndmask_b32_e32 v58, v58, v74, vcc
	v_cndmask_b32_e32 v57, v75, v57, vcc
	v_cndmask_b32_e32 v59, v59, v75, vcc
	v_add_u32_e32 v69, 0x81000, v131
	v_add_u32_e32 v65, v64, v129
	v_add_u32_e32 v76, v69, v129
	v_add_u32_e32 v77, v69, v118
	v_add_u32_e32 v78, v69, v116
	v_add_u32_e32 v69, v69, v130
	v_add_u32_e32 v68, v64, v118
	v_add_u32_e32 v70, v64, v116
	v_add_u32_e32 v64, v64, v130
	s_waitcnt vmcnt(9)
	v_mul_f32_e32 v52, v146, v52
	v_mul_f32_e32 v54, v146, v54
	v_mul_f32_e32 v53, v147, v53
	v_mul_f32_e32 v55, v147, v55
	v_mul_f32_e32 v48, v146, v48
	v_mul_f32_e32 v50, v146, v50
	v_mul_f32_e32 v49, v147, v49
	v_mul_f32_e32 v51, v147, v51
	v_mul_f32_e32 v60, v146, v60
	v_mul_f32_e32 v62, v146, v62
	v_mul_f32_e32 v61, v147, v61
	v_mul_f32_e32 v63, v147, v63
	v_mul_f32_e32 v56, v146, v56
	v_mul_f32_e32 v58, v146, v58
	v_mul_f32_e32 v57, v147, v57
	v_mul_f32_e32 v59, v147, v59
	v_cvt_pk_bf16_f32 v52, v52, v54
	v_cvt_pk_bf16_f32 v53, v53, v55
	v_cvt_pk_bf16_f32 v48, v48, v50
	v_cvt_pk_bf16_f32 v49, v49, v51
	v_cvt_pk_bf16_f32 v50, v60, v62
	v_cvt_pk_bf16_f32 v51, v61, v63
	v_cvt_pk_bf16_f32 v54, v56, v58
	v_cvt_pk_bf16_f32 v55, v57, v59
	global_store_dword v65, v52, s[8:9]
	global_store_dword v76, v53, s[8:9]
	global_store_dword v68, v48, s[8:9]
	global_store_dword v77, v49, s[8:9]
	global_store_dword v70, v50, s[8:9]
	global_store_dword v78, v51, s[8:9]
	global_store_dword v64, v54, s[8:9]
	global_store_dword v69, v55, s[8:9]
	v_add_u32_e32 v149, 0xa0, v128
	v_ashrrev_i32_e32 v153, 31, v149
	v_mov_b32_e32 v154, v149
	v_mov_b32_e32 v155, v153
	v_lshl_add_u64 v[156:157], v[154:155], 2, s[0:1]
	global_load_dwordx2 v[146:147], v[156:157], off
	v_add_u32_e32 v48, 0x90, v128
	v_ashrrev_i32_e32 v49, 31, v48
	v_lshl_add_u64 v[50:51], v[48:49], 2, s[0:1]
	s_nop 0
	v_cndmask_b32_e32 v49, v36, v38, vcc
	v_cndmask_b32_e32 v52, v37, v39, vcc
	v_cndmask_b32_e32 v54, v32, v34, vcc
	v_cndmask_b32_e32 v55, v33, v35, vcc
	v_cndmask_b32_e32 v56, v44, v46, vcc
	v_cndmask_b32_e32 v57, v45, v47, vcc
	v_cndmask_b32_e32 v58, v40, v42, vcc
	v_cndmask_b32_e32 v59, v41, v43, vcc
	v_mov_b32_dpp v49, v49 quad_perm:[1,0,3,2] row_mask:0xf bank_mask:0xf bound_ctrl:1
	v_mov_b32_dpp v52, v52 quad_perm:[1,0,3,2] row_mask:0xf bank_mask:0xf bound_ctrl:1
	v_mov_b32_dpp v54, v54 quad_perm:[1,0,3,2] row_mask:0xf bank_mask:0xf bound_ctrl:1
	v_mov_b32_dpp v55, v55 quad_perm:[1,0,3,2] row_mask:0xf bank_mask:0xf bound_ctrl:1
	v_mov_b32_dpp v56, v56 quad_perm:[1,0,3,2] row_mask:0xf bank_mask:0xf bound_ctrl:1
	v_mov_b32_dpp v57, v57 quad_perm:[1,0,3,2] row_mask:0xf bank_mask:0xf bound_ctrl:1
	v_mov_b32_dpp v58, v58 quad_perm:[1,0,3,2] row_mask:0xf bank_mask:0xf bound_ctrl:1
	v_mov_b32_dpp v59, v59 quad_perm:[1,0,3,2] row_mask:0xf bank_mask:0xf bound_ctrl:1
	v_cndmask_b32_e32 v36, v49, v36, vcc
	v_cndmask_b32_e32 v38, v38, v49, vcc
	v_lshlrev_b32_e32 v48, 12, v48
	v_cndmask_b32_e32 v37, v52, v37, vcc
	v_cndmask_b32_e32 v39, v39, v52, vcc
	v_cndmask_b32_e32 v32, v54, v32, vcc
	v_cndmask_b32_e32 v34, v34, v54, vcc
	v_cndmask_b32_e32 v33, v55, v33, vcc
	v_cndmask_b32_e32 v35, v35, v55, vcc
	v_cndmask_b32_e32 v44, v56, v44, vcc
	v_cndmask_b32_e32 v46, v46, v56, vcc
	v_cndmask_b32_e32 v45, v57, v45, vcc
	v_cndmask_b32_e32 v47, v47, v57, vcc
	v_cndmask_b32_e32 v40, v58, v40, vcc
	v_cndmask_b32_e32 v42, v42, v58, vcc
	v_cndmask_b32_e32 v41, v59, v41, vcc
	v_cndmask_b32_e32 v43, v43, v59, vcc
	v_add_u32_e32 v53, 0x91000, v131
	v_add_u32_e32 v49, v48, v129
	v_add_u32_e32 v60, v53, v129
	v_add_u32_e32 v61, v53, v118
	v_add_u32_e32 v62, v53, v116
	v_add_u32_e32 v53, v53, v130
	v_add_u32_e32 v52, v48, v118
	v_add_u32_e32 v54, v48, v116
	v_add_u32_e32 v48, v48, v130
	s_waitcnt vmcnt(9)
; DEVINL float sigm(float x) { return 1.f / (1.f + __expf(-x)); }
; template <int EPI, bool GATHER>
; DEVINL void gemm_tile(const Params& p, const u16* __restrict__ A, int lda, const int* __restrict__ rowidx,
;                       const u16* __restrict__ Bt, int ldb, int K, int brow, int bcol, int orow, int ocol) {
;     ...
;     for (int m = 0; m < 4; ++m) {
;       const int rA = row0 + ai * HALF + m * 16 + (odd ? 2 : 0);
;       float gate[2] = {0.f, 0.f};
;       if (EPI == EPI_MOE2) { gate[0] = ((const float*)(ws + O_SELG))[rA]; gate[1] = ((const float*)(ws + O_SELG))[rA + 1]; }
; #pragma unroll
;       for (int bj = 0; bj < (EPI == EPI_HID ? 1 : 2); ++bj)
; #pragma unroll
;         for (int n = 0; n < 2; ++n) {
;           const int cc = bj * HALF + n * 16;
;           f32x4 v = acc[ai][bj][m][n];
;           if (EPI == EPI_HID) {
; #pragma unroll
;             for (int j = 0; j < 4; ++j) { const float a1 = acc[ai][0][m][n][j], a3 = acc[ai][1][m][n][j]; v[j] = a1 * sigm(a1) * a3; }
;           }
;           float lo[2], hi[2];
;           xchg_pairs(v, odd, lo, hi);
; #pragma unroll
;           for (int k = 0; k < 2; ++k) {
;             const unsigned row = (unsigned)(rA + k);
;             if (EPI == EPI_HID) {
;               *(unsigned*)(ws + O_HID + (row * 1024u + (unsigned)(colp + cc)) * 2u) = pk2(lo[k], hi[k]);
;             } else if (EPI == EPI_COLS) {
;               *(unsigned*)(ws + O_COLS + (row * (unsigned)NCP + (unsigned)(colp + cc)) * 2u) = pk2(lo[k], hi[k]);
;             } else if (EPI == EPI_MOE2) {
;               *(unsigned*)(ws + O_EO + (row * 2048u + (unsigned)(colp + cc)) * 2u) = pk2(gate[k] * lo[k], gate[k] * hi[k]);
	v_mul_f32_e32 v36, v150, v36
	v_mul_f32_e32 v38, v150, v38
	v_mul_f32_e32 v37, v151, v37
	v_mul_f32_e32 v39, v151, v39
	v_mul_f32_e32 v32, v150, v32
	v_mul_f32_e32 v34, v150, v34
	v_mul_f32_e32 v33, v151, v33
	v_mul_f32_e32 v35, v151, v35
	v_mul_f32_e32 v44, v150, v44
	v_mul_f32_e32 v46, v150, v46
	v_mul_f32_e32 v45, v151, v45
	v_mul_f32_e32 v47, v151, v47
	v_mul_f32_e32 v40, v150, v40
	v_mul_f32_e32 v42, v150, v42
	v_mul_f32_e32 v41, v151, v41
	v_mul_f32_e32 v43, v151, v43
	v_cvt_pk_bf16_f32 v36, v36, v38
	v_cvt_pk_bf16_f32 v37, v37, v39
	v_cvt_pk_bf16_f32 v32, v32, v34
	v_cvt_pk_bf16_f32 v33, v33, v35
	v_cvt_pk_bf16_f32 v34, v44, v46
	v_cvt_pk_bf16_f32 v35, v45, v47
	v_cvt_pk_bf16_f32 v38, v40, v42
	v_cvt_pk_bf16_f32 v39, v41, v43
	global_store_dword v49, v36, s[8:9]
	global_store_dword v60, v37, s[8:9]
	global_store_dword v52, v32, s[8:9]
	global_store_dword v61, v33, s[8:9]
	global_store_dword v54, v34, s[8:9]
	global_store_dword v62, v35, s[8:9]
	global_store_dword v48, v38, s[8:9]
	global_store_dword v53, v39, s[8:9]
	v_add_u32_e32 v149, 0xb0, v128
	v_ashrrev_i32_e32 v153, 31, v149
	v_mov_b32_e32 v154, v149
	v_mov_b32_e32 v155, v153
	v_lshl_add_u64 v[156:157], v[154:155], 2, s[0:1]
	global_load_dwordx2 v[150:151], v[156:157], off
	v_add_u32_e32 v32, 0xa0, v128
	v_ashrrev_i32_e32 v33, 31, v32
	v_lshl_add_u64 v[34:35], v[32:33], 2, s[0:1]
	s_nop 0
	v_cndmask_b32_e32 v33, v20, v22, vcc
	v_cndmask_b32_e32 v36, v21, v23, vcc
	v_cndmask_b32_e32 v38, v16, v18, vcc
	v_cndmask_b32_e32 v39, v17, v19, vcc
	v_cndmask_b32_e32 v40, v28, v30, vcc
	v_cndmask_b32_e32 v41, v29, v31, vcc
	v_cndmask_b32_e32 v42, v24, v26, vcc
	v_cndmask_b32_e32 v43, v25, v27, vcc
	v_mov_b32_dpp v33, v33 quad_perm:[1,0,3,2] row_mask:0xf bank_mask:0xf bound_ctrl:1
	v_mov_b32_dpp v36, v36 quad_perm:[1,0,3,2] row_mask:0xf bank_mask:0xf bound_ctrl:1
	v_mov_b32_dpp v38, v38 quad_perm:[1,0,3,2] row_mask:0xf bank_mask:0xf bound_ctrl:1
	v_mov_b32_dpp v39, v39 quad_perm:[1,0,3,2] row_mask:0xf bank_mask:0xf bound_ctrl:1
	v_mov_b32_dpp v40, v40 quad_perm:[1,0,3,2] row_mask:0xf bank_mask:0xf bound_ctrl:1
	v_mov_b32_dpp v41, v41 quad_perm:[1,0,3,2] row_mask:0xf bank_mask:0xf bound_ctrl:1
	v_mov_b32_dpp v42, v42 quad_perm:[1,0,3,2] row_mask:0xf bank_mask:0xf bound_ctrl:1
	v_mov_b32_dpp v43, v43 quad_perm:[1,0,3,2] row_mask:0xf bank_mask:0xf bound_ctrl:1
	v_cndmask_b32_e32 v20, v33, v20, vcc
	v_cndmask_b32_e32 v22, v22, v33, vcc
	v_lshlrev_b32_e32 v32, 12, v32
	v_cndmask_b32_e32 v21, v36, v21, vcc
	v_cndmask_b32_e32 v23, v23, v36, vcc
	v_cndmask_b32_e32 v16, v38, v16, vcc
	v_cndmask_b32_e32 v18, v18, v38, vcc
	v_cndmask_b32_e32 v17, v39, v17, vcc
	v_cndmask_b32_e32 v19, v19, v39, vcc
	v_cndmask_b32_e32 v28, v40, v28, vcc
	v_cndmask_b32_e32 v30, v30, v40, vcc
	v_cndmask_b32_e32 v29, v41, v29, vcc
	v_cndmask_b32_e32 v31, v31, v41, vcc
	v_cndmask_b32_e32 v24, v42, v24, vcc
	v_cndmask_b32_e32 v26, v26, v42, vcc
	v_cndmask_b32_e32 v25, v43, v25, vcc
	v_cndmask_b32_e32 v27, v27, v43, vcc
	v_add_u32_e32 v37, 0xa1000, v131
	v_add_u32_e32 v33, v32, v129
	v_add_u32_e32 v44, v37, v129
	v_add_u32_e32 v45, v37, v118
	v_add_u32_e32 v46, v37, v116
	v_add_u32_e32 v37, v37, v130
	v_add_u32_e32 v36, v32, v118
	v_add_u32_e32 v38, v32, v116
	v_add_u32_e32 v32, v32, v130
	s_waitcnt vmcnt(9)
; DEVINL float sigm(float x) { return 1.f / (1.f + __expf(-x)); }
; template <int EPI, bool GATHER>
; DEVINL void gemm_tile(const Params& p, const u16* __restrict__ A, int lda, const int* __restrict__ rowidx,
;                       const u16* __restrict__ Bt, int ldb, int K, int brow, int bcol, int orow, int ocol) {
;     ...
;     for (int m = 0; m < 4; ++m) {
;       const int rA = row0 + ai * HALF + m * 16 + (odd ? 2 : 0);
;       float gate[2] = {0.f, 0.f};
;       if (EPI == EPI_MOE2) { gate[0] = ((const float*)(ws + O_SELG))[rA]; gate[1] = ((const float*)(ws + O_SELG))[rA + 1]; }
; #pragma unroll
;       for (int bj = 0; bj < (EPI == EPI_HID ? 1 : 2); ++bj)
; #pragma unroll
;         for (int n = 0; n < 2; ++n) {
;           const int cc = bj * HALF + n * 16;
;           f32x4 v = acc[ai][bj][m][n];
;           if (EPI == EPI_HID) {
; #pragma unroll
;             for (int j = 0; j < 4; ++j) { const float a1 = acc[ai][0][m][n][j], a3 = acc[ai][1][m][n][j]; v[j] = a1 * sigm(a1) * a3; }
;           }
;           float lo[2], hi[2];
;           xchg_pairs(v, odd, lo, hi);
; #pragma unroll
;           for (int k = 0; k < 2; ++k) {
;             const unsigned row = (unsigned)(rA + k);
;             if (EPI == EPI_HID) {
;               *(unsigned*)(ws + O_HID + (row * 1024u + (unsigned)(colp + cc)) * 2u) = pk2(lo[k], hi[k]);
;             } else if (EPI == EPI_COLS) {
;               *(unsigned*)(ws + O_COLS + (row * (unsigned)NCP + (unsigned)(colp + cc)) * 2u) = pk2(lo[k], hi[k]);
;             } else if (EPI == EPI_MOE2) {
;               *(unsigned*)(ws + O_EO + (row * 2048u + (unsigned)(colp + cc)) * 2u) = pk2(gate[k] * lo[k], gate[k] * hi[k]);
	v_mul_f32_e32 v20, v146, v20
	v_mul_f32_e32 v22, v146, v22
	v_mul_f32_e32 v21, v147, v21
	v_mul_f32_e32 v23, v147, v23
	v_mul_f32_e32 v16, v146, v16
	v_mul_f32_e32 v18, v146, v18
	v_mul_f32_e32 v17, v147, v17
	v_mul_f32_e32 v19, v147, v19
	v_mul_f32_e32 v28, v146, v28
	v_mul_f32_e32 v30, v146, v30
	v_mul_f32_e32 v29, v147, v29
	v_mul_f32_e32 v31, v147, v31
	v_mul_f32_e32 v24, v146, v24
	v_mul_f32_e32 v26, v146, v26
	v_mul_f32_e32 v25, v147, v25
	v_mul_f32_e32 v27, v147, v27
	v_cvt_pk_bf16_f32 v20, v20, v22
	v_cvt_pk_bf16_f32 v21, v21, v23
	v_cvt_pk_bf16_f32 v16, v16, v18
	v_cvt_pk_bf16_f32 v17, v17, v19
	v_cvt_pk_bf16_f32 v18, v28, v30
	v_cvt_pk_bf16_f32 v19, v29, v31
	v_cvt_pk_bf16_f32 v22, v24, v26
	v_cvt_pk_bf16_f32 v23, v25, v27
	global_store_dword v33, v20, s[8:9]
	global_store_dword v44, v21, s[8:9]
	global_store_dword v36, v16, s[8:9]
	global_store_dword v45, v17, s[8:9]
	global_store_dword v38, v18, s[8:9]
	global_store_dword v46, v19, s[8:9]
	global_store_dword v32, v22, s[8:9]
	global_store_dword v37, v23, s[8:9]
	v_add_u32_e32 v16, 0xb0, v128
	v_ashrrev_i32_e32 v17, 31, v16
	v_lshl_add_u64 v[18:19], v[16:17], 2, s[0:1]
	s_nop 0
	v_cndmask_b32_e32 v17, v4, v6, vcc
	v_cndmask_b32_e32 v20, v5, v7, vcc
	v_cndmask_b32_e32 v22, v0, v2, vcc
	v_cndmask_b32_e32 v23, v1, v3, vcc
	v_cndmask_b32_e32 v24, v12, v14, vcc
	v_cndmask_b32_e32 v25, v13, v15, vcc
	v_cndmask_b32_e32 v26, v8, v10, vcc
	v_cndmask_b32_e32 v27, v9, v11, vcc
	v_mov_b32_dpp v17, v17 quad_perm:[1,0,3,2] row_mask:0xf bank_mask:0xf bound_ctrl:1
	v_mov_b32_dpp v20, v20 quad_perm:[1,0,3,2] row_mask:0xf bank_mask:0xf bound_ctrl:1
	v_mov_b32_dpp v22, v22 quad_perm:[1,0,3,2] row_mask:0xf bank_mask:0xf bound_ctrl:1
	v_mov_b32_dpp v23, v23 quad_perm:[1,0,3,2] row_mask:0xf bank_mask:0xf bound_ctrl:1
	v_mov_b32_dpp v24, v24 quad_perm:[1,0,3,2] row_mask:0xf bank_mask:0xf bound_ctrl:1
	v_mov_b32_dpp v25, v25 quad_perm:[1,0,3,2] row_mask:0xf bank_mask:0xf bound_ctrl:1
	v_mov_b32_dpp v26, v26 quad_perm:[1,0,3,2] row_mask:0xf bank_mask:0xf bound_ctrl:1
	v_mov_b32_dpp v27, v27 quad_perm:[1,0,3,2] row_mask:0xf bank_mask:0xf bound_ctrl:1
	v_cndmask_b32_e32 v4, v17, v4, vcc
	v_cndmask_b32_e32 v6, v6, v17, vcc
	v_lshlrev_b32_e32 v16, 12, v16
	v_cndmask_b32_e32 v5, v20, v5, vcc
	v_cndmask_b32_e32 v7, v7, v20, vcc
	v_cndmask_b32_e32 v0, v22, v0, vcc
	v_cndmask_b32_e32 v2, v2, v22, vcc
	v_cndmask_b32_e32 v1, v23, v1, vcc
	v_cndmask_b32_e32 v3, v3, v23, vcc
	v_cndmask_b32_e32 v12, v24, v12, vcc
	v_cndmask_b32_e32 v14, v14, v24, vcc
	v_cndmask_b32_e32 v13, v25, v13, vcc
	v_cndmask_b32_e32 v15, v15, v25, vcc
	v_cndmask_b32_e32 v8, v26, v8, vcc
	v_cndmask_b32_e32 v10, v10, v26, vcc
	v_cndmask_b32_e32 v9, v27, v9, vcc
	v_cndmask_b32_e32 v11, v11, v27, vcc
	v_add_u32_e32 v21, 0xb1000, v131
	v_add_u32_e32 v17, v16, v129
	v_add_u32_e32 v28, v21, v129
	v_add_u32_e32 v29, v21, v118
	v_add_u32_e32 v30, v21, v116
	v_add_u32_e32 v21, v21, v130
	v_add_u32_e32 v20, v16, v118
	v_add_u32_e32 v22, v16, v116
	v_add_u32_e32 v16, v16, v130
	s_waitcnt vmcnt(8)
	v_mul_f32_e32 v4, v150, v4
	v_mul_f32_e32 v6, v150, v6
	v_mul_f32_e32 v5, v151, v5
	v_mul_f32_e32 v7, v151, v7
	v_mul_f32_e32 v0, v150, v0
	v_mul_f32_e32 v2, v150, v2
	v_mul_f32_e32 v1, v151, v1
	v_mul_f32_e32 v3, v151, v3
	v_mul_f32_e32 v12, v150, v12
	v_mul_f32_e32 v14, v150, v14
	v_mul_f32_e32 v13, v151, v13
	v_mul_f32_e32 v15, v151, v15
	v_mul_f32_e32 v8, v150, v8
	v_mul_f32_e32 v10, v150, v10
	v_mul_f32_e32 v9, v151, v9
	v_mul_f32_e32 v11, v151, v11
	v_cvt_pk_bf16_f32 v4, v4, v6
	v_cvt_pk_bf16_f32 v5, v5, v7
	v_cvt_pk_bf16_f32 v0, v0, v2
	v_cvt_pk_bf16_f32 v1, v1, v3
	v_cvt_pk_bf16_f32 v2, v12, v14
	v_cvt_pk_bf16_f32 v3, v13, v15
	v_cvt_pk_bf16_f32 v6, v8, v10
	v_cvt_pk_bf16_f32 v7, v9, v11
	global_store_dword v17, v4, s[8:9]
	global_store_dword v28, v5, s[8:9]
	global_store_dword v20, v0, s[8:9]
	global_store_dword v29, v1, s[8:9]
	global_store_dword v22, v2, s[8:9]
	global_store_dword v30, v3, s[8:9]
	global_store_dword v16, v6, s[8:9]
	global_store_dword v21, v7, s[8:9]
	s_add_i32 s2, s2, s94
	s_add_i32 s48, s48, s94
	s_add_i32 s39, s39, s40
	s_add_i32 s47, s47, s60
	s_cmpk_lt_i32 s2, 0x200
	s_barrier
	s_cbranch_scc0 .LBB0_1037
